# IEEE f32 division expansions (div_scale/fmas/fixup) replaced by v_rcp_f32 + mul in sigmoid/silu/gelu epilogues
# speedup vs baseline: 1.0407x; 1.0407x over previous
; DI float sigm(float x) { return 1.f / (1.f + __expf(-x)); }
; DI u32x4 pack8(const float* f) { u32x4 o; o.x = pack2(f[0], f[1]); o.y = pack2(f[2], f[3]); o.z = pack2(f[4], f[5]); o.w = pack2(f[6], f[7]); return o; }
; DI void lds_barrier() { asm volatile("s_waitcnt lgkmcnt(0)\n\ts_barrier" ::: "memory"); }
; DI int tid512() { int t = threadIdx.x; asm volatile("" : "+v"(t)); return t; }
; template <int AI, int BJ>
; DI void stage_q(const f32x4 (&acc)[2][2][4][2], float* Cs) {
;   const int t = tid512(), wid = t >> 6, lane = t & 63, wr = wid >> 2, wc = wid & 3, fr = lane & 15, fq = lane >> 4;
;   lds_barrier();
; #pragma unroll
;   for (int m = 0; m < 4; ++m)
; #pragma unroll
;     for (int n = 0; n < 2; ++n)
; #pragma unroll
;       for (int j = 0; j < 4; ++j) Cs[(wr * 64 + m * 16 + fq * 4 + j) * CST + wc * 32 + n * 16 + fr] = acc[AI][BJ][m][n][j];
;   lds_barrier();
; }
; template <int AI, int BJ, int PASS>
; DI void f3_proc(PREF p, const f32x4 (&acc)[2][2][4][2], int mt, int dt, float* Cs, const u32x4 (&g)[4]) {
;   const int t = tid512();
;   const int row0 = mt * 256 + AI * 128, col0 = dt * 256 + BJ * 128;
;   const int c = (t & 15) * 8;
;   stage_q<AI, BJ>(acc, Cs);
; #pragma unroll
;   for (int q = 0; q < 4; ++q) {
;     int r = (t >> 4) + 32 * q;
;     float v[8]; ld8(Cs + r * CST + c, v);
;     if (PASS == 0) {
; #pragma unroll
;       for (int j = 0; j < 8; ++j) v[j] = sigm(v[j]);
;     } else {
;       float gf[8]; unpack8(g[q], gf);
; #pragma unroll
;       for (int j = 0; j < 8; ++j) v[j] *= gf[j];
;     }
;     *(u32x4*)((u16*)p.fbuf + (size_t)(row0 + r) * 1024 + col0 + c) = pack8(v);
;   }
; }
.LBB0_43:
	s_or_b64 exec, exec, s[16:17]
	v_mov_b32_e32 v132, v168
	s_lshl_b32 s24, s35, 8
	v_lshlrev_b32_e32 v0, 3, v132
	v_and_b32_e32 v133, 0x78, v0
	v_mov_b32_e32 v0, v168
	s_waitcnt lgkmcnt(0)
	s_barrier
	s_nop 0
	v_and_b32_e32 v130, 15, v0
	v_lshrrev_b32_e32 v131, 2, v0
	v_lshlrev_b32_e32 v0, 1, v0
	v_lshlrev_b32_e32 v130, 2, v130
	v_and_b32_e32 v131, 0xfffffcc, v131
	v_and_or_b32 v0, v0, s89, v130
	v_mad_u64_u32 v[130:131], s[0:1], v131, s92, v[0:1]
	v_add_u32_e32 v0, 0x400, v130
	ds_write2_b32 v130, v118, v126 offset1:16
	ds_write2_b32 v130, v119, v127 offset0:132 offset1:148
	ds_write2_b32 v0, v120, v128 offset0:8 offset1:24
	ds_write2_b32 v0, v121, v129 offset0:140 offset1:156
	v_add_u32_e32 v0, 0x2000, v130
	ds_write2_b32 v0, v114, v122 offset0:64 offset1:80
	ds_write2_b32 v0, v115, v123 offset0:196 offset1:212
	v_add_u32_e32 v0, 0x2400, v130
	ds_write2_b32 v0, v116, v124 offset0:72 offset1:88
	ds_write2_b32 v0, v117, v125 offset0:204 offset1:220
	v_add_u32_e32 v0, 0x4000, v130
	ds_write2_b32 v0, v106, v110 offset0:128 offset1:144
	v_add_u32_e32 v0, 0x4400, v130
	ds_write2_b32 v0, v107, v111 offset0:4 offset1:20
	ds_write2_b32 v0, v108, v112 offset0:136 offset1:152
	v_add_u32_e32 v0, 0x4800, v130
	ds_write2_b32 v0, v109, v113 offset0:12 offset1:28
	v_add_u32_e32 v0, 0x6000, v130
	ds_write2_b32 v0, v98, v102 offset0:192 offset1:208
	v_add_u32_e32 v0, 0x6400, v130
	ds_write2_b32 v0, v99, v103 offset0:68 offset1:84
	ds_write2_b32 v0, v100, v104 offset0:200 offset1:216
	v_add_u32_e32 v0, 0x6800, v130
	v_ashrrev_i32_e32 v100, 4, v132
	ds_write2_b32 v0, v101, v105 offset0:76 offset1:92
	v_mul_lo_u32 v0, v100, s92
	s_waitcnt lgkmcnt(0)
	s_barrier
	v_lshl_add_u32 v102, v133, 2, v0
	s_waitcnt vmcnt(0)
	ds_read_b128 v[104:107], v102
	ds_read_b128 v[108:111], v102 offset:16
	s_lshl_b32 s0, s18, 8
	s_ashr_i32 s1, s0, 31
	s_lshl_b64 s[0:1], s[0:1], 1
	s_waitcnt lgkmcnt(1)
	v_mul_f32_e32 v0, 0xbfb8aa3b, v104
	v_exp_f32_e32 v0, v0
	s_add_u32 s16, s14, s0
	s_addc_u32 s17, s15, s1
	v_mul_f32_e32 v105, 0xbfb8aa3b, v105
	v_add_f32_e32 v101, 1.0, v0
	v_lshlrev_b32_e32 v0, 1, v133
	v_lshl_add_u64 v[98:99], s[16:17], 0, v[0:1]
	v_exp_f32_e32 v105, v105
	s_nop 0
	v_add_f32_e32 v103, 1.0, v105
	v_rcp_f32_e32 v0, v101
	v_mul_f32_e32 v106, 0xbfb8aa3b, v106
	v_exp_f32_e32 v106, v106
	s_nop 0
	v_add_f32_e32 v105, 1.0, v106
	v_rcp_f32_e32 v101, v103
	v_mul_f32_e32 v107, 0xbfb8aa3b, v107
	v_exp_f32_e32 v107, v107
	s_nop 0
	v_add_f32_e32 v106, 1.0, v107
	s_waitcnt lgkmcnt(0)
	v_mul_f32_e32 v108, 0xbfb8aa3b, v108
	v_exp_f32_e32 v108, v108
	v_rcp_f32_e32 v103, v105
	v_add_f32_e32 v107, 1.0, v108
	v_rcp_f32_e32 v113, v106
	v_mul_f32_e32 v106, 0xbfb8aa3b, v109
	v_exp_f32_e32 v106, v106
	s_nop 0
	v_add_f32_e32 v106, 1.0, v106
	v_rcp_f32_e32 v112, v107
	v_mul_f32_e32 v107, 0xbfb8aa3b, v110
	v_exp_f32_e32 v107, v107
	s_nop 0
	v_add_f32_e32 v107, 1.0, v107
	v_rcp_f32_e32 v114, v106
	v_mul_f32_e32 v106, 0xbfb8aa3b, v111
	v_exp_f32_e32 v106, v106
	s_nop 0
	v_add_f32_e32 v106, 1.0, v106
	v_rcp_f32_e32 v111, v107
	v_cvt_pk_bf16_f32 v110, v112, v114
	s_nop 1
	v_rcp_f32_e32 v116, v106
	ds_read_b128 v[104:107], v102 offset:16896
	v_cvt_pk_bf16_f32 v108, v0, v101
	s_nop 1
	v_cvt_pk_bf16_f32 v109, v103, v113
	s_nop 1
	ds_read_b128 v[112:115], v102 offset:16912
	v_add_u32_e32 v100, s24, v100
	s_waitcnt lgkmcnt(1)
	v_mul_f32_e32 v0, 0xbfb8aa3b, v104
	v_exp_f32_e32 v0, v0
	v_ashrrev_i32_e32 v101, 31, v100
	v_cvt_pk_bf16_f32 v111, v111, v116
	s_nop 1
	v_lshlrev_b64 v[116:117], 11, v[100:101]
	v_add_f32_e32 v0, 1.0, v0
	v_mul_f32_e32 v105, 0xbfb8aa3b, v105
	v_lshl_add_u64 v[116:117], v[98:99], 0, v[116:117]
	v_exp_f32_e32 v105, v105
	global_store_dwordx4 v[116:117], v[108:111], off
	v_mul_f32_e32 v106, 0xbfb8aa3b, v106
	v_exp_f32_e32 v106, v106
	v_add_f32_e32 v103, 1.0, v105
	v_rcp_f32_e32 v0, v0
	v_mul_f32_e32 v107, 0xbfb8aa3b, v107
	v_add_f32_e32 v105, 1.0, v106
	v_rcp_f32_e32 v101, v103
	v_exp_f32_e32 v107, v107
	s_nop 0
	v_add_f32_e32 v106, 1.0, v107
	s_waitcnt lgkmcnt(0)
	v_mul_f32_e32 v108, 0xbfb8aa3b, v112
	v_exp_f32_e32 v108, v108
	v_rcp_f32_e32 v103, v105
	v_add_f32_e32 v107, 1.0, v108
	v_rcp_f32_e32 v109, v106
	v_mul_f32_e32 v106, 0xbfb8aa3b, v113
	v_exp_f32_e32 v106, v106
	s_nop 0
	v_add_f32_e32 v106, 1.0, v106
	v_rcp_f32_e32 v110, v107
	v_mul_f32_e32 v107, 0xbfb8aa3b, v114
	v_exp_f32_e32 v107, v107
	s_nop 0
	v_add_f32_e32 v107, 1.0, v107
	v_rcp_f32_e32 v111, v106
	v_mul_f32_e32 v106, 0xbfb8aa3b, v115
	v_exp_f32_e32 v106, v106
	s_nop 0
	v_add_f32_e32 v106, 1.0, v106
	v_rcp_f32_e32 v116, v107
	v_cvt_pk_bf16_f32 v109, v103, v109
	s_nop 1
	v_rcp_f32_e32 v117, v106
	ds_read_b128 v[104:107], v102 offset:33792
	ds_read_b128 v[112:115], v102 offset:33808
	v_cvt_pk_bf16_f32 v108, v0, v101
	s_nop 1
	v_cvt_pk_bf16_f32 v110, v110, v111
	s_nop 1
	v_cvt_pk_bf16_f32 v111, v116, v117
	s_nop 1
	s_waitcnt lgkmcnt(1)
	v_mul_f32_e32 v0, 0xbfb8aa3b, v104
	v_exp_f32_e32 v0, v0
	v_add_u32_e32 v116, 32, v100
	v_ashrrev_i32_e32 v117, 31, v116
	v_lshlrev_b64 v[116:117], 11, v[116:117]
	v_add_f32_e32 v0, 1.0, v0
	v_mul_f32_e32 v105, 0xbfb8aa3b, v105
	v_lshl_add_u64 v[116:117], v[98:99], 0, v[116:117]
	v_exp_f32_e32 v105, v105
	global_store_dwordx4 v[116:117], v[108:111], off
	v_mul_f32_e32 v106, 0xbfb8aa3b, v106
	v_exp_f32_e32 v106, v106
	v_add_f32_e32 v104, 1.0, v105
	v_rcp_f32_e32 v0, v0
	v_mul_f32_e32 v107, 0xbfb8aa3b, v107
	v_add_f32_e32 v105, 1.0, v106
	v_exp_f32_e32 v107, v107
	v_rcp_f32_e32 v101, v104
	v_add_f32_e32 v106, 1.0, v107
	s_waitcnt lgkmcnt(0)
; DI float sigm(float x) { return 1.f / (1.f + __expf(-x)); }
; DI u32x4 pack8(const float* f) { u32x4 o; o.x = pack2(f[0], f[1]); o.y = pack2(f[2], f[3]); o.z = pack2(f[4], f[5]); o.w = pack2(f[6], f[7]); return o; }
; DI void lds_barrier() { asm volatile("s_waitcnt lgkmcnt(0)\n\ts_barrier" ::: "memory"); }
; DI int tid512() { int t = threadIdx.x; asm volatile("" : "+v"(t)); return t; }
; template <int AI, int BJ>
; DI void stage_q(const f32x4 (&acc)[2][2][4][2], float* Cs) {
;   const int t = tid512(), wid = t >> 6, lane = t & 63, wr = wid >> 2, wc = wid & 3, fr = lane & 15, fq = lane >> 4;
;   lds_barrier();
; #pragma unroll
;   for (int m = 0; m < 4; ++m)
; #pragma unroll
;     for (int n = 0; n < 2; ++n)
; #pragma unroll
;       for (int j = 0; j < 4; ++j) Cs[(wr * 64 + m * 16 + fq * 4 + j) * CST + wc * 32 + n * 16 + fr] = acc[AI][BJ][m][n][j];
;   lds_barrier();
; }
; template <int AI, int BJ, int PASS>
; DI void f3_proc(PREF p, const f32x4 (&acc)[2][2][4][2], int mt, int dt, float* Cs, const u32x4 (&g)[4]) {
;   const int t = tid512();
;   const int row0 = mt * 256 + AI * 128, col0 = dt * 256 + BJ * 128;
;   const int c = (t & 15) * 8;
;   stage_q<AI, BJ>(acc, Cs);
; #pragma unroll
;   for (int q = 0; q < 4; ++q) {
;     int r = (t >> 4) + 32 * q;
;     float v[8]; ld8(Cs + r * CST + c, v);
;     if (PASS == 0) {
; #pragma unroll
;       for (int j = 0; j < 8; ++j) v[j] = sigm(v[j]);
;     } else {
;       float gf[8]; unpack8(g[q], gf);
; #pragma unroll
;       for (int j = 0; j < 8; ++j) v[j] *= gf[j];
;     }
;     *(u32x4*)((u16*)p.fbuf + (size_t)(row0 + r) * 1024 + col0 + c) = pack8(v);
;   }
; }
	v_mul_f32_e32 v108, 0xbfb8aa3b, v112
	v_exp_f32_e32 v108, v108
	v_rcp_f32_e32 v103, v105
	v_add_f32_e32 v107, 1.0, v108
	v_rcp_f32_e32 v109, v106
	v_mul_f32_e32 v106, 0xbfb8aa3b, v113
	v_exp_f32_e32 v106, v106
	s_nop 0
	v_add_f32_e32 v106, 1.0, v106
	v_rcp_f32_e32 v110, v107
	v_mul_f32_e32 v107, 0xbfb8aa3b, v114
	v_exp_f32_e32 v107, v107
	s_nop 0
	v_add_f32_e32 v107, 1.0, v107
	v_rcp_f32_e32 v111, v106
	v_mul_f32_e32 v106, 0xbfb8aa3b, v115
	v_exp_f32_e32 v106, v106
	s_nop 0
	v_add_f32_e32 v106, 1.0, v106
	v_rcp_f32_e32 v116, v107
	v_cvt_pk_bf16_f32 v109, v103, v109
	s_nop 1
	v_rcp_f32_e32 v117, v106
	ds_read_b128 v[104:107], v102 offset:50688
	ds_read_b128 v[112:115], v102 offset:50704
	v_cvt_pk_bf16_f32 v108, v0, v101
	s_nop 1
	v_add_u32_e32 v102, 64, v100
	v_ashrrev_i32_e32 v103, 31, v102
	s_waitcnt lgkmcnt(1)
	v_mul_f32_e32 v0, 0xbfb8aa3b, v104
	v_exp_f32_e32 v0, v0
	v_lshlrev_b64 v[102:103], 11, v[102:103]
	v_lshl_add_u64 v[102:103], v[98:99], 0, v[102:103]
	v_cvt_pk_bf16_f32 v110, v110, v111
	s_nop 1
	v_add_f32_e32 v0, 1.0, v0
	v_cvt_pk_bf16_f32 v111, v116, v117
	s_nop 1
	global_store_dwordx4 v[102:103], v[108:111], off
	v_mul_f32_e32 v105, 0xbfb8aa3b, v105
	v_exp_f32_e32 v105, v105
	s_nop 0
	v_add_f32_e32 v102, 1.0, v105
	v_mul_f32_e32 v104, 0xbfb8aa3b, v106
	v_rcp_f32_e32 v0, v0
	v_exp_f32_e32 v104, v104
	s_nop 0
	v_add_f32_e32 v104, 1.0, v104
	v_rcp_f32_e32 v101, v102
	v_mul_f32_e32 v107, 0xbfb8aa3b, v107
	v_exp_f32_e32 v107, v107
	s_nop 0
	v_add_f32_e32 v105, 1.0, v107
	s_waitcnt lgkmcnt(0)
	v_mul_f32_e32 v106, 0xbfb8aa3b, v112
	v_rcp_f32_e32 v103, v104
	v_exp_f32_e32 v106, v106
	s_nop 0
	v_add_f32_e32 v106, 1.0, v106
	v_rcp_f32_e32 v104, v105
	v_mul_f32_e32 v108, 0xbfb8aa3b, v113
	v_exp_f32_e32 v108, v108
	s_nop 0
	v_add_f32_e32 v107, 1.0, v108
	v_rcp_f32_e32 v105, v106
	v_mul_f32_e32 v109, 0xbfb8aa3b, v114
	v_exp_f32_e32 v109, v109
	s_nop 0
	v_add_f32_e32 v108, 1.0, v109
	v_rcp_f32_e32 v106, v107
	v_mul_f32_e32 v110, 0xbfb8aa3b, v115
	v_exp_f32_e32 v110, v110
	s_nop 0
	v_add_f32_e32 v109, 1.0, v110
	v_rcp_f32_e32 v107, v108
	v_add_u32_e32 v100, 0x60, v100
	v_rcp_f32_e32 v108, v109
	v_cvt_pk_bf16_f32 v102, v0, v101
	s_nop 1
	v_ashrrev_i32_e32 v101, 31, v100
	v_lshlrev_b64 v[100:101], 11, v[100:101]
	v_lshl_add_u64 v[98:99], v[98:99], 0, v[100:101]
	v_mov_b32_e32 v100, v168
	v_cvt_pk_bf16_f32 v103, v103, v104
	s_nop 1
	v_cvt_pk_bf16_f32 v104, v105, v106
	s_nop 1
	v_cvt_pk_bf16_f32 v105, v107, v108
	s_nop 1
	global_store_dwordx4 v[98:99], v[102:105], off
	s_or_b32 s25, s24, 0x80
	v_lshlrev_b32_e32 v0, 3, v100
	v_and_b32_e32 v101, 0x78, v0
	v_mov_b32_e32 v0, v168
	s_waitcnt lgkmcnt(0)
	s_barrier
	s_nop 0
	v_and_b32_e32 v98, 15, v0
	v_lshrrev_b32_e32 v99, 2, v0
	v_lshlrev_b32_e32 v0, 1, v0
	v_lshlrev_b32_e32 v98, 2, v98
	v_and_b32_e32 v99, 0xfffffcc, v99
	v_and_or_b32 v0, v0, s89, v98
	v_mad_u64_u32 v[98:99], s[0:1], v99, s92, v[0:1]
	v_add_u32_e32 v0, 0x400, v98
	ds_write2_b32 v98, v86, v94 offset1:16
	ds_write2_b32 v98, v87, v95 offset0:132 offset1:148
	ds_write2_b32 v0, v88, v96 offset0:8 offset1:24
	ds_write2_b32 v0, v89, v97 offset0:140 offset1:156
	v_add_u32_e32 v0, 0x2000, v98
	ds_write2_b32 v0, v82, v90 offset0:64 offset1:80
	ds_write2_b32 v0, v83, v91 offset0:196 offset1:212
	v_add_u32_e32 v0, 0x2400, v98
	ds_write2_b32 v0, v84, v92 offset0:72 offset1:88
	ds_write2_b32 v0, v85, v93 offset0:204 offset1:220
	v_add_u32_e32 v0, 0x4000, v98
	ds_write2_b32 v0, v74, v78 offset0:128 offset1:144
	v_add_u32_e32 v0, 0x4400, v98
	ds_write2_b32 v0, v75, v79 offset0:4 offset1:20
	ds_write2_b32 v0, v76, v80 offset0:136 offset1:152
	v_add_u32_e32 v0, 0x4800, v98
	ds_write2_b32 v0, v77, v81 offset0:12 offset1:28
	v_add_u32_e32 v0, 0x6000, v98
	ds_write2_b32 v0, v66, v70 offset0:192 offset1:208
	v_add_u32_e32 v0, 0x6400, v98
	ds_write2_b32 v0, v67, v71 offset0:68 offset1:84
	ds_write2_b32 v0, v68, v72 offset0:200 offset1:216
	v_add_u32_e32 v0, 0x6800, v98
	ds_write2_b32 v0, v69, v73 offset0:76 offset1:92
	v_ashrrev_i32_e32 v0, 4, v100
	v_mul_lo_u32 v66, v0, s92
	s_waitcnt lgkmcnt(0)
	s_barrier
	v_lshl_add_u32 v68, v101, 2, v66
	ds_read_b128 v[70:73], v68
	ds_read_b128 v[74:77], v68 offset:16
	s_waitcnt lgkmcnt(1)
	v_mul_f32_e32 v66, 0xbfb8aa3b, v70
	v_exp_f32_e32 v66, v66
	v_mul_f32_e32 v71, 0xbfb8aa3b, v71
	v_exp_f32_e32 v71, v71
	v_mul_f32_e32 v72, 0xbfb8aa3b, v72
	v_add_f32_e32 v66, 1.0, v66
	v_exp_f32_e32 v72, v72
	v_mul_f32_e32 v73, 0xbfb8aa3b, v73
	v_exp_f32_e32 v73, v73
	v_add_f32_e32 v70, 1.0, v71
	v_rcp_f32_e32 v66, v66
	s_waitcnt lgkmcnt(0)
	v_mul_f32_e32 v74, 0xbfb8aa3b, v74
	v_add_f32_e32 v71, 1.0, v72
	v_rcp_f32_e32 v67, v70
	v_exp_f32_e32 v74, v74
	v_add_f32_e32 v72, 1.0, v73
	v_rcp_f32_e32 v69, v71
	v_mul_f32_e32 v75, 0xbfb8aa3b, v75
	v_add_f32_e32 v73, 1.0, v74
	v_rcp_f32_e32 v71, v72
	v_exp_f32_e32 v75, v75
	s_nop 0
	v_add_f32_e32 v74, 1.0, v75
	v_rcp_f32_e32 v72, v73
	v_mul_f32_e32 v76, 0xbfb8aa3b, v76
	v_exp_f32_e32 v76, v76
	s_nop 0
	v_add_f32_e32 v75, 1.0, v76
	v_rcp_f32_e32 v73, v74
	v_mul_f32_e32 v77, 0xbfb8aa3b, v77
	v_exp_f32_e32 v77, v77
	s_nop 0
	v_add_f32_e32 v76, 1.0, v77
	v_rcp_f32_e32 v78, v75
	v_cvt_pk_bf16_f32 v72, v72, v73
	s_nop 1
	v_rcp_f32_e32 v79, v76
	ds_read_b128 v[74:77], v68 offset:16896
	v_cvt_pk_bf16_f32 v70, v66, v67
	s_nop 1
	v_cvt_pk_bf16_f32 v73, v78, v79
	s_nop 1
	v_add_u32_e32 v66, s24, v0
	ds_read_b128 v[78:81], v68 offset:16912
	s_waitcnt lgkmcnt(1)
; DI float sigm(float x) { return 1.f / (1.f + __expf(-x)); }
; DI u32x4 pack8(const float* f) { u32x4 o; o.x = pack2(f[0], f[1]); o.y = pack2(f[2], f[3]); o.z = pack2(f[4], f[5]); o.w = pack2(f[6], f[7]); return o; }
; DI void lds_barrier() { asm volatile("s_waitcnt lgkmcnt(0)\n\ts_barrier" ::: "memory"); }
; DI int tid512() { int t = threadIdx.x; asm volatile("" : "+v"(t)); return t; }
; template <int AI, int BJ>
; DI void stage_q(const f32x4 (&acc)[2][2][4][2], float* Cs) {
;   const int t = tid512(), wid = t >> 6, lane = t & 63, wr = wid >> 2, wc = wid & 3, fr = lane & 15, fq = lane >> 4;
;   lds_barrier();
; #pragma unroll
;   for (int m = 0; m < 4; ++m)
; #pragma unroll
;     for (int n = 0; n < 2; ++n)
; #pragma unroll
;       for (int j = 0; j < 4; ++j) Cs[(wr * 64 + m * 16 + fq * 4 + j) * CST + wc * 32 + n * 16 + fr] = acc[AI][BJ][m][n][j];
;   lds_barrier();
; }
; template <int AI, int BJ, int PASS>
; DI void f3_proc(PREF p, const f32x4 (&acc)[2][2][4][2], int mt, int dt, float* Cs, const u32x4 (&g)[4]) {
;   const int t = tid512();
;   const int row0 = mt * 256 + AI * 128, col0 = dt * 256 + BJ * 128;
;   const int c = (t & 15) * 8;
;   stage_q<AI, BJ>(acc, Cs);
; #pragma unroll
;   for (int q = 0; q < 4; ++q) {
;     int r = (t >> 4) + 32 * q;
;     float v[8]; ld8(Cs + r * CST + c, v);
;     if (PASS == 0) {
; #pragma unroll
;       for (int j = 0; j < 8; ++j) v[j] = sigm(v[j]);
;     } else {
;       float gf[8]; unpack8(g[q], gf);
; #pragma unroll
;       for (int j = 0; j < 8; ++j) v[j] *= gf[j];
;     }
;     *(u32x4*)((u16*)p.fbuf + (size_t)(row0 + r) * 1024 + col0 + c) = pack8(v);
;   }
; }
	v_mul_f32_e32 v0, 0xbfb8aa3b, v74
	v_exp_f32_e32 v0, v0
	v_ashrrev_i32_e32 v67, 31, v66
	v_lshlrev_b64 v[82:83], 11, v[66:67]
	v_cvt_pk_bf16_f32 v71, v69, v71
	s_nop 1
	v_add_f32_e32 v67, 1.0, v0
	v_lshl_add_u64 v[82:83], s[16:17], 0, v[82:83]
	v_lshlrev_b32_e32 v0, 1, v101
	v_lshl_add_u64 v[82:83], v[82:83], 0, v[0:1]
	global_store_dwordx4 v[82:83], v[70:73], off offset:256
	v_add_u32_e32 v82, 32, v66
	v_ashrrev_i32_e32 v83, 31, v82
	v_mul_f32_e32 v72, 0xbfb8aa3b, v75
	v_exp_f32_e32 v72, v72
	s_nop 0
	v_add_f32_e32 v70, 1.0, v72
	v_rcp_f32_e32 v67, v67
	v_mul_f32_e32 v74, 0xbfb8aa3b, v76
	v_exp_f32_e32 v74, v74
	s_nop 0
	v_add_f32_e32 v72, 1.0, v74
	v_mul_f32_e32 v73, 0xbfb8aa3b, v77
	v_rcp_f32_e32 v69, v70
	v_exp_f32_e32 v73, v73
	s_nop 0
	v_add_f32_e32 v73, 1.0, v73
	v_rcp_f32_e32 v71, v72
	s_waitcnt lgkmcnt(0)
	v_mul_f32_e32 v75, 0xbfb8aa3b, v78
	v_exp_f32_e32 v75, v75
	s_nop 0
	v_add_f32_e32 v74, 1.0, v75
	v_rcp_f32_e32 v72, v73
	v_mul_f32_e32 v76, 0xbfb8aa3b, v79
	v_exp_f32_e32 v76, v76
	s_nop 0
	v_add_f32_e32 v75, 1.0, v76
	v_rcp_f32_e32 v73, v74
	v_mul_f32_e32 v77, 0xbfb8aa3b, v80
	v_exp_f32_e32 v77, v77
	s_nop 0
	v_add_f32_e32 v76, 1.0, v77
	v_rcp_f32_e32 v78, v75
	v_mul_f32_e32 v75, 0xbfb8aa3b, v81
	v_exp_f32_e32 v75, v75
	s_nop 0
	v_add_f32_e32 v75, 1.0, v75
	v_rcp_f32_e32 v79, v76
	v_cvt_pk_bf16_f32 v71, v71, v72
	s_nop 1
	v_rcp_f32_e32 v80, v75
	ds_read_b128 v[74:77], v68 offset:33792
	v_cvt_pk_bf16_f32 v70, v67, v69
	s_nop 1
	v_cvt_pk_bf16_f32 v72, v73, v78
	s_nop 1
	v_cvt_pk_bf16_f32 v73, v79, v80
	s_nop 1
	ds_read_b128 v[78:81], v68 offset:33808
	s_waitcnt lgkmcnt(1)
	v_mul_f32_e32 v67, 0xbfb8aa3b, v74
	v_exp_f32_e32 v67, v67
	v_lshlrev_b64 v[82:83], 11, v[82:83]
	v_lshl_add_u64 v[82:83], s[16:17], 0, v[82:83]
	v_lshl_add_u64 v[82:83], v[82:83], 0, v[0:1]
	v_add_f32_e32 v67, 1.0, v67
	global_store_dwordx4 v[82:83], v[70:73], off offset:256
	s_nop 1
	v_mul_f32_e32 v72, 0xbfb8aa3b, v75
	v_exp_f32_e32 v72, v72
	s_nop 0
	v_add_f32_e32 v70, 1.0, v72
	v_rcp_f32_e32 v67, v67
	v_mul_f32_e32 v74, 0xbfb8aa3b, v76
	v_exp_f32_e32 v74, v74
	s_nop 0
	v_add_f32_e32 v72, 1.0, v74
	v_mul_f32_e32 v73, 0xbfb8aa3b, v77
	v_rcp_f32_e32 v69, v70
	v_exp_f32_e32 v73, v73
	s_nop 0
	v_add_f32_e32 v73, 1.0, v73
	v_rcp_f32_e32 v71, v72
	s_waitcnt lgkmcnt(0)
	v_mul_f32_e32 v75, 0xbfb8aa3b, v78
	v_exp_f32_e32 v75, v75
	s_nop 0
	v_add_f32_e32 v74, 1.0, v75
	v_rcp_f32_e32 v72, v73
	v_mul_f32_e32 v76, 0xbfb8aa3b, v79
	v_exp_f32_e32 v76, v76
	s_nop 0
	v_add_f32_e32 v75, 1.0, v76
	v_rcp_f32_e32 v73, v74
	v_mul_f32_e32 v77, 0xbfb8aa3b, v80
	v_exp_f32_e32 v77, v77
	s_nop 0
	v_add_f32_e32 v76, 1.0, v77
	v_rcp_f32_e32 v78, v75
	v_mul_f32_e32 v75, 0xbfb8aa3b, v81
	v_exp_f32_e32 v75, v75
	s_nop 0
	v_add_f32_e32 v75, 1.0, v75
	v_rcp_f32_e32 v79, v76
	v_cvt_pk_bf16_f32 v71, v71, v72
	s_nop 1
	v_rcp_f32_e32 v80, v75
	ds_read_b128 v[74:77], v68 offset:50688
	v_cvt_pk_bf16_f32 v70, v67, v69
	s_nop 1
	v_cvt_pk_bf16_f32 v72, v73, v78
	s_nop 1
	v_cvt_pk_bf16_f32 v73, v79, v80
	s_nop 1
	ds_read_b128 v[78:81], v68 offset:50704
	s_waitcnt lgkmcnt(1)
	v_mul_f32_e32 v67, 0xbfb8aa3b, v74
	v_exp_f32_e32 v67, v67
	v_add_u32_e32 v68, 64, v66
	v_ashrrev_i32_e32 v69, 31, v68
	v_lshlrev_b64 v[68:69], 11, v[68:69]
	v_add_f32_e32 v67, 1.0, v67
	v_lshl_add_u64 v[68:69], s[16:17], 0, v[68:69]
	v_lshl_add_u64 v[68:69], v[68:69], 0, v[0:1]
	global_store_dwordx4 v[68:69], v[70:73], off offset:256
	s_nop 1
	v_mul_f32_e32 v70, 0xbfb8aa3b, v75
	s_nop 0
	v_exp_f32_e32 v70, v70
	s_nop 0
	v_add_f32_e32 v70, 1.0, v70
	v_rcp_f32_e32 v67, v67
	v_mul_f32_e32 v73, 0xbfb8aa3b, v76
	v_exp_f32_e32 v73, v73
	s_nop 0
	v_add_f32_e32 v71, 1.0, v73
	v_mul_f32_e32 v72, 0xbfb8aa3b, v77
	v_exp_f32_e32 v72, v72
	v_rcp_f32_e32 v68, v70
	v_add_f32_e32 v72, 1.0, v72
	s_waitcnt lgkmcnt(0)
	v_mul_f32_e32 v74, 0xbfb8aa3b, v78
	v_exp_f32_e32 v74, v74
	v_rcp_f32_e32 v69, v71
	v_add_f32_e32 v73, 1.0, v74
	v_mul_f32_e32 v75, 0xbfb8aa3b, v79
	v_exp_f32_e32 v75, v75
	v_rcp_f32_e32 v70, v72
	v_add_f32_e32 v74, 1.0, v75
	v_mul_f32_e32 v76, 0xbfb8aa3b, v80
	v_exp_f32_e32 v76, v76
	v_rcp_f32_e32 v71, v73
	v_add_f32_e32 v75, 1.0, v76
	v_mul_f32_e32 v77, 0xbfb8aa3b, v81
	v_exp_f32_e32 v77, v77
	v_rcp_f32_e32 v72, v74
	v_add_f32_e32 v76, 1.0, v77
	v_rcp_f32_e32 v73, v75
	v_add_u32_e32 v66, 0x60, v66
	v_cvt_pk_bf16_f32 v68, v67, v68
	s_nop 1
	v_ashrrev_i32_e32 v67, 31, v66
	v_lshlrev_b64 v[66:67], 11, v[66:67]
	v_lshl_add_u64 v[66:67], s[16:17], 0, v[66:67]
	v_lshl_add_u64 v[66:67], v[66:67], 0, v[0:1]
	v_rcp_f32_e32 v74, v76
	v_cvt_pk_bf16_f32 v69, v69, v70
	s_nop 1
	v_cvt_pk_bf16_f32 v70, v71, v72
	s_nop 1
	v_cvt_pk_bf16_f32 v71, v73, v74
	s_nop 1
	global_store_dwordx4 v[66:67], v[68:71], off offset:256
	s_nop 1
	v_mov_b32_e32 v68, v168
	s_nop 0
	v_lshlrev_b32_e32 v0, 3, v68
	v_and_b32_e32 v69, 0x78, v0
	v_mov_b32_e32 v0, v168
	s_waitcnt lgkmcnt(0)
	s_barrier
	s_nop 0
	v_and_b32_e32 v66, 15, v0
	v_lshrrev_b32_e32 v67, 2, v0
	v_lshlrev_b32_e32 v0, 1, v0
	v_lshlrev_b32_e32 v66, 2, v66
	v_and_b32_e32 v67, 0xfffffcc, v67
	v_and_or_b32 v0, v0, s89, v66
	v_mad_u64_u32 v[66:67], s[0:1], v67, s92, v[0:1]
	v_add_u32_e32 v0, 0x400, v66
	ds_write2_b32 v66, v54, v62 offset1:16
	ds_write2_b32 v66, v55, v63 offset0:132 offset1:148
	ds_write2_b32 v0, v56, v64 offset0:8 offset1:24
	ds_write2_b32 v0, v57, v65 offset0:140 offset1:156
	v_add_u32_e32 v0, 0x2000, v66
	ds_write2_b32 v0, v50, v58 offset0:64 offset1:80
	ds_write2_b32 v0, v51, v59 offset0:196 offset1:212
	v_add_u32_e32 v0, 0x2400, v66
	ds_write2_b32 v0, v52, v60 offset0:72 offset1:88
	ds_write2_b32 v0, v53, v61 offset0:204 offset1:220
	v_add_u32_e32 v0, 0x4000, v66
	ds_write2_b32 v0, v42, v46 offset0:128 offset1:144
	v_add_u32_e32 v0, 0x4400, v66
	ds_write2_b32 v0, v43, v47 offset0:4 offset1:20
	ds_write2_b32 v0, v44, v48 offset0:136 offset1:152
	v_add_u32_e32 v0, 0x4800, v66
	ds_write2_b32 v0, v45, v49 offset0:12 offset1:28
	v_add_u32_e32 v0, 0x6000, v66
	ds_write2_b32 v0, v34, v38 offset0:192 offset1:208
	v_add_u32_e32 v0, 0x6400, v66
	ds_write2_b32 v0, v35, v39 offset0:68 offset1:84
	ds_write2_b32 v0, v36, v40 offset0:200 offset1:216
	v_add_u32_e32 v0, 0x6800, v66
	v_ashrrev_i32_e32 v36, 4, v68
	ds_write2_b32 v0, v37, v41 offset0:76 offset1:92
	v_mul_lo_u32 v0, v36, s92
	s_waitcnt lgkmcnt(0)
	s_barrier
; DI float sigm(float x) { return 1.f / (1.f + __expf(-x)); }
; DI u32x4 pack8(const float* f) { u32x4 o; o.x = pack2(f[0], f[1]); o.y = pack2(f[2], f[3]); o.z = pack2(f[4], f[5]); o.w = pack2(f[6], f[7]); return o; }
; DI void lds_barrier() { asm volatile("s_waitcnt lgkmcnt(0)\n\ts_barrier" ::: "memory"); }
; DI int tid512() { int t = threadIdx.x; asm volatile("" : "+v"(t)); return t; }
; template <int AI, int BJ>
; DI void stage_q(const f32x4 (&acc)[2][2][4][2], float* Cs) {
;   const int t = tid512(), wid = t >> 6, lane = t & 63, wr = wid >> 2, wc = wid & 3, fr = lane & 15, fq = lane >> 4;
;   lds_barrier();
; #pragma unroll
;   for (int m = 0; m < 4; ++m)
; #pragma unroll
;     for (int n = 0; n < 2; ++n)
; #pragma unroll
;       for (int j = 0; j < 4; ++j) Cs[(wr * 64 + m * 16 + fq * 4 + j) * CST + wc * 32 + n * 16 + fr] = acc[AI][BJ][m][n][j];
;   lds_barrier();
; }
; template <int AI, int BJ, int PASS>
; DI void f3_proc(PREF p, const f32x4 (&acc)[2][2][4][2], int mt, int dt, float* Cs, const u32x4 (&g)[4]) {
;   const int t = tid512();
;   const int row0 = mt * 256 + AI * 128, col0 = dt * 256 + BJ * 128;
;   const int c = (t & 15) * 8;
;   stage_q<AI, BJ>(acc, Cs);
; #pragma unroll
;   for (int q = 0; q < 4; ++q) {
;     int r = (t >> 4) + 32 * q;
;     float v[8]; ld8(Cs + r * CST + c, v);
;     if (PASS == 0) {
; #pragma unroll
;       for (int j = 0; j < 8; ++j) v[j] = sigm(v[j]);
;     } else {
;       float gf[8]; unpack8(g[q], gf);
; #pragma unroll
;       for (int j = 0; j < 8; ++j) v[j] *= gf[j];
;     }
;     *(u32x4*)((u16*)p.fbuf + (size_t)(row0 + r) * 1024 + col0 + c) = pack8(v);
;   }
; }
	v_lshl_add_u32 v38, v69, 2, v0
	ds_read_b128 v[40:43], v38
	ds_read_b128 v[44:47], v38 offset:16
	v_add_u32_e32 v36, s25, v36
	s_waitcnt lgkmcnt(1)
	v_mul_f32_e32 v0, 0xbfb8aa3b, v40
	v_exp_f32_e32 v0, v0
	v_mul_f32_e32 v41, 0xbfb8aa3b, v41
	v_exp_f32_e32 v41, v41
	v_mul_f32_e32 v42, 0xbfb8aa3b, v42
	v_add_f32_e32 v37, 1.0, v0
	v_lshlrev_b32_e32 v0, 1, v69
	v_lshl_add_u64 v[34:35], s[16:17], 0, v[0:1]
	v_exp_f32_e32 v42, v42
	v_add_f32_e32 v39, 1.0, v41
	v_rcp_f32_e32 v0, v37
	v_mul_f32_e32 v43, 0xbfb8aa3b, v43
	v_add_f32_e32 v41, 1.0, v42
	v_rcp_f32_e32 v37, v39
	v_exp_f32_e32 v43, v43
	s_nop 0
	v_add_f32_e32 v42, 1.0, v43
	s_waitcnt lgkmcnt(0)
	v_mul_f32_e32 v44, 0xbfb8aa3b, v44
	v_exp_f32_e32 v44, v44
	v_rcp_f32_e32 v39, v41
	v_add_f32_e32 v43, 1.0, v44
	v_rcp_f32_e32 v49, v42
	v_mul_f32_e32 v42, 0xbfb8aa3b, v45
	v_exp_f32_e32 v42, v42
	s_nop 0
	v_add_f32_e32 v42, 1.0, v42
	v_rcp_f32_e32 v48, v43
	v_mul_f32_e32 v43, 0xbfb8aa3b, v46
	v_exp_f32_e32 v43, v43
	s_nop 0
	v_add_f32_e32 v43, 1.0, v43
	v_rcp_f32_e32 v50, v42
	v_mul_f32_e32 v42, 0xbfb8aa3b, v47
	v_exp_f32_e32 v42, v42
	s_nop 0
	v_add_f32_e32 v42, 1.0, v42
	v_rcp_f32_e32 v47, v43
	v_cvt_pk_bf16_f32 v46, v48, v50
	s_nop 1
	v_rcp_f32_e32 v52, v42
	ds_read_b128 v[40:43], v38 offset:16896
	v_cvt_pk_bf16_f32 v44, v0, v37
	s_nop 1
	v_cvt_pk_bf16_f32 v45, v39, v49
	s_nop 1
	ds_read_b128 v[48:51], v38 offset:16912
	v_ashrrev_i32_e32 v37, 31, v36
	s_waitcnt lgkmcnt(1)
	v_mul_f32_e32 v0, 0xbfb8aa3b, v40
	v_exp_f32_e32 v0, v0
	v_cvt_pk_bf16_f32 v47, v47, v52
	s_nop 1
	v_lshlrev_b64 v[52:53], 11, v[36:37]
	v_mul_f32_e32 v41, 0xbfb8aa3b, v41
	v_add_f32_e32 v0, 1.0, v0
	v_lshl_add_u64 v[52:53], v[34:35], 0, v[52:53]
	v_exp_f32_e32 v41, v41
	global_store_dwordx4 v[52:53], v[44:47], off
	v_add_f32_e32 v39, 1.0, v41
	v_rcp_f32_e32 v0, v0
	v_mul_f32_e32 v42, 0xbfb8aa3b, v42
	v_exp_f32_e32 v42, v42
	s_nop 0
	v_add_f32_e32 v41, 1.0, v42
	v_rcp_f32_e32 v37, v39
	v_mul_f32_e32 v43, 0xbfb8aa3b, v43
	v_exp_f32_e32 v43, v43
	s_nop 0
	v_add_f32_e32 v42, 1.0, v43
	s_waitcnt lgkmcnt(0)
	v_mul_f32_e32 v44, 0xbfb8aa3b, v48
	v_exp_f32_e32 v44, v44
	v_rcp_f32_e32 v39, v41
	v_add_f32_e32 v43, 1.0, v44
	v_rcp_f32_e32 v45, v42
	v_mul_f32_e32 v42, 0xbfb8aa3b, v49
	v_exp_f32_e32 v42, v42
	s_nop 0
	v_add_f32_e32 v42, 1.0, v42
	v_rcp_f32_e32 v46, v43
	v_mul_f32_e32 v43, 0xbfb8aa3b, v50
	v_exp_f32_e32 v43, v43
	s_nop 0
	v_add_f32_e32 v43, 1.0, v43
	v_rcp_f32_e32 v47, v42
	v_mul_f32_e32 v42, 0xbfb8aa3b, v51
	v_exp_f32_e32 v42, v42
	s_nop 0
	v_add_f32_e32 v42, 1.0, v42
	v_rcp_f32_e32 v52, v43
	v_cvt_pk_bf16_f32 v45, v39, v45
	s_nop 1
	v_rcp_f32_e32 v53, v42
	ds_read_b128 v[40:43], v38 offset:33792
	ds_read_b128 v[48:51], v38 offset:33808
	v_cvt_pk_bf16_f32 v44, v0, v37
	s_nop 1
	v_cvt_pk_bf16_f32 v46, v46, v47
	s_nop 1
	v_cvt_pk_bf16_f32 v47, v52, v53
	s_nop 1
	s_waitcnt lgkmcnt(1)
	v_mul_f32_e32 v0, 0xbfb8aa3b, v40
	v_exp_f32_e32 v0, v0
	v_add_u32_e32 v52, 32, v36
	v_ashrrev_i32_e32 v53, 31, v52
	v_lshlrev_b64 v[52:53], 11, v[52:53]
	v_add_f32_e32 v0, 1.0, v0
	v_mul_f32_e32 v41, 0xbfb8aa3b, v41
	v_lshl_add_u64 v[52:53], v[34:35], 0, v[52:53]
	v_exp_f32_e32 v41, v41
	global_store_dwordx4 v[52:53], v[44:47], off
	v_mul_f32_e32 v42, 0xbfb8aa3b, v42
	v_exp_f32_e32 v42, v42
	v_add_f32_e32 v40, 1.0, v41
	v_rcp_f32_e32 v0, v0
	v_mul_f32_e32 v43, 0xbfb8aa3b, v43
	v_add_f32_e32 v41, 1.0, v42
	v_exp_f32_e32 v43, v43
	v_rcp_f32_e32 v37, v40
	v_add_f32_e32 v42, 1.0, v43
	s_waitcnt lgkmcnt(0)
	v_mul_f32_e32 v44, 0xbfb8aa3b, v48
	v_exp_f32_e32 v44, v44
	v_rcp_f32_e32 v39, v41
	v_add_f32_e32 v43, 1.0, v44
	v_rcp_f32_e32 v45, v42
	v_mul_f32_e32 v42, 0xbfb8aa3b, v49
	v_exp_f32_e32 v42, v42
	s_nop 0
	v_add_f32_e32 v42, 1.0, v42
	v_rcp_f32_e32 v46, v43
	v_mul_f32_e32 v43, 0xbfb8aa3b, v50
	v_exp_f32_e32 v43, v43
	s_nop 0
	v_add_f32_e32 v43, 1.0, v43
	v_rcp_f32_e32 v47, v42
	v_mul_f32_e32 v42, 0xbfb8aa3b, v51
	v_exp_f32_e32 v42, v42
	s_nop 0
	v_add_f32_e32 v42, 1.0, v42
	v_rcp_f32_e32 v52, v43
	v_cvt_pk_bf16_f32 v45, v39, v45
	s_nop 1
	v_rcp_f32_e32 v53, v42
	ds_read_b128 v[40:43], v38 offset:50688
	ds_read_b128 v[48:51], v38 offset:50704
	v_cvt_pk_bf16_f32 v44, v0, v37
	s_nop 1
	v_add_u32_e32 v38, 64, v36
	v_ashrrev_i32_e32 v39, 31, v38
	s_waitcnt lgkmcnt(1)
	v_mul_f32_e32 v0, 0xbfb8aa3b, v40
	v_exp_f32_e32 v0, v0
	v_lshlrev_b64 v[38:39], 11, v[38:39]
	v_lshl_add_u64 v[38:39], v[34:35], 0, v[38:39]
	v_cvt_pk_bf16_f32 v46, v46, v47
	s_nop 1
	v_add_f32_e32 v0, 1.0, v0
	v_cvt_pk_bf16_f32 v47, v52, v53
	s_nop 1
	global_store_dwordx4 v[38:39], v[44:47], off
	v_mul_f32_e32 v41, 0xbfb8aa3b, v41
	v_exp_f32_e32 v41, v41
	s_nop 0
	v_add_f32_e32 v38, 1.0, v41
	v_mul_f32_e32 v40, 0xbfb8aa3b, v42
	v_rcp_f32_e32 v0, v0
	v_exp_f32_e32 v40, v40
	s_nop 0
	v_add_f32_e32 v40, 1.0, v40
	v_rcp_f32_e32 v37, v38
	v_mul_f32_e32 v43, 0xbfb8aa3b, v43
	v_exp_f32_e32 v43, v43
	s_nop 0
	v_add_f32_e32 v41, 1.0, v43
	s_waitcnt lgkmcnt(0)
	v_mul_f32_e32 v42, 0xbfb8aa3b, v48
	v_rcp_f32_e32 v39, v40
	v_exp_f32_e32 v42, v42
	s_nop 0
	v_add_f32_e32 v42, 1.0, v42
	v_rcp_f32_e32 v40, v41
	v_mul_f32_e32 v44, 0xbfb8aa3b, v49
	v_exp_f32_e32 v44, v44
	s_nop 0
	v_add_f32_e32 v43, 1.0, v44
	v_rcp_f32_e32 v41, v42
	v_mul_f32_e32 v45, 0xbfb8aa3b, v50
	v_exp_f32_e32 v45, v45
	s_nop 0
	v_add_f32_e32 v44, 1.0, v45
	v_rcp_f32_e32 v42, v43
	v_mul_f32_e32 v46, 0xbfb8aa3b, v51
	v_exp_f32_e32 v46, v46
	s_nop 0
	v_add_f32_e32 v45, 1.0, v46
	v_rcp_f32_e32 v43, v44
	v_add_u32_e32 v36, 0x60, v36
	v_rcp_f32_e32 v44, v45
	v_cvt_pk_bf16_f32 v38, v0, v37
	s_nop 1
	v_ashrrev_i32_e32 v37, 31, v36
	v_lshlrev_b64 v[36:37], 11, v[36:37]
	v_lshl_add_u64 v[34:35], v[34:35], 0, v[36:37]
	v_mov_b32_e32 v36, v168
	v_cvt_pk_bf16_f32 v39, v39, v40
	s_nop 1
	v_cvt_pk_bf16_f32 v40, v41, v42
	s_nop 1
	v_cvt_pk_bf16_f32 v41, v43, v44
	s_nop 1
	global_store_dwordx4 v[34:35], v[38:41], off
	s_nop 0
	v_lshlrev_b32_e32 v0, 3, v36
	v_and_b32_e32 v37, 0x78, v0
	v_mov_b32_e32 v0, v168
	s_waitcnt lgkmcnt(0)
	s_barrier
; DI float sigm(float x) { return 1.f / (1.f + __expf(-x)); }
; DI u32x4 pack8(const float* f) { u32x4 o; o.x = pack2(f[0], f[1]); o.y = pack2(f[2], f[3]); o.z = pack2(f[4], f[5]); o.w = pack2(f[6], f[7]); return o; }
; DI void lds_barrier() { asm volatile("s_waitcnt lgkmcnt(0)\n\ts_barrier" ::: "memory"); }
; DI int tid512() { int t = threadIdx.x; asm volatile("" : "+v"(t)); return t; }
; template <int AI, int BJ>
; DI void stage_q(const f32x4 (&acc)[2][2][4][2], float* Cs) {
;   const int t = tid512(), wid = t >> 6, lane = t & 63, wr = wid >> 2, wc = wid & 3, fr = lane & 15, fq = lane >> 4;
;   lds_barrier();
; #pragma unroll
;   for (int m = 0; m < 4; ++m)
; #pragma unroll
;     for (int n = 0; n < 2; ++n)
; #pragma unroll
;       for (int j = 0; j < 4; ++j) Cs[(wr * 64 + m * 16 + fq * 4 + j) * CST + wc * 32 + n * 16 + fr] = acc[AI][BJ][m][n][j];
;   lds_barrier();
; }
; template <int AI, int BJ, int PASS>
; DI void f3_proc(PREF p, const f32x4 (&acc)[2][2][4][2], int mt, int dt, float* Cs, const u32x4 (&g)[4]) {
;   const int t = tid512();
;   const int row0 = mt * 256 + AI * 128, col0 = dt * 256 + BJ * 128;
;   const int c = (t & 15) * 8;
;   stage_q<AI, BJ>(acc, Cs);
; #pragma unroll
;   for (int q = 0; q < 4; ++q) {
;     int r = (t >> 4) + 32 * q;
;     float v[8]; ld8(Cs + r * CST + c, v);
;     if (PASS == 0) {
; #pragma unroll
;       for (int j = 0; j < 8; ++j) v[j] = sigm(v[j]);
;     } else {
;       float gf[8]; unpack8(g[q], gf);
; #pragma unroll
;       for (int j = 0; j < 8; ++j) v[j] *= gf[j];
;     }
;     *(u32x4*)((u16*)p.fbuf + (size_t)(row0 + r) * 1024 + col0 + c) = pack8(v);
;   }
; }
	s_nop 0
	v_and_b32_e32 v34, 15, v0
	v_lshrrev_b32_e32 v35, 2, v0
	v_lshlrev_b32_e32 v0, 1, v0
	v_lshlrev_b32_e32 v34, 2, v34
	v_and_b32_e32 v35, 0xfffffcc, v35
	v_and_or_b32 v0, v0, s89, v34
	v_mad_u64_u32 v[34:35], s[0:1], v35, s92, v[0:1]
	v_add_u32_e32 v0, 0x400, v34
	ds_write2_b32 v34, v22, v30 offset1:16
	ds_write2_b32 v34, v23, v31 offset0:132 offset1:148
	ds_write2_b32 v0, v24, v32 offset0:8 offset1:24
	ds_write2_b32 v0, v25, v33 offset0:140 offset1:156
	v_add_u32_e32 v0, 0x2000, v34
	ds_write2_b32 v0, v18, v26 offset0:64 offset1:80
	ds_write2_b32 v0, v19, v27 offset0:196 offset1:212
	v_add_u32_e32 v0, 0x2400, v34
	ds_write2_b32 v0, v20, v28 offset0:72 offset1:88
	ds_write2_b32 v0, v21, v29 offset0:204 offset1:220
	v_add_u32_e32 v0, 0x4000, v34
	ds_write2_b32 v0, v10, v14 offset0:128 offset1:144
	v_add_u32_e32 v0, 0x4400, v34
	ds_write2_b32 v0, v11, v15 offset0:4 offset1:20
	ds_write2_b32 v0, v12, v16 offset0:136 offset1:152
	v_add_u32_e32 v0, 0x4800, v34
	ds_write2_b32 v0, v13, v17 offset0:12 offset1:28
	v_add_u32_e32 v0, 0x6000, v34
	ds_write2_b32 v0, v2, v6 offset0:192 offset1:208
	v_add_u32_e32 v0, 0x6400, v34
	ds_write2_b32 v0, v3, v7 offset0:68 offset1:84
	ds_write2_b32 v0, v4, v8 offset0:200 offset1:216
	v_add_u32_e32 v0, 0x6800, v34
	ds_write2_b32 v0, v5, v9 offset0:76 offset1:92
	v_ashrrev_i32_e32 v0, 4, v36
	v_mul_lo_u32 v2, v0, s92
	s_waitcnt lgkmcnt(0)
	s_barrier
	v_lshl_add_u32 v4, v37, 2, v2
	ds_read_b128 v[6:9], v4
	ds_read_b128 v[10:13], v4 offset:16
	s_waitcnt lgkmcnt(1)
	v_mul_f32_e32 v2, 0xbfb8aa3b, v6
	v_exp_f32_e32 v2, v2
	v_mul_f32_e32 v7, 0xbfb8aa3b, v7
	v_exp_f32_e32 v7, v7
	v_mul_f32_e32 v8, 0xbfb8aa3b, v8
	v_add_f32_e32 v2, 1.0, v2
	v_exp_f32_e32 v8, v8
	v_mul_f32_e32 v9, 0xbfb8aa3b, v9
	v_exp_f32_e32 v9, v9
	v_add_f32_e32 v6, 1.0, v7
	v_rcp_f32_e32 v2, v2
	s_waitcnt lgkmcnt(0)
	v_mul_f32_e32 v10, 0xbfb8aa3b, v10
	v_add_f32_e32 v7, 1.0, v8
	v_rcp_f32_e32 v3, v6
	v_exp_f32_e32 v10, v10
	v_add_f32_e32 v8, 1.0, v9
	v_rcp_f32_e32 v5, v7
	v_mul_f32_e32 v11, 0xbfb8aa3b, v11
	v_add_f32_e32 v9, 1.0, v10
	v_rcp_f32_e32 v7, v8
	v_exp_f32_e32 v11, v11
	s_nop 0
	v_add_f32_e32 v10, 1.0, v11
	v_rcp_f32_e32 v8, v9
	v_mul_f32_e32 v12, 0xbfb8aa3b, v12
	v_exp_f32_e32 v12, v12
	s_nop 0
	v_add_f32_e32 v11, 1.0, v12
	v_rcp_f32_e32 v9, v10
	v_mul_f32_e32 v13, 0xbfb8aa3b, v13
	v_exp_f32_e32 v13, v13
	s_nop 0
	v_add_f32_e32 v12, 1.0, v13
	v_rcp_f32_e32 v14, v11
	v_cvt_pk_bf16_f32 v8, v8, v9
	s_nop 1
	v_rcp_f32_e32 v15, v12
	ds_read_b128 v[10:13], v4 offset:16896
	v_cvt_pk_bf16_f32 v6, v2, v3
	s_nop 1
	v_cvt_pk_bf16_f32 v9, v14, v15
	s_nop 1
	v_add_u32_e32 v2, s25, v0
	ds_read_b128 v[14:17], v4 offset:16912
	s_waitcnt lgkmcnt(1)
	v_mul_f32_e32 v0, 0xbfb8aa3b, v10
	v_exp_f32_e32 v0, v0
	v_ashrrev_i32_e32 v3, 31, v2
	v_lshlrev_b64 v[18:19], 11, v[2:3]
	v_cvt_pk_bf16_f32 v7, v5, v7
	s_nop 1
	v_add_f32_e32 v3, 1.0, v0
	v_lshl_add_u64 v[18:19], s[16:17], 0, v[18:19]
	v_lshlrev_b32_e32 v0, 1, v37
	v_lshl_add_u64 v[18:19], v[18:19], 0, v[0:1]
	global_store_dwordx4 v[18:19], v[6:9], off offset:256
	v_add_u32_e32 v18, 32, v2
	v_ashrrev_i32_e32 v19, 31, v18
	v_mul_f32_e32 v8, 0xbfb8aa3b, v11
	v_exp_f32_e32 v8, v8
	s_nop 0
	v_add_f32_e32 v6, 1.0, v8
	v_rcp_f32_e32 v3, v3
	v_mul_f32_e32 v10, 0xbfb8aa3b, v12
	v_exp_f32_e32 v10, v10
	s_nop 0
	v_add_f32_e32 v8, 1.0, v10
	v_mul_f32_e32 v9, 0xbfb8aa3b, v13
	v_rcp_f32_e32 v5, v6
	v_exp_f32_e32 v9, v9
	s_nop 0
	v_add_f32_e32 v9, 1.0, v9
	v_rcp_f32_e32 v7, v8
	s_waitcnt lgkmcnt(0)
	v_mul_f32_e32 v11, 0xbfb8aa3b, v14
	v_exp_f32_e32 v11, v11
	s_nop 0
	v_add_f32_e32 v10, 1.0, v11
	v_rcp_f32_e32 v8, v9
	v_mul_f32_e32 v12, 0xbfb8aa3b, v15
	v_exp_f32_e32 v12, v12
	s_nop 0
	v_add_f32_e32 v11, 1.0, v12
	v_rcp_f32_e32 v9, v10
	v_mul_f32_e32 v13, 0xbfb8aa3b, v16
	v_exp_f32_e32 v13, v13
	s_nop 0
	v_add_f32_e32 v12, 1.0, v13
	v_rcp_f32_e32 v14, v11
	v_mul_f32_e32 v11, 0xbfb8aa3b, v17
	v_exp_f32_e32 v11, v11
	s_nop 0
	v_add_f32_e32 v11, 1.0, v11
	v_rcp_f32_e32 v15, v12
	v_cvt_pk_bf16_f32 v7, v7, v8
	s_nop 1
	v_rcp_f32_e32 v16, v11
	ds_read_b128 v[10:13], v4 offset:33792
	v_cvt_pk_bf16_f32 v6, v3, v5
	s_nop 1
	v_cvt_pk_bf16_f32 v8, v9, v14
	s_nop 1
	v_cvt_pk_bf16_f32 v9, v15, v16
	s_nop 1
	ds_read_b128 v[14:17], v4 offset:33808
	s_waitcnt lgkmcnt(1)
	v_mul_f32_e32 v3, 0xbfb8aa3b, v10
	v_exp_f32_e32 v3, v3
	v_lshlrev_b64 v[18:19], 11, v[18:19]
	v_lshl_add_u64 v[18:19], s[16:17], 0, v[18:19]
	v_lshl_add_u64 v[18:19], v[18:19], 0, v[0:1]
	v_add_f32_e32 v3, 1.0, v3
	global_store_dwordx4 v[18:19], v[6:9], off offset:256
	s_nop 1
	v_mul_f32_e32 v8, 0xbfb8aa3b, v11
	v_exp_f32_e32 v8, v8
	s_nop 0
	v_add_f32_e32 v6, 1.0, v8
	v_rcp_f32_e32 v3, v3
	v_mul_f32_e32 v10, 0xbfb8aa3b, v12
	v_exp_f32_e32 v10, v10
	s_nop 0
	v_add_f32_e32 v8, 1.0, v10
	v_mul_f32_e32 v9, 0xbfb8aa3b, v13
	v_rcp_f32_e32 v5, v6
	v_exp_f32_e32 v9, v9
	s_nop 0
	v_add_f32_e32 v9, 1.0, v9
	v_rcp_f32_e32 v7, v8
	s_waitcnt lgkmcnt(0)
; DI float sigm(float x) { return 1.f / (1.f + __expf(-x)); }
; DI void lds_barrier() { asm volatile("s_waitcnt lgkmcnt(0)\n\ts_barrier" ::: "memory"); }
;     ...
;   const int t = tid512();
;   const int wid = t >> 6, lane = t & 63, wr = wid >> 2, wc = wid & 3, fr = lane & 15, fq = lane >> 4;
;   int r0, c0, r1, c1;
;   g_stage_rc(t * 16, r0, c0); g_stage_rc(t * 16 + 8192, r1, c1);
;   const int oa0 = r0 * LDA + c0, oa1 = r1 * LDA + c1, ob0 = r0 * LDB + c0, ob1 = r1 * LDB + c1;
;   const int obr = fr * 64 + fq * 16, rdo = obr ^ (((obr >> 9) & 1) << 5);
;   bf16x8 At[4][2], B0[2][2], B1[2][2];
;   constexpr int nt = K / 64;
;   lds_barrier();
;   G_STAGE(G_SB(0, 0), B, ob0, ob1, LDB, 0, KB(0)); G_STAGE(G_SA(0, 0), A, oa0, oa1, LDA, 0, KA(0));
;   G_STAGE(G_SB(0, 1), B, ob0, ob1, LDB, 128, KB(0)); G_STAGE(G_SA(0, 1), A, oa0, oa1, LDA, 128, KA(0));
;   if (wr == 1) G_BAR;
;   G_WAIT_V(4); G_BAR;
;   G_STAGE(G_SB(1, 0), B, ob0, ob1, LDB, 0, KB(1)); G_STAGE(G_SA(1, 0), A, oa0, oa1, LDA, 0, KA(1)); G_STAGE(G_SB(1, 1), B, ob0, ob1, LDB, 128, KB(1));
;   G_WAIT_V(6); G_BAR;
; template <int AI, int BJ, int PASS>
; DI void f3_proc(PREF p, const f32x4 (&acc)[2][2][4][2], int mt, int dt, float* Cs, const u32x4 (&g)[4]) {
;   const int t = tid512();
;   const int row0 = mt * 256 + AI * 128, col0 = dt * 256 + BJ * 128;
;   const int c = (t & 15) * 8;
;   stage_q<AI, BJ>(acc, Cs);
; #pragma unroll
;   for (int q = 0; q < 4; ++q) {
;     int r = (t >> 4) + 32 * q;
;     float v[8]; ld8(Cs + r * CST + c, v);
;     if (PASS == 0) {
; #pragma unroll
;       for (int j = 0; j < 8; ++j) v[j] = sigm(v[j]);
;     } else {
;       float gf[8]; unpack8(g[q], gf);
; #pragma unroll
;       for (int j = 0; j < 8; ++j) v[j] *= gf[j];
;     }
;     *(u32x4*)((u16*)p.fbuf + (size_t)(row0 + r) * 1024 + col0 + c) = pack8(v);
;   }
; }
; DI void f3_phase(PREF p, int l, unsigned char* lds_all) {
;     ...
;       gemm256<1024, 1024, 1024>(acc, p.X + (size_t)mt * 256 * 1024, W + O_PLEG + (size_t)dt * 256 * 1024, shm, p);
;       u32x4 gd[4];
;       f3_proc<0, 0, 0>(p, acc, mt, dt, Cs, gd); f3_proc<0, 1, 0>(p, acc, mt, dt, Cs, gd);
;       f3_proc<1, 0, 0>(p, acc, mt, dt, Cs, gd); f3_proc<1, 1, 0>(p, acc, mt, dt, Cs, gd);
;     }
;     f32x4 acc[2][2][4][2]; zero_acc256(acc);
;     gemm256<256, 256, 256>(acc, p.pb + (size_t)mt * 256 * 256, W + O_PLE + (size_t)dt * 256 * 256, shm, p);
	v_mul_f32_e32 v11, 0xbfb8aa3b, v14
	v_exp_f32_e32 v11, v11
	s_nop 0
	v_add_f32_e32 v10, 1.0, v11
	v_rcp_f32_e32 v8, v9
	v_mul_f32_e32 v12, 0xbfb8aa3b, v15
	v_exp_f32_e32 v12, v12
	s_nop 0
	v_add_f32_e32 v11, 1.0, v12
	v_rcp_f32_e32 v9, v10
	v_mul_f32_e32 v13, 0xbfb8aa3b, v16
	v_exp_f32_e32 v13, v13
	s_nop 0
	v_add_f32_e32 v12, 1.0, v13
	v_rcp_f32_e32 v14, v11
	v_mul_f32_e32 v11, 0xbfb8aa3b, v17
	v_exp_f32_e32 v11, v11
	s_nop 0
	v_add_f32_e32 v11, 1.0, v11
	v_rcp_f32_e32 v15, v12
	v_cvt_pk_bf16_f32 v7, v7, v8
	s_nop 1
	v_rcp_f32_e32 v16, v11
	ds_read_b128 v[10:13], v4 offset:50688
	v_cvt_pk_bf16_f32 v6, v3, v5
	s_nop 1
	v_cvt_pk_bf16_f32 v8, v9, v14
	s_nop 1
	v_cvt_pk_bf16_f32 v9, v15, v16
	s_nop 1
	ds_read_b128 v[14:17], v4 offset:50704
	s_waitcnt lgkmcnt(1)
	v_mul_f32_e32 v3, 0xbfb8aa3b, v10
	v_exp_f32_e32 v3, v3
	v_add_u32_e32 v4, 64, v2
	v_ashrrev_i32_e32 v5, 31, v4
	v_lshlrev_b64 v[4:5], 11, v[4:5]
	v_add_f32_e32 v3, 1.0, v3
	v_lshl_add_u64 v[4:5], s[16:17], 0, v[4:5]
	v_lshl_add_u64 v[4:5], v[4:5], 0, v[0:1]
	global_store_dwordx4 v[4:5], v[6:9], off offset:256
	s_nop 1
	v_mul_f32_e32 v6, 0xbfb8aa3b, v11
	s_nop 0
	v_exp_f32_e32 v6, v6
	s_nop 0
	v_add_f32_e32 v6, 1.0, v6
	v_rcp_f32_e32 v3, v3
	v_mul_f32_e32 v9, 0xbfb8aa3b, v12
	v_exp_f32_e32 v9, v9
	s_nop 0
	v_add_f32_e32 v7, 1.0, v9
	v_mul_f32_e32 v8, 0xbfb8aa3b, v13
	v_exp_f32_e32 v8, v8
	v_rcp_f32_e32 v4, v6
	v_add_f32_e32 v8, 1.0, v8
	s_waitcnt lgkmcnt(0)
	v_mul_f32_e32 v10, 0xbfb8aa3b, v14
	v_exp_f32_e32 v10, v10
	v_rcp_f32_e32 v5, v7
	v_add_f32_e32 v9, 1.0, v10
	v_mul_f32_e32 v11, 0xbfb8aa3b, v15
	v_exp_f32_e32 v11, v11
	v_rcp_f32_e32 v6, v8
	v_add_f32_e32 v10, 1.0, v11
	v_mul_f32_e32 v12, 0xbfb8aa3b, v16
	v_exp_f32_e32 v12, v12
	v_rcp_f32_e32 v7, v9
	v_add_f32_e32 v11, 1.0, v12
	v_mul_f32_e32 v13, 0xbfb8aa3b, v17
	v_exp_f32_e32 v13, v13
	v_rcp_f32_e32 v8, v10
	v_add_f32_e32 v12, 1.0, v13
	v_rcp_f32_e32 v9, v11
	v_add_u32_e32 v2, 0x60, v2
	v_cvt_pk_bf16_f32 v4, v3, v4
	s_nop 1
	v_ashrrev_i32_e32 v3, 31, v2
	v_lshlrev_b64 v[2:3], 11, v[2:3]
	v_lshl_add_u64 v[2:3], s[16:17], 0, v[2:3]
	v_lshl_add_u64 v[2:3], v[2:3], 0, v[0:1]
	s_lshl_b32 s0, s35, 17
	v_mov_b32_e32 v0, v168
	v_rcp_f32_e32 v10, v12
	v_cvt_pk_bf16_f32 v5, v5, v6
	s_nop 1
	v_cvt_pk_bf16_f32 v6, v7, v8
	s_nop 1
	v_cvt_pk_bf16_f32 v7, v9, v10
	s_nop 1
	global_store_dwordx4 v[2:3], v[4:7], off offset:256
	s_add_u32 s20, s10, s0
	s_addc_u32 s21, s11, 0
	v_lshlrev_b32_e32 v18, 4, v0
	v_and_b32_e32 v2, 32, v0
	s_lshl_b64 s[0:1], s[18:19], 17
	v_bitop3_b32 v2, v18, v2, 48 bitop3:0x6c
	s_add_u32 s18, s30, s0
	v_lshrrev_b32_e32 v3, 3, v0
	v_bfe_u32 v4, v0, 2, 4
	s_mov_b32 s0, 0xfffff0
	v_lshrrev_b32_e32 v5, 1, v0
	v_lshrrev_b32_e32 v2, 1, v2
	v_add_u32_e32 v19, 0x2000, v18
	v_and_or_b32 v3, v3, s0, v4
	v_and_or_b32 v5, v5, 32, v2
	v_lshrrev_b32_e32 v2, 7, v19
	v_and_or_b32 v4, v2, s0, v4
	v_lshl_or_b32 v2, v3, 8, v5
	v_lshl_or_b32 v4, v4, 8, v5
	v_ashrrev_i32_e32 v3, 31, v2
	v_add_u32_e32 v22, 0x10000, v18
	s_addc_u32 s19, s31, s1
	v_lshlrev_b64 v[2:3], 1, v[2:3]
	v_readfirstlane_b32 s0, v22
	v_ashrrev_i32_e32 v5, 31, v4
	v_add_u32_e32 v23, 0x12000, v18
	s_waitcnt lgkmcnt(0)
	s_barrier
	v_lshl_add_u64 v[6:7], s[18:19], 0, v[2:3]
	s_mov_b32 m0, s0
	v_lshlrev_b64 v[4:5], 1, v[4:5]
	v_readfirstlane_b32 s0, v23
	global_load_lds_dwordx4 v[6:7], off
	v_lshl_add_u64 v[8:9], s[18:19], 0, v[4:5]
	s_mov_b32 m0, s0
	v_readfirstlane_b32 s0, v18
	global_load_lds_dwordx4 v[8:9], off
	v_lshl_add_u64 v[10:11], s[20:21], 0, v[2:3]
	s_mov_b32 m0, s0
	v_readfirstlane_b32 s0, v19
	global_load_lds_dwordx4 v[10:11], off
	s_mov_b32 m0, s0
	s_add_u32 s0, s18, 0x10000
	v_add_u32_e32 v20, 0x14000, v18
	v_lshl_add_u64 v[14:15], s[20:21], 0, v[4:5]
	s_addc_u32 s1, s19, 0
	v_readfirstlane_b32 s22, v20
	global_load_lds_dwordx4 v[14:15], off
	v_lshl_add_u64 v[12:13], s[0:1], 0, v[2:3]
	s_mov_b32 m0, s22
	v_add_u32_e32 v21, 0x16000, v18
	global_load_lds_dwordx4 v[12:13], off
	v_lshl_add_u64 v[12:13], s[0:1], 0, v[4:5]
	v_readfirstlane_b32 s0, v21
	s_mov_b32 m0, s0
	s_add_u32 s0, s20, 0x10000
	v_add_u32_e32 v16, 0x4000, v18
	s_addc_u32 s1, s21, 0
	v_readfirstlane_b32 s22, v16
	global_load_lds_dwordx4 v[12:13], off
	v_lshl_add_u64 v[12:13], s[0:1], 0, v[2:3]
	s_mov_b32 m0, s22
	v_add_u32_e32 v17, 0x6000, v18
	global_load_lds_dwordx4 v[12:13], off
	v_lshl_add_u64 v[12:13], s[0:1], 0, v[4:5]
	v_readfirstlane_b32 s0, v17
	s_mov_b32 m0, s0
	s_nop 0
	global_load_lds_dwordx4 v[12:13], off
	v_ashrrev_i32_e32 v12, 8, v0
	v_cmp_eq_u32_e32 vcc, 1, v12
	s_and_saveexec_b64 s[22:23], vcc
	s_cbranch_execz .LBB0_45
	s_barrier

; DI float sigm(float x) { return 1.f / (1.f + __expf(-x)); }
; DI void gate_reg(PREF p, int l, int n, f32x4 (&acc)[2][2][4][2], int dt) {
;     ...
;       for (int m = 0; m < 4; ++m) {
;         float b[8]; unpack8(bn[m], b);
;         float v[8];
; #pragma unroll
;         for (int nn = 0; nn < 2; ++nn)
; #pragma unroll
;           for (int j = 0; j < 4; ++j) v[nn * 4 + j] = sigm(acc[ai][bj][m][nn][j] + bias[bj][nn]) * b[nn * 4 + j];
;         if (n > 0) {
;           float o[8]; unpack8(pv[m], o);
; #pragma unroll
;           for (int e = 0; e < 8; ++e) v[e] += o[e];
;         }
.LBB0_116:
	s_waitcnt vmcnt(0)
	v_add_f32_e32 v0, v158, v184
	v_mul_f32_e32 v0, 0xbfb8aa3b, v0
	v_exp_f32_e32 v158, v0
	v_add_f32_e32 v0, v159, v184
	v_mul_f32_e32 v0, 0xbfb8aa3b, v0
	v_exp_f32_e32 v159, v0
	v_lshlrev_b32_e32 v186, 16, v154
	v_and_b32_e32 v187, 0xffff0000, v154
	v_pk_add_f32 v[158:159], v[158:159], 1.0 op_sel_hi:[1,0]
	s_nop 0
	v_rcp_f32_e32 v159, v159
	v_rcp_f32_e32 v158, v158
	v_add_f32_e32 v0, v160, v184
	v_mul_f32_e32 v0, 0xbfb8aa3b, v0
	v_exp_f32_e32 v160, v0
	v_add_f32_e32 v0, v161, v184
	v_mul_f32_e32 v0, 0xbfb8aa3b, v0
	v_exp_f32_e32 v161, v0
	v_pk_mul_f32 v[158:159], v[158:159], v[186:187]
	v_lshlrev_b32_e32 v154, 16, v155
	v_and_b32_e32 v155, 0xffff0000, v155
	v_pk_add_f32 v[160:161], v[160:161], 1.0 op_sel_hi:[1,0]
	s_nop 0
	v_rcp_f32_e32 v161, v161
	v_rcp_f32_e32 v160, v160
	v_add_f32_e32 v0, v150, v183
	v_mul_f32_e32 v0, 0xbfb8aa3b, v0
	v_exp_f32_e32 v150, v0
	v_add_f32_e32 v0, v151, v183
	v_mul_f32_e32 v0, 0xbfb8aa3b, v0
	v_exp_f32_e32 v151, v0
	v_pk_mul_f32 v[154:155], v[160:161], v[154:155]
	v_lshlrev_b32_e32 v160, 16, v156
	v_and_b32_e32 v161, 0xffff0000, v156
	v_pk_add_f32 v[150:151], v[150:151], 1.0 op_sel_hi:[1,0]
	s_nop 0
	v_rcp_f32_e32 v151, v151
	v_rcp_f32_e32 v150, v150
	v_add_f32_e32 v0, v152, v183
	v_mul_f32_e32 v0, 0xbfb8aa3b, v0
	v_exp_f32_e32 v152, v0
	v_add_f32_e32 v0, v153, v183
	v_mul_f32_e32 v0, 0xbfb8aa3b, v0
	v_exp_f32_e32 v153, v0
	v_pk_mul_f32 v[150:151], v[150:151], v[160:161]
	v_lshlrev_b32_e32 v156, 16, v157
	v_and_b32_e32 v157, 0xffff0000, v157
	v_pk_add_f32 v[152:153], v[152:153], 1.0 op_sel_hi:[1,0]
	s_nop 0
	v_rcp_f32_e32 v153, v153
	v_rcp_f32_e32 v152, v152
	s_nop 0
	v_pk_mul_f32 v[152:153], v[152:153], v[156:157]
	s_and_b64 vcc, exec, s[8:9]
	s_cbranch_vccnz .LBB0_118
	v_lshlrev_b32_e32 v156, 16, v42
	v_and_b32_e32 v157, 0xffff0000, v42
	v_pk_add_f32 v[158:159], v[158:159], v[156:157]
	v_lshlrev_b32_e32 v156, 16, v43
	v_and_b32_e32 v157, 0xffff0000, v43
	v_pk_add_f32 v[154:155], v[154:155], v[156:157]
	v_lshlrev_b32_e32 v156, 16, v44
	v_and_b32_e32 v157, 0xffff0000, v44
	v_pk_add_f32 v[150:151], v[150:151], v[156:157]
	v_lshlrev_b32_e32 v156, 16, v45
	v_and_b32_e32 v157, 0xffff0000, v45
	v_pk_add_f32 v[152:153], v[152:153], v[156:157]

; DI float sigm(float x) { return 1.f / (1.f + __expf(-x)); }
; DI void gate_reg(PREF p, int l, int n, f32x4 (&acc)[2][2][4][2], int dt) {
;     ...
;       for (int m = 0; m < 4; ++m) {
;         float b[8]; unpack8(bn[m], b);
;         float v[8];
; #pragma unroll
;         for (int nn = 0; nn < 2; ++nn)
; #pragma unroll
;           for (int j = 0; j < 4; ++j) v[nn * 4 + j] = sigm(acc[ai][bj][m][nn][j] + bias[bj][nn]) * b[nn * 4 + j];
;         if (n > 0) {
;           float o[8]; unpack8(pv[m], o);
; #pragma unroll
;           for (int e = 0; e < 8; ++e) v[e] += o[e];
;         }
.LBB0_120:
	v_add_f32_e32 v0, v146, v184
	v_mul_f32_e32 v0, 0xbfb8aa3b, v0
	v_exp_f32_e32 v146, v0
	v_add_f32_e32 v0, v147, v184
	v_mul_f32_e32 v0, 0xbfb8aa3b, v0
	v_exp_f32_e32 v147, v0
	v_lshlrev_b32_e32 v156, 16, v142
	v_and_b32_e32 v157, 0xffff0000, v142
	v_pk_add_f32 v[146:147], v[146:147], 1.0 op_sel_hi:[1,0]
	s_nop 0
	v_rcp_f32_e32 v147, v147
	v_rcp_f32_e32 v146, v146
	v_add_f32_e32 v0, v148, v184
	v_mul_f32_e32 v0, 0xbfb8aa3b, v0
	v_exp_f32_e32 v148, v0
	v_add_f32_e32 v0, v149, v184
	v_mul_f32_e32 v0, 0xbfb8aa3b, v0
	v_exp_f32_e32 v149, v0
	v_pk_mul_f32 v[146:147], v[146:147], v[156:157]
	v_lshlrev_b32_e32 v142, 16, v143
	v_and_b32_e32 v143, 0xffff0000, v143
	v_pk_add_f32 v[148:149], v[148:149], 1.0 op_sel_hi:[1,0]
	s_nop 0
	v_rcp_f32_e32 v149, v149
	v_rcp_f32_e32 v148, v148
	v_add_f32_e32 v0, v138, v183
	v_mul_f32_e32 v0, 0xbfb8aa3b, v0
	v_exp_f32_e32 v138, v0
	v_add_f32_e32 v0, v139, v183
	v_mul_f32_e32 v0, 0xbfb8aa3b, v0
	v_exp_f32_e32 v139, v0
	v_pk_mul_f32 v[142:143], v[148:149], v[142:143]
	v_lshlrev_b32_e32 v148, 16, v144
	v_and_b32_e32 v149, 0xffff0000, v144
	v_pk_add_f32 v[138:139], v[138:139], 1.0 op_sel_hi:[1,0]
	s_nop 0
	v_rcp_f32_e32 v139, v139
	v_rcp_f32_e32 v138, v138
	v_add_f32_e32 v0, v140, v183
	v_mul_f32_e32 v0, 0xbfb8aa3b, v0
	v_exp_f32_e32 v140, v0
	v_add_f32_e32 v0, v141, v183
	v_mul_f32_e32 v0, 0xbfb8aa3b, v0
	v_exp_f32_e32 v141, v0
	v_pk_mul_f32 v[138:139], v[138:139], v[148:149]
	v_lshlrev_b32_e32 v144, 16, v145
	v_and_b32_e32 v145, 0xffff0000, v145
	v_pk_add_f32 v[140:141], v[140:141], 1.0 op_sel_hi:[1,0]
	s_nop 0
	v_rcp_f32_e32 v141, v141
	v_rcp_f32_e32 v140, v140
	s_nop 0
	v_pk_mul_f32 v[140:141], v[140:141], v[144:145]
	s_and_b64 vcc, exec, s[8:9]
	s_cbranch_vccnz .LBB0_122
	v_lshlrev_b32_e32 v144, 16, v30
	v_and_b32_e32 v145, 0xffff0000, v30
	v_pk_add_f32 v[146:147], v[146:147], v[144:145]
	v_lshlrev_b32_e32 v144, 16, v31
	v_and_b32_e32 v145, 0xffff0000, v31
	v_pk_add_f32 v[142:143], v[142:143], v[144:145]
	v_lshlrev_b32_e32 v144, 16, v32
	v_and_b32_e32 v145, 0xffff0000, v32
	v_pk_add_f32 v[138:139], v[138:139], v[144:145]
	v_lshlrev_b32_e32 v144, 16, v33
	v_and_b32_e32 v145, 0xffff0000, v33
	v_pk_add_f32 v[140:141], v[140:141], v[144:145]

; DI float sigm(float x) { return 1.f / (1.f + __expf(-x)); }
; DI void gate_reg(PREF p, int l, int n, f32x4 (&acc)[2][2][4][2], int dt) {
;     ...
;       for (int m = 0; m < 4; ++m) {
;         float b[8]; unpack8(bn[m], b);
;         float v[8];
; #pragma unroll
;         for (int nn = 0; nn < 2; ++nn)
; #pragma unroll
;           for (int j = 0; j < 4; ++j) v[nn * 4 + j] = sigm(acc[ai][bj][m][nn][j] + bias[bj][nn]) * b[nn * 4 + j];
;         if (n > 0) {
;           float o[8]; unpack8(pv[m], o);
; #pragma unroll
;           for (int e = 0; e < 8; ++e) v[e] += o[e];
;         }
.LBB0_124:
	v_add_f32_e32 v0, v134, v184
	v_mul_f32_e32 v0, 0xbfb8aa3b, v0
	v_exp_f32_e32 v134, v0
	v_add_f32_e32 v0, v135, v184
	v_mul_f32_e32 v0, 0xbfb8aa3b, v0
	v_exp_f32_e32 v135, v0
	v_lshlrev_b32_e32 v144, 16, v130
	v_and_b32_e32 v145, 0xffff0000, v130
	v_pk_add_f32 v[134:135], v[134:135], 1.0 op_sel_hi:[1,0]
	s_nop 0
	v_rcp_f32_e32 v135, v135
	v_rcp_f32_e32 v134, v134
	v_add_f32_e32 v0, v136, v184
	v_mul_f32_e32 v0, 0xbfb8aa3b, v0
	v_exp_f32_e32 v136, v0
	v_add_f32_e32 v0, v137, v184
	v_mul_f32_e32 v0, 0xbfb8aa3b, v0
	v_exp_f32_e32 v137, v0
	v_pk_mul_f32 v[134:135], v[134:135], v[144:145]
	v_lshlrev_b32_e32 v130, 16, v131
	v_and_b32_e32 v131, 0xffff0000, v131
	v_pk_add_f32 v[136:137], v[136:137], 1.0 op_sel_hi:[1,0]
	s_nop 0
	v_rcp_f32_e32 v137, v137
	v_rcp_f32_e32 v136, v136
	v_add_f32_e32 v0, v126, v183
	v_mul_f32_e32 v0, 0xbfb8aa3b, v0
	v_exp_f32_e32 v126, v0
	v_add_f32_e32 v0, v127, v183
	v_mul_f32_e32 v0, 0xbfb8aa3b, v0
	v_exp_f32_e32 v127, v0
	v_pk_mul_f32 v[130:131], v[136:137], v[130:131]
	v_lshlrev_b32_e32 v136, 16, v132
	v_and_b32_e32 v137, 0xffff0000, v132
	v_pk_add_f32 v[126:127], v[126:127], 1.0 op_sel_hi:[1,0]
	s_nop 0
	v_rcp_f32_e32 v127, v127
	v_rcp_f32_e32 v126, v126
	v_add_f32_e32 v0, v128, v183
	v_mul_f32_e32 v0, 0xbfb8aa3b, v0
	v_pk_mul_f32 v[136:137], v[126:127], v[136:137]
	v_exp_f32_e32 v126, v0
	v_add_f32_e32 v0, v129, v183
	v_mul_f32_e32 v0, 0xbfb8aa3b, v0
	v_exp_f32_e32 v127, v0
	v_lshlrev_b32_e32 v128, 16, v133
	v_and_b32_e32 v129, 0xffff0000, v133
	v_pk_add_f32 v[126:127], v[126:127], 1.0 op_sel_hi:[1,0]
	s_nop 0
	v_rcp_f32_e32 v127, v127
	v_rcp_f32_e32 v126, v126
	s_nop 0
	v_pk_mul_f32 v[132:133], v[126:127], v[128:129]
	s_and_b64 vcc, exec, s[8:9]
	s_cbranch_vccnz .LBB0_126
	v_lshlrev_b32_e32 v126, 16, v18
	v_and_b32_e32 v127, 0xffff0000, v18
	v_pk_add_f32 v[134:135], v[134:135], v[126:127]
	v_lshlrev_b32_e32 v126, 16, v19
	v_and_b32_e32 v127, 0xffff0000, v19
	v_pk_add_f32 v[130:131], v[130:131], v[126:127]
	v_lshlrev_b32_e32 v126, 16, v20
	v_and_b32_e32 v127, 0xffff0000, v20
	v_pk_add_f32 v[136:137], v[136:137], v[126:127]
	v_lshlrev_b32_e32 v126, 16, v21
	v_and_b32_e32 v127, 0xffff0000, v21
	v_pk_add_f32 v[132:133], v[132:133], v[126:127]

; DI float sigm(float x) { return 1.f / (1.f + __expf(-x)); }
; DI void gate_reg(PREF p, int l, int n, f32x4 (&acc)[2][2][4][2], int dt) {
;     ...
;       for (int m = 0; m < 4; ++m) {
;         float b[8]; unpack8(bn[m], b);
;         float v[8];
; #pragma unroll
;         for (int nn = 0; nn < 2; ++nn)
; #pragma unroll
;           for (int j = 0; j < 4; ++j) v[nn * 4 + j] = sigm(acc[ai][bj][m][nn][j] + bias[bj][nn]) * b[nn * 4 + j];
;         if (n > 0) {
;           float o[8]; unpack8(pv[m], o);
; #pragma unroll
;           for (int e = 0; e < 8; ++e) v[e] += o[e];
;         }
.LBB0_128:
	v_add_f32_e32 v0, v122, v184
	v_mul_f32_e32 v0, 0xbfb8aa3b, v0
	v_exp_f32_e32 v122, v0
	v_add_f32_e32 v0, v123, v184
	v_mul_f32_e32 v0, 0xbfb8aa3b, v0
	v_exp_f32_e32 v123, v0
	v_lshlrev_b32_e32 v126, 16, v118
	v_and_b32_e32 v127, 0xffff0000, v118
	v_pk_add_f32 v[122:123], v[122:123], 1.0 op_sel_hi:[1,0]
	s_nop 0
	v_rcp_f32_e32 v123, v123
	v_rcp_f32_e32 v122, v122
	v_add_f32_e32 v0, v124, v184
	v_mul_f32_e32 v0, 0xbfb8aa3b, v0
	v_pk_mul_f32 v[144:145], v[122:123], v[126:127]
	v_exp_f32_e32 v122, v0
	v_add_f32_e32 v0, v125, v184
	v_mul_f32_e32 v0, 0xbfb8aa3b, v0
	v_exp_f32_e32 v123, v0
	v_lshlrev_b32_e32 v118, 16, v119
	v_and_b32_e32 v119, 0xffff0000, v119
	v_pk_add_f32 v[122:123], v[122:123], 1.0 op_sel_hi:[1,0]
	s_nop 0
	v_rcp_f32_e32 v123, v123
	v_rcp_f32_e32 v122, v122
	v_add_f32_e32 v0, v114, v183
	v_mul_f32_e32 v0, 0xbfb8aa3b, v0
	v_exp_f32_e32 v114, v0
	v_add_f32_e32 v0, v115, v183
	v_mul_f32_e32 v0, 0xbfb8aa3b, v0
	v_exp_f32_e32 v115, v0
	v_pk_mul_f32 v[148:149], v[122:123], v[118:119]
	v_lshlrev_b32_e32 v118, 16, v120
	v_and_b32_e32 v119, 0xffff0000, v120
	v_pk_add_f32 v[114:115], v[114:115], 1.0 op_sel_hi:[1,0]
	s_nop 0
	v_rcp_f32_e32 v115, v115
	v_rcp_f32_e32 v114, v114
	v_add_f32_e32 v0, v116, v183
	v_mul_f32_e32 v0, 0xbfb8aa3b, v0
	v_pk_mul_f32 v[156:157], v[114:115], v[118:119]
	v_exp_f32_e32 v114, v0
	v_add_f32_e32 v0, v117, v183
	v_mul_f32_e32 v0, 0xbfb8aa3b, v0
	v_exp_f32_e32 v115, v0
	v_lshlrev_b32_e32 v116, 16, v121
	v_and_b32_e32 v117, 0xffff0000, v121
	v_pk_add_f32 v[114:115], v[114:115], 1.0 op_sel_hi:[1,0]
	s_nop 0
	v_rcp_f32_e32 v115, v115
	v_rcp_f32_e32 v114, v114
	s_nop 0
	v_pk_mul_f32 v[160:161], v[114:115], v[116:117]
	s_and_b64 vcc, exec, s[8:9]
	s_cbranch_vccnz .LBB0_130
	v_lshlrev_b32_e32 v114, 16, v6
	v_and_b32_e32 v115, 0xffff0000, v6
	v_pk_add_f32 v[144:145], v[144:145], v[114:115]
	v_lshlrev_b32_e32 v114, 16, v7
	v_and_b32_e32 v115, 0xffff0000, v7
	v_pk_add_f32 v[148:149], v[148:149], v[114:115]
	v_lshlrev_b32_e32 v114, 16, v8
	v_and_b32_e32 v115, 0xffff0000, v8
	v_pk_add_f32 v[156:157], v[156:157], v[114:115]
	v_lshlrev_b32_e32 v114, 16, v9
	v_and_b32_e32 v115, 0xffff0000, v9
	v_pk_add_f32 v[160:161], v[160:161], v[114:115]

; DI float sigm(float x) { return 1.f / (1.f + __expf(-x)); }
; DI void gate_reg(PREF p, int l, int n, f32x4 (&acc)[2][2][4][2], int dt) {
;     ...
;       for (int m = 0; m < 4; ++m) {
;         float b[8]; unpack8(bn[m], b);
;         float v[8];
; #pragma unroll
;         for (int nn = 0; nn < 2; ++nn)
; #pragma unroll
;           for (int j = 0; j < 4; ++j) v[nn * 4 + j] = sigm(acc[ai][bj][m][nn][j] + bias[bj][nn]) * b[nn * 4 + j];
;         if (n > 0) {
;           float o[8]; unpack8(pv[m], o);
; #pragma unroll
;           for (int e = 0; e < 8; ++e) v[e] += o[e];
;         }
.LBB0_140:
	v_add_f32_e32 v0, v110, v182
	v_mul_f32_e32 v0, 0xbfb8aa3b, v0
	v_exp_f32_e32 v110, v0
	v_add_f32_e32 v0, v111, v182
	v_mul_f32_e32 v0, 0xbfb8aa3b, v0
	v_exp_f32_e32 v111, v0
	s_waitcnt vmcnt(3)
	v_lshlrev_b32_e32 v186, 16, v126
	v_and_b32_e32 v187, 0xffff0000, v126
	v_pk_add_f32 v[110:111], v[110:111], 1.0 op_sel_hi:[1,0]
	s_nop 0
	v_rcp_f32_e32 v111, v111
	v_rcp_f32_e32 v110, v110
	v_add_f32_e32 v0, v112, v182
	v_mul_f32_e32 v0, 0xbfb8aa3b, v0
	v_exp_f32_e32 v112, v0
	v_add_f32_e32 v0, v113, v182
	v_mul_f32_e32 v0, 0xbfb8aa3b, v0
	v_exp_f32_e32 v113, v0
	v_pk_mul_f32 v[110:111], v[110:111], v[186:187]
	v_lshlrev_b32_e32 v126, 16, v127
	v_and_b32_e32 v127, 0xffff0000, v127
	v_pk_add_f32 v[112:113], v[112:113], 1.0 op_sel_hi:[1,0]
	s_nop 0
	v_rcp_f32_e32 v113, v113
	v_rcp_f32_e32 v112, v112
	v_add_f32_e32 v0, v106, v162
	v_mul_f32_e32 v0, 0xbfb8aa3b, v0
	v_exp_f32_e32 v106, v0
	v_add_f32_e32 v0, v107, v162
	v_mul_f32_e32 v0, 0xbfb8aa3b, v0
	v_exp_f32_e32 v107, v0
	v_pk_mul_f32 v[112:113], v[112:113], v[126:127]
	v_lshlrev_b32_e32 v126, 16, v128
	v_and_b32_e32 v127, 0xffff0000, v128
	v_pk_add_f32 v[106:107], v[106:107], 1.0 op_sel_hi:[1,0]
	s_nop 0
	v_rcp_f32_e32 v107, v107
	v_rcp_f32_e32 v106, v106
	v_add_f32_e32 v0, v108, v162
	v_mul_f32_e32 v0, 0xbfb8aa3b, v0
	v_exp_f32_e32 v108, v0
	v_add_f32_e32 v0, v109, v162
	v_mul_f32_e32 v0, 0xbfb8aa3b, v0
	v_exp_f32_e32 v109, v0
	v_pk_mul_f32 v[106:107], v[106:107], v[126:127]
	v_lshlrev_b32_e32 v126, 16, v129
	v_and_b32_e32 v127, 0xffff0000, v129
	v_pk_add_f32 v[108:109], v[108:109], 1.0 op_sel_hi:[1,0]
	s_nop 0
	v_rcp_f32_e32 v109, v109
	v_rcp_f32_e32 v108, v108
	s_nop 0
	v_pk_mul_f32 v[108:109], v[108:109], v[126:127]
	s_and_b64 vcc, exec, s[8:9]
	s_cbranch_vccnz .LBB0_142
	v_lshlrev_b32_e32 v126, 16, v42
	v_and_b32_e32 v127, 0xffff0000, v42
	v_pk_add_f32 v[110:111], v[110:111], v[126:127]
	v_lshlrev_b32_e32 v126, 16, v43
	v_and_b32_e32 v127, 0xffff0000, v43
	v_pk_add_f32 v[112:113], v[112:113], v[126:127]
	v_lshlrev_b32_e32 v126, 16, v44
	v_and_b32_e32 v127, 0xffff0000, v44
	v_pk_add_f32 v[106:107], v[106:107], v[126:127]
	v_lshlrev_b32_e32 v126, 16, v45
	v_and_b32_e32 v127, 0xffff0000, v45
	v_pk_add_f32 v[108:109], v[108:109], v[126:127]

; DI float sigm(float x) { return 1.f / (1.f + __expf(-x)); }
; DI void gate_reg(PREF p, int l, int n, f32x4 (&acc)[2][2][4][2], int dt) {
;     ...
;       for (int m = 0; m < 4; ++m) {
;         float b[8]; unpack8(bn[m], b);
;         float v[8];
; #pragma unroll
;         for (int nn = 0; nn < 2; ++nn)
; #pragma unroll
;           for (int j = 0; j < 4; ++j) v[nn * 4 + j] = sigm(acc[ai][bj][m][nn][j] + bias[bj][nn]) * b[nn * 4 + j];
;         if (n > 0) {
;           float o[8]; unpack8(pv[m], o);
; #pragma unroll
;           for (int e = 0; e < 8; ++e) v[e] += o[e];
;         }
.LBB0_144:
	v_add_f32_e32 v0, v102, v182
	v_mul_f32_e32 v0, 0xbfb8aa3b, v0
	v_exp_f32_e32 v102, v0
	v_add_f32_e32 v0, v103, v182
	v_mul_f32_e32 v0, 0xbfb8aa3b, v0
	v_exp_f32_e32 v103, v0
	s_waitcnt vmcnt(2)
	v_lshlrev_b32_e32 v126, 16, v122
	v_and_b32_e32 v127, 0xffff0000, v122
	v_pk_add_f32 v[102:103], v[102:103], 1.0 op_sel_hi:[1,0]
	s_nop 0
	v_rcp_f32_e32 v103, v103
	v_rcp_f32_e32 v102, v102
	v_add_f32_e32 v0, v104, v182
	v_mul_f32_e32 v0, 0xbfb8aa3b, v0
	v_exp_f32_e32 v104, v0
	v_add_f32_e32 v0, v105, v182
	v_mul_f32_e32 v0, 0xbfb8aa3b, v0
	v_exp_f32_e32 v105, v0
	v_pk_mul_f32 v[102:103], v[102:103], v[126:127]
	v_lshlrev_b32_e32 v122, 16, v123
	v_and_b32_e32 v123, 0xffff0000, v123
	v_pk_add_f32 v[104:105], v[104:105], 1.0 op_sel_hi:[1,0]
	s_nop 0
	v_rcp_f32_e32 v105, v105
	v_rcp_f32_e32 v104, v104
	v_add_f32_e32 v0, v98, v162
	v_mul_f32_e32 v0, 0xbfb8aa3b, v0
	v_exp_f32_e32 v98, v0
	v_add_f32_e32 v0, v99, v162
	v_mul_f32_e32 v0, 0xbfb8aa3b, v0
	v_exp_f32_e32 v99, v0
	v_pk_mul_f32 v[104:105], v[104:105], v[122:123]
	v_lshlrev_b32_e32 v122, 16, v124
	v_and_b32_e32 v123, 0xffff0000, v124
	v_pk_add_f32 v[98:99], v[98:99], 1.0 op_sel_hi:[1,0]
	s_nop 0
	v_rcp_f32_e32 v99, v99
	v_rcp_f32_e32 v98, v98
	v_add_f32_e32 v0, v100, v162
	v_mul_f32_e32 v0, 0xbfb8aa3b, v0
	v_exp_f32_e32 v100, v0
	v_add_f32_e32 v0, v101, v162
	v_mul_f32_e32 v0, 0xbfb8aa3b, v0
	v_exp_f32_e32 v101, v0
	v_pk_mul_f32 v[98:99], v[98:99], v[122:123]
	v_lshlrev_b32_e32 v122, 16, v125
	v_and_b32_e32 v123, 0xffff0000, v125
	v_pk_add_f32 v[100:101], v[100:101], 1.0 op_sel_hi:[1,0]
	s_nop 0
	v_rcp_f32_e32 v101, v101
	v_rcp_f32_e32 v100, v100
	s_nop 0
	v_pk_mul_f32 v[100:101], v[100:101], v[122:123]
	s_and_b64 vcc, exec, s[8:9]
	s_cbranch_vccnz .LBB0_146
	v_lshlrev_b32_e32 v122, 16, v30
	v_and_b32_e32 v123, 0xffff0000, v30
	v_pk_add_f32 v[102:103], v[102:103], v[122:123]
	v_lshlrev_b32_e32 v122, 16, v31
	v_and_b32_e32 v123, 0xffff0000, v31
	v_pk_add_f32 v[104:105], v[104:105], v[122:123]
	v_lshlrev_b32_e32 v122, 16, v32
	v_and_b32_e32 v123, 0xffff0000, v32
	v_pk_add_f32 v[98:99], v[98:99], v[122:123]
	v_lshlrev_b32_e32 v122, 16, v33
	v_and_b32_e32 v123, 0xffff0000, v33
	v_pk_add_f32 v[100:101], v[100:101], v[122:123]

; DI float sigm(float x) { return 1.f / (1.f + __expf(-x)); }
; DI void gate_reg(PREF p, int l, int n, f32x4 (&acc)[2][2][4][2], int dt) {
;     ...
;       for (int m = 0; m < 4; ++m) {
;         float b[8]; unpack8(bn[m], b);
;         float v[8];
; #pragma unroll
;         for (int nn = 0; nn < 2; ++nn)
; #pragma unroll
;           for (int j = 0; j < 4; ++j) v[nn * 4 + j] = sigm(acc[ai][bj][m][nn][j] + bias[bj][nn]) * b[nn * 4 + j];
;         if (n > 0) {
;           float o[8]; unpack8(pv[m], o);
; #pragma unroll
;           for (int e = 0; e < 8; ++e) v[e] += o[e];
;         }
.LBB0_148:
	v_add_f32_e32 v0, v94, v182
	v_mul_f32_e32 v0, 0xbfb8aa3b, v0
	v_exp_f32_e32 v94, v0
	v_add_f32_e32 v0, v95, v182
	v_mul_f32_e32 v0, 0xbfb8aa3b, v0
	v_exp_f32_e32 v95, v0
	s_waitcnt vmcnt(1)
	v_lshlrev_b32_e32 v122, 16, v118
	v_and_b32_e32 v123, 0xffff0000, v118
	v_pk_add_f32 v[94:95], v[94:95], 1.0 op_sel_hi:[1,0]
	s_nop 0
	v_rcp_f32_e32 v95, v95
	v_rcp_f32_e32 v94, v94
	v_add_f32_e32 v0, v96, v182
	v_mul_f32_e32 v0, 0xbfb8aa3b, v0
	v_pk_mul_f32 v[122:123], v[94:95], v[122:123]
	v_exp_f32_e32 v94, v0
	v_add_f32_e32 v0, v97, v182
	v_mul_f32_e32 v0, 0xbfb8aa3b, v0
	v_exp_f32_e32 v95, v0
	v_lshlrev_b32_e32 v96, 16, v119
	v_and_b32_e32 v97, 0xffff0000, v119
	v_pk_add_f32 v[94:95], v[94:95], 1.0 op_sel_hi:[1,0]
	s_nop 0
	v_rcp_f32_e32 v95, v95
	v_rcp_f32_e32 v94, v94
	v_add_f32_e32 v0, v90, v162
	v_mul_f32_e32 v0, 0xbfb8aa3b, v0
	v_exp_f32_e32 v90, v0
	v_add_f32_e32 v0, v91, v162
	v_mul_f32_e32 v0, 0xbfb8aa3b, v0
	v_exp_f32_e32 v91, v0
	v_pk_mul_f32 v[118:119], v[94:95], v[96:97]
	v_lshlrev_b32_e32 v94, 16, v120
	v_and_b32_e32 v95, 0xffff0000, v120
	v_pk_add_f32 v[90:91], v[90:91], 1.0 op_sel_hi:[1,0]
	s_nop 0
	v_rcp_f32_e32 v91, v91
	v_rcp_f32_e32 v90, v90
	v_add_f32_e32 v0, v92, v162
	v_mul_f32_e32 v0, 0xbfb8aa3b, v0
	v_pk_mul_f32 v[124:125], v[90:91], v[94:95]
	v_exp_f32_e32 v90, v0
	v_add_f32_e32 v0, v93, v162
	v_mul_f32_e32 v0, 0xbfb8aa3b, v0
	v_exp_f32_e32 v91, v0
	v_lshlrev_b32_e32 v92, 16, v121
	v_and_b32_e32 v93, 0xffff0000, v121
	v_pk_add_f32 v[90:91], v[90:91], 1.0 op_sel_hi:[1,0]
	s_nop 0
	v_rcp_f32_e32 v91, v91
	v_rcp_f32_e32 v90, v90
	s_nop 0
	v_pk_mul_f32 v[120:121], v[90:91], v[92:93]
	s_and_b64 vcc, exec, s[8:9]
	s_cbranch_vccnz .LBB0_150
	v_lshlrev_b32_e32 v90, 16, v18
	v_and_b32_e32 v91, 0xffff0000, v18
	v_pk_add_f32 v[122:123], v[122:123], v[90:91]
	v_lshlrev_b32_e32 v90, 16, v19
	v_and_b32_e32 v91, 0xffff0000, v19
	v_pk_add_f32 v[118:119], v[118:119], v[90:91]
	v_lshlrev_b32_e32 v90, 16, v20
	v_and_b32_e32 v91, 0xffff0000, v20
	v_pk_add_f32 v[124:125], v[124:125], v[90:91]
	v_lshlrev_b32_e32 v90, 16, v21
	v_and_b32_e32 v91, 0xffff0000, v21
	v_pk_add_f32 v[120:121], v[120:121], v[90:91]

; DI float sigm(float x) { return 1.f / (1.f + __expf(-x)); }
; DI void gate_reg(PREF p, int l, int n, f32x4 (&acc)[2][2][4][2], int dt) {
;     ...
;       for (int m = 0; m < 4; ++m) {
;         float b[8]; unpack8(bn[m], b);
;         float v[8];
; #pragma unroll
;         for (int nn = 0; nn < 2; ++nn)
; #pragma unroll
;           for (int j = 0; j < 4; ++j) v[nn * 4 + j] = sigm(acc[ai][bj][m][nn][j] + bias[bj][nn]) * b[nn * 4 + j];
;         if (n > 0) {
;           float o[8]; unpack8(pv[m], o);
; #pragma unroll
;           for (int e = 0; e < 8; ++e) v[e] += o[e];
;         }
.LBB0_152:
	v_add_f32_e32 v0, v86, v182
	v_mul_f32_e32 v0, 0xbfb8aa3b, v0
	v_exp_f32_e32 v86, v0
	v_add_f32_e32 v0, v87, v182
	v_mul_f32_e32 v0, 0xbfb8aa3b, v0
	v_exp_f32_e32 v87, v0
	s_waitcnt vmcnt(0)
	v_lshlrev_b32_e32 v90, 16, v114
	v_and_b32_e32 v91, 0xffff0000, v114
	v_pk_add_f32 v[86:87], v[86:87], 1.0 op_sel_hi:[1,0]
	s_nop 0
	v_rcp_f32_e32 v87, v87
	v_rcp_f32_e32 v86, v86
	v_add_f32_e32 v0, v88, v182
	v_mul_f32_e32 v0, 0xbfb8aa3b, v0
	v_pk_mul_f32 v[126:127], v[86:87], v[90:91]
	v_exp_f32_e32 v86, v0
	v_add_f32_e32 v0, v89, v182
	v_mul_f32_e32 v0, 0xbfb8aa3b, v0
	v_exp_f32_e32 v87, v0
	v_lshlrev_b32_e32 v88, 16, v115
	v_and_b32_e32 v89, 0xffff0000, v115
	v_pk_add_f32 v[86:87], v[86:87], 1.0 op_sel_hi:[1,0]
	s_nop 0
	v_rcp_f32_e32 v87, v87
	v_rcp_f32_e32 v86, v86
	v_add_f32_e32 v0, v82, v162
	v_mul_f32_e32 v0, 0xbfb8aa3b, v0
	v_exp_f32_e32 v82, v0
	v_add_f32_e32 v0, v83, v162
	v_mul_f32_e32 v0, 0xbfb8aa3b, v0
	v_exp_f32_e32 v83, v0
	v_pk_mul_f32 v[114:115], v[86:87], v[88:89]
	v_lshlrev_b32_e32 v86, 16, v116
	v_and_b32_e32 v87, 0xffff0000, v116
	v_pk_add_f32 v[82:83], v[82:83], 1.0 op_sel_hi:[1,0]
	s_nop 0
	v_rcp_f32_e32 v83, v83
	v_rcp_f32_e32 v82, v82
	v_add_f32_e32 v0, v84, v162
	v_mul_f32_e32 v0, 0xbfb8aa3b, v0
	v_pk_mul_f32 v[128:129], v[82:83], v[86:87]
	v_exp_f32_e32 v82, v0
	v_add_f32_e32 v0, v85, v162
	v_mul_f32_e32 v0, 0xbfb8aa3b, v0
	v_exp_f32_e32 v83, v0
	v_lshlrev_b32_e32 v84, 16, v117
	v_and_b32_e32 v85, 0xffff0000, v117
	v_pk_add_f32 v[82:83], v[82:83], 1.0 op_sel_hi:[1,0]
	s_nop 0
	v_rcp_f32_e32 v83, v83
	v_rcp_f32_e32 v82, v82
	s_nop 0
	v_pk_mul_f32 v[116:117], v[82:83], v[84:85]
	s_and_b64 vcc, exec, s[8:9]
	s_cbranch_vccnz .LBB0_154
	v_lshlrev_b32_e32 v82, 16, v6
	v_and_b32_e32 v83, 0xffff0000, v6
	v_pk_add_f32 v[126:127], v[126:127], v[82:83]
	v_lshlrev_b32_e32 v82, 16, v7
	v_and_b32_e32 v83, 0xffff0000, v7
	v_pk_add_f32 v[114:115], v[114:115], v[82:83]
	v_lshlrev_b32_e32 v82, 16, v8
	v_and_b32_e32 v83, 0xffff0000, v8
	v_pk_add_f32 v[128:129], v[128:129], v[82:83]
	v_lshlrev_b32_e32 v82, 16, v9
	v_and_b32_e32 v83, 0xffff0000, v9
	v_pk_add_f32 v[116:117], v[116:117], v[82:83]

; DI float sigm(float x) { return 1.f / (1.f + __expf(-x)); }
; DI void gate_reg(PREF p, int l, int n, f32x4 (&acc)[2][2][4][2], int dt) {
;     ...
;   for (int ai = 0; ai < 2; ++ai)
; #pragma unroll
;     for (int bj = 0; bj < 2; ++bj) {
;       __builtin_amdgcn_sched_barrier(0);
;       u32x4 bn[4], pv[4];
; #pragma unroll
;       for (int m = 0; m < 4; ++m) {
;         bn[m] = sbn[((ai * 2 + bj) * 4 + m) * 64];
;         if (n > 0) pv[m] = ssum[((ai * 2 + bj) * 4 + m) * 64];
;       }
; #pragma unroll
;       for (int m = 0; m < 4; ++m) {
;         float b[8]; unpack8(bn[m], b);
;         float v[8];
; #pragma unroll
;         for (int nn = 0; nn < 2; ++nn)
; #pragma unroll
;           for (int j = 0; j < 4; ++j) v[nn * 4 + j] = sigm(acc[ai][bj][m][nn][j] + bias[bj][nn]) * b[nn * 4 + j];
;         if (n > 0) {
;           float o[8]; unpack8(pv[m], o);
; #pragma unroll
;           for (int e = 0; e < 8; ++e) v[e] += o[e];
;         }
.LBB0_164:
	v_add_f32_e32 v0, v78, v184
	v_mul_f32_e32 v0, 0xbfb8aa3b, v0
	v_exp_f32_e32 v78, v0
	v_add_f32_e32 v0, v79, v184
	v_mul_f32_e32 v0, 0xbfb8aa3b, v0
	v_exp_f32_e32 v79, v0
	s_waitcnt vmcnt(3)
	v_lshlrev_b32_e32 v186, 16, v94
	v_and_b32_e32 v187, 0xffff0000, v94
	v_pk_add_f32 v[78:79], v[78:79], 1.0 op_sel_hi:[1,0]
	s_nop 0
	v_rcp_f32_e32 v79, v79
	v_rcp_f32_e32 v78, v78
	v_add_f32_e32 v0, v80, v184
	v_mul_f32_e32 v0, 0xbfb8aa3b, v0
	v_exp_f32_e32 v80, v0
	v_add_f32_e32 v0, v81, v184
	v_mul_f32_e32 v0, 0xbfb8aa3b, v0
	v_exp_f32_e32 v81, v0
	v_pk_mul_f32 v[78:79], v[78:79], v[186:187]
	v_lshlrev_b32_e32 v94, 16, v95
	v_and_b32_e32 v95, 0xffff0000, v95
	v_pk_add_f32 v[80:81], v[80:81], 1.0 op_sel_hi:[1,0]
	s_nop 0
	v_rcp_f32_e32 v81, v81
	v_rcp_f32_e32 v80, v80
	v_add_f32_e32 v0, v74, v183
	v_mul_f32_e32 v0, 0xbfb8aa3b, v0
	v_exp_f32_e32 v74, v0
	v_add_f32_e32 v0, v75, v183
	v_mul_f32_e32 v0, 0xbfb8aa3b, v0
	v_exp_f32_e32 v75, v0
	v_pk_mul_f32 v[80:81], v[80:81], v[94:95]
	v_lshlrev_b32_e32 v94, 16, v96
	v_and_b32_e32 v95, 0xffff0000, v96
	v_pk_add_f32 v[74:75], v[74:75], 1.0 op_sel_hi:[1,0]
	s_nop 0
	v_rcp_f32_e32 v75, v75
	v_rcp_f32_e32 v74, v74
	v_add_f32_e32 v0, v76, v183
	v_mul_f32_e32 v0, 0xbfb8aa3b, v0
	v_exp_f32_e32 v76, v0
	v_add_f32_e32 v0, v77, v183
	v_mul_f32_e32 v0, 0xbfb8aa3b, v0
	v_exp_f32_e32 v77, v0
	v_pk_mul_f32 v[74:75], v[74:75], v[94:95]
	v_lshlrev_b32_e32 v94, 16, v97
	v_and_b32_e32 v95, 0xffff0000, v97
	v_pk_add_f32 v[76:77], v[76:77], 1.0 op_sel_hi:[1,0]
	s_nop 0
	v_rcp_f32_e32 v77, v77
	v_rcp_f32_e32 v76, v76
	s_nop 0
	v_pk_mul_f32 v[76:77], v[76:77], v[94:95]
	s_and_b64 vcc, exec, s[8:9]
	s_cbranch_vccnz .LBB0_166
	v_lshlrev_b32_e32 v94, 16, v42
	v_and_b32_e32 v95, 0xffff0000, v42
	v_pk_add_f32 v[78:79], v[78:79], v[94:95]
	v_lshlrev_b32_e32 v94, 16, v43
	v_and_b32_e32 v95, 0xffff0000, v43
	v_pk_add_f32 v[80:81], v[80:81], v[94:95]
	v_lshlrev_b32_e32 v94, 16, v44
	v_and_b32_e32 v95, 0xffff0000, v44
	v_pk_add_f32 v[74:75], v[74:75], v[94:95]
	v_lshlrev_b32_e32 v94, 16, v45
	v_and_b32_e32 v95, 0xffff0000, v45
	v_pk_add_f32 v[76:77], v[76:77], v[94:95]

; DI float sigm(float x) { return 1.f / (1.f + __expf(-x)); }
; DI void gate_reg(PREF p, int l, int n, f32x4 (&acc)[2][2][4][2], int dt) {
;     ...
;   for (int ai = 0; ai < 2; ++ai)
; #pragma unroll
;     for (int bj = 0; bj < 2; ++bj) {
;       __builtin_amdgcn_sched_barrier(0);
;       u32x4 bn[4], pv[4];
; #pragma unroll
;       for (int m = 0; m < 4; ++m) {
;         bn[m] = sbn[((ai * 2 + bj) * 4 + m) * 64];
;         if (n > 0) pv[m] = ssum[((ai * 2 + bj) * 4 + m) * 64];
;       }
; #pragma unroll
;       for (int m = 0; m < 4; ++m) {
;         float b[8]; unpack8(bn[m], b);
;         float v[8];
; #pragma unroll
;         for (int nn = 0; nn < 2; ++nn)
; #pragma unroll
;           for (int j = 0; j < 4; ++j) v[nn * 4 + j] = sigm(acc[ai][bj][m][nn][j] + bias[bj][nn]) * b[nn * 4 + j];
;         if (n > 0) {
;           float o[8]; unpack8(pv[m], o);
; #pragma unroll
;           for (int e = 0; e < 8; ++e) v[e] += o[e];
;         }
.LBB0_168:
	v_add_f32_e32 v0, v70, v184
	v_mul_f32_e32 v0, 0xbfb8aa3b, v0
	v_exp_f32_e32 v70, v0
	v_add_f32_e32 v0, v71, v184
	v_mul_f32_e32 v0, 0xbfb8aa3b, v0
	v_exp_f32_e32 v71, v0
	s_waitcnt vmcnt(2)
	v_lshlrev_b32_e32 v94, 16, v90
	v_and_b32_e32 v95, 0xffff0000, v90
	v_pk_add_f32 v[70:71], v[70:71], 1.0 op_sel_hi:[1,0]
	s_nop 0
	v_rcp_f32_e32 v71, v71
	v_rcp_f32_e32 v70, v70
	v_add_f32_e32 v0, v72, v184
	v_mul_f32_e32 v0, 0xbfb8aa3b, v0
	v_exp_f32_e32 v72, v0
	v_add_f32_e32 v0, v73, v184
	v_mul_f32_e32 v0, 0xbfb8aa3b, v0
	v_exp_f32_e32 v73, v0
	v_pk_mul_f32 v[70:71], v[70:71], v[94:95]
	v_lshlrev_b32_e32 v90, 16, v91
	v_and_b32_e32 v91, 0xffff0000, v91
	v_pk_add_f32 v[72:73], v[72:73], 1.0 op_sel_hi:[1,0]
	s_nop 0
	v_rcp_f32_e32 v73, v73
	v_rcp_f32_e32 v72, v72
	v_add_f32_e32 v0, v66, v183
	v_mul_f32_e32 v0, 0xbfb8aa3b, v0
	v_exp_f32_e32 v66, v0
	v_add_f32_e32 v0, v67, v183
	v_mul_f32_e32 v0, 0xbfb8aa3b, v0
	v_exp_f32_e32 v67, v0
	v_pk_mul_f32 v[72:73], v[72:73], v[90:91]
	v_lshlrev_b32_e32 v90, 16, v92
	v_and_b32_e32 v91, 0xffff0000, v92
	v_pk_add_f32 v[66:67], v[66:67], 1.0 op_sel_hi:[1,0]
	s_nop 0
	v_rcp_f32_e32 v67, v67
	v_rcp_f32_e32 v66, v66
	v_add_f32_e32 v0, v68, v183
	v_mul_f32_e32 v0, 0xbfb8aa3b, v0
	v_exp_f32_e32 v68, v0
	v_add_f32_e32 v0, v69, v183
	v_mul_f32_e32 v0, 0xbfb8aa3b, v0
	v_exp_f32_e32 v69, v0
	v_pk_mul_f32 v[66:67], v[66:67], v[90:91]
	v_lshlrev_b32_e32 v90, 16, v93
	v_and_b32_e32 v91, 0xffff0000, v93
	v_pk_add_f32 v[68:69], v[68:69], 1.0 op_sel_hi:[1,0]
	s_nop 0
	v_rcp_f32_e32 v69, v69
	v_rcp_f32_e32 v68, v68
	s_nop 0
	v_pk_mul_f32 v[68:69], v[68:69], v[90:91]
	s_and_b64 vcc, exec, s[8:9]
	s_cbranch_vccnz .LBB0_170
	v_lshlrev_b32_e32 v90, 16, v30
	v_and_b32_e32 v91, 0xffff0000, v30
	v_pk_add_f32 v[70:71], v[70:71], v[90:91]
	v_lshlrev_b32_e32 v90, 16, v31
	v_and_b32_e32 v91, 0xffff0000, v31
	v_pk_add_f32 v[72:73], v[72:73], v[90:91]
	v_lshlrev_b32_e32 v90, 16, v32
	v_and_b32_e32 v91, 0xffff0000, v32
	v_pk_add_f32 v[66:67], v[66:67], v[90:91]
	v_lshlrev_b32_e32 v90, 16, v33
	v_and_b32_e32 v91, 0xffff0000, v33
	v_pk_add_f32 v[68:69], v[68:69], v[90:91]

; DI float sigm(float x) { return 1.f / (1.f + __expf(-x)); }
; DI void gate_reg(PREF p, int l, int n, f32x4 (&acc)[2][2][4][2], int dt) {
;     ...
;   for (int ai = 0; ai < 2; ++ai)
; #pragma unroll
;     for (int bj = 0; bj < 2; ++bj) {
;       __builtin_amdgcn_sched_barrier(0);
;       u32x4 bn[4], pv[4];
; #pragma unroll
;       for (int m = 0; m < 4; ++m) {
;         bn[m] = sbn[((ai * 2 + bj) * 4 + m) * 64];
;         if (n > 0) pv[m] = ssum[((ai * 2 + bj) * 4 + m) * 64];
;       }
; #pragma unroll
;       for (int m = 0; m < 4; ++m) {
;         float b[8]; unpack8(bn[m], b);
;         float v[8];
; #pragma unroll
;         for (int nn = 0; nn < 2; ++nn)
; #pragma unroll
;           for (int j = 0; j < 4; ++j) v[nn * 4 + j] = sigm(acc[ai][bj][m][nn][j] + bias[bj][nn]) * b[nn * 4 + j];
;         if (n > 0) {
;           float o[8]; unpack8(pv[m], o);
; #pragma unroll
;           for (int e = 0; e < 8; ++e) v[e] += o[e];
;         }
.LBB0_172:
	v_add_f32_e32 v0, v62, v184
	v_mul_f32_e32 v0, 0xbfb8aa3b, v0
	v_exp_f32_e32 v62, v0
	v_add_f32_e32 v0, v63, v184
	v_mul_f32_e32 v0, 0xbfb8aa3b, v0
	v_exp_f32_e32 v63, v0
	s_waitcnt vmcnt(1)
	v_lshlrev_b32_e32 v90, 16, v86
	v_and_b32_e32 v91, 0xffff0000, v86
	v_pk_add_f32 v[62:63], v[62:63], 1.0 op_sel_hi:[1,0]
	s_nop 0
	v_rcp_f32_e32 v63, v63
	v_rcp_f32_e32 v62, v62
	v_add_f32_e32 v0, v64, v184
	v_mul_f32_e32 v0, 0xbfb8aa3b, v0
	v_pk_mul_f32 v[90:91], v[62:63], v[90:91]
	v_exp_f32_e32 v62, v0
	v_add_f32_e32 v0, v65, v184
	v_mul_f32_e32 v0, 0xbfb8aa3b, v0
	v_exp_f32_e32 v63, v0
	v_lshlrev_b32_e32 v64, 16, v87
	v_and_b32_e32 v65, 0xffff0000, v87
	v_pk_add_f32 v[62:63], v[62:63], 1.0 op_sel_hi:[1,0]
	s_nop 0
	v_rcp_f32_e32 v63, v63
	v_rcp_f32_e32 v62, v62
	v_add_f32_e32 v0, v58, v183
	v_mul_f32_e32 v0, 0xbfb8aa3b, v0
	v_exp_f32_e32 v58, v0
	v_add_f32_e32 v0, v59, v183
	v_mul_f32_e32 v0, 0xbfb8aa3b, v0
	v_exp_f32_e32 v59, v0
	v_pk_mul_f32 v[86:87], v[62:63], v[64:65]
	v_lshlrev_b32_e32 v62, 16, v88
	v_and_b32_e32 v63, 0xffff0000, v88
	v_pk_add_f32 v[58:59], v[58:59], 1.0 op_sel_hi:[1,0]
	s_nop 0
	v_rcp_f32_e32 v59, v59
	v_rcp_f32_e32 v58, v58
	v_add_f32_e32 v0, v60, v183
	v_mul_f32_e32 v0, 0xbfb8aa3b, v0
	v_pk_mul_f32 v[92:93], v[58:59], v[62:63]
	v_exp_f32_e32 v58, v0
	v_add_f32_e32 v0, v61, v183
	v_mul_f32_e32 v0, 0xbfb8aa3b, v0
	v_exp_f32_e32 v59, v0
	v_lshlrev_b32_e32 v60, 16, v89
	v_and_b32_e32 v61, 0xffff0000, v89
	v_pk_add_f32 v[58:59], v[58:59], 1.0 op_sel_hi:[1,0]
	s_nop 0
	v_rcp_f32_e32 v59, v59
	v_rcp_f32_e32 v58, v58
	s_nop 0
	v_pk_mul_f32 v[88:89], v[58:59], v[60:61]
	s_and_b64 vcc, exec, s[8:9]
	s_cbranch_vccnz .LBB0_174
	v_lshlrev_b32_e32 v58, 16, v18
	v_and_b32_e32 v59, 0xffff0000, v18
	v_pk_add_f32 v[90:91], v[90:91], v[58:59]
	v_lshlrev_b32_e32 v58, 16, v19
	v_and_b32_e32 v59, 0xffff0000, v19
	v_pk_add_f32 v[86:87], v[86:87], v[58:59]
	v_lshlrev_b32_e32 v58, 16, v20
	v_and_b32_e32 v59, 0xffff0000, v20
	v_pk_add_f32 v[92:93], v[92:93], v[58:59]
	v_lshlrev_b32_e32 v58, 16, v21
	v_and_b32_e32 v59, 0xffff0000, v21
	v_pk_add_f32 v[88:89], v[88:89], v[58:59]

; DI float sigm(float x) { return 1.f / (1.f + __expf(-x)); }
; DI void gate_reg(PREF p, int l, int n, f32x4 (&acc)[2][2][4][2], int dt) {
;     ...
;   for (int ai = 0; ai < 2; ++ai)
; #pragma unroll
;     for (int bj = 0; bj < 2; ++bj) {
;       __builtin_amdgcn_sched_barrier(0);
;       u32x4 bn[4], pv[4];
; #pragma unroll
;       for (int m = 0; m < 4; ++m) {
;         bn[m] = sbn[((ai * 2 + bj) * 4 + m) * 64];
;         if (n > 0) pv[m] = ssum[((ai * 2 + bj) * 4 + m) * 64];
;       }
; #pragma unroll
;       for (int m = 0; m < 4; ++m) {
;         float b[8]; unpack8(bn[m], b);
;         float v[8];
; #pragma unroll
;         for (int nn = 0; nn < 2; ++nn)
; #pragma unroll
;           for (int j = 0; j < 4; ++j) v[nn * 4 + j] = sigm(acc[ai][bj][m][nn][j] + bias[bj][nn]) * b[nn * 4 + j];
;         if (n > 0) {
;           float o[8]; unpack8(pv[m], o);
; #pragma unroll
;           for (int e = 0; e < 8; ++e) v[e] += o[e];
;         }
.LBB0_176:
	v_add_f32_e32 v0, v54, v184
	v_mul_f32_e32 v0, 0xbfb8aa3b, v0
	v_exp_f32_e32 v54, v0
	v_add_f32_e32 v0, v55, v184
	v_mul_f32_e32 v0, 0xbfb8aa3b, v0
	v_exp_f32_e32 v55, v0
	s_waitcnt vmcnt(0)
	v_lshlrev_b32_e32 v58, 16, v82
	v_and_b32_e32 v59, 0xffff0000, v82
	v_pk_add_f32 v[54:55], v[54:55], 1.0 op_sel_hi:[1,0]
	s_nop 0
	v_rcp_f32_e32 v55, v55
	v_rcp_f32_e32 v54, v54
	v_add_f32_e32 v0, v56, v184
	v_mul_f32_e32 v0, 0xbfb8aa3b, v0
	v_pk_mul_f32 v[94:95], v[54:55], v[58:59]
	v_exp_f32_e32 v54, v0
	v_add_f32_e32 v0, v57, v184
	v_mul_f32_e32 v0, 0xbfb8aa3b, v0
	v_exp_f32_e32 v55, v0
	v_lshlrev_b32_e32 v56, 16, v83
	v_and_b32_e32 v57, 0xffff0000, v83
	v_pk_add_f32 v[54:55], v[54:55], 1.0 op_sel_hi:[1,0]
	s_nop 0
	v_rcp_f32_e32 v55, v55
	v_rcp_f32_e32 v54, v54
	v_add_f32_e32 v0, v50, v183
	v_mul_f32_e32 v0, 0xbfb8aa3b, v0
	v_exp_f32_e32 v50, v0
	v_add_f32_e32 v0, v51, v183
	v_mul_f32_e32 v0, 0xbfb8aa3b, v0
	v_exp_f32_e32 v51, v0
	v_pk_mul_f32 v[82:83], v[54:55], v[56:57]
	v_lshlrev_b32_e32 v54, 16, v84
	v_and_b32_e32 v55, 0xffff0000, v84
	v_pk_add_f32 v[50:51], v[50:51], 1.0 op_sel_hi:[1,0]
	s_nop 0
	v_rcp_f32_e32 v51, v51
	v_rcp_f32_e32 v50, v50
	v_add_f32_e32 v0, v52, v183
	v_mul_f32_e32 v0, 0xbfb8aa3b, v0
	v_pk_mul_f32 v[96:97], v[50:51], v[54:55]
	v_exp_f32_e32 v50, v0
	v_add_f32_e32 v0, v53, v183
	v_mul_f32_e32 v0, 0xbfb8aa3b, v0
	v_exp_f32_e32 v51, v0
	v_lshlrev_b32_e32 v52, 16, v85
	v_and_b32_e32 v53, 0xffff0000, v85
	v_pk_add_f32 v[50:51], v[50:51], 1.0 op_sel_hi:[1,0]
	s_nop 0
	v_rcp_f32_e32 v51, v51
	v_rcp_f32_e32 v50, v50
	s_nop 0
	v_pk_mul_f32 v[84:85], v[50:51], v[52:53]
	s_and_b64 vcc, exec, s[8:9]
	s_cbranch_vccnz .LBB0_178
	v_lshlrev_b32_e32 v50, 16, v6
	v_and_b32_e32 v51, 0xffff0000, v6
	v_pk_add_f32 v[94:95], v[94:95], v[50:51]
	v_lshlrev_b32_e32 v50, 16, v7
	v_and_b32_e32 v51, 0xffff0000, v7
	v_pk_add_f32 v[82:83], v[82:83], v[50:51]
	v_lshlrev_b32_e32 v50, 16, v8
	v_and_b32_e32 v51, 0xffff0000, v8
	v_pk_add_f32 v[96:97], v[96:97], v[50:51]
	v_lshlrev_b32_e32 v50, 16, v9
	v_and_b32_e32 v51, 0xffff0000, v9
	v_pk_add_f32 v[84:85], v[84:85], v[50:51]

; DI float sigm(float x) { return 1.f / (1.f + __expf(-x)); }
; DI void gate_reg(PREF p, int l, int n, f32x4 (&acc)[2][2][4][2], int dt) {
;     ...
;   for (int ai = 0; ai < 2; ++ai)
; #pragma unroll
;     for (int bj = 0; bj < 2; ++bj) {
;       __builtin_amdgcn_sched_barrier(0);
;       u32x4 bn[4], pv[4];
; #pragma unroll
;       for (int m = 0; m < 4; ++m) {
;         bn[m] = sbn[((ai * 2 + bj) * 4 + m) * 64];
;         if (n > 0) pv[m] = ssum[((ai * 2 + bj) * 4 + m) * 64];
;       }
; #pragma unroll
;       for (int m = 0; m < 4; ++m) {
;         float b[8]; unpack8(bn[m], b);
;         float v[8];
; #pragma unroll
;         for (int nn = 0; nn < 2; ++nn)
; #pragma unroll
;           for (int j = 0; j < 4; ++j) v[nn * 4 + j] = sigm(acc[ai][bj][m][nn][j] + bias[bj][nn]) * b[nn * 4 + j];
;         if (n > 0) {
;           float o[8]; unpack8(pv[m], o);
; #pragma unroll
;           for (int e = 0; e < 8; ++e) v[e] += o[e];
;         }
.LBB0_188:
	v_add_f32_e32 v0, v46, v182
	v_mul_f32_e32 v0, 0xbfb8aa3b, v0
	v_exp_f32_e32 v46, v0
	v_add_f32_e32 v0, v47, v182
	v_mul_f32_e32 v0, 0xbfb8aa3b, v0
	v_exp_f32_e32 v47, v0
	s_waitcnt vmcnt(3)
	v_lshlrev_b32_e32 v166, 16, v62
	v_and_b32_e32 v167, 0xffff0000, v62
	v_pk_add_f32 v[46:47], v[46:47], 1.0 op_sel_hi:[1,0]
	s_nop 0
	v_rcp_f32_e32 v47, v47
	v_rcp_f32_e32 v46, v46
	v_add_f32_e32 v0, v48, v182
	v_mul_f32_e32 v0, 0xbfb8aa3b, v0
	v_exp_f32_e32 v48, v0
	v_add_f32_e32 v0, v49, v182
	v_mul_f32_e32 v0, 0xbfb8aa3b, v0
	v_exp_f32_e32 v49, v0
	v_pk_mul_f32 v[46:47], v[46:47], v[166:167]
	v_lshlrev_b32_e32 v62, 16, v63
	v_and_b32_e32 v63, 0xffff0000, v63
	v_pk_add_f32 v[48:49], v[48:49], 1.0 op_sel_hi:[1,0]
	s_nop 0
	v_rcp_f32_e32 v49, v49
	v_rcp_f32_e32 v48, v48
	v_add_f32_e32 v0, v38, v162
	v_mul_f32_e32 v0, 0xbfb8aa3b, v0
	v_exp_f32_e32 v38, v0
	v_add_f32_e32 v0, v39, v162
	v_mul_f32_e32 v0, 0xbfb8aa3b, v0
	v_exp_f32_e32 v39, v0
	v_pk_mul_f32 v[48:49], v[48:49], v[62:63]
	v_lshlrev_b32_e32 v62, 16, v64
	v_and_b32_e32 v63, 0xffff0000, v64
	v_pk_add_f32 v[38:39], v[38:39], 1.0 op_sel_hi:[1,0]
	s_nop 0
	v_rcp_f32_e32 v39, v39
	v_rcp_f32_e32 v38, v38
	v_add_f32_e32 v0, v40, v162
	v_mul_f32_e32 v0, 0xbfb8aa3b, v0
	v_exp_f32_e32 v40, v0
	v_add_f32_e32 v0, v41, v162
	v_mul_f32_e32 v0, 0xbfb8aa3b, v0
	v_exp_f32_e32 v41, v0
	v_pk_mul_f32 v[38:39], v[38:39], v[62:63]
	v_lshlrev_b32_e32 v62, 16, v65
	v_and_b32_e32 v63, 0xffff0000, v65
	v_pk_add_f32 v[40:41], v[40:41], 1.0 op_sel_hi:[1,0]
	s_nop 0
	v_rcp_f32_e32 v41, v41
	v_rcp_f32_e32 v40, v40
	s_nop 0
	v_pk_mul_f32 v[40:41], v[40:41], v[62:63]
	s_and_b64 vcc, exec, s[8:9]
	s_cbranch_vccnz .LBB0_190
	v_lshlrev_b32_e32 v62, 16, v42
	v_and_b32_e32 v63, 0xffff0000, v42
	v_lshlrev_b32_e32 v42, 16, v43
	v_and_b32_e32 v43, 0xffff0000, v43
	v_pk_add_f32 v[48:49], v[48:49], v[42:43]
	v_lshlrev_b32_e32 v42, 16, v44
	v_and_b32_e32 v43, 0xffff0000, v44
	v_pk_add_f32 v[38:39], v[38:39], v[42:43]
	v_lshlrev_b32_e32 v42, 16, v45
	v_and_b32_e32 v43, 0xffff0000, v45
	v_pk_add_f32 v[46:47], v[46:47], v[62:63]
	v_pk_add_f32 v[40:41], v[40:41], v[42:43]

; DI float sigm(float x) { return 1.f / (1.f + __expf(-x)); }
; DI void gate_reg(PREF p, int l, int n, f32x4 (&acc)[2][2][4][2], int dt) {
;     ...
;   for (int ai = 0; ai < 2; ++ai)
; #pragma unroll
;     for (int bj = 0; bj < 2; ++bj) {
;       __builtin_amdgcn_sched_barrier(0);
;       u32x4 bn[4], pv[4];
; #pragma unroll
;       for (int m = 0; m < 4; ++m) {
;         bn[m] = sbn[((ai * 2 + bj) * 4 + m) * 64];
;         if (n > 0) pv[m] = ssum[((ai * 2 + bj) * 4 + m) * 64];
;       }
; #pragma unroll
;       for (int m = 0; m < 4; ++m) {
;         float b[8]; unpack8(bn[m], b);
;         float v[8];
; #pragma unroll
;         for (int nn = 0; nn < 2; ++nn)
; #pragma unroll
;           for (int j = 0; j < 4; ++j) v[nn * 4 + j] = sigm(acc[ai][bj][m][nn][j] + bias[bj][nn]) * b[nn * 4 + j];
;         if (n > 0) {
;           float o[8]; unpack8(pv[m], o);
; #pragma unroll
;           for (int e = 0; e < 8; ++e) v[e] += o[e];
;         }
.LBB0_192:
	v_add_f32_e32 v0, v34, v182
	v_mul_f32_e32 v0, 0xbfb8aa3b, v0
	v_exp_f32_e32 v34, v0
	v_add_f32_e32 v0, v35, v182
	v_mul_f32_e32 v0, 0xbfb8aa3b, v0
	v_exp_f32_e32 v35, v0
	s_waitcnt vmcnt(2)
	v_lshlrev_b32_e32 v42, 16, v58
	v_and_b32_e32 v43, 0xffff0000, v58
	v_pk_add_f32 v[34:35], v[34:35], 1.0 op_sel_hi:[1,0]
	s_nop 0
	v_rcp_f32_e32 v35, v35
	v_rcp_f32_e32 v34, v34
	v_add_f32_e32 v0, v36, v182
	v_mul_f32_e32 v0, 0xbfb8aa3b, v0
	v_exp_f32_e32 v36, v0
	v_add_f32_e32 v0, v37, v182
	v_mul_f32_e32 v0, 0xbfb8aa3b, v0
	v_exp_f32_e32 v37, v0
	v_pk_mul_f32 v[34:35], v[34:35], v[42:43]
	v_lshlrev_b32_e32 v42, 16, v59
	v_and_b32_e32 v43, 0xffff0000, v59
	v_pk_add_f32 v[36:37], v[36:37], 1.0 op_sel_hi:[1,0]
	s_nop 0
	v_rcp_f32_e32 v37, v37
	v_rcp_f32_e32 v36, v36
	v_add_f32_e32 v0, v26, v162
	v_mul_f32_e32 v0, 0xbfb8aa3b, v0
	v_exp_f32_e32 v26, v0
	v_add_f32_e32 v0, v27, v162
	v_mul_f32_e32 v0, 0xbfb8aa3b, v0
	v_exp_f32_e32 v27, v0
	v_pk_mul_f32 v[36:37], v[36:37], v[42:43]
	v_lshlrev_b32_e32 v42, 16, v60
	v_and_b32_e32 v43, 0xffff0000, v60
	v_pk_add_f32 v[26:27], v[26:27], 1.0 op_sel_hi:[1,0]
	s_nop 0
	v_rcp_f32_e32 v27, v27
	v_rcp_f32_e32 v26, v26
	v_add_f32_e32 v0, v28, v162
	v_mul_f32_e32 v0, 0xbfb8aa3b, v0
	v_exp_f32_e32 v28, v0
	v_add_f32_e32 v0, v29, v162
	v_mul_f32_e32 v0, 0xbfb8aa3b, v0
	v_exp_f32_e32 v29, v0
	v_pk_mul_f32 v[26:27], v[26:27], v[42:43]
	v_lshlrev_b32_e32 v42, 16, v61
	v_and_b32_e32 v43, 0xffff0000, v61
	v_pk_add_f32 v[28:29], v[28:29], 1.0 op_sel_hi:[1,0]
	s_nop 0
	v_rcp_f32_e32 v29, v29
	v_rcp_f32_e32 v28, v28
	s_nop 0
	v_pk_mul_f32 v[28:29], v[28:29], v[42:43]
	s_and_b64 vcc, exec, s[8:9]
	s_cbranch_vccnz .LBB0_194
	v_lshlrev_b32_e32 v42, 16, v30
	v_and_b32_e32 v43, 0xffff0000, v30
	v_lshlrev_b32_e32 v30, 16, v31
	v_and_b32_e32 v31, 0xffff0000, v31
	v_pk_add_f32 v[36:37], v[36:37], v[30:31]
	v_lshlrev_b32_e32 v30, 16, v32
	v_and_b32_e32 v31, 0xffff0000, v32
	v_pk_add_f32 v[26:27], v[26:27], v[30:31]
	v_lshlrev_b32_e32 v30, 16, v33
	v_and_b32_e32 v31, 0xffff0000, v33
	v_pk_add_f32 v[34:35], v[34:35], v[42:43]
	v_pk_add_f32 v[28:29], v[28:29], v[30:31]

; DI float sigm(float x) { return 1.f / (1.f + __expf(-x)); }
; DI void gate_reg(PREF p, int l, int n, f32x4 (&acc)[2][2][4][2], int dt) {
;     ...
;   for (int ai = 0; ai < 2; ++ai)
; #pragma unroll
;     for (int bj = 0; bj < 2; ++bj) {
;       __builtin_amdgcn_sched_barrier(0);
;       u32x4 bn[4], pv[4];
; #pragma unroll
;       for (int m = 0; m < 4; ++m) {
;         bn[m] = sbn[((ai * 2 + bj) * 4 + m) * 64];
;         if (n > 0) pv[m] = ssum[((ai * 2 + bj) * 4 + m) * 64];
;       }
; #pragma unroll
;       for (int m = 0; m < 4; ++m) {
;         float b[8]; unpack8(bn[m], b);
;         float v[8];
; #pragma unroll
;         for (int nn = 0; nn < 2; ++nn)
; #pragma unroll
;           for (int j = 0; j < 4; ++j) v[nn * 4 + j] = sigm(acc[ai][bj][m][nn][j] + bias[bj][nn]) * b[nn * 4 + j];
;         if (n > 0) {
;           float o[8]; unpack8(pv[m], o);
; #pragma unroll
;           for (int e = 0; e < 8; ++e) v[e] += o[e];
;         }
.LBB0_196:
	v_add_f32_e32 v0, v22, v182
	v_mul_f32_e32 v0, 0xbfb8aa3b, v0
	v_exp_f32_e32 v22, v0
	v_add_f32_e32 v0, v23, v182
	v_mul_f32_e32 v0, 0xbfb8aa3b, v0
	v_exp_f32_e32 v23, v0
	s_waitcnt vmcnt(1)
	v_lshlrev_b32_e32 v30, 16, v54
	v_and_b32_e32 v31, 0xffff0000, v54
	v_pk_add_f32 v[22:23], v[22:23], 1.0 op_sel_hi:[1,0]
	s_nop 0
	v_rcp_f32_e32 v23, v23
	v_rcp_f32_e32 v22, v22
	v_add_f32_e32 v0, v24, v182
	v_mul_f32_e32 v0, 0xbfb8aa3b, v0
	v_exp_f32_e32 v24, v0
	v_add_f32_e32 v0, v25, v182
	v_mul_f32_e32 v0, 0xbfb8aa3b, v0
	v_exp_f32_e32 v25, v0
	v_pk_mul_f32 v[22:23], v[22:23], v[30:31]
	v_lshlrev_b32_e32 v30, 16, v55
	v_and_b32_e32 v31, 0xffff0000, v55
	v_pk_add_f32 v[24:25], v[24:25], 1.0 op_sel_hi:[1,0]
	s_nop 0
	v_rcp_f32_e32 v25, v25
	v_rcp_f32_e32 v24, v24
	v_add_f32_e32 v0, v14, v162
	v_mul_f32_e32 v0, 0xbfb8aa3b, v0
	v_exp_f32_e32 v14, v0
	v_add_f32_e32 v0, v15, v162
	v_mul_f32_e32 v0, 0xbfb8aa3b, v0
	v_exp_f32_e32 v15, v0
	v_pk_mul_f32 v[24:25], v[24:25], v[30:31]
	v_lshlrev_b32_e32 v30, 16, v56
	v_and_b32_e32 v31, 0xffff0000, v56
	v_pk_add_f32 v[14:15], v[14:15], 1.0 op_sel_hi:[1,0]
	s_nop 0
	v_rcp_f32_e32 v15, v15
	v_rcp_f32_e32 v14, v14
	v_add_f32_e32 v0, v16, v162
	v_mul_f32_e32 v0, 0xbfb8aa3b, v0
	v_exp_f32_e32 v16, v0
	v_add_f32_e32 v0, v17, v162
	v_mul_f32_e32 v0, 0xbfb8aa3b, v0
	v_exp_f32_e32 v17, v0
	v_pk_mul_f32 v[14:15], v[14:15], v[30:31]
	v_lshlrev_b32_e32 v30, 16, v57
	v_and_b32_e32 v31, 0xffff0000, v57
	v_pk_add_f32 v[16:17], v[16:17], 1.0 op_sel_hi:[1,0]
	s_nop 0
	v_rcp_f32_e32 v17, v17
	v_rcp_f32_e32 v16, v16
	s_nop 0
	v_pk_mul_f32 v[16:17], v[16:17], v[30:31]
	s_and_b64 vcc, exec, s[8:9]
	s_cbranch_vccnz .LBB0_198
	v_lshlrev_b32_e32 v30, 16, v18
	v_and_b32_e32 v31, 0xffff0000, v18
	v_lshlrev_b32_e32 v18, 16, v19
	v_and_b32_e32 v19, 0xffff0000, v19
	v_pk_add_f32 v[24:25], v[24:25], v[18:19]
	v_lshlrev_b32_e32 v18, 16, v20
	v_and_b32_e32 v19, 0xffff0000, v20
	v_pk_add_f32 v[14:15], v[14:15], v[18:19]
	v_lshlrev_b32_e32 v18, 16, v21
	v_and_b32_e32 v19, 0xffff0000, v21
	v_pk_add_f32 v[22:23], v[22:23], v[30:31]
	v_pk_add_f32 v[16:17], v[16:17], v[18:19]

; DI float sigm(float x) { return 1.f / (1.f + __expf(-x)); }
; DI void gate_reg(PREF p, int l, int n, f32x4 (&acc)[2][2][4][2], int dt) {
;     ...
;   for (int ai = 0; ai < 2; ++ai)
; #pragma unroll
;     for (int bj = 0; bj < 2; ++bj) {
;       __builtin_amdgcn_sched_barrier(0);
;       u32x4 bn[4], pv[4];
; #pragma unroll
;       for (int m = 0; m < 4; ++m) {
;         bn[m] = sbn[((ai * 2 + bj) * 4 + m) * 64];
;         if (n > 0) pv[m] = ssum[((ai * 2 + bj) * 4 + m) * 64];
;       }
; #pragma unroll
;       for (int m = 0; m < 4; ++m) {
;         float b[8]; unpack8(bn[m], b);
;         float v[8];
; #pragma unroll
;         for (int nn = 0; nn < 2; ++nn)
; #pragma unroll
;           for (int j = 0; j < 4; ++j) v[nn * 4 + j] = sigm(acc[ai][bj][m][nn][j] + bias[bj][nn]) * b[nn * 4 + j];
;         if (n > 0) {
;           float o[8]; unpack8(pv[m], o);
; #pragma unroll
;           for (int e = 0; e < 8; ++e) v[e] += o[e];
;         }
.LBB0_200:
	v_add_f32_e32 v0, v10, v182
	v_mul_f32_e32 v0, 0xbfb8aa3b, v0
	v_exp_f32_e32 v10, v0
	v_add_f32_e32 v0, v11, v182
	v_mul_f32_e32 v0, 0xbfb8aa3b, v0
	v_exp_f32_e32 v11, v0
	s_waitcnt vmcnt(0)
	v_lshlrev_b32_e32 v18, 16, v50
	v_and_b32_e32 v19, 0xffff0000, v50
	v_pk_add_f32 v[10:11], v[10:11], 1.0 op_sel_hi:[1,0]
	s_nop 0
	v_rcp_f32_e32 v11, v11
	v_rcp_f32_e32 v10, v10
	v_add_f32_e32 v0, v12, v182
	v_mul_f32_e32 v0, 0xbfb8aa3b, v0
	v_exp_f32_e32 v12, v0
	v_add_f32_e32 v0, v13, v182
	v_mul_f32_e32 v0, 0xbfb8aa3b, v0
	v_exp_f32_e32 v13, v0
	v_pk_mul_f32 v[10:11], v[10:11], v[18:19]
	v_lshlrev_b32_e32 v18, 16, v51
	v_and_b32_e32 v19, 0xffff0000, v51
	v_pk_add_f32 v[12:13], v[12:13], 1.0 op_sel_hi:[1,0]
	s_nop 0
	v_rcp_f32_e32 v13, v13
	v_rcp_f32_e32 v12, v12
	v_add_f32_e32 v0, v2, v162
	v_mul_f32_e32 v0, 0xbfb8aa3b, v0
	v_exp_f32_e32 v2, v0
	v_add_f32_e32 v0, v3, v162
	v_mul_f32_e32 v0, 0xbfb8aa3b, v0
	v_exp_f32_e32 v3, v0
	v_pk_mul_f32 v[12:13], v[12:13], v[18:19]
	v_lshlrev_b32_e32 v18, 16, v52
	v_and_b32_e32 v19, 0xffff0000, v52
	v_pk_add_f32 v[2:3], v[2:3], 1.0 op_sel_hi:[1,0]
	s_nop 0
	v_rcp_f32_e32 v3, v3
	v_rcp_f32_e32 v2, v2
	v_add_f32_e32 v0, v4, v162
	v_mul_f32_e32 v0, 0xbfb8aa3b, v0
	v_exp_f32_e32 v4, v0
	v_add_f32_e32 v0, v5, v162
	v_mul_f32_e32 v0, 0xbfb8aa3b, v0
	v_exp_f32_e32 v5, v0
	v_pk_mul_f32 v[2:3], v[2:3], v[18:19]
	v_lshlrev_b32_e32 v18, 16, v53
	v_and_b32_e32 v19, 0xffff0000, v53
	v_pk_add_f32 v[4:5], v[4:5], 1.0 op_sel_hi:[1,0]
	s_nop 0
	v_rcp_f32_e32 v5, v5
	v_rcp_f32_e32 v4, v4
	s_nop 0
	v_pk_mul_f32 v[4:5], v[4:5], v[18:19]
	s_and_b64 vcc, exec, s[8:9]
	s_cbranch_vccnz .LBB0_202
	v_lshlrev_b32_e32 v18, 16, v6
	v_and_b32_e32 v19, 0xffff0000, v6
	v_lshlrev_b32_e32 v6, 16, v7
	v_and_b32_e32 v7, 0xffff0000, v7
	v_pk_add_f32 v[12:13], v[12:13], v[6:7]
	v_lshlrev_b32_e32 v6, 16, v8
	v_and_b32_e32 v7, 0xffff0000, v8
	v_pk_add_f32 v[2:3], v[2:3], v[6:7]
	v_lshlrev_b32_e32 v6, 16, v9
	v_and_b32_e32 v7, 0xffff0000, v9
	v_pk_add_f32 v[10:11], v[10:11], v[18:19]
	v_pk_add_f32 v[4:5], v[4:5], v[6:7]

; DI float sigm(float x) { return 1.f / (1.f + __expf(-x)); }
; DI float silu(float x) { return x / (1.f + __expf(-x)); }
; DI u32x4 pack8(const float* f) { u32x4 o; o.x = pack2(f[0], f[1]); o.y = pack2(f[2], f[3]); o.z = pack2(f[4], f[5]); o.w = pack2(f[6], f[7]); return o; }
; DI void lds_barrier() { asm volatile("s_waitcnt lgkmcnt(0)\n\ts_barrier" ::: "memory"); }
; DI int tid512() { int t = threadIdx.x; asm volatile("" : "+v"(t)); return t; }
; template <int AI, int BJ>
; DI void stage_q(const f32x4 (&acc)[2][2][4][2], float* Cs) {
;   const int t = tid512(), wid = t >> 6, lane = t & 63, wr = wid >> 2, wc = wid & 3, fr = lane & 15, fq = lane >> 4;
;   lds_barrier();
; #pragma unroll
;   for (int m = 0; m < 4; ++m)
; #pragma unroll
;     for (int n = 0; n < 2; ++n)
; #pragma unroll
;       for (int j = 0; j < 4; ++j) Cs[(wr * 64 + m * 16 + fq * 4 + j) * CST + wc * 32 + n * 16 + fr] = acc[AI][BJ][m][n][j];
;   lds_barrier();
; }
; template <int AI, int BJ>
; DI void glu_quadrant(PREF p, const f32x4 (&acc)[2][2][4][2], int mt, int nt, float* Cs) {
;   const int t = tid512();
;   const int row0 = mt * 256 + AI * 128, oc0 = (nt * 2 + BJ) * 64, c = (t & 7) * 8;
;   u32x4 zr[2];
; #pragma unroll
;   for (int q = 0; q < 2; ++q) zr[q] = *(const u32x4*)(p.hb + (size_t)(row0 + (t >> 3) + 64 * q) * HW + OFF_CZ + oc0 + c);
;   stage_q<AI, BJ>(acc, Cs);
; #pragma unroll
;   for (int q = 0; q < 2; ++q) {
;     const int r = (t >> 3) + 64 * q;
;     float v[8], g[8]; ld8(Cs + r * CST + c, v); ld8(Cs + r * CST + 64 + c, g);
;     float z[8]; unpack8(zr[q], z);
; #pragma unroll
;     for (int j = 0; j < 8; ++j) v[j] = v[j] * sigm(g[j]) * silu(z[j]);
;     *(u32x4*)(p.ys + (size_t)(row0 + r) * 1024 + 512 + oc0 + c) = pack8(v);
;   }
.LBB0_214:
	s_or_b64 exec, exec, s[16:17]
	v_mov_b32_e32 v0, v168
	s_lshl_b32 s14, s14, 8
	v_ashrrev_i32_e32 v147, 3, v0
	v_lshlrev_b32_e32 v98, 3, v0
	v_add_u32_e32 v142, s14, v147
	v_mov_b64_e32 v[138:139], s[8:9]
	v_and_b32_e32 v146, 56, v98
	v_mad_i64_i32 v[98:99], s[0:1], v142, s60, v[138:139]
	s_lshl_b32 s52, s25, 8
	v_lshl_add_u64 v[98:99], v[98:99], 0, s[52:53]
	v_lshlrev_b32_e32 v0, 1, v146
	v_lshl_add_u64 v[98:99], v[98:99], 0, v[0:1]
	global_load_dwordx4 v[118:121], v[98:99], off offset:3392
	v_add_u32_e32 v140, 64, v142
	v_mad_i64_i32 v[98:99], s[0:1], v140, s60, v[138:139]
	v_lshl_add_u64 v[98:99], v[98:99], 0, s[52:53]
	v_lshl_add_u64 v[98:99], v[98:99], 0, v[0:1]
	v_mov_b32_e32 v144, v168
	global_load_dwordx4 v[98:101], v[98:99], off offset:3392
	s_waitcnt lgkmcnt(0)
	s_barrier
	v_ashrrev_i32_e32 v143, 31, v142
	v_and_b32_e32 v145, 15, v144
	v_lshrrev_b32_e32 v148, 2, v144
	v_lshlrev_b32_e32 v144, 1, v144
	v_lshlrev_b32_e32 v145, 2, v145
	v_and_b32_e32 v148, 0xfffffcc, v148
	v_and_or_b32 v144, v144, s89, v145
	v_mad_u64_u32 v[144:145], s[0:1], v148, s92, v[144:145]
	ds_write2_b32 v144, v126, v134 offset1:16
	ds_write2_b32 v144, v127, v135 offset0:132 offset1:148
	v_add_u32_e32 v126, 0x400, v144
	ds_write2_b32 v126, v128, v136 offset0:8 offset1:24
	ds_write2_b32 v126, v129, v137 offset0:140 offset1:156
	v_add_u32_e32 v126, 0x2000, v144
	ds_write2_b32 v126, v122, v130 offset0:64 offset1:80
	ds_write2_b32 v126, v123, v131 offset0:196 offset1:212
	v_add_u32_e32 v122, 0x2400, v144
	ds_write2_b32 v122, v124, v132 offset0:72 offset1:88
	ds_write2_b32 v122, v125, v133 offset0:204 offset1:220
	v_add_u32_e32 v122, 0x4000, v144
	ds_write2_b32 v122, v110, v114 offset0:128 offset1:144
	v_add_u32_e32 v110, 0x4400, v144
	ds_write2_b32 v110, v111, v115 offset0:4 offset1:20
	ds_write2_b32 v110, v112, v116 offset0:136 offset1:152
	v_add_u32_e32 v110, 0x4800, v144
	ds_write2_b32 v110, v113, v117 offset0:12 offset1:28
	v_add_u32_e32 v110, 0x6000, v144
	ds_write2_b32 v110, v102, v106 offset0:192 offset1:208
	v_add_u32_e32 v102, 0x6400, v144
	ds_write2_b32 v102, v103, v107 offset0:68 offset1:84
	ds_write2_b32 v102, v104, v108 offset0:200 offset1:216
	v_add_u32_e32 v102, 0x6800, v144
	ds_write2_b32 v102, v105, v109 offset0:76 offset1:92
	v_mul_lo_u32 v102, v147, s92
	s_waitcnt lgkmcnt(0)
	s_barrier
	v_lshl_add_u32 v122, v146, 2, v102
	s_waitcnt vmcnt(0)
	ds_read_b128 v[110:113], v122
	ds_read_b128 v[102:105], v122 offset:16
	ds_read_b128 v[114:117], v122 offset:256
	ds_read_b128 v[106:109], v122 offset:272
	v_ashrrev_i32_e32 v141, 31, v140
	s_waitcnt lgkmcnt(1)
	v_mul_f32_e32 v114, 0xbfb8aa3b, v114
	v_exp_f32_e32 v127, v114
	s_waitcnt lgkmcnt(0)
	v_mul_f32_e32 v106, 0xbfb8aa3b, v106
	v_lshlrev_b32_e32 v125, 16, v118
	v_mul_f32_e32 v114, 0xbfb8aa3b, v125
	v_exp_f32_e32 v126, v114
	v_and_b32_e32 v128, 0xffff0000, v118
	v_lshlrev_b32_e32 v129, 16, v119
	v_and_b32_e32 v124, 0xffff0000, v119
	v_pk_add_f32 v[126:127], v[126:127], 1.0 op_sel_hi:[1,0]
	v_lshlrev_b32_e32 v119, 16, v121
	v_and_b32_e32 v118, 0xffff0000, v121
	v_lshlrev_b32_e32 v123, 16, v120
	v_and_b32_e32 v120, 0xffff0000, v120
	v_rcp_f32_e32 v114, v126
	s_nop 0
	v_mul_f32_e32 v114, v125, v114
	v_rcp_f32_e32 v121, v127
	s_nop 0
	v_mul_f32_e32 v110, v110, v121
	v_mul_f32_e32 v110, v114, v110
	v_mul_f32_e32 v114, 0xbfb8aa3b, v115
	v_exp_f32_e32 v115, v114
	v_mul_f32_e32 v114, 0xbfb8aa3b, v128
	v_exp_f32_e32 v114, v114
	s_nop 0
	v_pk_add_f32 v[114:115], v[114:115], 1.0 op_sel_hi:[1,0]
	s_nop 0
	v_rcp_f32_e32 v121, v114
	s_nop 0
	v_mul_f32_e32 v114, v128, v121
	v_rcp_f32_e32 v115, v115
	s_nop 0
	v_mul_f32_e32 v111, v111, v115
	v_mul_f32_e32 v111, v114, v111
	v_mul_f32_e32 v114, 0xbfb8aa3b, v116
	v_exp_f32_e32 v115, v114
	v_mul_f32_e32 v114, 0xbfb8aa3b, v129
	v_exp_f32_e32 v114, v114
	s_nop 0
	v_pk_add_f32 v[114:115], v[114:115], 1.0 op_sel_hi:[1,0]
	s_nop 0
	v_rcp_f32_e32 v116, v114
	s_nop 0
	v_mul_f32_e32 v114, v129, v116
	v_rcp_f32_e32 v115, v115
	s_nop 0
	v_mul_f32_e32 v112, v112, v115
	v_mul_f32_e32 v112, v114, v112
	v_mul_f32_e32 v114, 0xbfb8aa3b, v117
	v_exp_f32_e32 v115, v114
	v_mul_f32_e32 v114, 0xbfb8aa3b, v124
	v_exp_f32_e32 v114, v114
	s_nop 0
	v_pk_add_f32 v[114:115], v[114:115], 1.0 op_sel_hi:[1,0]
	s_nop 0
	v_rcp_f32_e32 v116, v114
	s_nop 0
	v_mul_f32_e32 v114, v124, v116
	v_rcp_f32_e32 v115, v115
	s_nop 0
	v_mul_f32_e32 v113, v113, v115
	v_exp_f32_e32 v115, v106
	v_mul_f32_e32 v106, 0xbfb8aa3b, v123
	v_mul_f32_e32 v113, v114, v113
	v_exp_f32_e32 v114, v106
	v_lshlrev_b32_e32 v125, 16, v100
	v_pk_add_f32 v[114:115], v[114:115], 1.0 op_sel_hi:[1,0]
	s_nop 0
	v_rcp_f32_e32 v106, v114
	s_nop 0
	v_mul_f32_e32 v106, v123, v106
	v_and_b32_e32 v124, 0xffff0000, v99
	v_rcp_f32_e32 v114, v115
	s_nop 0
	v_mul_f32_e32 v102, v102, v114
	v_mul_f32_e32 v114, v106, v102
	v_mul_f32_e32 v102, 0xbfb8aa3b, v107
	v_exp_f32_e32 v107, v102
	v_mul_f32_e32 v102, 0xbfb8aa3b, v120
	v_exp_f32_e32 v106, v102
	v_lshlrev_b32_e32 v123, 16, v99
	v_pk_add_f32 v[106:107], v[106:107], 1.0 op_sel_hi:[1,0]
	s_nop 0
	v_rcp_f32_e32 v102, v106
	s_nop 0
	v_mul_f32_e32 v102, v120, v102
	v_rcp_f32_e32 v106, v107
	s_nop 0
	v_mul_f32_e32 v103, v103, v106
	v_mul_f32_e32 v106, v102, v103
	v_mul_f32_e32 v102, 0xbfb8aa3b, v108
	v_exp_f32_e32 v103, v102
	v_mul_f32_e32 v102, 0xbfb8aa3b, v119
	v_exp_f32_e32 v102, v102
	s_nop 0
	v_pk_add_f32 v[102:103], v[102:103], 1.0 op_sel_hi:[1,0]
	s_nop 0
	v_rcp_f32_e32 v107, v102
	s_nop 0
	v_mul_f32_e32 v102, v119, v107
	v_lshlrev_b32_e32 v119, 16, v98
	v_rcp_f32_e32 v103, v103
	s_nop 0
	v_mul_f32_e32 v103, v104, v103
	v_mul_f32_e32 v107, v102, v103
	v_mul_f32_e32 v102, 0xbfb8aa3b, v109
	v_exp_f32_e32 v103, v102
	v_mul_f32_e32 v102, 0xbfb8aa3b, v118
	v_exp_f32_e32 v102, v102
	s_nop 0
	v_pk_add_f32 v[102:103], v[102:103], 1.0 op_sel_hi:[1,0]
	s_nop 0
	v_rcp_f32_e32 v104, v102
	s_nop 0
	v_mul_f32_e32 v102, v118, v104
	v_and_b32_e32 v118, 0xffff0000, v100
	v_lshlrev_b32_e32 v100, 16, v101
	v_rcp_f32_e32 v103, v103
	s_nop 0
	v_mul_f32_e32 v103, v105, v103
	v_mul_f32_e32 v105, v102, v103
	v_cvt_pk_bf16_f32 v104, v114, v106
	s_nop 1
	v_cvt_pk_bf16_f32 v105, v107, v105
	s_nop 1
	v_lshlrev_b64 v[106:107], 11, v[142:143]
	v_lshl_add_u64 v[106:107], s[10:11], 0, v[106:107]
	v_lshl_add_u64 v[106:107], v[106:107], 0, s[52:53]
	v_lshl_add_u64 v[106:107], v[106:107], 0, v[0:1]
	v_cvt_pk_bf16_f32 v102, v110, v111
	s_nop 1
	v_cvt_pk_bf16_f32 v103, v112, v113
	s_nop 1
	global_store_dwordx4 v[106:107], v[102:105], off offset:1024
	ds_read_b128 v[110:113], v122 offset:33792
	ds_read_b128 v[102:105], v122 offset:33808
	ds_read_b128 v[114:117], v122 offset:34048
	ds_read_b128 v[106:109], v122 offset:34064
	v_and_b32_e32 v122, 0xffff0000, v98
	v_and_b32_e32 v98, 0xffff0000, v101
	s_waitcnt lgkmcnt(1)
; DI float sigm(float x) { return 1.f / (1.f + __expf(-x)); }
; DI float silu(float x) { return x / (1.f + __expf(-x)); }
; DI u32x4 pack8(const float* f) { u32x4 o; o.x = pack2(f[0], f[1]); o.y = pack2(f[2], f[3]); o.z = pack2(f[4], f[5]); o.w = pack2(f[6], f[7]); return o; }
; DI void lds_barrier() { asm volatile("s_waitcnt lgkmcnt(0)\n\ts_barrier" ::: "memory"); }
; DI int tid512() { int t = threadIdx.x; asm volatile("" : "+v"(t)); return t; }
; template <int AI, int BJ>
; DI void stage_q(const f32x4 (&acc)[2][2][4][2], float* Cs) {
;   const int t = tid512(), wid = t >> 6, lane = t & 63, wr = wid >> 2, wc = wid & 3, fr = lane & 15, fq = lane >> 4;
;   lds_barrier();
; #pragma unroll
;   for (int m = 0; m < 4; ++m)
; #pragma unroll
;     for (int n = 0; n < 2; ++n)
; #pragma unroll
;       for (int j = 0; j < 4; ++j) Cs[(wr * 64 + m * 16 + fq * 4 + j) * CST + wc * 32 + n * 16 + fr] = acc[AI][BJ][m][n][j];
;   lds_barrier();
; }
; template <int AI, int BJ>
; DI void glu_quadrant(PREF p, const f32x4 (&acc)[2][2][4][2], int mt, int nt, float* Cs) {
;   const int t = tid512();
;   const int row0 = mt * 256 + AI * 128, oc0 = (nt * 2 + BJ) * 64, c = (t & 7) * 8;
;   u32x4 zr[2];
; #pragma unroll
;   for (int q = 0; q < 2; ++q) zr[q] = *(const u32x4*)(p.hb + (size_t)(row0 + (t >> 3) + 64 * q) * HW + OFF_CZ + oc0 + c);
;   stage_q<AI, BJ>(acc, Cs);
; #pragma unroll
;   for (int q = 0; q < 2; ++q) {
;     const int r = (t >> 3) + 64 * q;
;     float v[8], g[8]; ld8(Cs + r * CST + c, v); ld8(Cs + r * CST + 64 + c, g);
;     float z[8]; unpack8(zr[q], z);
; #pragma unroll
;     for (int j = 0; j < 8; ++j) v[j] = v[j] * sigm(g[j]) * silu(z[j]);
;     *(u32x4*)(p.ys + (size_t)(row0 + r) * 1024 + 512 + oc0 + c) = pack8(v);
;   }
	v_mul_f32_e32 v99, 0xbfb8aa3b, v114
	v_exp_f32_e32 v121, v99
	v_mul_f32_e32 v99, 0xbfb8aa3b, v119
	v_exp_f32_e32 v120, v99
	s_waitcnt lgkmcnt(0)
	v_mul_f32_e32 v106, 0xbfb8aa3b, v106
	v_pk_add_f32 v[120:121], v[120:121], 1.0 op_sel_hi:[1,0]
	s_nop 0
	v_rcp_f32_e32 v99, v120
	s_nop 0
	v_mul_f32_e32 v99, v119, v99
	v_rcp_f32_e32 v101, v121
	s_nop 0
	v_mul_f32_e32 v101, v110, v101
	v_mul_f32_e32 v99, v99, v101
	v_mul_f32_e32 v101, 0xbfb8aa3b, v115
	v_exp_f32_e32 v115, v101
	v_mul_f32_e32 v101, 0xbfb8aa3b, v122
	v_exp_f32_e32 v114, v101
	s_nop 0
	v_pk_add_f32 v[114:115], v[114:115], 1.0 op_sel_hi:[1,0]
	s_nop 0
	v_rcp_f32_e32 v101, v114
	s_nop 0
	v_mul_f32_e32 v101, v122, v101
	v_rcp_f32_e32 v110, v115
	s_nop 0
	v_mul_f32_e32 v110, v111, v110
	v_mul_f32_e32 v101, v101, v110
	v_mul_f32_e32 v110, 0xbfb8aa3b, v116
	v_exp_f32_e32 v111, v110
	v_mul_f32_e32 v110, 0xbfb8aa3b, v123
	v_exp_f32_e32 v110, v110
	s_nop 0
	v_pk_add_f32 v[110:111], v[110:111], 1.0 op_sel_hi:[1,0]
	s_nop 0
	v_rcp_f32_e32 v114, v110
	s_nop 0
	v_mul_f32_e32 v110, v123, v114
	v_rcp_f32_e32 v111, v111
	s_nop 0
	v_mul_f32_e32 v111, v112, v111
	v_mul_f32_e32 v110, v110, v111
	v_mul_f32_e32 v111, 0xbfb8aa3b, v117
	v_exp_f32_e32 v115, v111
	v_mul_f32_e32 v111, 0xbfb8aa3b, v124
	v_exp_f32_e32 v114, v111
	s_nop 0
	v_pk_add_f32 v[114:115], v[114:115], 1.0 op_sel_hi:[1,0]
	s_nop 0
	v_rcp_f32_e32 v111, v114
	s_nop 0
	v_mul_f32_e32 v111, v124, v111
	v_rcp_f32_e32 v112, v115
	s_nop 0
	v_mul_f32_e32 v112, v113, v112
	v_exp_f32_e32 v113, v106
	v_mul_f32_e32 v106, 0xbfb8aa3b, v125
	v_mul_f32_e32 v111, v111, v112
	v_exp_f32_e32 v112, v106
	s_nop 0
	v_pk_add_f32 v[112:113], v[112:113], 1.0 op_sel_hi:[1,0]
	s_nop 0
	v_rcp_f32_e32 v106, v112
	s_nop 0
	v_mul_f32_e32 v106, v125, v106
	v_rcp_f32_e32 v112, v113
	s_nop 0
	v_mul_f32_e32 v102, v102, v112
	v_mul_f32_e32 v112, v106, v102
	v_mul_f32_e32 v102, 0xbfb8aa3b, v107
	v_exp_f32_e32 v107, v102
	v_mul_f32_e32 v102, 0xbfb8aa3b, v118
	v_exp_f32_e32 v106, v102
	s_nop 0
	v_pk_add_f32 v[106:107], v[106:107], 1.0 op_sel_hi:[1,0]
	s_nop 0
	v_rcp_f32_e32 v102, v106
	s_nop 0
	v_mul_f32_e32 v102, v118, v102
	v_rcp_f32_e32 v106, v107
	s_nop 0
	v_mul_f32_e32 v103, v103, v106
	v_mul_f32_e32 v106, v102, v103
	v_mul_f32_e32 v102, 0xbfb8aa3b, v108
	v_exp_f32_e32 v103, v102
	v_mul_f32_e32 v102, 0xbfb8aa3b, v100
	v_exp_f32_e32 v102, v102
	s_nop 0
	v_pk_add_f32 v[102:103], v[102:103], 1.0 op_sel_hi:[1,0]
	s_nop 0
	v_rcp_f32_e32 v107, v102
	s_nop 0
	v_mul_f32_e32 v100, v100, v107
	v_rcp_f32_e32 v102, v103
	s_nop 0
	v_mul_f32_e32 v102, v104, v102
	v_mul_f32_e32 v104, v100, v102
	v_mul_f32_e32 v100, 0xbfb8aa3b, v109
	v_exp_f32_e32 v103, v100
	v_mul_f32_e32 v100, 0xbfb8aa3b, v98
	v_exp_f32_e32 v102, v100
	s_nop 0
	v_pk_add_f32 v[102:103], v[102:103], 1.0 op_sel_hi:[1,0]
	s_nop 0
	v_rcp_f32_e32 v100, v102
	s_nop 0
	v_mul_f32_e32 v98, v98, v100
	v_rcp_f32_e32 v100, v103
	s_nop 0
	v_mul_f32_e32 v100, v105, v100
	v_mul_f32_e32 v102, v98, v100
	v_cvt_pk_bf16_f32 v98, v99, v101
	s_nop 1
	v_cvt_pk_bf16_f32 v101, v104, v102
	s_nop 1
	v_lshlrev_b64 v[102:103], 11, v[140:141]
	v_lshl_add_u64 v[102:103], s[10:11], 0, v[102:103]
	v_lshl_add_u64 v[102:103], v[102:103], 0, s[52:53]
	v_lshl_add_u64 v[102:103], v[102:103], 0, v[0:1]
	v_mov_b32_e32 v0, v168
	v_cvt_pk_bf16_f32 v99, v110, v111
	s_nop 1
	v_cvt_pk_bf16_f32 v100, v112, v106
	s_nop 1
	global_store_dwordx4 v[102:103], v[98:101], off offset:1024
	v_mov_b32_e32 v110, v168
	v_ashrrev_i32_e32 v113, 3, v0
	v_lshlrev_b32_e32 v98, 3, v0
	v_add_u32_e32 v104, s14, v113
	v_and_b32_e32 v112, 56, v98
	v_mad_i64_i32 v[98:99], s[0:1], v104, s60, v[138:139]
	v_lshl_add_u64 v[98:99], v[98:99], 0, s[52:53]
	v_lshlrev_b32_e32 v0, 1, v112
	v_lshl_add_u64 v[98:99], v[98:99], 0, v[0:1]
	global_load_dwordx4 v[106:109], v[98:99], off offset:3520
	v_add_u32_e32 v102, 64, v104
	v_mad_i64_i32 v[98:99], s[0:1], v102, s60, v[138:139]
	v_lshl_add_u64 v[98:99], v[98:99], 0, s[52:53]
	v_lshl_add_u64 v[98:99], v[98:99], 0, v[0:1]
	global_load_dwordx4 v[98:101], v[98:99], off offset:3520
	s_waitcnt lgkmcnt(0)
	s_barrier
	v_ashrrev_i32_e32 v105, 31, v104
	v_and_b32_e32 v111, 15, v110
	v_lshrrev_b32_e32 v114, 2, v110
	v_lshlrev_b32_e32 v110, 1, v110
	v_lshlrev_b32_e32 v111, 2, v111
	v_and_b32_e32 v114, 0xfffffcc, v114
	v_and_or_b32 v110, v110, s89, v111
	v_mad_u64_u32 v[110:111], s[0:1], v114, s92, v[110:111]
	ds_write2_b32 v110, v86, v94 offset1:16
	ds_write2_b32 v110, v87, v95 offset0:132 offset1:148
	v_add_u32_e32 v86, 0x400, v110
	ds_write2_b32 v86, v88, v96 offset0:8 offset1:24
	ds_write2_b32 v86, v89, v97 offset0:140 offset1:156
	v_add_u32_e32 v86, 0x2000, v110
	ds_write2_b32 v86, v82, v90 offset0:64 offset1:80
	ds_write2_b32 v86, v83, v91 offset0:196 offset1:212
	v_add_u32_e32 v82, 0x2400, v110
	ds_write2_b32 v82, v84, v92 offset0:72 offset1:88
	ds_write2_b32 v82, v85, v93 offset0:204 offset1:220
	v_add_u32_e32 v82, 0x4000, v110
	ds_write2_b32 v82, v74, v78 offset0:128 offset1:144
	v_add_u32_e32 v74, 0x4400, v110
	ds_write2_b32 v74, v75, v79 offset0:4 offset1:20
	ds_write2_b32 v74, v76, v80 offset0:136 offset1:152
	v_add_u32_e32 v74, 0x4800, v110
	ds_write2_b32 v74, v77, v81 offset0:12 offset1:28
	v_add_u32_e32 v74, 0x6000, v110
	ds_write2_b32 v74, v66, v70 offset0:192 offset1:208
	v_add_u32_e32 v66, 0x6400, v110
	ds_write2_b32 v66, v67, v71 offset0:68 offset1:84
	ds_write2_b32 v66, v68, v72 offset0:200 offset1:216
	v_add_u32_e32 v66, 0x6800, v110
	ds_write2_b32 v66, v69, v73 offset0:76 offset1:92
	v_mul_lo_u32 v66, v113, s92
	s_waitcnt lgkmcnt(0)
	s_barrier
; DI float sigm(float x) { return 1.f / (1.f + __expf(-x)); }
; DI float silu(float x) { return x / (1.f + __expf(-x)); }
; DI u32x4 pack8(const float* f) { u32x4 o; o.x = pack2(f[0], f[1]); o.y = pack2(f[2], f[3]); o.z = pack2(f[4], f[5]); o.w = pack2(f[6], f[7]); return o; }
; DI void lds_barrier() { asm volatile("s_waitcnt lgkmcnt(0)\n\ts_barrier" ::: "memory"); }
; DI int tid512() { int t = threadIdx.x; asm volatile("" : "+v"(t)); return t; }
; template <int AI, int BJ>
; DI void stage_q(const f32x4 (&acc)[2][2][4][2], float* Cs) {
;   const int t = tid512(), wid = t >> 6, lane = t & 63, wr = wid >> 2, wc = wid & 3, fr = lane & 15, fq = lane >> 4;
;   lds_barrier();
; #pragma unroll
;   for (int m = 0; m < 4; ++m)
; #pragma unroll
;     for (int n = 0; n < 2; ++n)
; #pragma unroll
;       for (int j = 0; j < 4; ++j) Cs[(wr * 64 + m * 16 + fq * 4 + j) * CST + wc * 32 + n * 16 + fr] = acc[AI][BJ][m][n][j];
;   lds_barrier();
; }
; template <int AI, int BJ>
; DI void glu_quadrant(PREF p, const f32x4 (&acc)[2][2][4][2], int mt, int nt, float* Cs) {
;   const int t = tid512();
;   const int row0 = mt * 256 + AI * 128, oc0 = (nt * 2 + BJ) * 64, c = (t & 7) * 8;
;   u32x4 zr[2];
; #pragma unroll
;   for (int q = 0; q < 2; ++q) zr[q] = *(const u32x4*)(p.hb + (size_t)(row0 + (t >> 3) + 64 * q) * HW + OFF_CZ + oc0 + c);
;   stage_q<AI, BJ>(acc, Cs);
; #pragma unroll
;   for (int q = 0; q < 2; ++q) {
;     const int r = (t >> 3) + 64 * q;
;     float v[8], g[8]; ld8(Cs + r * CST + c, v); ld8(Cs + r * CST + 64 + c, g);
;     float z[8]; unpack8(zr[q], z);
; #pragma unroll
;     for (int j = 0; j < 8; ++j) v[j] = v[j] * sigm(g[j]) * silu(z[j]);
;     *(u32x4*)(p.ys + (size_t)(row0 + r) * 1024 + 512 + oc0 + c) = pack8(v);
;   }
	v_lshl_add_u32 v82, v112, 2, v66
	ds_read_b128 v[74:77], v82
	ds_read_b128 v[66:69], v82 offset:16
	ds_read_b128 v[78:81], v82 offset:256
	ds_read_b128 v[70:73], v82 offset:272
	v_ashrrev_i32_e32 v103, 31, v102
	s_bitset1_b32 s14, 7
	s_waitcnt lgkmcnt(1)
	v_mul_f32_e32 v78, 0xbfb8aa3b, v78
	v_exp_f32_e32 v87, v78
	s_waitcnt lgkmcnt(0)
	v_mul_f32_e32 v70, 0xbfb8aa3b, v70
	s_waitcnt vmcnt(1)
	v_lshlrev_b32_e32 v88, 16, v106
	v_mul_f32_e32 v78, 0xbfb8aa3b, v88
	v_exp_f32_e32 v86, v78
	v_and_b32_e32 v89, 0xffff0000, v106
	v_lshlrev_b32_e32 v90, 16, v107
	v_and_b32_e32 v91, 0xffff0000, v107
	v_pk_add_f32 v[86:87], v[86:87], 1.0 op_sel_hi:[1,0]
	v_lshlrev_b32_e32 v92, 16, v108
	v_and_b32_e32 v85, 0xffff0000, v108
	v_lshlrev_b32_e32 v84, 16, v109
	v_and_b32_e32 v83, 0xffff0000, v109
	v_rcp_f32_e32 v78, v86
	s_nop 0
	v_mul_f32_e32 v78, v88, v78
	v_rcp_f32_e32 v86, v87
	s_nop 0
	v_mul_f32_e32 v74, v74, v86
	v_mul_f32_e32 v74, v78, v74
	v_mul_f32_e32 v78, 0xbfb8aa3b, v79
	v_exp_f32_e32 v79, v78
	v_mul_f32_e32 v78, 0xbfb8aa3b, v89
	v_exp_f32_e32 v78, v78
	s_nop 0
	v_pk_add_f32 v[78:79], v[78:79], 1.0 op_sel_hi:[1,0]
	s_nop 0
	v_rcp_f32_e32 v86, v78
	s_nop 0
	v_mul_f32_e32 v78, v89, v86
	v_rcp_f32_e32 v79, v79
	s_nop 0
	v_mul_f32_e32 v75, v75, v79
	v_mul_f32_e32 v75, v78, v75
	v_mul_f32_e32 v78, 0xbfb8aa3b, v80
	v_exp_f32_e32 v79, v78
	v_mul_f32_e32 v78, 0xbfb8aa3b, v90
	v_exp_f32_e32 v78, v78
	s_nop 0
	v_pk_add_f32 v[78:79], v[78:79], 1.0 op_sel_hi:[1,0]
	s_nop 0
	v_rcp_f32_e32 v80, v78
	s_nop 0
	v_mul_f32_e32 v78, v90, v80
	s_waitcnt vmcnt(0)
	v_and_b32_e32 v90, 0xffff0000, v99
	v_rcp_f32_e32 v79, v79
	s_nop 0
	v_mul_f32_e32 v76, v76, v79
	v_mul_f32_e32 v76, v78, v76
	v_mul_f32_e32 v78, 0xbfb8aa3b, v81
	v_exp_f32_e32 v79, v78
	v_mul_f32_e32 v78, 0xbfb8aa3b, v91
	v_exp_f32_e32 v78, v78
	v_lshlrev_b32_e32 v89, 16, v99
	v_pk_add_f32 v[78:79], v[78:79], 1.0 op_sel_hi:[1,0]
	s_nop 0
	v_rcp_f32_e32 v80, v78
	s_nop 0
	v_mul_f32_e32 v78, v91, v80
	v_lshlrev_b32_e32 v91, 16, v100
	v_rcp_f32_e32 v79, v79
	s_nop 0
	v_mul_f32_e32 v77, v77, v79
	v_exp_f32_e32 v79, v70
	v_mul_f32_e32 v70, 0xbfb8aa3b, v92
	v_mul_f32_e32 v77, v78, v77
	v_exp_f32_e32 v78, v70
	v_and_b32_e32 v88, 0xffff0000, v98
	v_pk_add_f32 v[78:79], v[78:79], 1.0 op_sel_hi:[1,0]
	s_nop 0
	v_rcp_f32_e32 v70, v78
	s_nop 0
	v_mul_f32_e32 v70, v92, v70
	v_rcp_f32_e32 v78, v79
	s_nop 0
	v_mul_f32_e32 v66, v66, v78
	v_mul_f32_e32 v78, v70, v66
	v_mul_f32_e32 v66, 0xbfb8aa3b, v71
	v_exp_f32_e32 v71, v66
	v_mul_f32_e32 v66, 0xbfb8aa3b, v85
	v_exp_f32_e32 v70, v66
	s_nop 0
	v_pk_add_f32 v[70:71], v[70:71], 1.0 op_sel_hi:[1,0]
	s_nop 0
	v_rcp_f32_e32 v66, v70
	s_nop 0
	v_mul_f32_e32 v66, v85, v66
	v_rcp_f32_e32 v70, v71
	s_nop 0
	v_mul_f32_e32 v67, v67, v70
	v_mul_f32_e32 v70, v66, v67
	v_mul_f32_e32 v66, 0xbfb8aa3b, v72
	v_exp_f32_e32 v67, v66
	v_mul_f32_e32 v66, 0xbfb8aa3b, v84
	v_exp_f32_e32 v66, v66
	v_lshlrev_b32_e32 v85, 16, v98
	v_pk_add_f32 v[66:67], v[66:67], 1.0 op_sel_hi:[1,0]
	s_nop 0
	v_rcp_f32_e32 v71, v66
	s_nop 0
	v_mul_f32_e32 v66, v84, v71
	v_and_b32_e32 v84, 0xffff0000, v100
	v_rcp_f32_e32 v67, v67
	s_nop 0
	v_mul_f32_e32 v67, v68, v67
	v_mul_f32_e32 v71, v66, v67
	v_mul_f32_e32 v66, 0xbfb8aa3b, v73
	v_exp_f32_e32 v67, v66
	v_mul_f32_e32 v66, 0xbfb8aa3b, v83
	v_exp_f32_e32 v66, v66
	s_nop 0
	v_pk_add_f32 v[66:67], v[66:67], 1.0 op_sel_hi:[1,0]
	s_nop 0
	v_rcp_f32_e32 v68, v66
	s_nop 0
	v_mul_f32_e32 v66, v83, v68
	v_lshlrev_b32_e32 v83, 16, v101
	v_rcp_f32_e32 v67, v67
	s_nop 0
	v_mul_f32_e32 v67, v69, v67
	v_mul_f32_e32 v69, v66, v67
	v_cvt_pk_bf16_f32 v68, v78, v70
	s_nop 1
	v_cvt_pk_bf16_f32 v69, v71, v69
	s_nop 1
	v_lshlrev_b64 v[70:71], 11, v[104:105]
	v_lshl_add_u64 v[70:71], s[10:11], 0, v[70:71]
	v_lshl_add_u64 v[70:71], v[70:71], 0, s[52:53]
	v_lshl_add_u64 v[70:71], v[70:71], 0, v[0:1]
	v_cvt_pk_bf16_f32 v66, v74, v75
	s_nop 1
	v_cvt_pk_bf16_f32 v67, v76, v77
	s_nop 1
	global_store_dwordx4 v[70:71], v[66:69], off offset:1152
	ds_read_b128 v[74:77], v82 offset:33792
	ds_read_b128 v[66:69], v82 offset:33808
	ds_read_b128 v[78:81], v82 offset:34048
	ds_read_b128 v[70:73], v82 offset:34064
	v_and_b32_e32 v82, 0xffff0000, v101
	s_waitcnt lgkmcnt(1)
	v_mul_f32_e32 v78, 0xbfb8aa3b, v78
	v_exp_f32_e32 v87, v78
	v_mul_f32_e32 v78, 0xbfb8aa3b, v85
	v_exp_f32_e32 v86, v78
	s_waitcnt lgkmcnt(0)
; DI float sigm(float x) { return 1.f / (1.f + __expf(-x)); }
; DI float silu(float x) { return x / (1.f + __expf(-x)); }
; DI u32x4 pack8(const float* f) { u32x4 o; o.x = pack2(f[0], f[1]); o.y = pack2(f[2], f[3]); o.z = pack2(f[4], f[5]); o.w = pack2(f[6], f[7]); return o; }
; DI void lds_barrier() { asm volatile("s_waitcnt lgkmcnt(0)\n\ts_barrier" ::: "memory"); }
; DI int tid512() { int t = threadIdx.x; asm volatile("" : "+v"(t)); return t; }
; template <int AI, int BJ>
; DI void stage_q(const f32x4 (&acc)[2][2][4][2], float* Cs) {
;   const int t = tid512(), wid = t >> 6, lane = t & 63, wr = wid >> 2, wc = wid & 3, fr = lane & 15, fq = lane >> 4;
;   lds_barrier();
; #pragma unroll
;   for (int m = 0; m < 4; ++m)
; #pragma unroll
;     for (int n = 0; n < 2; ++n)
; #pragma unroll
;       for (int j = 0; j < 4; ++j) Cs[(wr * 64 + m * 16 + fq * 4 + j) * CST + wc * 32 + n * 16 + fr] = acc[AI][BJ][m][n][j];
;   lds_barrier();
; }
; template <int AI, int BJ>
; DI void glu_quadrant(PREF p, const f32x4 (&acc)[2][2][4][2], int mt, int nt, float* Cs) {
;   const int t = tid512();
;   const int row0 = mt * 256 + AI * 128, oc0 = (nt * 2 + BJ) * 64, c = (t & 7) * 8;
;   u32x4 zr[2];
; #pragma unroll
;   for (int q = 0; q < 2; ++q) zr[q] = *(const u32x4*)(p.hb + (size_t)(row0 + (t >> 3) + 64 * q) * HW + OFF_CZ + oc0 + c);
;   stage_q<AI, BJ>(acc, Cs);
; #pragma unroll
;   for (int q = 0; q < 2; ++q) {
;     const int r = (t >> 3) + 64 * q;
;     float v[8], g[8]; ld8(Cs + r * CST + c, v); ld8(Cs + r * CST + 64 + c, g);
;     float z[8]; unpack8(zr[q], z);
; #pragma unroll
;     for (int j = 0; j < 8; ++j) v[j] = v[j] * sigm(g[j]) * silu(z[j]);
;     *(u32x4*)(p.ys + (size_t)(row0 + r) * 1024 + 512 + oc0 + c) = pack8(v);
;   }
	v_mul_f32_e32 v70, 0xbfb8aa3b, v70
	v_pk_add_f32 v[86:87], v[86:87], 1.0 op_sel_hi:[1,0]
	s_nop 0
	v_rcp_f32_e32 v78, v86
	s_nop 0
	v_mul_f32_e32 v78, v85, v78
	v_rcp_f32_e32 v85, v87
	s_nop 0
	v_mul_f32_e32 v74, v74, v85
	v_mul_f32_e32 v74, v78, v74
	v_mul_f32_e32 v78, 0xbfb8aa3b, v79
	v_exp_f32_e32 v79, v78
	v_mul_f32_e32 v78, 0xbfb8aa3b, v88
	v_exp_f32_e32 v78, v78
	s_nop 0
	v_pk_add_f32 v[78:79], v[78:79], 1.0 op_sel_hi:[1,0]
	s_nop 0
	v_rcp_f32_e32 v85, v78
	s_nop 0
	v_mul_f32_e32 v78, v88, v85
	v_rcp_f32_e32 v79, v79
	s_nop 0
	v_mul_f32_e32 v75, v75, v79
	v_mul_f32_e32 v75, v78, v75
	v_mul_f32_e32 v78, 0xbfb8aa3b, v80
	v_exp_f32_e32 v79, v78
	v_mul_f32_e32 v78, 0xbfb8aa3b, v89
	v_exp_f32_e32 v78, v78
	s_nop 0
	v_pk_add_f32 v[78:79], v[78:79], 1.0 op_sel_hi:[1,0]
	s_nop 0
	v_rcp_f32_e32 v80, v78
	s_nop 0
	v_mul_f32_e32 v78, v89, v80
	v_rcp_f32_e32 v79, v79
	s_nop 0
	v_mul_f32_e32 v76, v76, v79
	v_mul_f32_e32 v76, v78, v76
	v_mul_f32_e32 v78, 0xbfb8aa3b, v81
	v_exp_f32_e32 v79, v78
	v_mul_f32_e32 v78, 0xbfb8aa3b, v90
	v_exp_f32_e32 v78, v78
	s_nop 0
	v_pk_add_f32 v[78:79], v[78:79], 1.0 op_sel_hi:[1,0]
	s_nop 0
	v_rcp_f32_e32 v80, v78
	s_nop 0
	v_mul_f32_e32 v78, v90, v80
	v_rcp_f32_e32 v79, v79
	s_nop 0
	v_mul_f32_e32 v77, v77, v79
	v_exp_f32_e32 v79, v70
	v_mul_f32_e32 v70, 0xbfb8aa3b, v91
	v_mul_f32_e32 v77, v78, v77
	v_exp_f32_e32 v78, v70
	s_nop 0
	v_pk_add_f32 v[78:79], v[78:79], 1.0 op_sel_hi:[1,0]
	s_nop 0
	v_rcp_f32_e32 v70, v78
	s_nop 0
	v_mul_f32_e32 v70, v91, v70
	v_rcp_f32_e32 v78, v79
	s_nop 0
	v_mul_f32_e32 v66, v66, v78
	v_mul_f32_e32 v78, v70, v66
	v_mul_f32_e32 v66, 0xbfb8aa3b, v71
	v_exp_f32_e32 v71, v66
	v_mul_f32_e32 v66, 0xbfb8aa3b, v84
	v_exp_f32_e32 v70, v66
	s_nop 0
	v_pk_add_f32 v[70:71], v[70:71], 1.0 op_sel_hi:[1,0]
	s_nop 0
	v_rcp_f32_e32 v66, v70
	s_nop 0
	v_mul_f32_e32 v66, v84, v66
	v_rcp_f32_e32 v70, v71
	s_nop 0
	v_mul_f32_e32 v67, v67, v70
	v_mul_f32_e32 v70, v66, v67
	v_mul_f32_e32 v66, 0xbfb8aa3b, v72
	v_exp_f32_e32 v67, v66
	v_mul_f32_e32 v66, 0xbfb8aa3b, v83
	v_exp_f32_e32 v66, v66
	s_nop 0
	v_pk_add_f32 v[66:67], v[66:67], 1.0 op_sel_hi:[1,0]
	s_nop 0
	v_rcp_f32_e32 v71, v66
	s_nop 0
	v_mul_f32_e32 v66, v83, v71
	v_rcp_f32_e32 v67, v67
	s_nop 0
	v_mul_f32_e32 v67, v68, v67
	v_mul_f32_e32 v71, v66, v67
	v_mul_f32_e32 v66, 0xbfb8aa3b, v73
	v_exp_f32_e32 v67, v66
	v_mul_f32_e32 v66, 0xbfb8aa3b, v82
	v_exp_f32_e32 v66, v66
	s_nop 0
	v_pk_add_f32 v[66:67], v[66:67], 1.0 op_sel_hi:[1,0]
	s_nop 0
	v_rcp_f32_e32 v68, v66
	s_nop 0
	v_mul_f32_e32 v66, v82, v68
	v_rcp_f32_e32 v67, v67
	s_nop 0
	v_mul_f32_e32 v67, v69, v67
	v_mul_f32_e32 v69, v66, v67
	v_cvt_pk_bf16_f32 v68, v78, v70
	s_nop 1
	v_cvt_pk_bf16_f32 v69, v71, v69
	s_nop 1
	v_lshlrev_b64 v[70:71], 11, v[102:103]
	v_lshl_add_u64 v[70:71], s[10:11], 0, v[70:71]
	v_lshl_add_u64 v[70:71], v[70:71], 0, s[52:53]
	v_lshl_add_u64 v[70:71], v[70:71], 0, v[0:1]
	v_mov_b32_e32 v0, v168
	v_cvt_pk_bf16_f32 v66, v74, v75
	s_nop 1
	v_cvt_pk_bf16_f32 v67, v76, v77
	s_nop 1
	global_store_dwordx4 v[70:71], v[66:69], off offset:1152
	v_mov_b32_e32 v78, v168
	v_ashrrev_i32_e32 v81, 3, v0
	v_lshlrev_b32_e32 v66, 3, v0
	v_add_u32_e32 v72, s14, v81
	v_and_b32_e32 v80, 56, v66
	v_mad_i64_i32 v[66:67], s[0:1], v72, s60, v[138:139]
	v_lshl_add_u64 v[66:67], v[66:67], 0, s[52:53]
	v_lshlrev_b32_e32 v0, 1, v80
	v_lshl_add_u64 v[66:67], v[66:67], 0, v[0:1]
	global_load_dwordx4 v[74:77], v[66:67], off offset:3392
	v_add_u32_e32 v70, 64, v72
	v_mad_i64_i32 v[66:67], s[0:1], v70, s60, v[138:139]
	v_lshl_add_u64 v[66:67], v[66:67], 0, s[52:53]
	v_lshl_add_u64 v[66:67], v[66:67], 0, v[0:1]
	global_load_dwordx4 v[66:69], v[66:67], off offset:3392
	s_waitcnt lgkmcnt(0)
	s_barrier
	v_ashrrev_i32_e32 v73, 31, v72
	v_and_b32_e32 v79, 15, v78
	v_lshrrev_b32_e32 v82, 2, v78
	v_lshlrev_b32_e32 v78, 1, v78
	v_lshlrev_b32_e32 v79, 2, v79
	v_and_b32_e32 v82, 0xfffffcc, v82
	v_and_or_b32 v78, v78, s89, v79
	v_mad_u64_u32 v[78:79], s[0:1], v82, s92, v[78:79]
	ds_write2_b32 v78, v54, v62 offset1:16
	ds_write2_b32 v78, v55, v63 offset0:132 offset1:148
	v_add_u32_e32 v54, 0x400, v78
	ds_write2_b32 v54, v56, v64 offset0:8 offset1:24
	ds_write2_b32 v54, v57, v65 offset0:140 offset1:156
	v_add_u32_e32 v54, 0x2000, v78
	ds_write2_b32 v54, v50, v58 offset0:64 offset1:80
	ds_write2_b32 v54, v51, v59 offset0:196 offset1:212
	v_add_u32_e32 v50, 0x2400, v78
	ds_write2_b32 v50, v52, v60 offset0:72 offset1:88
	ds_write2_b32 v50, v53, v61 offset0:204 offset1:220
	v_add_u32_e32 v50, 0x4000, v78
	ds_write2_b32 v50, v42, v46 offset0:128 offset1:144
	v_add_u32_e32 v42, 0x4400, v78
	ds_write2_b32 v42, v43, v47 offset0:4 offset1:20
	ds_write2_b32 v42, v44, v48 offset0:136 offset1:152
	v_add_u32_e32 v42, 0x4800, v78
	ds_write2_b32 v42, v45, v49 offset0:12 offset1:28
	v_add_u32_e32 v42, 0x6000, v78
	ds_write2_b32 v42, v34, v38 offset0:192 offset1:208
	v_add_u32_e32 v34, 0x6400, v78
	ds_write2_b32 v34, v35, v39 offset0:68 offset1:84
	ds_write2_b32 v34, v36, v40 offset0:200 offset1:216
	v_add_u32_e32 v34, 0x6800, v78
	ds_write2_b32 v34, v37, v41 offset0:76 offset1:92
	v_mul_lo_u32 v34, v81, s92
	s_waitcnt lgkmcnt(0)
	s_barrier
; DI float sigm(float x) { return 1.f / (1.f + __expf(-x)); }
; DI float silu(float x) { return x / (1.f + __expf(-x)); }
; DI u32x4 pack8(const float* f) { u32x4 o; o.x = pack2(f[0], f[1]); o.y = pack2(f[2], f[3]); o.z = pack2(f[4], f[5]); o.w = pack2(f[6], f[7]); return o; }
; DI void lds_barrier() { asm volatile("s_waitcnt lgkmcnt(0)\n\ts_barrier" ::: "memory"); }
; DI int tid512() { int t = threadIdx.x; asm volatile("" : "+v"(t)); return t; }
; template <int AI, int BJ>
; DI void stage_q(const f32x4 (&acc)[2][2][4][2], float* Cs) {
;   const int t = tid512(), wid = t >> 6, lane = t & 63, wr = wid >> 2, wc = wid & 3, fr = lane & 15, fq = lane >> 4;
;   lds_barrier();
; #pragma unroll
;   for (int m = 0; m < 4; ++m)
; #pragma unroll
;     for (int n = 0; n < 2; ++n)
; #pragma unroll
;       for (int j = 0; j < 4; ++j) Cs[(wr * 64 + m * 16 + fq * 4 + j) * CST + wc * 32 + n * 16 + fr] = acc[AI][BJ][m][n][j];
;   lds_barrier();
; }
; template <int AI, int BJ>
; DI void glu_quadrant(PREF p, const f32x4 (&acc)[2][2][4][2], int mt, int nt, float* Cs) {
;   const int t = tid512();
;   const int row0 = mt * 256 + AI * 128, oc0 = (nt * 2 + BJ) * 64, c = (t & 7) * 8;
;   u32x4 zr[2];
; #pragma unroll
;   for (int q = 0; q < 2; ++q) zr[q] = *(const u32x4*)(p.hb + (size_t)(row0 + (t >> 3) + 64 * q) * HW + OFF_CZ + oc0 + c);
;   stage_q<AI, BJ>(acc, Cs);
; #pragma unroll
;   for (int q = 0; q < 2; ++q) {
;     const int r = (t >> 3) + 64 * q;
;     float v[8], g[8]; ld8(Cs + r * CST + c, v); ld8(Cs + r * CST + 64 + c, g);
;     float z[8]; unpack8(zr[q], z);
; #pragma unroll
;     for (int j = 0; j < 8; ++j) v[j] = v[j] * sigm(g[j]) * silu(z[j]);
;     *(u32x4*)(p.ys + (size_t)(row0 + r) * 1024 + 512 + oc0 + c) = pack8(v);
;   }
	v_lshl_add_u32 v50, v80, 2, v34
	ds_read_b128 v[42:45], v50
	ds_read_b128 v[34:37], v50 offset:16
	ds_read_b128 v[46:49], v50 offset:256
	ds_read_b128 v[38:41], v50 offset:272
	v_ashrrev_i32_e32 v71, 31, v70
	s_waitcnt lgkmcnt(1)
	v_mul_f32_e32 v46, 0xbfb8aa3b, v46
	v_exp_f32_e32 v55, v46
	s_waitcnt lgkmcnt(0)
	v_mul_f32_e32 v38, 0xbfb8aa3b, v38
	s_waitcnt vmcnt(1)
	v_lshlrev_b32_e32 v56, 16, v74
	v_mul_f32_e32 v46, 0xbfb8aa3b, v56
	v_exp_f32_e32 v54, v46
	v_and_b32_e32 v57, 0xffff0000, v74
	v_lshlrev_b32_e32 v58, 16, v75
	v_and_b32_e32 v59, 0xffff0000, v75
	v_pk_add_f32 v[54:55], v[54:55], 1.0 op_sel_hi:[1,0]
	v_lshlrev_b32_e32 v60, 16, v76
	v_and_b32_e32 v53, 0xffff0000, v76
	v_lshlrev_b32_e32 v52, 16, v77
	v_and_b32_e32 v51, 0xffff0000, v77
	v_rcp_f32_e32 v46, v54
	s_nop 0
	v_mul_f32_e32 v46, v56, v46
	v_rcp_f32_e32 v54, v55
	s_nop 0
	v_mul_f32_e32 v42, v42, v54
	v_mul_f32_e32 v42, v46, v42
	v_mul_f32_e32 v46, 0xbfb8aa3b, v47
	v_exp_f32_e32 v47, v46
	v_mul_f32_e32 v46, 0xbfb8aa3b, v57
	v_exp_f32_e32 v46, v46
	s_nop 0
	v_pk_add_f32 v[46:47], v[46:47], 1.0 op_sel_hi:[1,0]
	s_nop 0
	v_rcp_f32_e32 v54, v46
	s_nop 0
	v_mul_f32_e32 v46, v57, v54
	v_rcp_f32_e32 v47, v47
	s_nop 0
	v_mul_f32_e32 v43, v43, v47
	v_mul_f32_e32 v43, v46, v43
	v_mul_f32_e32 v46, 0xbfb8aa3b, v48
	v_exp_f32_e32 v47, v46
	v_mul_f32_e32 v46, 0xbfb8aa3b, v58
	v_exp_f32_e32 v46, v46
	s_nop 0
	v_pk_add_f32 v[46:47], v[46:47], 1.0 op_sel_hi:[1,0]
	s_nop 0
	v_rcp_f32_e32 v48, v46
	s_nop 0
	v_mul_f32_e32 v46, v58, v48
	s_waitcnt vmcnt(0)
	v_and_b32_e32 v58, 0xffff0000, v67
	v_rcp_f32_e32 v47, v47
	s_nop 0
	v_mul_f32_e32 v44, v44, v47
	v_mul_f32_e32 v44, v46, v44
	v_mul_f32_e32 v46, 0xbfb8aa3b, v49
	v_exp_f32_e32 v47, v46
	v_mul_f32_e32 v46, 0xbfb8aa3b, v59
	v_exp_f32_e32 v46, v46
	v_lshlrev_b32_e32 v57, 16, v67
	v_pk_add_f32 v[46:47], v[46:47], 1.0 op_sel_hi:[1,0]
	s_nop 0
	v_rcp_f32_e32 v48, v46
	s_nop 0
	v_mul_f32_e32 v46, v59, v48
	v_lshlrev_b32_e32 v59, 16, v68
	v_rcp_f32_e32 v47, v47
	s_nop 0
	v_mul_f32_e32 v45, v45, v47
	v_exp_f32_e32 v47, v38
	v_mul_f32_e32 v38, 0xbfb8aa3b, v60
	v_mul_f32_e32 v45, v46, v45
	v_exp_f32_e32 v46, v38
	v_and_b32_e32 v56, 0xffff0000, v66
	v_pk_add_f32 v[46:47], v[46:47], 1.0 op_sel_hi:[1,0]
	s_nop 0
	v_rcp_f32_e32 v38, v46
	s_nop 0
	v_mul_f32_e32 v38, v60, v38
	v_rcp_f32_e32 v46, v47
	s_nop 0
	v_mul_f32_e32 v34, v34, v46
	v_mul_f32_e32 v46, v38, v34
	v_mul_f32_e32 v34, 0xbfb8aa3b, v39
	v_exp_f32_e32 v39, v34
	v_mul_f32_e32 v34, 0xbfb8aa3b, v53
	v_exp_f32_e32 v38, v34
	s_nop 0
	v_pk_add_f32 v[38:39], v[38:39], 1.0 op_sel_hi:[1,0]
	s_nop 0
	v_rcp_f32_e32 v34, v38
	s_nop 0
	v_mul_f32_e32 v34, v53, v34
	v_rcp_f32_e32 v38, v39
	s_nop 0
	v_mul_f32_e32 v35, v35, v38
	v_mul_f32_e32 v38, v34, v35
	v_mul_f32_e32 v34, 0xbfb8aa3b, v40
	v_exp_f32_e32 v35, v34
	v_mul_f32_e32 v34, 0xbfb8aa3b, v52
	v_exp_f32_e32 v34, v34
	v_lshlrev_b32_e32 v53, 16, v66
	v_pk_add_f32 v[34:35], v[34:35], 1.0 op_sel_hi:[1,0]
	s_nop 0
	v_rcp_f32_e32 v39, v34
	s_nop 0
	v_mul_f32_e32 v34, v52, v39
	v_and_b32_e32 v52, 0xffff0000, v68
	v_rcp_f32_e32 v35, v35
	s_nop 0
	v_mul_f32_e32 v35, v36, v35
	v_mul_f32_e32 v39, v34, v35
	v_mul_f32_e32 v34, 0xbfb8aa3b, v41
	v_exp_f32_e32 v35, v34
	v_mul_f32_e32 v34, 0xbfb8aa3b, v51
	v_exp_f32_e32 v34, v34
	s_nop 0
	v_pk_add_f32 v[34:35], v[34:35], 1.0 op_sel_hi:[1,0]
	s_nop 0
	v_rcp_f32_e32 v36, v34
	s_nop 0
	v_mul_f32_e32 v34, v51, v36
	v_lshlrev_b32_e32 v51, 16, v69
	v_rcp_f32_e32 v35, v35
	s_nop 0
	v_mul_f32_e32 v35, v37, v35
	v_mul_f32_e32 v37, v34, v35
	v_cvt_pk_bf16_f32 v36, v46, v38
	s_nop 1
	v_cvt_pk_bf16_f32 v37, v39, v37
	s_nop 1
	v_lshlrev_b64 v[38:39], 11, v[72:73]
	v_lshl_add_u64 v[38:39], s[10:11], 0, v[38:39]
	v_lshl_add_u64 v[38:39], v[38:39], 0, s[52:53]
	v_lshl_add_u64 v[38:39], v[38:39], 0, v[0:1]
	v_cvt_pk_bf16_f32 v34, v42, v43
	s_nop 1
	v_cvt_pk_bf16_f32 v35, v44, v45
	s_nop 1
	global_store_dwordx4 v[38:39], v[34:37], off offset:1024
	ds_read_b128 v[42:45], v50 offset:33792
	ds_read_b128 v[34:37], v50 offset:33808
	ds_read_b128 v[46:49], v50 offset:34048
	ds_read_b128 v[38:41], v50 offset:34064
	v_and_b32_e32 v50, 0xffff0000, v69
	s_waitcnt lgkmcnt(1)
	v_mul_f32_e32 v46, 0xbfb8aa3b, v46
	v_exp_f32_e32 v55, v46
	v_mul_f32_e32 v46, 0xbfb8aa3b, v53
	v_exp_f32_e32 v54, v46
	s_waitcnt lgkmcnt(0)
; DI float sigm(float x) { return 1.f / (1.f + __expf(-x)); }
; DI float silu(float x) { return x / (1.f + __expf(-x)); }
; DI u32x4 pack8(const float* f) { u32x4 o; o.x = pack2(f[0], f[1]); o.y = pack2(f[2], f[3]); o.z = pack2(f[4], f[5]); o.w = pack2(f[6], f[7]); return o; }
; DI void lds_barrier() { asm volatile("s_waitcnt lgkmcnt(0)\n\ts_barrier" ::: "memory"); }
; DI int tid512() { int t = threadIdx.x; asm volatile("" : "+v"(t)); return t; }
; template <int AI, int BJ>
; DI void stage_q(const f32x4 (&acc)[2][2][4][2], float* Cs) {
;   const int t = tid512(), wid = t >> 6, lane = t & 63, wr = wid >> 2, wc = wid & 3, fr = lane & 15, fq = lane >> 4;
;   lds_barrier();
; #pragma unroll
;   for (int m = 0; m < 4; ++m)
; #pragma unroll
;     for (int n = 0; n < 2; ++n)
; #pragma unroll
;       for (int j = 0; j < 4; ++j) Cs[(wr * 64 + m * 16 + fq * 4 + j) * CST + wc * 32 + n * 16 + fr] = acc[AI][BJ][m][n][j];
;   lds_barrier();
; }
; template <int AI, int BJ>
; DI void glu_quadrant(PREF p, const f32x4 (&acc)[2][2][4][2], int mt, int nt, float* Cs) {
;   const int t = tid512();
;   const int row0 = mt * 256 + AI * 128, oc0 = (nt * 2 + BJ) * 64, c = (t & 7) * 8;
;   u32x4 zr[2];
; #pragma unroll
;   for (int q = 0; q < 2; ++q) zr[q] = *(const u32x4*)(p.hb + (size_t)(row0 + (t >> 3) + 64 * q) * HW + OFF_CZ + oc0 + c);
;   stage_q<AI, BJ>(acc, Cs);
; #pragma unroll
;   for (int q = 0; q < 2; ++q) {
;     const int r = (t >> 3) + 64 * q;
;     float v[8], g[8]; ld8(Cs + r * CST + c, v); ld8(Cs + r * CST + 64 + c, g);
;     float z[8]; unpack8(zr[q], z);
; #pragma unroll
;     for (int j = 0; j < 8; ++j) v[j] = v[j] * sigm(g[j]) * silu(z[j]);
;     *(u32x4*)(p.ys + (size_t)(row0 + r) * 1024 + 512 + oc0 + c) = pack8(v);
;   }
	v_mul_f32_e32 v38, 0xbfb8aa3b, v38
	v_pk_add_f32 v[54:55], v[54:55], 1.0 op_sel_hi:[1,0]
	s_nop 0
	v_rcp_f32_e32 v46, v54
	s_nop 0
	v_mul_f32_e32 v46, v53, v46
	v_rcp_f32_e32 v53, v55
	s_nop 0
	v_mul_f32_e32 v42, v42, v53
	v_mul_f32_e32 v42, v46, v42
	v_mul_f32_e32 v46, 0xbfb8aa3b, v47
	v_exp_f32_e32 v47, v46
	v_mul_f32_e32 v46, 0xbfb8aa3b, v56
	v_exp_f32_e32 v46, v46
	s_nop 0
	v_pk_add_f32 v[46:47], v[46:47], 1.0 op_sel_hi:[1,0]
	s_nop 0
	v_rcp_f32_e32 v53, v46
	s_nop 0
	v_mul_f32_e32 v46, v56, v53
	v_rcp_f32_e32 v47, v47
	s_nop 0
	v_mul_f32_e32 v43, v43, v47
	v_mul_f32_e32 v43, v46, v43
	v_mul_f32_e32 v46, 0xbfb8aa3b, v48
	v_exp_f32_e32 v47, v46
	v_mul_f32_e32 v46, 0xbfb8aa3b, v57
	v_exp_f32_e32 v46, v46
	s_nop 0
	v_pk_add_f32 v[46:47], v[46:47], 1.0 op_sel_hi:[1,0]
	s_nop 0
	v_rcp_f32_e32 v48, v46
	s_nop 0
	v_mul_f32_e32 v46, v57, v48
	v_rcp_f32_e32 v47, v47
	s_nop 0
	v_mul_f32_e32 v44, v44, v47
	v_mul_f32_e32 v44, v46, v44
	v_mul_f32_e32 v46, 0xbfb8aa3b, v49
	v_exp_f32_e32 v47, v46
	v_mul_f32_e32 v46, 0xbfb8aa3b, v58
	v_exp_f32_e32 v46, v46
	s_nop 0
	v_pk_add_f32 v[46:47], v[46:47], 1.0 op_sel_hi:[1,0]
	s_nop 0
	v_rcp_f32_e32 v48, v46
	s_nop 0
	v_mul_f32_e32 v46, v58, v48
	v_rcp_f32_e32 v47, v47
	s_nop 0
	v_mul_f32_e32 v45, v45, v47
	v_exp_f32_e32 v47, v38
	v_mul_f32_e32 v38, 0xbfb8aa3b, v59
	v_mul_f32_e32 v45, v46, v45
	v_exp_f32_e32 v46, v38
	s_nop 0
	v_pk_add_f32 v[46:47], v[46:47], 1.0 op_sel_hi:[1,0]
	s_nop 0
	v_rcp_f32_e32 v38, v46
	s_nop 0
	v_mul_f32_e32 v38, v59, v38
	v_rcp_f32_e32 v46, v47
	s_nop 0
	v_mul_f32_e32 v34, v34, v46
	v_mul_f32_e32 v46, v38, v34
	v_mul_f32_e32 v34, 0xbfb8aa3b, v39
	v_exp_f32_e32 v39, v34
	v_mul_f32_e32 v34, 0xbfb8aa3b, v52
	v_exp_f32_e32 v38, v34
	s_nop 0
	v_pk_add_f32 v[38:39], v[38:39], 1.0 op_sel_hi:[1,0]
	s_nop 0
	v_rcp_f32_e32 v34, v38
	s_nop 0
	v_mul_f32_e32 v34, v52, v34
	v_rcp_f32_e32 v38, v39
	s_nop 0
	v_mul_f32_e32 v35, v35, v38
	v_mul_f32_e32 v38, v34, v35
	v_mul_f32_e32 v34, 0xbfb8aa3b, v40
	v_exp_f32_e32 v35, v34
	v_mul_f32_e32 v34, 0xbfb8aa3b, v51
	v_exp_f32_e32 v34, v34
	s_nop 0
	v_pk_add_f32 v[34:35], v[34:35], 1.0 op_sel_hi:[1,0]
	s_nop 0
	v_rcp_f32_e32 v39, v34
	s_nop 0
	v_mul_f32_e32 v34, v51, v39
	v_rcp_f32_e32 v35, v35
	s_nop 0
	v_mul_f32_e32 v35, v36, v35
	v_mul_f32_e32 v39, v34, v35
	v_mul_f32_e32 v34, 0xbfb8aa3b, v41
	v_exp_f32_e32 v35, v34
	v_mul_f32_e32 v34, 0xbfb8aa3b, v50
	v_exp_f32_e32 v34, v34
	s_nop 0
	v_pk_add_f32 v[34:35], v[34:35], 1.0 op_sel_hi:[1,0]
	s_nop 0
	v_rcp_f32_e32 v36, v34
	s_nop 0
	v_mul_f32_e32 v34, v50, v36
	v_rcp_f32_e32 v35, v35
	s_nop 0
	v_mul_f32_e32 v35, v37, v35
	v_mul_f32_e32 v37, v34, v35
	v_cvt_pk_bf16_f32 v36, v46, v38
	s_nop 1
	v_cvt_pk_bf16_f32 v37, v39, v37
	s_nop 1
	v_lshlrev_b64 v[38:39], 11, v[70:71]
	v_lshl_add_u64 v[38:39], s[10:11], 0, v[38:39]
	v_lshl_add_u64 v[38:39], v[38:39], 0, s[52:53]
	v_lshl_add_u64 v[38:39], v[38:39], 0, v[0:1]
	v_mov_b32_e32 v0, v168
	v_cvt_pk_bf16_f32 v34, v42, v43
	s_nop 1
	v_cvt_pk_bf16_f32 v35, v44, v45
	s_nop 1
	global_store_dwordx4 v[38:39], v[34:37], off offset:1024
	v_mov_b32_e32 v46, v168
	v_ashrrev_i32_e32 v49, 3, v0
	v_lshlrev_b32_e32 v34, 3, v0
	v_add_u32_e32 v40, s14, v49
	v_and_b32_e32 v48, 56, v34
	v_mad_i64_i32 v[34:35], s[0:1], v40, s60, v[138:139]
	v_lshl_add_u64 v[34:35], v[34:35], 0, s[52:53]
	v_lshlrev_b32_e32 v0, 1, v48
	v_lshl_add_u64 v[34:35], v[34:35], 0, v[0:1]
	global_load_dwordx4 v[42:45], v[34:35], off offset:3520
	v_add_u32_e32 v38, 64, v40
	v_mad_i64_i32 v[34:35], s[0:1], v38, s60, v[138:139]
	v_lshl_add_u64 v[34:35], v[34:35], 0, s[52:53]
	v_lshl_add_u64 v[34:35], v[34:35], 0, v[0:1]
	global_load_dwordx4 v[34:37], v[34:35], off offset:3520
	s_waitcnt lgkmcnt(0)
	s_barrier
	v_ashrrev_i32_e32 v41, 31, v40
	v_and_b32_e32 v47, 15, v46
	v_lshrrev_b32_e32 v50, 2, v46
	v_lshlrev_b32_e32 v46, 1, v46
	v_lshlrev_b32_e32 v47, 2, v47
	v_and_b32_e32 v50, 0xfffffcc, v50
	v_and_or_b32 v46, v46, s89, v47
	v_mad_u64_u32 v[46:47], s[0:1], v50, s92, v[46:47]
	ds_write2_b32 v46, v22, v30 offset1:16
	ds_write2_b32 v46, v23, v31 offset0:132 offset1:148
	v_add_u32_e32 v22, 0x400, v46
	ds_write2_b32 v22, v24, v32 offset0:8 offset1:24
	ds_write2_b32 v22, v25, v33 offset0:140 offset1:156
	v_add_u32_e32 v22, 0x2000, v46
	ds_write2_b32 v22, v18, v26 offset0:64 offset1:80
	ds_write2_b32 v22, v19, v27 offset0:196 offset1:212
	v_add_u32_e32 v18, 0x2400, v46
	ds_write2_b32 v18, v20, v28 offset0:72 offset1:88
	ds_write2_b32 v18, v21, v29 offset0:204 offset1:220
	v_add_u32_e32 v18, 0x4000, v46
	ds_write2_b32 v18, v10, v14 offset0:128 offset1:144
	v_add_u32_e32 v10, 0x4400, v46
	ds_write2_b32 v10, v11, v15 offset0:4 offset1:20
	ds_write2_b32 v10, v12, v16 offset0:136 offset1:152
	v_add_u32_e32 v10, 0x4800, v46
	ds_write2_b32 v10, v13, v17 offset0:12 offset1:28
	v_add_u32_e32 v10, 0x6000, v46
	ds_write2_b32 v10, v2, v6 offset0:192 offset1:208
	v_add_u32_e32 v2, 0x6400, v46
	ds_write2_b32 v2, v3, v7 offset0:68 offset1:84
	ds_write2_b32 v2, v4, v8 offset0:200 offset1:216
	v_add_u32_e32 v2, 0x6800, v46
	ds_write2_b32 v2, v5, v9 offset0:76 offset1:92
	v_mul_lo_u32 v2, v49, s92
	s_waitcnt lgkmcnt(0)
	s_barrier
; DI float sigm(float x) { return 1.f / (1.f + __expf(-x)); }
; DI float silu(float x) { return x / (1.f + __expf(-x)); }
; DI u32x4 pack8(const float* f) { u32x4 o; o.x = pack2(f[0], f[1]); o.y = pack2(f[2], f[3]); o.z = pack2(f[4], f[5]); o.w = pack2(f[6], f[7]); return o; }
; DI void lds_barrier() { asm volatile("s_waitcnt lgkmcnt(0)\n\ts_barrier" ::: "memory"); }
; DI int tid512() { int t = threadIdx.x; asm volatile("" : "+v"(t)); return t; }
; template <int AI, int BJ>
; DI void stage_q(const f32x4 (&acc)[2][2][4][2], float* Cs) {
;   const int t = tid512(), wid = t >> 6, lane = t & 63, wr = wid >> 2, wc = wid & 3, fr = lane & 15, fq = lane >> 4;
;   lds_barrier();
; #pragma unroll
;   for (int m = 0; m < 4; ++m)
; #pragma unroll
;     for (int n = 0; n < 2; ++n)
; #pragma unroll
;       for (int j = 0; j < 4; ++j) Cs[(wr * 64 + m * 16 + fq * 4 + j) * CST + wc * 32 + n * 16 + fr] = acc[AI][BJ][m][n][j];
;   lds_barrier();
; }
; template <int AI, int BJ>
; DI void glu_quadrant(PREF p, const f32x4 (&acc)[2][2][4][2], int mt, int nt, float* Cs) {
;   const int t = tid512();
;   const int row0 = mt * 256 + AI * 128, oc0 = (nt * 2 + BJ) * 64, c = (t & 7) * 8;
;   u32x4 zr[2];
; #pragma unroll
;   for (int q = 0; q < 2; ++q) zr[q] = *(const u32x4*)(p.hb + (size_t)(row0 + (t >> 3) + 64 * q) * HW + OFF_CZ + oc0 + c);
;   stage_q<AI, BJ>(acc, Cs);
; #pragma unroll
;   for (int q = 0; q < 2; ++q) {
;     const int r = (t >> 3) + 64 * q;
;     float v[8], g[8]; ld8(Cs + r * CST + c, v); ld8(Cs + r * CST + 64 + c, g);
;     float z[8]; unpack8(zr[q], z);
; #pragma unroll
;     for (int j = 0; j < 8; ++j) v[j] = v[j] * sigm(g[j]) * silu(z[j]);
;     *(u32x4*)(p.ys + (size_t)(row0 + r) * 1024 + 512 + oc0 + c) = pack8(v);
;   }
	v_lshl_add_u32 v18, v48, 2, v2
	ds_read_b128 v[10:13], v18
	ds_read_b128 v[2:5], v18 offset:16
	ds_read_b128 v[14:17], v18 offset:256
	ds_read_b128 v[6:9], v18 offset:272
	v_ashrrev_i32_e32 v39, 31, v38
	s_waitcnt lgkmcnt(1)
	v_mul_f32_e32 v14, 0xbfb8aa3b, v14
	v_exp_f32_e32 v23, v14
	s_waitcnt lgkmcnt(0)
	v_mul_f32_e32 v6, 0xbfb8aa3b, v6
	s_waitcnt vmcnt(1)
	v_lshlrev_b32_e32 v24, 16, v42
	v_mul_f32_e32 v14, 0xbfb8aa3b, v24
	v_exp_f32_e32 v22, v14
	v_and_b32_e32 v25, 0xffff0000, v42
	v_lshlrev_b32_e32 v26, 16, v43
	v_and_b32_e32 v27, 0xffff0000, v43
	v_pk_add_f32 v[22:23], v[22:23], 1.0 op_sel_hi:[1,0]
	v_lshlrev_b32_e32 v28, 16, v44
	v_and_b32_e32 v21, 0xffff0000, v44
	v_lshlrev_b32_e32 v20, 16, v45
	v_and_b32_e32 v19, 0xffff0000, v45
	v_rcp_f32_e32 v14, v22
	s_nop 0
	v_mul_f32_e32 v14, v24, v14
	v_rcp_f32_e32 v22, v23
	s_nop 0
	v_mul_f32_e32 v10, v10, v22
	v_mul_f32_e32 v10, v14, v10
	v_mul_f32_e32 v14, 0xbfb8aa3b, v15
	v_exp_f32_e32 v15, v14
	v_mul_f32_e32 v14, 0xbfb8aa3b, v25
	v_exp_f32_e32 v14, v14
	s_nop 0
	v_pk_add_f32 v[14:15], v[14:15], 1.0 op_sel_hi:[1,0]
	s_nop 0
	v_rcp_f32_e32 v22, v14
	s_nop 0
	v_mul_f32_e32 v14, v25, v22
	v_rcp_f32_e32 v15, v15
	s_nop 0
	v_mul_f32_e32 v11, v11, v15
	v_mul_f32_e32 v11, v14, v11
	v_mul_f32_e32 v14, 0xbfb8aa3b, v16
	v_exp_f32_e32 v15, v14
	v_mul_f32_e32 v14, 0xbfb8aa3b, v26
	v_exp_f32_e32 v14, v14
	s_nop 0
	v_pk_add_f32 v[14:15], v[14:15], 1.0 op_sel_hi:[1,0]
	s_nop 0
	v_rcp_f32_e32 v16, v14
	s_nop 0
	v_mul_f32_e32 v14, v26, v16
	s_waitcnt vmcnt(0)
	v_and_b32_e32 v26, 0xffff0000, v35
	v_rcp_f32_e32 v15, v15
	s_nop 0
	v_mul_f32_e32 v12, v12, v15
	v_mul_f32_e32 v12, v14, v12
	v_mul_f32_e32 v14, 0xbfb8aa3b, v17
	v_exp_f32_e32 v15, v14
	v_mul_f32_e32 v14, 0xbfb8aa3b, v27
	v_exp_f32_e32 v14, v14
	v_lshlrev_b32_e32 v25, 16, v35
	v_pk_add_f32 v[14:15], v[14:15], 1.0 op_sel_hi:[1,0]
	s_nop 0
	v_rcp_f32_e32 v16, v14
	s_nop 0
	v_mul_f32_e32 v14, v27, v16
	v_lshlrev_b32_e32 v27, 16, v36
	v_rcp_f32_e32 v15, v15
	s_nop 0
	v_mul_f32_e32 v13, v13, v15
	v_exp_f32_e32 v15, v6
	v_mul_f32_e32 v6, 0xbfb8aa3b, v28
	v_mul_f32_e32 v13, v14, v13
	v_exp_f32_e32 v14, v6
	v_and_b32_e32 v24, 0xffff0000, v34
	v_pk_add_f32 v[14:15], v[14:15], 1.0 op_sel_hi:[1,0]
	s_nop 0
	v_rcp_f32_e32 v6, v14
	s_nop 0
	v_mul_f32_e32 v6, v28, v6
	v_rcp_f32_e32 v14, v15
	s_nop 0
	v_mul_f32_e32 v2, v2, v14
	v_mul_f32_e32 v14, v6, v2
	v_mul_f32_e32 v2, 0xbfb8aa3b, v7
	v_exp_f32_e32 v7, v2
	v_mul_f32_e32 v2, 0xbfb8aa3b, v21
	v_exp_f32_e32 v6, v2
	s_nop 0
	v_pk_add_f32 v[6:7], v[6:7], 1.0 op_sel_hi:[1,0]
	s_nop 0
	v_rcp_f32_e32 v2, v6
	s_nop 0
	v_mul_f32_e32 v2, v21, v2
	v_rcp_f32_e32 v6, v7
	s_nop 0
	v_mul_f32_e32 v3, v3, v6
	v_mul_f32_e32 v6, v2, v3
	v_mul_f32_e32 v2, 0xbfb8aa3b, v8
	v_exp_f32_e32 v3, v2
	v_mul_f32_e32 v2, 0xbfb8aa3b, v20
	v_exp_f32_e32 v2, v2
	v_lshlrev_b32_e32 v21, 16, v34
	v_pk_add_f32 v[2:3], v[2:3], 1.0 op_sel_hi:[1,0]
	s_nop 0
	v_rcp_f32_e32 v7, v2
	s_nop 0
	v_mul_f32_e32 v2, v20, v7
	v_and_b32_e32 v20, 0xffff0000, v36
	v_rcp_f32_e32 v3, v3
	s_nop 0
	v_mul_f32_e32 v3, v4, v3
	v_mul_f32_e32 v7, v2, v3
	v_mul_f32_e32 v2, 0xbfb8aa3b, v9
	v_exp_f32_e32 v3, v2
	v_mul_f32_e32 v2, 0xbfb8aa3b, v19
	v_exp_f32_e32 v2, v2
	s_nop 0
	v_pk_add_f32 v[2:3], v[2:3], 1.0 op_sel_hi:[1,0]
	s_nop 0
	v_rcp_f32_e32 v4, v2
	s_nop 0
	v_mul_f32_e32 v2, v19, v4
	v_lshlrev_b32_e32 v19, 16, v37
	v_rcp_f32_e32 v3, v3
	s_nop 0
	v_mul_f32_e32 v3, v5, v3
	v_mul_f32_e32 v5, v2, v3
	v_cvt_pk_bf16_f32 v4, v14, v6
	s_nop 1
	v_cvt_pk_bf16_f32 v5, v7, v5
	s_nop 1
	v_lshlrev_b64 v[6:7], 11, v[40:41]
	v_lshl_add_u64 v[6:7], s[10:11], 0, v[6:7]
	v_lshl_add_u64 v[6:7], v[6:7], 0, s[52:53]
	v_lshl_add_u64 v[6:7], v[6:7], 0, v[0:1]
	v_cvt_pk_bf16_f32 v2, v10, v11
	s_nop 1
	v_cvt_pk_bf16_f32 v3, v12, v13
	s_nop 1
	global_store_dwordx4 v[6:7], v[2:5], off offset:1152
	ds_read_b128 v[10:13], v18 offset:33792
	ds_read_b128 v[2:5], v18 offset:33808
	ds_read_b128 v[14:17], v18 offset:34048
	ds_read_b128 v[6:9], v18 offset:34064
	v_and_b32_e32 v18, 0xffff0000, v37
	s_waitcnt lgkmcnt(1)
; DI u32x4 pack8(const float* f) { u32x4 o; o.x = pack2(f[0], f[1]); o.y = pack2(f[2], f[3]); o.z = pack2(f[4], f[5]); o.w = pack2(f[6], f[7]); return o; }
; DI int tid512() { int t = threadIdx.x; asm volatile("" : "+v"(t)); return t; }
; DI float sigm(float x) { return 1.f / (1.f + __expf(-x)); }
; DI float silu(float x) { return x / (1.f + __expf(-x)); }
; template <int AI, int BJ>
; DI void glu_quadrant(PREF p, const f32x4 (&acc)[2][2][4][2], int mt, int nt, float* Cs) {
;   const int t = tid512();
;   const int row0 = mt * 256 + AI * 128, oc0 = (nt * 2 + BJ) * 64, c = (t & 7) * 8;
;   u32x4 zr[2];
; #pragma unroll
;   for (int q = 0; q < 2; ++q) zr[q] = *(const u32x4*)(p.hb + (size_t)(row0 + (t >> 3) + 64 * q) * HW + OFF_CZ + oc0 + c);
;   stage_q<AI, BJ>(acc, Cs);
; #pragma unroll
;   for (int q = 0; q < 2; ++q) {
;     const int r = (t >> 3) + 64 * q;
;     float v[8], g[8]; ld8(Cs + r * CST + c, v); ld8(Cs + r * CST + 64 + c, g);
;     float z[8]; unpack8(zr[q], z);
; #pragma unroll
;     for (int j = 0; j < 8; ++j) v[j] = v[j] * sigm(g[j]) * silu(z[j]);
;     *(u32x4*)(p.ys + (size_t)(row0 + r) * 1024 + 512 + oc0 + c) = pack8(v);
;   }
	v_mul_f32_e32 v14, 0xbfb8aa3b, v14
	v_exp_f32_e32 v23, v14
	v_mul_f32_e32 v14, 0xbfb8aa3b, v21
	v_exp_f32_e32 v22, v14
	s_waitcnt lgkmcnt(0)
	v_mul_f32_e32 v6, 0xbfb8aa3b, v6
	v_pk_add_f32 v[22:23], v[22:23], 1.0 op_sel_hi:[1,0]
	s_nop 0
	v_rcp_f32_e32 v14, v22
	s_nop 0
	v_mul_f32_e32 v14, v21, v14
	v_rcp_f32_e32 v21, v23
	s_nop 0
	v_mul_f32_e32 v10, v10, v21
	v_mul_f32_e32 v10, v14, v10
	v_mul_f32_e32 v14, 0xbfb8aa3b, v15
	v_exp_f32_e32 v15, v14
	v_mul_f32_e32 v14, 0xbfb8aa3b, v24
	v_exp_f32_e32 v14, v14
	s_nop 0
	v_pk_add_f32 v[14:15], v[14:15], 1.0 op_sel_hi:[1,0]
	s_nop 0
	v_rcp_f32_e32 v21, v14
	s_nop 0
	v_mul_f32_e32 v14, v24, v21
	v_rcp_f32_e32 v15, v15
	s_nop 0
	v_mul_f32_e32 v11, v11, v15
	v_mul_f32_e32 v11, v14, v11
	v_mul_f32_e32 v14, 0xbfb8aa3b, v16
	v_exp_f32_e32 v15, v14
	v_mul_f32_e32 v14, 0xbfb8aa3b, v25
	v_exp_f32_e32 v14, v14
	s_nop 0
	v_pk_add_f32 v[14:15], v[14:15], 1.0 op_sel_hi:[1,0]
	s_nop 0
	v_rcp_f32_e32 v16, v14
	s_nop 0
	v_mul_f32_e32 v14, v25, v16
	v_rcp_f32_e32 v15, v15
	s_nop 0
	v_mul_f32_e32 v12, v12, v15
	v_mul_f32_e32 v12, v14, v12
	v_mul_f32_e32 v14, 0xbfb8aa3b, v17
	v_exp_f32_e32 v15, v14
	v_mul_f32_e32 v14, 0xbfb8aa3b, v26
	v_exp_f32_e32 v14, v14
	s_nop 0
	v_pk_add_f32 v[14:15], v[14:15], 1.0 op_sel_hi:[1,0]
	s_nop 0
	v_rcp_f32_e32 v16, v14
	s_nop 0
	v_mul_f32_e32 v14, v26, v16
	v_rcp_f32_e32 v15, v15
	s_nop 0
	v_mul_f32_e32 v13, v13, v15
	v_exp_f32_e32 v15, v6
	v_mul_f32_e32 v6, 0xbfb8aa3b, v27
	v_mul_f32_e32 v13, v14, v13
	v_exp_f32_e32 v14, v6
	s_nop 0
	v_pk_add_f32 v[14:15], v[14:15], 1.0 op_sel_hi:[1,0]
	s_nop 0
	v_rcp_f32_e32 v6, v14
	s_nop 0
	v_mul_f32_e32 v6, v27, v6
	v_rcp_f32_e32 v14, v15
	s_nop 0
	v_mul_f32_e32 v2, v2, v14
	v_mul_f32_e32 v14, v6, v2
	v_mul_f32_e32 v2, 0xbfb8aa3b, v7
	v_exp_f32_e32 v7, v2
	v_mul_f32_e32 v2, 0xbfb8aa3b, v20
	v_exp_f32_e32 v6, v2
	s_nop 0
	v_pk_add_f32 v[6:7], v[6:7], 1.0 op_sel_hi:[1,0]
	s_nop 0
	v_rcp_f32_e32 v2, v6
	s_nop 0
	v_mul_f32_e32 v2, v20, v2
	v_rcp_f32_e32 v6, v7
	s_nop 0
	v_mul_f32_e32 v3, v3, v6
	v_mul_f32_e32 v6, v2, v3
	v_mul_f32_e32 v2, 0xbfb8aa3b, v8
	v_exp_f32_e32 v3, v2
	v_mul_f32_e32 v2, 0xbfb8aa3b, v19
	v_exp_f32_e32 v2, v2
	s_nop 0
	v_pk_add_f32 v[2:3], v[2:3], 1.0 op_sel_hi:[1,0]
	s_nop 0
	v_rcp_f32_e32 v7, v2
	s_nop 0
	v_mul_f32_e32 v2, v19, v7
	v_rcp_f32_e32 v3, v3
	s_nop 0
	v_mul_f32_e32 v3, v4, v3
	v_mul_f32_e32 v7, v2, v3
	v_mul_f32_e32 v2, 0xbfb8aa3b, v9
	v_exp_f32_e32 v3, v2
	v_mul_f32_e32 v2, 0xbfb8aa3b, v18
	v_exp_f32_e32 v2, v2
	s_nop 0
	v_pk_add_f32 v[2:3], v[2:3], 1.0 op_sel_hi:[1,0]
	s_nop 0
	v_rcp_f32_e32 v4, v2
	s_nop 0
	v_mul_f32_e32 v2, v18, v4
	v_readlane_b32 s0, v254, 32
	s_add_i32 s24, s24, s0
	s_cmpk_lt_i32 s24, 0x100
	v_rcp_f32_e32 v3, v3
	s_nop 0
	v_mul_f32_e32 v3, v5, v3
	v_mul_f32_e32 v5, v2, v3
	v_cvt_pk_bf16_f32 v4, v14, v6
	s_nop 1
	v_cvt_pk_bf16_f32 v5, v7, v5
	s_nop 1
	v_lshlrev_b64 v[6:7], 11, v[38:39]
	v_lshl_add_u64 v[6:7], s[10:11], 0, v[6:7]
	v_lshl_add_u64 v[6:7], v[6:7], 0, s[52:53]
	v_lshl_add_u64 v[6:7], v[6:7], 0, v[0:1]
	v_cvt_pk_bf16_f32 v2, v10, v11
	s_nop 1
	v_cvt_pk_bf16_f32 v3, v12, v13
	s_nop 1
	global_store_dwordx4 v[6:7], v[2:5], off offset:1152
	s_cbranch_scc0 .LBB0_221

; DI unsigned pack2(float a, float b) { unsigned r; asm("v_cvt_pk_bf16_f32 %0, %1, %2\n\ts_nop 1" : "=v"(r) : "v"(a), "v"(b)); return r; }
; DI float lo2f(unsigned u) { return __uint_as_float(u << 16); }
; DI float hi2f(unsigned u) { return __uint_as_float(u & 0xffff0000u); }
; DI float silu(float x) { return x / (1.f + __expf(-x)); }
; template <int DQK, bool WIN>
; DI void attn_item(const u16* __restrict__ Qb, int ldq, const u16* __restrict__ Kb, int ldk, const u16* __restrict__ Vtb, int qb,
;                   float qscale, float sink2, const u16* __restrict__ zb, int ldz, u16* __restrict__ ob, int ldo, u16* lds) {
;     ...
;   float lt = lsum + __shfl_xor(lsum, 32);
;   float inv = 1.f / lt;
;   u32x2 zr[8];
; #pragma unroll
;   for (int e = 0; e < 8; ++e) zr[e] = *(const u32x2*)(zb + (size_t)qrow * ldz + (e >> 2) * 32 + 8 * (e & 3) + 4 * hh);
; #pragma unroll
;   for (int vb = 0; vb < 2; ++vb)
; #pragma unroll
;     for (int g4 = 0; g4 < 4; ++g4) {
;       int vd0 = vb * 32 + 8 * g4 + 4 * hh;
;       u32x2 z = zr[vb * 4 + g4];
;       float a0 = o[vb][4 * g4 + 0] * inv * silu(lo2f(z.x));
;       float a1 = o[vb][4 * g4 + 1] * inv * silu(hi2f(z.x));
;       float a2 = o[vb][4 * g4 + 2] * inv * silu(lo2f(z.y));
;       float a3 = o[vb][4 * g4 + 3] * inv * silu(hi2f(z.y));
;       u32x2 ov; ov.x = pack2(a0, a1); ov.y = pack2(a2, a3);
;       *(u32x2*)(ob + (size_t)qrow * ldo + vd0) = ov;
;     }
.LBB0_229:
	s_lshl_b32 s1, s28, 11
	s_add_u32 s8, s14, s1
	s_mul_i32 s0, s28, 0x1540
	s_addc_u32 s9, s15, 0
	s_add_u32 s0, s12, s0
	v_and_b32_e32 v34, 64, v172
	s_addc_u32 s1, s13, 0
	s_lshl_b32 s20, s27, 7
	v_xor_b32_e32 v0, 32, v172
	v_add_u32_e32 v34, 64, v34
	s_add_u32 s0, s0, s20
	v_cmp_lt_i32_e32 vcc, v0, v34
	s_addc_u32 s1, s1, 0
	v_mov_b64_e32 v[34:35], s[0:1]
	v_cndmask_b32_e32 v0, v172, v0, vcc
	v_lshlrev_b32_e32 v0, 2, v0
	ds_bpermute_b32 v162, v0, v142
	v_mad_i64_i32 v[34:35], s[0:1], v130, s60, v[34:35]
	v_lshlrev_b32_e32 v0, 1, v146
	v_lshl_add_u64 v[34:35], v[34:35], 0, v[0:1]
	global_load_dwordx2 v[50:51], v[34:35], off offset:2368
	global_load_dwordx2 v[46:47], v[34:35], off offset:2384
	global_load_dwordx2 v[44:45], v[34:35], off offset:2400
	global_load_dwordx2 v[42:43], v[34:35], off offset:2416
	global_load_dwordx2 v[40:41], v[34:35], off offset:2432
	global_load_dwordx2 v[38:39], v[34:35], off offset:2448
	global_load_dwordx2 v[36:37], v[34:35], off offset:2464
	s_nop 0
	global_load_dwordx2 v[34:35], v[34:35], off offset:2480
	s_add_u32 s8, s8, s20
	s_addc_u32 s9, s9, 0
	v_lshlrev_b64 v[48:49], 11, v[130:131]
	v_lshl_add_u64 v[48:49], s[8:9], 0, v[48:49]
	s_add_i32 s26, s26, s71
	s_cmpk_gt_i32 s26, 0x3ff
	s_waitcnt vmcnt(7)
	v_lshlrev_b32_e32 v52, 16, v50
	v_mul_f32_e32 v53, 0xbfb8aa3b, v52
	v_exp_f32_e32 v53, v53
	v_and_b32_e32 v50, 0xffff0000, v50
	v_add_f32_e32 v53, 1.0, v53
	v_rcp_f32_e32 v54, v53
	s_nop 0
	v_mul_f32_e32 v54, v52, v54
	v_mul_f32_e32 v52, 0xbfb8aa3b, v50
	v_exp_f32_e32 v52, v52
	s_nop 0
	v_add_f32_e32 v52, 1.0, v52
	v_rcp_f32_e32 v53, v52
	s_nop 0
	v_mul_f32_e32 v55, v50, v53
	v_lshlrev_b32_e32 v50, 16, v51
	v_mul_f32_e32 v52, 0xbfb8aa3b, v50
	v_exp_f32_e32 v143, v52
	s_waitcnt lgkmcnt(0)
	v_pk_add_f32 v[52:53], v[142:143], v[162:163]
	s_nop 0
	v_rcp_f32_e32 v56, v53
	s_nop 0
	v_mul_f32_e32 v53, v50, v56
	v_rcp_f32_e32 v50, v52
	s_nop 0
	v_mul_f32_e32 v20, v20, v50
	v_mul_f32_e32 v52, v20, v53
	v_mul_f32_e32 v20, v21, v50
	v_and_b32_e32 v21, 0xffff0000, v51
	v_mul_f32_e32 v51, 0xbfb8aa3b, v21
	v_exp_f32_e32 v51, v51
	v_mul_f32_e32 v18, v18, v50
	v_mul_f32_e32 v18, v18, v54
	v_mul_f32_e32 v19, v19, v50
	v_add_f32_e32 v51, 1.0, v51
	v_mul_f32_e32 v19, v19, v55
	v_rcp_f32_e32 v53, v51
	s_nop 0
	v_mul_f32_e32 v21, v21, v53
	v_mul_f32_e32 v21, v20, v21
	v_cvt_pk_bf16_f32 v20, v18, v19
	s_nop 1
	v_lshl_add_u64 v[18:19], v[48:49], 0, v[0:1]
	v_cvt_pk_bf16_f32 v21, v52, v21
	s_nop 1
	global_store_dwordx2 v[18:19], v[20:21], off offset:512
	s_waitcnt vmcnt(7)
	v_lshlrev_b32_e32 v20, 16, v46
	v_mul_f32_e32 v21, 0xbfb8aa3b, v20
	v_exp_f32_e32 v21, v21
	v_mul_f32_e32 v0, v22, v50
	v_add_f32_e32 v21, 1.0, v21
	v_rcp_f32_e32 v22, v21
	s_nop 0
	v_mul_f32_e32 v20, v20, v22
	v_and_b32_e32 v21, 0xffff0000, v46
	v_mul_f32_e32 v22, 0xbfb8aa3b, v21
	v_exp_f32_e32 v22, v22
	v_mul_f32_e32 v0, v0, v20
	v_mul_f32_e32 v20, v23, v50
	v_add_f32_e32 v22, 1.0, v22
	v_rcp_f32_e32 v23, v22
	s_nop 0
	v_mul_f32_e32 v21, v21, v23
	v_lshlrev_b32_e32 v22, 16, v47
	v_mul_f32_e32 v23, 0xbfb8aa3b, v22
	v_exp_f32_e32 v23, v23
	v_mul_f32_e32 v20, v20, v21
	v_mul_f32_e32 v21, v24, v50
	v_cvt_pk_bf16_f32 v20, v0, v20
	s_nop 1
	v_add_f32_e32 v23, 1.0, v23
	v_mul_f32_e32 v0, v26, v50
	v_rcp_f32_e32 v24, v23
	s_nop 0
	v_mul_f32_e32 v22, v22, v24
	v_and_b32_e32 v23, 0xffff0000, v47
	v_mul_f32_e32 v24, 0xbfb8aa3b, v23
	v_exp_f32_e32 v24, v24
	v_mul_f32_e32 v21, v21, v22
	v_mul_f32_e32 v22, v25, v50
	v_add_f32_e32 v24, 1.0, v24
	v_rcp_f32_e32 v25, v24
	s_nop 0
	v_mul_f32_e32 v23, v23, v25
	v_mul_f32_e32 v22, v22, v23
	v_cvt_pk_bf16_f32 v21, v21, v22
	s_nop 1
	global_store_dwordx2 v[18:19], v[20:21], off offset:528
	s_waitcnt vmcnt(7)
	v_lshlrev_b32_e32 v20, 16, v44
	v_mul_f32_e32 v21, 0xbfb8aa3b, v20
	v_exp_f32_e32 v21, v21
	s_nop 0
	v_add_f32_e32 v21, 1.0, v21
	v_rcp_f32_e32 v22, v21
	s_nop 0
	v_mul_f32_e32 v20, v20, v22
	v_and_b32_e32 v21, 0xffff0000, v44
	v_mul_f32_e32 v22, 0xbfb8aa3b, v21
	v_exp_f32_e32 v22, v22
	v_mul_f32_e32 v0, v0, v20
	v_mul_f32_e32 v20, v27, v50
	v_add_f32_e32 v22, 1.0, v22
	v_rcp_f32_e32 v23, v22
	s_nop 0
	v_mul_f32_e32 v21, v21, v23
	v_lshlrev_b32_e32 v22, 16, v45
	v_mul_f32_e32 v23, 0xbfb8aa3b, v22
	v_exp_f32_e32 v23, v23
	v_mul_f32_e32 v20, v20, v21
	v_mul_f32_e32 v21, v28, v50
	v_cvt_pk_bf16_f32 v20, v0, v20
	s_nop 1
	v_add_f32_e32 v23, 1.0, v23
	v_mul_f32_e32 v0, v30, v50
	v_rcp_f32_e32 v24, v23
	s_nop 0
	v_mul_f32_e32 v22, v22, v24
	v_and_b32_e32 v23, 0xffff0000, v45
	v_mul_f32_e32 v24, 0xbfb8aa3b, v23
	v_exp_f32_e32 v24, v24
	v_mul_f32_e32 v21, v21, v22
	v_mul_f32_e32 v22, v29, v50
	v_add_f32_e32 v24, 1.0, v24
	v_rcp_f32_e32 v25, v24
	s_nop 0
	v_mul_f32_e32 v23, v23, v25
	v_mul_f32_e32 v22, v22, v23
	v_cvt_pk_bf16_f32 v21, v21, v22
	s_nop 1
	global_store_dwordx2 v[18:19], v[20:21], off offset:544
	s_waitcnt vmcnt(7)
; DI unsigned pack2(float a, float b) { unsigned r; asm("v_cvt_pk_bf16_f32 %0, %1, %2\n\ts_nop 1" : "=v"(r) : "v"(a), "v"(b)); return r; }
; DI float lo2f(unsigned u) { return __uint_as_float(u << 16); }
; DI float hi2f(unsigned u) { return __uint_as_float(u & 0xffff0000u); }
; DI float silu(float x) { return x / (1.f + __expf(-x)); }
; template <int DQK, bool WIN>
; DI void attn_item(const u16* __restrict__ Qb, int ldq, const u16* __restrict__ Kb, int ldk, const u16* __restrict__ Vtb, int qb,
;                   float qscale, float sink2, const u16* __restrict__ zb, int ldz, u16* __restrict__ ob, int ldo, u16* lds) {
;     ...
;   for (int e = 0; e < 8; ++e) zr[e] = *(const u32x2*)(zb + (size_t)qrow * ldz + (e >> 2) * 32 + 8 * (e & 3) + 4 * hh);
; #pragma unroll
;   for (int vb = 0; vb < 2; ++vb)
; #pragma unroll
;     for (int g4 = 0; g4 < 4; ++g4) {
;       int vd0 = vb * 32 + 8 * g4 + 4 * hh;
;       u32x2 z = zr[vb * 4 + g4];
;       float a0 = o[vb][4 * g4 + 0] * inv * silu(lo2f(z.x));
;       float a1 = o[vb][4 * g4 + 1] * inv * silu(hi2f(z.x));
;       float a2 = o[vb][4 * g4 + 2] * inv * silu(lo2f(z.y));
;       float a3 = o[vb][4 * g4 + 3] * inv * silu(hi2f(z.y));
;       u32x2 ov; ov.x = pack2(a0, a1); ov.y = pack2(a2, a3);
;       *(u32x2*)(ob + (size_t)qrow * ldo + vd0) = ov;
;     }
	v_lshlrev_b32_e32 v20, 16, v42
	v_mul_f32_e32 v21, 0xbfb8aa3b, v20
	v_exp_f32_e32 v21, v21
	s_nop 0
	v_add_f32_e32 v21, 1.0, v21
	v_rcp_f32_e32 v22, v21
	s_nop 0
	v_mul_f32_e32 v20, v20, v22
	v_and_b32_e32 v21, 0xffff0000, v42
	v_mul_f32_e32 v22, 0xbfb8aa3b, v21
	v_exp_f32_e32 v22, v22
	v_mul_f32_e32 v0, v0, v20
	v_mul_f32_e32 v20, v31, v50
	v_add_f32_e32 v22, 1.0, v22
	v_rcp_f32_e32 v23, v22
	s_nop 0
	v_mul_f32_e32 v21, v21, v23
	v_lshlrev_b32_e32 v22, 16, v43
	v_mul_f32_e32 v23, 0xbfb8aa3b, v22
	v_exp_f32_e32 v23, v23
	v_mul_f32_e32 v20, v20, v21
	v_mul_f32_e32 v21, v32, v50
	v_cvt_pk_bf16_f32 v20, v0, v20
	s_nop 1
	v_add_f32_e32 v23, 1.0, v23
	v_mul_f32_e32 v0, v2, v50
	s_waitcnt vmcnt(6)
	v_lshlrev_b32_e32 v2, 16, v40
	v_rcp_f32_e32 v24, v23
	s_nop 0
	v_mul_f32_e32 v22, v22, v24
	v_and_b32_e32 v23, 0xffff0000, v43
	v_mul_f32_e32 v24, 0xbfb8aa3b, v23
	v_exp_f32_e32 v24, v24
	v_mul_f32_e32 v21, v21, v22
	v_mul_f32_e32 v22, v33, v50
	v_add_f32_e32 v24, 1.0, v24
	v_rcp_f32_e32 v25, v24
	s_nop 0
	v_mul_f32_e32 v23, v23, v25
	v_mul_f32_e32 v22, v22, v23
	v_cvt_pk_bf16_f32 v21, v21, v22
	s_nop 1
	global_store_dwordx2 v[18:19], v[20:21], off offset:560
	v_mul_f32_e32 v20, 0xbfb8aa3b, v2
	v_exp_f32_e32 v20, v20
	s_nop 0
	v_add_f32_e32 v20, 1.0, v20
	v_rcp_f32_e32 v21, v20
	s_nop 0
	v_mul_f32_e32 v2, v2, v21
	v_mul_f32_e32 v0, v0, v2
	v_mul_f32_e32 v2, v3, v50
	v_and_b32_e32 v3, 0xffff0000, v40
	v_mul_f32_e32 v20, 0xbfb8aa3b, v3
	v_exp_f32_e32 v20, v20
	s_nop 0
	v_add_f32_e32 v20, 1.0, v20
	v_rcp_f32_e32 v21, v20
	s_nop 0
	v_mul_f32_e32 v3, v3, v21
	v_mul_f32_e32 v2, v2, v3
	v_mul_f32_e32 v3, v4, v50
	v_lshlrev_b32_e32 v4, 16, v41
	v_mul_f32_e32 v20, 0xbfb8aa3b, v4
	v_exp_f32_e32 v20, v20
	v_cvt_pk_bf16_f32 v2, v0, v2
	s_nop 1
	v_mul_f32_e32 v0, v6, v50
	v_add_f32_e32 v20, 1.0, v20
	v_rcp_f32_e32 v21, v20
	s_nop 0
	v_mul_f32_e32 v4, v4, v21
	v_mul_f32_e32 v3, v3, v4
	v_mul_f32_e32 v4, v5, v50
	v_and_b32_e32 v5, 0xffff0000, v41
	v_mul_f32_e32 v20, 0xbfb8aa3b, v5
	v_exp_f32_e32 v20, v20
	s_nop 0
	v_add_f32_e32 v20, 1.0, v20
	v_rcp_f32_e32 v21, v20
	s_nop 0
	v_mul_f32_e32 v5, v5, v21
	v_mul_f32_e32 v4, v4, v5
	v_cvt_pk_bf16_f32 v3, v3, v4
	s_nop 1
	global_store_dwordx2 v[18:19], v[2:3], off offset:576
	s_waitcnt vmcnt(7)
	v_lshlrev_b32_e32 v2, 16, v38
	v_mul_f32_e32 v3, 0xbfb8aa3b, v2
	v_exp_f32_e32 v3, v3
	s_nop 0
	v_add_f32_e32 v3, 1.0, v3
	v_rcp_f32_e32 v4, v3
	s_nop 0
	v_mul_f32_e32 v2, v2, v4
	v_and_b32_e32 v3, 0xffff0000, v38
	v_mul_f32_e32 v4, 0xbfb8aa3b, v3
	v_exp_f32_e32 v4, v4
	v_mul_f32_e32 v0, v0, v2
	v_mul_f32_e32 v2, v7, v50
	v_add_f32_e32 v4, 1.0, v4
	v_rcp_f32_e32 v5, v4
	s_nop 0
	v_mul_f32_e32 v3, v3, v5
	v_lshlrev_b32_e32 v4, 16, v39
	v_mul_f32_e32 v5, 0xbfb8aa3b, v4
	v_exp_f32_e32 v5, v5
	v_mul_f32_e32 v2, v2, v3
	v_mul_f32_e32 v3, v8, v50
	v_cvt_pk_bf16_f32 v2, v0, v2
	s_nop 1
	v_add_f32_e32 v5, 1.0, v5
	v_mul_f32_e32 v0, v10, v50
	v_rcp_f32_e32 v6, v5
	s_nop 0
	v_mul_f32_e32 v4, v4, v6
	v_and_b32_e32 v5, 0xffff0000, v39
	v_mul_f32_e32 v6, 0xbfb8aa3b, v5
	v_exp_f32_e32 v6, v6
	v_mul_f32_e32 v3, v3, v4
	v_mul_f32_e32 v4, v9, v50
	v_add_f32_e32 v6, 1.0, v6
	v_rcp_f32_e32 v7, v6
	s_nop 0
	v_mul_f32_e32 v5, v5, v7
	v_mul_f32_e32 v4, v4, v5
	v_cvt_pk_bf16_f32 v3, v3, v4
	s_nop 1
	global_store_dwordx2 v[18:19], v[2:3], off offset:592
	s_waitcnt vmcnt(7)
	v_lshlrev_b32_e32 v2, 16, v36
	v_mul_f32_e32 v3, 0xbfb8aa3b, v2
	v_exp_f32_e32 v3, v3
	s_nop 0
	v_add_f32_e32 v3, 1.0, v3
	v_rcp_f32_e32 v4, v3
	s_nop 0
	v_mul_f32_e32 v2, v2, v4
	v_and_b32_e32 v3, 0xffff0000, v36
	v_mul_f32_e32 v4, 0xbfb8aa3b, v3
	v_exp_f32_e32 v4, v4
	v_mul_f32_e32 v0, v0, v2
	v_mul_f32_e32 v2, v11, v50
	v_add_f32_e32 v4, 1.0, v4
	v_rcp_f32_e32 v5, v4
	s_nop 0
	v_mul_f32_e32 v3, v3, v5
	v_lshlrev_b32_e32 v4, 16, v37
	v_mul_f32_e32 v5, 0xbfb8aa3b, v4
	v_exp_f32_e32 v5, v5
	v_mul_f32_e32 v2, v2, v3
	v_mul_f32_e32 v3, v12, v50
	v_cvt_pk_bf16_f32 v2, v0, v2
	s_nop 1
	v_add_f32_e32 v5, 1.0, v5
	v_mul_f32_e32 v0, v14, v50
	v_rcp_f32_e32 v6, v5
	s_nop 0
	v_mul_f32_e32 v4, v4, v6
	v_and_b32_e32 v5, 0xffff0000, v37
	v_mul_f32_e32 v6, 0xbfb8aa3b, v5
	v_exp_f32_e32 v6, v6
	v_mul_f32_e32 v3, v3, v4
	v_mul_f32_e32 v4, v13, v50
	v_add_f32_e32 v6, 1.0, v6
	v_rcp_f32_e32 v7, v6
	s_nop 0
	v_mul_f32_e32 v5, v5, v7
	v_mul_f32_e32 v4, v4, v5
	v_cvt_pk_bf16_f32 v3, v3, v4
	s_nop 1
	global_store_dwordx2 v[18:19], v[2:3], off offset:608
	s_waitcnt vmcnt(7)
	v_lshlrev_b32_e32 v2, 16, v34
	v_mul_f32_e32 v3, 0xbfb8aa3b, v2
	v_exp_f32_e32 v3, v3
	s_nop 0
	v_add_f32_e32 v3, 1.0, v3
	v_rcp_f32_e32 v4, v3
	s_nop 0
	v_mul_f32_e32 v2, v2, v4
	v_and_b32_e32 v3, 0xffff0000, v34
	v_mul_f32_e32 v4, 0xbfb8aa3b, v3
	v_exp_f32_e32 v4, v4
	v_mul_f32_e32 v0, v0, v2
	v_mul_f32_e32 v2, v15, v50
	v_add_f32_e32 v4, 1.0, v4
	v_rcp_f32_e32 v5, v4
	s_nop 0
	v_mul_f32_e32 v3, v3, v5
	v_lshlrev_b32_e32 v4, 16, v35
	v_mul_f32_e32 v5, 0xbfb8aa3b, v4
	v_exp_f32_e32 v5, v5
	v_mul_f32_e32 v2, v2, v3
	v_mul_f32_e32 v3, v16, v50
	v_cvt_pk_bf16_f32 v2, v0, v2
	s_nop 1
	v_add_f32_e32 v5, 1.0, v5
	v_rcp_f32_e32 v6, v5
	s_nop 0
	v_mul_f32_e32 v4, v4, v6
	v_and_b32_e32 v5, 0xffff0000, v35
	v_mul_f32_e32 v6, 0xbfb8aa3b, v5
	v_exp_f32_e32 v6, v6
	v_mul_f32_e32 v3, v3, v4
	v_mul_f32_e32 v4, v17, v50
	v_add_f32_e32 v6, 1.0, v6
	v_rcp_f32_e32 v7, v6
	s_nop 0
	v_mul_f32_e32 v5, v5, v7
	v_mul_f32_e32 v4, v4, v5
	v_cvt_pk_bf16_f32 v3, v3, v4
	s_nop 1
	global_store_dwordx2 v[18:19], v[2:3], off offset:624
	s_cbranch_scc1 .LBB0_263

; DI int tidx() { int t = threadIdx.x & 255; asm volatile("" : "+v"(t)); return t; }
; #define GM_LOAD(RA, RB, KT)                                                                 \
;   _Pragma("unroll") for (int i = 0; i < 4; ++i) {                                           \
;     RA[i] = *(const u32x4*)(ag + (size_t)(32 * i) * lda + (KT) * 64);                       \
;     RB[i] = *(const u32x4*)(bg + (size_t)(32 * i) * ldb + (KT) * 64);                       \
;   }
; template <bool DEEP = true>
; DI void gemm_main(f32x4 (&acc)[4][4], const u16* __restrict__ A, int lda, const u16* __restrict__ B, int ldb, int K, u16* lds) {
;   const int tid = tidx(), lane = tid & 63, w = tid >> 6;
;   const int wm = w >> 1, wn = w & 1, fr = lane & 15, fq = lane >> 4;
;   const int lrow = tid >> 3, lch = (tid & 7) * 8, lsw = ((tid & 7) ^ (lrow & 7)) * 8;
;   const u16* ag = A + (size_t)lrow * lda + lch;
;   const u16* bg = B + (size_t)lrow * ldb + lch;
;   const int nk = K >> 6;
;   if (DEEP) {
;     u32x4 ra0[4], rb0[4], ra1[4], rb1[4];
;     GM_LOAD(ra0, rb0, 0)
;     GM_LOAD(ra1, rb1, 1)
;     __syncthreads();
;     GM_STORE(ra0, rb0, 0)
;     __syncthreads();
;     for (int kt = 0; kt < nk; kt += 2) {
;       if (kt + 2 < nk) { GM_LOAD(ra0, rb0, kt + 2) }
;       GM_COMPUTE(0)
;       __builtin_amdgcn_sched_barrier(0);
;       GM_STORE(ra1, rb1, 1)
;       __syncthreads();
;       if (kt + 3 < nk) { GM_LOAD(ra1, rb1, kt + 3) }
;       GM_COMPUTE(1)
;       __builtin_amdgcn_sched_barrier(0);
;       if (kt + 2 < nk) { GM_STORE(ra0, rb0, 0) }
;       __syncthreads();
;     }
.LBB0_265:
	s_and_b32 s14, s20, 0xffffff80
	v_mov_b32_e32 v82, v169
	s_ashr_i32 s15, s14, 31
	v_mov_b32_e32 v83, v169
	s_and_b32 s21, s19, 0x80
	s_lshl_b64 s[0:1], s[14:15], 9
	s_add_u32 s0, s12, s0
	v_ashrrev_i32_e32 v34, 3, v83
	v_ashrrev_i32_e32 v35, 31, v34
	s_addc_u32 s1, s13, s1
	s_lshl_b32 s15, s21, 9
	v_lshlrev_b64 v[2:3], 9, v[34:35]
	v_lshlrev_b32_e32 v0, 4, v83
	s_add_u32 s22, s17, s15
	v_lshl_add_u64 v[4:5], s[0:1], 0, v[2:3]
	v_and_b32_e32 v0, 0x70, v0
	s_addc_u32 s23, s18, 0
	v_lshl_add_u64 v[66:67], v[4:5], 0, v[0:1]
	v_lshl_add_u64 v[2:3], s[22:23], 0, v[2:3]
	v_add_co_u32_e32 v70, vcc, s35, v66
	v_lshl_add_u64 v[68:69], v[2:3], 0, v[0:1]
	s_nop 0
	v_addc_co_u32_e32 v71, vcc, 0, v67, vcc
	v_add_co_u32_e32 v72, vcc, s35, v68
	global_load_dwordx4 v[2:5], v[66:67], off
	global_load_dwordx4 v[6:9], v[68:69], off
	v_addc_co_u32_e32 v73, vcc, 0, v69, vcc
	v_add_co_u32_e32 v74, vcc, s37, v66
	global_load_dwordx4 v[10:13], v[70:71], off
	s_nop 0
	v_addc_co_u32_e32 v75, vcc, 0, v67, vcc
	v_add_co_u32_e32 v76, vcc, s37, v68
	global_load_dwordx4 v[18:21], v[74:75], off
	s_nop 0
	v_addc_co_u32_e32 v77, vcc, 0, v69, vcc
	v_add_co_u32_e32 v78, vcc, s40, v66
	global_load_dwordx4 v[14:17], v[72:73], off
	s_nop 0
	v_addc_co_u32_e32 v79, vcc, 0, v67, vcc
	global_load_dwordx4 v[26:29], v[78:79], off
	v_add_co_u32_e32 v80, vcc, s40, v68
	global_load_dwordx4 v[22:25], v[76:77], off
	s_nop 0
	v_addc_co_u32_e32 v81, vcc, 0, v69, vcc
	global_load_dwordx4 v[30:33], v[80:81], off
	v_xor_b32_e32 v0, v34, v83
	v_lshlrev_b32_e32 v0, 4, v0
	v_lshlrev_b32_e32 v34, 7, v34
	v_and_b32_e32 v0, 0x70, v0
	v_add3_u32 v85, s33, v0, v34
	global_load_dwordx4 v[46:49], v[66:67], off offset:128
	global_load_dwordx4 v[42:45], v[70:71], off offset:128
	global_load_dwordx4 v[38:41], v[74:75], off offset:128
	global_load_dwordx4 v[34:37], v[78:79], off offset:128
	global_load_dwordx4 v[62:65], v[68:69], off offset:128
	global_load_dwordx4 v[58:61], v[72:73], off offset:128
	global_load_dwordx4 v[54:57], v[76:77], off offset:128
	global_load_dwordx4 v[50:53], v[80:81], off offset:128
	s_barrier
	v_and_b32_e32 v84, 15, v83
	v_lshrrev_b32_e32 v86, 1, v83
	v_and_or_b32 v84, v86, s41, v84
	v_lshrrev_b32_e32 v0, 4, v83
	v_bfe_u32 v87, v83, 4, 2
	v_lshl_add_u32 v88, v84, 7, s33
	v_lshlrev_b32_e32 v84, 7, v83
	v_and_b32_e32 v83, 7, v83
	v_and_b32_e32 v84, 0x2780, v84
	v_bitop3_b32 v0, v0, v83, 3 bitop3:0x6c
	v_add_u32_e32 v89, s33, v84
	v_lshlrev_b32_e32 v0, 4, v0
	v_add_u32_e32 v86, v88, v0
	v_add_u32_e32 v84, v89, v0
	v_bitop3_b32 v0, v87, v83, 4 bitop3:0x36
	v_lshlrev_b32_e32 v0, 4, v0
	v_add_u32_e32 v83, v88, v0
	v_add_u32_e32 v0, v89, v0
	s_waitcnt vmcnt(15)
	ds_write_b128 v85, v[2:5]
	s_waitcnt vmcnt(13)
	ds_write_b128 v85, v[10:13] offset:4096
	s_waitcnt vmcnt(12)
	ds_write_b128 v85, v[18:21] offset:8192
	s_waitcnt vmcnt(10)
	ds_write_b128 v85, v[26:29] offset:12288
	ds_write_b128 v85, v[6:9] offset:16384
	ds_write_b128 v85, v[14:17] offset:20480
	s_waitcnt vmcnt(9)
	ds_write_b128 v85, v[22:25] offset:24576
	s_waitcnt vmcnt(8)
	ds_write_b128 v85, v[30:33] offset:28672
	s_waitcnt lgkmcnt(0)
	s_barrier
	global_load_dwordx4 v[2:5], v[66:67], off offset:256
	global_load_dwordx4 v[6:9], v[68:69], off offset:256
	global_load_dwordx4 v[10:13], v[70:71], off offset:256
	global_load_dwordx4 v[14:17], v[72:73], off offset:256
	global_load_dwordx4 v[18:21], v[74:75], off offset:256
	global_load_dwordx4 v[22:25], v[76:77], off offset:256
	global_load_dwordx4 v[26:29], v[78:79], off offset:256
	global_load_dwordx4 v[30:33], v[80:81], off offset:256
	s_setprio 1
	ds_read_b128 v[88:91], v86
	ds_read_b128 v[92:95], v86 offset:2048
	ds_read_b128 v[96:99], v86 offset:4096
	ds_read_b128 v[100:103], v86 offset:6144
	ds_read_b128 v[104:107], v84 offset:16384
	ds_read_b128 v[120:123], v84 offset:18432
	ds_read_b128 v[136:139], v84 offset:20480
	ds_read_b128 v[152:155], v84 offset:22528
	s_waitcnt lgkmcnt(3)
	v_mfma_f32_16x16x32_bf16 v[108:111], v[88:91], v[104:107], 0
	v_mfma_f32_16x16x32_bf16 v[112:115], v[92:95], v[104:107], 0
	v_mfma_f32_16x16x32_bf16 v[116:119], v[96:99], v[104:107], 0
	v_mfma_f32_16x16x32_bf16 v[104:107], v[100:103], v[104:107], 0
	s_waitcnt lgkmcnt(2)
	v_mfma_f32_16x16x32_bf16 v[124:127], v[88:91], v[120:123], 0
	v_mfma_f32_16x16x32_bf16 v[128:131], v[92:95], v[120:123], 0
	v_mfma_f32_16x16x32_bf16 v[132:135], v[96:99], v[120:123], 0
	v_mfma_f32_16x16x32_bf16 v[120:123], v[100:103], v[120:123], 0
	s_waitcnt lgkmcnt(1)
	v_mfma_f32_16x16x32_bf16 v[140:143], v[88:91], v[136:139], 0
	v_mfma_f32_16x16x32_bf16 v[144:147], v[92:95], v[136:139], 0
	v_mfma_f32_16x16x32_bf16 v[148:151], v[96:99], v[136:139], 0
	v_mfma_f32_16x16x32_bf16 v[136:139], v[100:103], v[136:139], 0
	s_waitcnt lgkmcnt(0)
	v_mfma_f32_16x16x32_bf16 v[88:91], v[88:91], v[152:155], 0
	v_mfma_f32_16x16x32_bf16 v[92:95], v[92:95], v[152:155], 0
	v_mfma_f32_16x16x32_bf16 v[96:99], v[96:99], v[152:155], 0
	v_mfma_f32_16x16x32_bf16 v[100:103], v[100:103], v[152:155], 0
	ds_read_b128 v[152:155], v83
	ds_read_b128 v[156:159], v83 offset:2048
	ds_read_b128 v[164:167], v83 offset:4096
	ds_read_b128 v[182:185], v83 offset:6144
	ds_read_b128 v[186:189], v0 offset:16384
	s_waitcnt lgkmcnt(0)
	v_mfma_f32_16x16x32_bf16 v[108:111], v[152:155], v[186:189], v[108:111]
	v_mfma_f32_16x16x32_bf16 v[112:115], v[156:159], v[186:189], v[112:115]
	v_mfma_f32_16x16x32_bf16 v[116:119], v[164:167], v[186:189], v[116:119]
	v_mfma_f32_16x16x32_bf16 v[104:107], v[182:185], v[186:189], v[104:107]
	ds_read_b128 v[186:189], v0 offset:18432
	s_waitcnt lgkmcnt(0)
	v_mfma_f32_16x16x32_bf16 v[124:127], v[152:155], v[186:189], v[124:127]
	v_mfma_f32_16x16x32_bf16 v[128:131], v[156:159], v[186:189], v[128:131]
	v_mfma_f32_16x16x32_bf16 v[132:135], v[164:167], v[186:189], v[132:135]
	v_mfma_f32_16x16x32_bf16 v[120:123], v[182:185], v[186:189], v[120:123]
	ds_read_b128 v[186:189], v0 offset:20480
	s_waitcnt lgkmcnt(0)
	v_mfma_f32_16x16x32_bf16 v[140:143], v[152:155], v[186:189], v[140:143]
	v_mfma_f32_16x16x32_bf16 v[144:147], v[156:159], v[186:189], v[144:147]
	v_mfma_f32_16x16x32_bf16 v[148:151], v[164:167], v[186:189], v[148:151]
	v_mfma_f32_16x16x32_bf16 v[136:139], v[182:185], v[186:189], v[136:139]
	ds_read_b128 v[186:189], v0 offset:22528
	s_waitcnt lgkmcnt(0)
	v_mfma_f32_16x16x32_bf16 v[88:91], v[152:155], v[186:189], v[88:91]
	v_mfma_f32_16x16x32_bf16 v[92:95], v[156:159], v[186:189], v[92:95]
	v_mfma_f32_16x16x32_bf16 v[96:99], v[164:167], v[186:189], v[96:99]
	v_mfma_f32_16x16x32_bf16 v[100:103], v[182:185], v[186:189], v[100:103]
	s_setprio 0
	s_waitcnt vmcnt(15)
	ds_write_b128 v85, v[46:49] offset:32768
	s_waitcnt vmcnt(11)
	ds_write_b128 v85, v[62:65] offset:49152
	ds_write_b128 v85, v[42:45] offset:36864
	s_waitcnt vmcnt(10)
	ds_write_b128 v85, v[58:61] offset:53248
	ds_write_b128 v85, v[38:41] offset:40960
	s_waitcnt vmcnt(9)
	ds_write_b128 v85, v[54:57] offset:57344
	ds_write_b128 v85, v[34:37] offset:45056
	s_waitcnt vmcnt(8)
	ds_write_b128 v85, v[50:53] offset:61440
	s_waitcnt lgkmcnt(0)
	s_barrier
; #define GM_LOAD(RA, RB, KT)                                                                 \
;   _Pragma("unroll") for (int i = 0; i < 4; ++i) {                                           \
;     RA[i] = *(const u32x4*)(ag + (size_t)(32 * i) * lda + (KT) * 64);                       \
;     RB[i] = *(const u32x4*)(bg + (size_t)(32 * i) * ldb + (KT) * 64);                       \
;   }
; template <bool DEEP = true>
; DI void gemm_main(f32x4 (&acc)[4][4], const u16* __restrict__ A, int lda, const u16* __restrict__ B, int ldb, int K, u16* lds) {
;     ...
;     for (int kt = 0; kt < nk; kt += 2) {
;       if (kt + 2 < nk) { GM_LOAD(ra0, rb0, kt + 2) }
;       GM_COMPUTE(0)
;       __builtin_amdgcn_sched_barrier(0);
;       GM_STORE(ra1, rb1, 1)
;       __syncthreads();
;       if (kt + 3 < nk) { GM_LOAD(ra1, rb1, kt + 3) }
;       GM_COMPUTE(1)
;       __builtin_amdgcn_sched_barrier(0);
;       if (kt + 2 < nk) { GM_STORE(ra0, rb0, 0) }
;       __syncthreads();
;     }
	global_load_dwordx4 v[34:37], v[66:67], off offset:384
	global_load_dwordx4 v[38:41], v[68:69], off offset:384
	global_load_dwordx4 v[42:45], v[70:71], off offset:384
	global_load_dwordx4 v[46:49], v[72:73], off offset:384
	global_load_dwordx4 v[50:53], v[74:75], off offset:384
	global_load_dwordx4 v[54:57], v[76:77], off offset:384
	global_load_dwordx4 v[58:61], v[78:79], off offset:384
	global_load_dwordx4 v[62:65], v[80:81], off offset:384
	s_setprio 1
	ds_read_b128 v[66:69], v86 offset:32768
	ds_read_b128 v[70:73], v86 offset:34816
	ds_read_b128 v[74:77], v86 offset:36864
	ds_read_b128 v[78:81], v86 offset:38912
	ds_read_b128 v[152:155], v84 offset:49152
	s_waitcnt lgkmcnt(0)
	v_mfma_f32_16x16x32_bf16 v[108:111], v[66:69], v[152:155], v[108:111]
	v_mfma_f32_16x16x32_bf16 v[112:115], v[70:73], v[152:155], v[112:115]
	v_mfma_f32_16x16x32_bf16 v[116:119], v[74:77], v[152:155], v[116:119]
	v_mfma_f32_16x16x32_bf16 v[104:107], v[78:81], v[152:155], v[104:107]
	ds_read_b128 v[152:155], v84 offset:51200
	s_waitcnt lgkmcnt(0)
	v_mfma_f32_16x16x32_bf16 v[124:127], v[66:69], v[152:155], v[124:127]
	v_mfma_f32_16x16x32_bf16 v[128:131], v[70:73], v[152:155], v[128:131]
	v_mfma_f32_16x16x32_bf16 v[132:135], v[74:77], v[152:155], v[132:135]
	v_mfma_f32_16x16x32_bf16 v[120:123], v[78:81], v[152:155], v[120:123]
	ds_read_b128 v[152:155], v84 offset:53248
	s_waitcnt lgkmcnt(0)
	v_mfma_f32_16x16x32_bf16 v[140:143], v[66:69], v[152:155], v[140:143]
	v_mfma_f32_16x16x32_bf16 v[144:147], v[70:73], v[152:155], v[144:147]
	v_mfma_f32_16x16x32_bf16 v[148:151], v[74:77], v[152:155], v[148:151]
	v_mfma_f32_16x16x32_bf16 v[136:139], v[78:81], v[152:155], v[136:139]
	ds_read_b128 v[152:155], v84 offset:55296
	s_waitcnt lgkmcnt(0)
	v_mfma_f32_16x16x32_bf16 v[66:69], v[66:69], v[152:155], v[88:91]
	v_mfma_f32_16x16x32_bf16 v[70:73], v[70:73], v[152:155], v[92:95]
	v_mfma_f32_16x16x32_bf16 v[74:77], v[74:77], v[152:155], v[96:99]
	v_mfma_f32_16x16x32_bf16 v[78:81], v[78:81], v[152:155], v[100:103]
	ds_read_b128 v[88:91], v83 offset:32768
	ds_read_b128 v[92:95], v83 offset:34816
	ds_read_b128 v[96:99], v83 offset:36864
	ds_read_b128 v[100:103], v83 offset:38912
	ds_read_b128 v[152:155], v0 offset:49152
	s_waitcnt lgkmcnt(0)
	v_mfma_f32_16x16x32_bf16 v[108:111], v[88:91], v[152:155], v[108:111]
	v_mfma_f32_16x16x32_bf16 v[112:115], v[92:95], v[152:155], v[112:115]
	v_mfma_f32_16x16x32_bf16 v[116:119], v[96:99], v[152:155], v[116:119]
	v_mfma_f32_16x16x32_bf16 v[104:107], v[100:103], v[152:155], v[104:107]
	ds_read_b128 v[152:155], v0 offset:51200
	s_waitcnt lgkmcnt(0)
	v_mfma_f32_16x16x32_bf16 v[124:127], v[88:91], v[152:155], v[124:127]
	v_mfma_f32_16x16x32_bf16 v[128:131], v[92:95], v[152:155], v[128:131]
	v_mfma_f32_16x16x32_bf16 v[132:135], v[96:99], v[152:155], v[132:135]
	v_mfma_f32_16x16x32_bf16 v[120:123], v[100:103], v[152:155], v[120:123]
	ds_read_b128 v[152:155], v0 offset:53248
	s_waitcnt lgkmcnt(0)
	v_mfma_f32_16x16x32_bf16 v[140:143], v[88:91], v[152:155], v[140:143]
	v_mfma_f32_16x16x32_bf16 v[144:147], v[92:95], v[152:155], v[144:147]
	v_mfma_f32_16x16x32_bf16 v[148:151], v[96:99], v[152:155], v[148:151]
	v_mfma_f32_16x16x32_bf16 v[136:139], v[100:103], v[152:155], v[136:139]
	ds_read_b128 v[152:155], v0 offset:55296
	s_waitcnt lgkmcnt(0)
	v_mfma_f32_16x16x32_bf16 v[66:69], v[88:91], v[152:155], v[66:69]
	v_mfma_f32_16x16x32_bf16 v[70:73], v[92:95], v[152:155], v[70:73]
	v_mfma_f32_16x16x32_bf16 v[74:77], v[96:99], v[152:155], v[74:77]
	v_mfma_f32_16x16x32_bf16 v[78:81], v[100:103], v[152:155], v[78:81]
	s_setprio 0
	s_waitcnt vmcnt(15)
	ds_write_b128 v85, v[2:5]
	s_waitcnt vmcnt(14)
	ds_write_b128 v85, v[6:9] offset:16384
	s_waitcnt vmcnt(13)
	ds_write_b128 v85, v[10:13] offset:4096
	s_waitcnt vmcnt(12)
	ds_write_b128 v85, v[14:17] offset:20480
	s_waitcnt vmcnt(11)
	ds_write_b128 v85, v[18:21] offset:8192
	s_waitcnt vmcnt(10)
	ds_write_b128 v85, v[22:25] offset:24576
	s_waitcnt vmcnt(9)
	ds_write_b128 v85, v[26:29] offset:12288
	s_waitcnt vmcnt(8)
	ds_write_b128 v85, v[30:33] offset:28672
	s_waitcnt lgkmcnt(0)
	s_barrier
	s_setprio 1
	ds_read_b128 v[2:5], v86
	ds_read_b128 v[6:9], v86 offset:2048
	ds_read_b128 v[10:13], v86 offset:4096
	ds_read_b128 v[14:17], v86 offset:6144
	ds_read_b128 v[18:21], v84 offset:16384
	ds_read_b128 v[88:91], v84 offset:18432
	s_waitcnt lgkmcnt(1)
	v_mfma_f32_16x16x32_bf16 v[22:25], v[2:5], v[18:21], v[108:111]
	v_mfma_f32_16x16x32_bf16 v[26:29], v[6:9], v[18:21], v[112:115]
	v_mfma_f32_16x16x32_bf16 v[30:33], v[10:13], v[18:21], v[116:119]
	v_mfma_f32_16x16x32_bf16 v[18:21], v[14:17], v[18:21], v[104:107]
	s_nop 2
	ds_read_b128 v[104:107], v84 offset:20480
	s_waitcnt lgkmcnt(1)
	v_mfma_f32_16x16x32_bf16 v[92:95], v[2:5], v[88:91], v[124:127]
	v_mfma_f32_16x16x32_bf16 v[96:99], v[6:9], v[88:91], v[128:131]
	v_mfma_f32_16x16x32_bf16 v[100:103], v[10:13], v[88:91], v[132:135]
	v_mfma_f32_16x16x32_bf16 v[88:91], v[14:17], v[88:91], v[120:123]
	s_nop 2
	ds_read_b128 v[120:123], v84 offset:22528
	s_waitcnt lgkmcnt(1)
	v_mfma_f32_16x16x32_bf16 v[108:111], v[2:5], v[104:107], v[140:143]
	v_mfma_f32_16x16x32_bf16 v[112:115], v[6:9], v[104:107], v[144:147]
	v_mfma_f32_16x16x32_bf16 v[116:119], v[10:13], v[104:107], v[148:151]
	v_mfma_f32_16x16x32_bf16 v[104:107], v[14:17], v[104:107], v[136:139]
	s_waitcnt lgkmcnt(0)
	v_mfma_f32_16x16x32_bf16 v[2:5], v[2:5], v[120:123], v[66:69]
	v_mfma_f32_16x16x32_bf16 v[6:9], v[6:9], v[120:123], v[70:73]
	v_mfma_f32_16x16x32_bf16 v[10:13], v[10:13], v[120:123], v[74:77]
	v_mfma_f32_16x16x32_bf16 v[14:17], v[14:17], v[120:123], v[78:81]
	ds_read_b128 v[66:69], v83
	ds_read_b128 v[70:73], v83 offset:2048
	ds_read_b128 v[74:77], v83 offset:4096
	ds_read_b128 v[78:81], v83 offset:6144
	ds_read_b128 v[120:123], v0 offset:16384
	s_waitcnt lgkmcnt(0)
; #define GM_LOAD(RA, RB, KT)                                                                 \
;   _Pragma("unroll") for (int i = 0; i < 4; ++i) {                                           \
;     RA[i] = *(const u32x4*)(ag + (size_t)(32 * i) * lda + (KT) * 64);                       \
;     RB[i] = *(const u32x4*)(bg + (size_t)(32 * i) * ldb + (KT) * 64);                       \
;   }
; template <bool DEEP = true>
; DI void gemm_main(f32x4 (&acc)[4][4], const u16* __restrict__ A, int lda, const u16* __restrict__ B, int ldb, int K, u16* lds) {
;     ...
;     for (int kt = 0; kt < nk; kt += 2) {
;       if (kt + 2 < nk) { GM_LOAD(ra0, rb0, kt + 2) }
;       GM_COMPUTE(0)
;       __builtin_amdgcn_sched_barrier(0);
;       GM_STORE(ra1, rb1, 1)
;       __syncthreads();
;       if (kt + 3 < nk) { GM_LOAD(ra1, rb1, kt + 3) }
;       GM_COMPUTE(1)
;       __builtin_amdgcn_sched_barrier(0);
;       if (kt + 2 < nk) { GM_STORE(ra0, rb0, 0) }
;       __syncthreads();
;     }
	v_mfma_f32_16x16x32_bf16 v[22:25], v[66:69], v[120:123], v[22:25]
	v_mfma_f32_16x16x32_bf16 v[26:29], v[70:73], v[120:123], v[26:29]
	v_mfma_f32_16x16x32_bf16 v[30:33], v[74:77], v[120:123], v[30:33]
	v_mfma_f32_16x16x32_bf16 v[18:21], v[78:81], v[120:123], v[18:21]
	ds_read_b128 v[120:123], v0 offset:18432
	s_waitcnt lgkmcnt(0)
	v_mfma_f32_16x16x32_bf16 v[92:95], v[66:69], v[120:123], v[92:95]
	v_mfma_f32_16x16x32_bf16 v[96:99], v[70:73], v[120:123], v[96:99]
	v_mfma_f32_16x16x32_bf16 v[100:103], v[74:77], v[120:123], v[100:103]
	v_mfma_f32_16x16x32_bf16 v[88:91], v[78:81], v[120:123], v[88:91]
	ds_read_b128 v[120:123], v0 offset:20480
	s_waitcnt lgkmcnt(0)
	v_mfma_f32_16x16x32_bf16 v[108:111], v[66:69], v[120:123], v[108:111]
	v_mfma_f32_16x16x32_bf16 v[112:115], v[70:73], v[120:123], v[112:115]
	v_mfma_f32_16x16x32_bf16 v[116:119], v[74:77], v[120:123], v[116:119]
	v_mfma_f32_16x16x32_bf16 v[104:107], v[78:81], v[120:123], v[104:107]
	ds_read_b128 v[120:123], v0 offset:22528
	s_waitcnt lgkmcnt(0)
	v_mfma_f32_16x16x32_bf16 v[2:5], v[66:69], v[120:123], v[2:5]
	v_mfma_f32_16x16x32_bf16 v[6:9], v[70:73], v[120:123], v[6:9]
	v_mfma_f32_16x16x32_bf16 v[10:13], v[74:77], v[120:123], v[10:13]
	v_mfma_f32_16x16x32_bf16 v[14:17], v[78:81], v[120:123], v[14:17]
	s_setprio 0
	s_waitcnt vmcnt(7)
	ds_write_b128 v85, v[34:37] offset:32768
	s_waitcnt vmcnt(6)
	ds_write_b128 v85, v[38:41] offset:49152
	s_waitcnt vmcnt(5)
	ds_write_b128 v85, v[42:45] offset:36864
	s_waitcnt vmcnt(4)
	ds_write_b128 v85, v[46:49] offset:53248
	s_waitcnt vmcnt(3)
	ds_write_b128 v85, v[50:53] offset:40960
	s_waitcnt vmcnt(2)
	ds_write_b128 v85, v[54:57] offset:57344
	s_waitcnt vmcnt(1)
	ds_write_b128 v85, v[58:61] offset:45056
	s_waitcnt vmcnt(0)
	ds_write_b128 v85, v[62:65] offset:61440
	s_waitcnt lgkmcnt(0)
	s_barrier
	s_setprio 1
	ds_read_b128 v[34:37], v86 offset:32768
	ds_read_b128 v[38:41], v86 offset:34816
	ds_read_b128 v[42:45], v86 offset:36864
	ds_read_b128 v[46:49], v86 offset:38912
	ds_read_b128 v[50:53], v84 offset:49152
	s_waitcnt lgkmcnt(0)
	v_mfma_f32_16x16x32_bf16 v[22:25], v[34:37], v[50:53], v[22:25]
	ds_read_b128 v[66:69], v84 offset:53248
	v_mfma_f32_16x16x32_bf16 v[26:29], v[38:41], v[50:53], v[26:29]
	v_mfma_f32_16x16x32_bf16 v[30:33], v[42:45], v[50:53], v[30:33]
	v_mfma_f32_16x16x32_bf16 v[18:21], v[46:49], v[50:53], v[18:21]
	ds_read_b128 v[50:53], v84 offset:51200
	ds_read_b128 v[84:87], v84 offset:55296
	s_waitcnt lgkmcnt(1)
	v_mfma_f32_16x16x32_bf16 v[54:57], v[34:37], v[50:53], v[92:95]
	v_mfma_f32_16x16x32_bf16 v[58:61], v[38:41], v[50:53], v[96:99]
	v_mfma_f32_16x16x32_bf16 v[62:65], v[42:45], v[50:53], v[100:103]
	v_mfma_f32_16x16x32_bf16 v[50:53], v[46:49], v[50:53], v[88:91]
	v_mfma_f32_16x16x32_bf16 v[70:73], v[34:37], v[66:69], v[108:111]
	v_mfma_f32_16x16x32_bf16 v[74:77], v[38:41], v[66:69], v[112:115]
	v_mfma_f32_16x16x32_bf16 v[78:81], v[42:45], v[66:69], v[116:119]
	v_mfma_f32_16x16x32_bf16 v[66:69], v[46:49], v[66:69], v[104:107]
	s_waitcnt lgkmcnt(0)
	v_mfma_f32_16x16x32_bf16 v[2:5], v[34:37], v[84:87], v[2:5]
	v_mfma_f32_16x16x32_bf16 v[6:9], v[38:41], v[84:87], v[6:9]
	v_mfma_f32_16x16x32_bf16 v[10:13], v[42:45], v[84:87], v[10:13]
	v_mfma_f32_16x16x32_bf16 v[14:17], v[46:49], v[84:87], v[14:17]
	ds_read_b128 v[34:37], v83 offset:32768
	ds_read_b128 v[38:41], v83 offset:34816
	ds_read_b128 v[42:45], v83 offset:36864
	ds_read_b128 v[46:49], v83 offset:38912
	ds_read_b128 v[84:87], v0 offset:49152
	s_waitcnt lgkmcnt(0)
	v_mfma_f32_16x16x32_bf16 v[22:25], v[34:37], v[84:87], v[22:25]
	v_mfma_f32_16x16x32_bf16 v[26:29], v[38:41], v[84:87], v[26:29]
	v_mfma_f32_16x16x32_bf16 v[30:33], v[42:45], v[84:87], v[30:33]
	v_mfma_f32_16x16x32_bf16 v[18:21], v[46:49], v[84:87], v[18:21]
	ds_read_b128 v[84:87], v0 offset:51200
	s_waitcnt lgkmcnt(0)
	v_mfma_f32_16x16x32_bf16 v[54:57], v[34:37], v[84:87], v[54:57]
	v_mfma_f32_16x16x32_bf16 v[58:61], v[38:41], v[84:87], v[58:61]
	v_mfma_f32_16x16x32_bf16 v[62:65], v[42:45], v[84:87], v[62:65]
	v_mfma_f32_16x16x32_bf16 v[50:53], v[46:49], v[84:87], v[50:53]
	ds_read_b128 v[84:87], v0 offset:53248
	s_waitcnt lgkmcnt(0)
	v_mfma_f32_16x16x32_bf16 v[70:73], v[34:37], v[84:87], v[70:73]
	v_mfma_f32_16x16x32_bf16 v[74:77], v[38:41], v[84:87], v[74:77]
	v_mfma_f32_16x16x32_bf16 v[78:81], v[42:45], v[84:87], v[78:81]
	v_mfma_f32_16x16x32_bf16 v[66:69], v[46:49], v[84:87], v[66:69]
	ds_read_b128 v[84:87], v0 offset:55296
	s_waitcnt lgkmcnt(0)
	v_mfma_f32_16x16x32_bf16 v[2:5], v[34:37], v[84:87], v[2:5]
	v_mfma_f32_16x16x32_bf16 v[6:9], v[38:41], v[84:87], v[6:9]
	v_mfma_f32_16x16x32_bf16 v[10:13], v[42:45], v[84:87], v[10:13]
	v_mfma_f32_16x16x32_bf16 v[14:17], v[46:49], v[84:87], v[14:17]
	s_setprio 0
	v_mov_b32_e32 v0, v169
	s_barrier
; DI int tidx() { int t = threadIdx.x & 255; asm volatile("" : "+v"(t)); return t; }
; DI float silu(float x) { return x / (1.f + __expf(-x)); }
; DI u32x4 pack8(const float* f) { u32x4 o; o.x = pack2(f[0], f[1]); o.y = pack2(f[2], f[3]); o.z = pack2(f[4], f[5]); o.w = pack2(f[6], f[7]); return o; }
; DI void stage_c(const f32x4 (&acc)[4][4], float* Cs) {
;   const int tid = tidx(), lane = tid & 63, w = tid >> 6;
;   const int wm = w >> 1, wn = w & 1, fr = lane & 15, fq = lane >> 4;
; #pragma unroll
;   for (int m = 0; m < 4; ++m)
; #pragma unroll
;     for (int n = 0; n < 4; ++n)
; #pragma unroll
;       for (int j = 0; j < 4; ++j) Cs[(wm * 64 + m * 16 + fq * 4 + j) * CST + wn * 64 + n * 16 + fr] = acc[m][n][j];
;   __syncthreads();
; DI void pw2_tile(PREF p, int l, int idx, unsigned char* ldsb) {
;     ...
;   stage_c(acc, Cs);
;   u32x4 zr[8];
; #pragma unroll
;   for (int q = 0; q < 8; ++q) zr[q] = *(const u32x4*)(p.hb + (size_t)(row0 + (tid >> 4) + 16 * q) * HW + OFF_AZ + col0 + (tid & 15) * 8);
; #pragma unroll
;   for (int q = 0; q < 8; ++q) {
;     int r = (tid >> 4) + 16 * q, c = (tid & 15) * 8;
;     float v[8]; ld8(Cs + r * CST + c, v);
;     float z[8]; unpack8(zr[q], z);
; #pragma unroll
;     for (int j = 0; j < 8; ++j) v[j] *= silu(z[j]);
;     *(u32x4*)(p.ys + (size_t)(row0 + r) * 1024 + col0 + c) = pack8(v);
;   }
	s_lshl_b32 s52, s21, 1
	v_lshrrev_b32_e32 v35, 2, v0
	v_lshrrev_b32_e32 v34, 1, v0
	v_and_b32_e32 v35, 12, v35
	v_and_or_b32 v34, v34, s42, v35
	v_and_b32_e32 v0, 0x4f, v0
	v_mul_lo_u32 v34, v34, s92
	v_lshlrev_b32_e32 v0, 2, v0
	v_add3_u32 v0, s33, v34, v0
	ds_write2_b32 v0, v22, v54 offset1:16
	ds_write2_b32 v0, v23, v55 offset0:132 offset1:148
	v_add_u32_e32 v22, 0x400, v0
	ds_write2_b32 v22, v24, v56 offset0:8 offset1:24
	ds_write2_b32 v22, v25, v57 offset0:140 offset1:156
	ds_write2_b32 v0, v70, v2 offset0:32 offset1:48
	ds_write2_b32 v0, v71, v3 offset0:164 offset1:180
	ds_write2_b32 v22, v72, v4 offset0:40 offset1:56
	ds_write2_b32 v22, v73, v5 offset0:172 offset1:188
	v_add_u32_e32 v2, 0x2000, v0
	v_add_u32_e32 v3, 0x2400, v0
	ds_write2_b32 v2, v26, v58 offset0:64 offset1:80
	ds_write2_b32 v2, v27, v59 offset0:196 offset1:212
	ds_write2_b32 v3, v28, v60 offset0:72 offset1:88
	ds_write2_b32 v3, v29, v61 offset0:204 offset1:220
	ds_write2_b32 v2, v74, v6 offset0:96 offset1:112
	ds_write2_b32 v2, v75, v7 offset0:228 offset1:244
	ds_write2_b32 v3, v76, v8 offset0:104 offset1:120
	ds_write2_b32 v3, v77, v9 offset0:236 offset1:252
	v_add_u32_e32 v2, 0x4000, v0
	v_add_u32_e32 v3, 0x4400, v0
	v_add_u32_e32 v4, 0x4800, v0
	ds_write2_b32 v2, v30, v62 offset0:128 offset1:144
	ds_write2_b32 v3, v31, v63 offset0:4 offset1:20
	ds_write2_b32 v3, v32, v64 offset0:136 offset1:152
	ds_write2_b32 v4, v33, v65 offset0:12 offset1:28
	ds_write2_b32 v2, v78, v10 offset0:160 offset1:176
	ds_write2_b32 v3, v79, v11 offset0:36 offset1:52
	ds_write2_b32 v3, v80, v12 offset0:168 offset1:184
	ds_write2_b32 v4, v81, v13 offset0:44 offset1:60
	v_add_u32_e32 v2, 0x6000, v0
	v_add_u32_e32 v3, 0x6400, v0
	v_add_u32_e32 v0, 0x6800, v0
	v_ashrrev_i32_e32 v30, 4, v82
	ds_write2_b32 v2, v18, v50 offset0:192 offset1:208
	ds_write2_b32 v3, v19, v51 offset0:68 offset1:84
	ds_write2_b32 v3, v20, v52 offset0:200 offset1:216
	ds_write2_b32 v0, v21, v53 offset0:76 offset1:92
	ds_write2_b32 v2, v66, v14 offset0:224 offset1:240
	ds_write2_b32 v3, v67, v15 offset0:100 offset1:116
	ds_write2_b32 v3, v68, v16 offset0:232 offset1:248
	ds_write2_b32 v0, v69, v17 offset0:108 offset1:124
	v_add_u32_e32 v54, s14, v30
	v_lshlrev_b32_e32 v0, 3, v82
	v_mov_b64_e32 v[2:3], s[8:9]
	v_and_b32_e32 v31, 0x78, v0
	v_mad_i64_i32 v[4:5], s[0:1], v54, s60, v[2:3]
	v_lshl_add_u64 v[4:5], v[4:5], 0, s[52:53]
	v_lshlrev_b32_e32 v0, 1, v31
	v_lshl_add_u64 v[4:5], v[4:5], 0, v[0:1]
	s_waitcnt lgkmcnt(0)
	s_barrier
	global_load_dwordx4 v[56:59], v[4:5], off offset:1024
	v_add_u32_e32 v52, 16, v54
	v_mad_i64_i32 v[4:5], s[0:1], v52, s60, v[2:3]
	v_lshl_add_u64 v[4:5], v[4:5], 0, s[52:53]
	v_lshl_add_u64 v[4:5], v[4:5], 0, v[0:1]
	v_add_u32_e32 v50, 32, v54
	global_load_dwordx4 v[26:29], v[4:5], off offset:1024
	v_mad_i64_i32 v[4:5], s[0:1], v50, s60, v[2:3]
	v_lshl_add_u64 v[4:5], v[4:5], 0, s[52:53]
	v_lshl_add_u64 v[4:5], v[4:5], 0, v[0:1]
	v_add_u32_e32 v48, 48, v54
	global_load_dwordx4 v[22:25], v[4:5], off offset:1024
	v_mad_i64_i32 v[4:5], s[0:1], v48, s60, v[2:3]
	v_lshl_add_u64 v[4:5], v[4:5], 0, s[52:53]
	v_lshl_add_u64 v[4:5], v[4:5], 0, v[0:1]
	v_add_u32_e32 v46, 64, v54
	global_load_dwordx4 v[18:21], v[4:5], off offset:1024
	v_mad_i64_i32 v[4:5], s[0:1], v46, s60, v[2:3]
	v_lshl_add_u64 v[4:5], v[4:5], 0, s[52:53]
	v_lshl_add_u64 v[4:5], v[4:5], 0, v[0:1]
	v_add_u32_e32 v44, 0x50, v54
	global_load_dwordx4 v[14:17], v[4:5], off offset:1024
	v_mad_i64_i32 v[4:5], s[0:1], v44, s60, v[2:3]
	v_lshl_add_u64 v[4:5], v[4:5], 0, s[52:53]
	v_lshl_add_u64 v[4:5], v[4:5], 0, v[0:1]
	v_add_u32_e32 v42, 0x60, v54
	v_add_u32_e32 v38, 0x70, v54
	global_load_dwordx4 v[10:13], v[4:5], off offset:1024
	v_mad_i64_i32 v[4:5], s[0:1], v42, s60, v[2:3]
	v_mad_i64_i32 v[2:3], s[0:1], v38, s60, v[2:3]
	s_add_u32 s0, s10, s52
	s_addc_u32 s1, s11, 0
	v_lshl_add_u64 v[40:41], s[0:1], 0, v[0:1]
	v_lshl_add_u64 v[4:5], v[4:5], 0, s[52:53]
	v_lshl_add_u64 v[2:3], v[2:3], 0, s[52:53]
	v_lshl_add_u64 v[4:5], v[4:5], 0, v[0:1]
	v_lshl_add_u64 v[2:3], v[2:3], 0, v[0:1]
	v_lshlrev_b32_e32 v31, 2, v31
	v_mul_lo_u32 v0, v30, s92
	v_add3_u32 v0, s33, v31, v0
	global_load_dwordx4 v[6:9], v[4:5], off offset:1024
	v_ashrrev_i32_e32 v55, 31, v54
	global_load_dwordx4 v[2:5], v[2:3], off offset:1024
	ds_read_b128 v[34:37], v0
	ds_read_b128 v[30:33], v0 offset:16
	v_ashrrev_i32_e32 v53, 31, v52
	v_ashrrev_i32_e32 v51, 31, v50
	v_ashrrev_i32_e32 v49, 31, v48
	v_ashrrev_i32_e32 v47, 31, v46
	v_ashrrev_i32_e32 v45, 31, v44
	v_ashrrev_i32_e32 v43, 31, v42
	v_ashrrev_i32_e32 v39, 31, v38
	s_add_i32 s16, s16, s71
	s_add_i32 s19, s19, s36
	s_add_i32 s20, s20, s84
	s_cmpk_gt_i32 s16, 0x1ff
	s_waitcnt vmcnt(7)
	v_lshlrev_b32_e32 v60, 16, v56
	v_and_b32_e32 v61, 0xffff0000, v56
	v_lshlrev_b32_e32 v64, 16, v59
	v_and_b32_e32 v56, 0xffff0000, v59
	v_mul_f32_e32 v59, 0xbfb8aa3b, v60
	v_exp_f32_e32 v59, v59
	v_lshlrev_b32_e32 v62, 16, v57
	v_and_b32_e32 v57, 0xffff0000, v57
	v_lshlrev_b32_e32 v63, 16, v58
	v_add_f32_e32 v59, 1.0, v59
	v_and_b32_e32 v58, 0xffff0000, v58
	v_rcp_f32_e32 v65, v59
	s_nop 0
	v_mul_f32_e32 v59, v60, v65
	s_waitcnt lgkmcnt(1)
	v_mul_f32_e32 v34, v59, v34
	v_mul_f32_e32 v59, 0xbfb8aa3b, v61
	v_exp_f32_e32 v59, v59
	s_nop 0
	v_add_f32_e32 v59, 1.0, v59
	v_rcp_f32_e32 v60, v59
	s_nop 0
	v_mul_f32_e32 v59, v61, v60
	v_mul_f32_e32 v35, v59, v35
	v_mul_f32_e32 v59, 0xbfb8aa3b, v62
	v_exp_f32_e32 v59, v59
	s_nop 0
	v_add_f32_e32 v59, 1.0, v59
	v_rcp_f32_e32 v60, v59
	s_nop 0
	v_mul_f32_e32 v59, v62, v60
	v_mul_f32_e32 v36, v59, v36
	v_mul_f32_e32 v59, 0xbfb8aa3b, v57
	v_exp_f32_e32 v59, v59
	s_nop 0
	v_add_f32_e32 v59, 1.0, v59
	v_rcp_f32_e32 v60, v59
	s_nop 0
	v_mul_f32_e32 v57, v57, v60
	v_mul_f32_e32 v37, v57, v37
	v_mul_f32_e32 v57, 0xbfb8aa3b, v63
	v_exp_f32_e32 v57, v57
	s_nop 0
	v_add_f32_e32 v57, 1.0, v57
	v_rcp_f32_e32 v59, v57
	s_nop 0
	v_mul_f32_e32 v57, v63, v59
	s_waitcnt lgkmcnt(0)
; DI u32x4 pack8(const float* f) { u32x4 o; o.x = pack2(f[0], f[1]); o.y = pack2(f[2], f[3]); o.z = pack2(f[4], f[5]); o.w = pack2(f[6], f[7]); return o; }
; DI float silu(float x) { return x / (1.f + __expf(-x)); }
; DI void pw2_tile(PREF p, int l, int idx, unsigned char* ldsb) {
;     ...
; #pragma unroll
;   for (int q = 0; q < 8; ++q) {
;     int r = (tid >> 4) + 16 * q, c = (tid & 15) * 8;
;     float v[8]; ld8(Cs + r * CST + c, v);
;     float z[8]; unpack8(zr[q], z);
; #pragma unroll
;     for (int j = 0; j < 8; ++j) v[j] *= silu(z[j]);
;     *(u32x4*)(p.ys + (size_t)(row0 + r) * 1024 + col0 + c) = pack8(v);
;   }
	v_mul_f32_e32 v57, v57, v30
	v_mul_f32_e32 v30, 0xbfb8aa3b, v58
	v_exp_f32_e32 v30, v30
	s_nop 0
	v_add_f32_e32 v30, 1.0, v30
	v_rcp_f32_e32 v59, v30
	s_nop 0
	v_mul_f32_e32 v30, v58, v59
	v_mul_f32_e32 v58, v30, v31
	v_mul_f32_e32 v30, 0xbfb8aa3b, v64
	v_exp_f32_e32 v30, v30
	s_nop 0
	v_add_f32_e32 v30, 1.0, v30
	v_rcp_f32_e32 v31, v30
	s_nop 0
	v_mul_f32_e32 v30, v64, v31
	v_mul_f32_e32 v59, v30, v32
	v_mul_f32_e32 v30, 0xbfb8aa3b, v56
	v_exp_f32_e32 v30, v30
	s_nop 0
	v_add_f32_e32 v30, 1.0, v30
	v_rcp_f32_e32 v31, v30
	s_nop 0
	v_mul_f32_e32 v30, v56, v31
	v_mul_f32_e32 v33, v30, v33
	v_cvt_pk_bf16_f32 v30, v34, v35
	s_nop 1
	v_lshlrev_b64 v[34:35], 11, v[54:55]
	s_waitcnt vmcnt(6)
	v_lshlrev_b32_e32 v54, 16, v26
	v_cvt_pk_bf16_f32 v32, v57, v58
	s_nop 1
	v_lshlrev_b32_e32 v56, 16, v27
	v_and_b32_e32 v57, 0xffff0000, v27
	v_mul_f32_e32 v27, 0xbfb8aa3b, v54
	v_exp_f32_e32 v27, v27
	v_cvt_pk_bf16_f32 v33, v59, v33
	s_nop 1
	v_and_b32_e32 v55, 0xffff0000, v26
	v_lshlrev_b32_e32 v59, 16, v29
	v_add_f32_e32 v27, 1.0, v27
	v_and_b32_e32 v26, 0xffff0000, v29
	v_lshl_add_u64 v[34:35], v[40:41], 0, v[34:35]
	v_cvt_pk_bf16_f32 v31, v36, v37
	s_nop 1
	global_store_dwordx4 v[34:35], v[30:33], off
	v_rcp_f32_e32 v29, v27
	s_nop 0
	v_mul_f32_e32 v27, v54, v29
	v_mul_f32_e32 v29, 0xbfb8aa3b, v55
	v_exp_f32_e32 v29, v29
	ds_read_b128 v[34:37], v0 offset:8448
	ds_read_b128 v[30:33], v0 offset:8464
	v_lshlrev_b32_e32 v58, 16, v28
	v_and_b32_e32 v28, 0xffff0000, v28
	v_add_f32_e32 v29, 1.0, v29
	s_waitcnt lgkmcnt(1)
	v_mul_f32_e32 v27, v27, v34
	v_rcp_f32_e32 v34, v29
	s_nop 0
	v_mul_f32_e32 v29, v55, v34
	v_mul_f32_e32 v34, 0xbfb8aa3b, v56
	v_exp_f32_e32 v34, v34
	v_mul_f32_e32 v29, v29, v35
	v_add_f32_e32 v34, 1.0, v34
	v_rcp_f32_e32 v35, v34
	s_nop 0
	v_mul_f32_e32 v34, v56, v35
	v_mul_f32_e32 v35, 0xbfb8aa3b, v57
	v_exp_f32_e32 v35, v35
	v_mul_f32_e32 v34, v34, v36
	v_add_f32_e32 v35, 1.0, v35
	v_rcp_f32_e32 v36, v35
	s_nop 0
	v_mul_f32_e32 v35, v57, v36
	v_mul_f32_e32 v36, 0xbfb8aa3b, v58
	v_exp_f32_e32 v36, v36
	v_mul_f32_e32 v35, v35, v37
	v_add_f32_e32 v36, 1.0, v36
	v_rcp_f32_e32 v37, v36
	s_nop 0
	v_mul_f32_e32 v36, v58, v37
	s_waitcnt lgkmcnt(0)
	v_mul_f32_e32 v30, v36, v30
	v_mul_f32_e32 v36, 0xbfb8aa3b, v28
	v_exp_f32_e32 v36, v36
	s_nop 0
	v_add_f32_e32 v36, 1.0, v36
	v_rcp_f32_e32 v37, v36
	s_nop 0
	v_mul_f32_e32 v28, v28, v37
	v_mul_f32_e32 v28, v28, v31
	v_mul_f32_e32 v31, 0xbfb8aa3b, v59
	v_exp_f32_e32 v31, v31
	v_cvt_pk_bf16_f32 v28, v30, v28
	s_nop 1
	s_nop 0
	v_add_f32_e32 v31, 1.0, v31
	v_rcp_f32_e32 v36, v31
	s_nop 0
	v_mul_f32_e32 v31, v59, v36
	v_mul_f32_e32 v31, v31, v32
	v_mul_f32_e32 v32, 0xbfb8aa3b, v26
	v_exp_f32_e32 v32, v32
	s_nop 0
	v_add_f32_e32 v32, 1.0, v32
	v_rcp_f32_e32 v36, v32
	s_nop 0
	v_mul_f32_e32 v26, v26, v36
	v_mul_f32_e32 v32, v26, v33
	v_cvt_pk_bf16_f32 v26, v27, v29
	s_nop 1
	v_cvt_pk_bf16_f32 v27, v34, v35
	s_nop 1
	s_waitcnt vmcnt(6)
	v_lshlrev_b32_e32 v34, 16, v22
	v_lshlrev_b32_e32 v36, 16, v23
	v_and_b32_e32 v37, 0xffff0000, v23
	v_mul_f32_e32 v23, 0xbfb8aa3b, v34
	v_exp_f32_e32 v23, v23
	v_cvt_pk_bf16_f32 v29, v31, v32
	s_nop 1
	v_lshlrev_b64 v[30:31], 11, v[52:53]
	v_and_b32_e32 v35, 0xffff0000, v22
	v_add_f32_e32 v23, 1.0, v23
	v_lshlrev_b32_e32 v53, 16, v25
	v_and_b32_e32 v22, 0xffff0000, v25
	v_lshl_add_u64 v[30:31], v[40:41], 0, v[30:31]
	global_store_dwordx4 v[30:31], v[26:29], off
	ds_read_b128 v[30:33], v0 offset:16896
	ds_read_b128 v[26:29], v0 offset:16912
	v_rcp_f32_e32 v25, v23
	s_nop 0
	v_mul_f32_e32 v23, v34, v25
	v_mul_f32_e32 v25, 0xbfb8aa3b, v35
	v_exp_f32_e32 v25, v25
	s_waitcnt lgkmcnt(1)
	v_mul_f32_e32 v23, v23, v30
	v_lshlrev_b32_e32 v52, 16, v24
	v_and_b32_e32 v24, 0xffff0000, v24
	v_add_f32_e32 v25, 1.0, v25
	v_rcp_f32_e32 v30, v25
	s_nop 0
	v_mul_f32_e32 v25, v35, v30
	v_mul_f32_e32 v30, 0xbfb8aa3b, v36
	v_exp_f32_e32 v30, v30
	v_mul_f32_e32 v25, v25, v31
	v_add_f32_e32 v30, 1.0, v30
	v_rcp_f32_e32 v31, v30
	s_nop 0
	v_mul_f32_e32 v30, v36, v31
	v_mul_f32_e32 v31, 0xbfb8aa3b, v37
	v_exp_f32_e32 v31, v31
	v_mul_f32_e32 v30, v30, v32
	v_add_f32_e32 v31, 1.0, v31
	v_rcp_f32_e32 v32, v31
	s_nop 0
	v_mul_f32_e32 v31, v37, v32
	v_mul_f32_e32 v32, 0xbfb8aa3b, v52
	v_exp_f32_e32 v32, v32
	v_mul_f32_e32 v31, v31, v33
	v_add_f32_e32 v32, 1.0, v32
	v_rcp_f32_e32 v33, v32
	s_nop 0
	v_mul_f32_e32 v32, v52, v33
	s_waitcnt lgkmcnt(0)
	v_mul_f32_e32 v26, v32, v26
	v_mul_f32_e32 v32, 0xbfb8aa3b, v24
	v_exp_f32_e32 v32, v32
	s_nop 0
	v_add_f32_e32 v32, 1.0, v32
	v_rcp_f32_e32 v33, v32
	s_nop 0
	v_mul_f32_e32 v24, v24, v33
	v_mul_f32_e32 v24, v24, v27
	v_mul_f32_e32 v27, 0xbfb8aa3b, v53
	v_exp_f32_e32 v27, v27
	v_cvt_pk_bf16_f32 v24, v26, v24
	s_nop 1
	s_nop 0
	v_add_f32_e32 v27, 1.0, v27
	v_rcp_f32_e32 v32, v27
	s_nop 0
	v_mul_f32_e32 v27, v53, v32
	v_mul_f32_e32 v27, v27, v28
	v_mul_f32_e32 v28, 0xbfb8aa3b, v22
	v_exp_f32_e32 v28, v28
	s_nop 0
	v_add_f32_e32 v28, 1.0, v28
	v_rcp_f32_e32 v32, v28
	s_nop 0
	v_mul_f32_e32 v22, v22, v32
	v_mul_f32_e32 v28, v22, v29
	v_cvt_pk_bf16_f32 v22, v23, v25
	s_nop 1
	v_cvt_pk_bf16_f32 v23, v30, v31
	s_nop 1
	s_waitcnt vmcnt(6)
	v_lshlrev_b32_e32 v30, 16, v18
	v_lshlrev_b32_e32 v32, 16, v19
	v_and_b32_e32 v33, 0xffff0000, v19
	v_mul_f32_e32 v19, 0xbfb8aa3b, v30
	v_exp_f32_e32 v19, v19
	v_and_b32_e32 v31, 0xffff0000, v18
	v_lshlrev_b32_e32 v35, 16, v21
	v_and_b32_e32 v18, 0xffff0000, v21
	v_add_f32_e32 v19, 1.0, v19
	v_cvt_pk_bf16_f32 v25, v27, v28
	s_nop 1
	v_lshlrev_b64 v[26:27], 11, v[50:51]
	v_lshl_add_u64 v[26:27], v[40:41], 0, v[26:27]
	v_rcp_f32_e32 v21, v19
	s_nop 0
	v_mul_f32_e32 v19, v30, v21
	v_mul_f32_e32 v21, 0xbfb8aa3b, v31
	global_store_dwordx4 v[26:27], v[22:25], off
	v_exp_f32_e32 v21, v21
	ds_read_b128 v[26:29], v0 offset:25344
	ds_read_b128 v[22:25], v0 offset:25360
	v_lshlrev_b32_e32 v34, 16, v20
	v_and_b32_e32 v20, 0xffff0000, v20
	v_add_f32_e32 v21, 1.0, v21
	s_waitcnt lgkmcnt(1)
; DI u32x4 pack8(const float* f) { u32x4 o; o.x = pack2(f[0], f[1]); o.y = pack2(f[2], f[3]); o.z = pack2(f[4], f[5]); o.w = pack2(f[6], f[7]); return o; }
; DI float silu(float x) { return x / (1.f + __expf(-x)); }
; DI void pw2_tile(PREF p, int l, int idx, unsigned char* ldsb) {
;     ...
; #pragma unroll
;   for (int q = 0; q < 8; ++q) {
;     int r = (tid >> 4) + 16 * q, c = (tid & 15) * 8;
;     float v[8]; ld8(Cs + r * CST + c, v);
;     float z[8]; unpack8(zr[q], z);
; #pragma unroll
;     for (int j = 0; j < 8; ++j) v[j] *= silu(z[j]);
;     *(u32x4*)(p.ys + (size_t)(row0 + r) * 1024 + col0 + c) = pack8(v);
;   }
	v_mul_f32_e32 v19, v19, v26
	v_rcp_f32_e32 v26, v21
	s_nop 0
	v_mul_f32_e32 v21, v31, v26
	v_mul_f32_e32 v26, 0xbfb8aa3b, v32
	v_exp_f32_e32 v26, v26
	v_mul_f32_e32 v21, v21, v27
	v_add_f32_e32 v26, 1.0, v26
	v_rcp_f32_e32 v27, v26
	s_nop 0
	v_mul_f32_e32 v26, v32, v27
	v_mul_f32_e32 v27, 0xbfb8aa3b, v33
	v_exp_f32_e32 v27, v27
	v_mul_f32_e32 v26, v26, v28
	v_add_f32_e32 v27, 1.0, v27
	v_rcp_f32_e32 v28, v27
	s_nop 0
	v_mul_f32_e32 v27, v33, v28
	v_mul_f32_e32 v28, 0xbfb8aa3b, v34
	v_exp_f32_e32 v28, v28
	v_mul_f32_e32 v27, v27, v29
	v_add_f32_e32 v28, 1.0, v28
	v_rcp_f32_e32 v29, v28
	s_nop 0
	v_mul_f32_e32 v28, v34, v29
	s_waitcnt lgkmcnt(0)
	v_mul_f32_e32 v22, v28, v22
	v_mul_f32_e32 v28, 0xbfb8aa3b, v20
	v_exp_f32_e32 v28, v28
	s_nop 0
	v_add_f32_e32 v28, 1.0, v28
	v_rcp_f32_e32 v29, v28
	s_nop 0
	v_mul_f32_e32 v20, v20, v29
	v_mul_f32_e32 v20, v20, v23
	v_mul_f32_e32 v23, 0xbfb8aa3b, v35
	v_exp_f32_e32 v23, v23
	v_cvt_pk_bf16_f32 v20, v22, v20
	s_nop 1
	s_nop 0
	v_add_f32_e32 v23, 1.0, v23
	v_rcp_f32_e32 v28, v23
	s_nop 0
	v_mul_f32_e32 v23, v35, v28
	v_mul_f32_e32 v23, v23, v24
	v_mul_f32_e32 v24, 0xbfb8aa3b, v18
	v_exp_f32_e32 v24, v24
	s_nop 0
	v_add_f32_e32 v24, 1.0, v24
	v_rcp_f32_e32 v28, v24
	s_nop 0
	v_mul_f32_e32 v18, v18, v28
	v_mul_f32_e32 v24, v18, v25
	v_cvt_pk_bf16_f32 v18, v19, v21
	s_nop 1
	v_cvt_pk_bf16_f32 v19, v26, v27
	s_nop 1
	s_waitcnt vmcnt(6)
	v_lshlrev_b32_e32 v26, 16, v14
	v_lshlrev_b32_e32 v28, 16, v15
	v_and_b32_e32 v29, 0xffff0000, v15
	v_mul_f32_e32 v15, 0xbfb8aa3b, v26
	v_exp_f32_e32 v15, v15
	v_and_b32_e32 v27, 0xffff0000, v14
	v_lshlrev_b32_e32 v31, 16, v17
	v_and_b32_e32 v14, 0xffff0000, v17
	v_add_f32_e32 v15, 1.0, v15
	v_cvt_pk_bf16_f32 v21, v23, v24
	s_nop 1
	v_lshlrev_b64 v[22:23], 11, v[48:49]
	v_lshl_add_u64 v[22:23], v[40:41], 0, v[22:23]
	v_rcp_f32_e32 v17, v15
	s_nop 0
	v_mul_f32_e32 v15, v26, v17
	v_mul_f32_e32 v17, 0xbfb8aa3b, v27
	global_store_dwordx4 v[22:23], v[18:21], off
	v_exp_f32_e32 v17, v17
	ds_read_b128 v[22:25], v0 offset:33792
	ds_read_b128 v[18:21], v0 offset:33808
	v_lshlrev_b32_e32 v30, 16, v16
	v_and_b32_e32 v16, 0xffff0000, v16
	v_add_f32_e32 v17, 1.0, v17
	s_waitcnt lgkmcnt(1)
	v_mul_f32_e32 v15, v15, v22
	v_rcp_f32_e32 v22, v17
	s_nop 0
	v_mul_f32_e32 v17, v27, v22
	v_mul_f32_e32 v22, 0xbfb8aa3b, v28
	v_exp_f32_e32 v22, v22
	v_mul_f32_e32 v17, v17, v23
	v_add_f32_e32 v22, 1.0, v22
	v_rcp_f32_e32 v23, v22
	s_nop 0
	v_mul_f32_e32 v22, v28, v23
	v_mul_f32_e32 v23, 0xbfb8aa3b, v29
	v_exp_f32_e32 v23, v23
	v_mul_f32_e32 v22, v22, v24
	v_add_f32_e32 v23, 1.0, v23
	v_rcp_f32_e32 v24, v23
	s_nop 0
	v_mul_f32_e32 v23, v29, v24
	v_mul_f32_e32 v24, 0xbfb8aa3b, v30
	v_exp_f32_e32 v24, v24
	v_mul_f32_e32 v23, v23, v25
	v_add_f32_e32 v24, 1.0, v24
	v_rcp_f32_e32 v25, v24
	s_nop 0
	v_mul_f32_e32 v24, v30, v25
	s_waitcnt lgkmcnt(0)
	v_mul_f32_e32 v18, v24, v18
	v_mul_f32_e32 v24, 0xbfb8aa3b, v16
	v_exp_f32_e32 v24, v24
	s_nop 0
	v_add_f32_e32 v24, 1.0, v24
	v_rcp_f32_e32 v25, v24
	s_nop 0
	v_mul_f32_e32 v16, v16, v25
	v_mul_f32_e32 v16, v16, v19
	v_mul_f32_e32 v19, 0xbfb8aa3b, v31
	v_exp_f32_e32 v19, v19
	v_cvt_pk_bf16_f32 v16, v18, v16
	s_nop 1
	s_nop 0
	v_add_f32_e32 v19, 1.0, v19
	v_rcp_f32_e32 v24, v19
	s_nop 0
	v_mul_f32_e32 v19, v31, v24
	v_mul_f32_e32 v19, v19, v20
	v_mul_f32_e32 v20, 0xbfb8aa3b, v14
	v_exp_f32_e32 v20, v20
	s_nop 0
	v_add_f32_e32 v20, 1.0, v20
	v_rcp_f32_e32 v24, v20
	s_nop 0
	v_mul_f32_e32 v14, v14, v24
	v_mul_f32_e32 v20, v14, v21
	v_cvt_pk_bf16_f32 v14, v15, v17
	s_nop 1
	v_cvt_pk_bf16_f32 v15, v22, v23
	s_nop 1
	s_waitcnt vmcnt(6)
	v_lshlrev_b32_e32 v22, 16, v10
	v_lshlrev_b32_e32 v24, 16, v11
	v_and_b32_e32 v25, 0xffff0000, v11
	v_mul_f32_e32 v11, 0xbfb8aa3b, v22
	v_exp_f32_e32 v11, v11
	v_and_b32_e32 v23, 0xffff0000, v10
	v_lshlrev_b32_e32 v27, 16, v13
	v_and_b32_e32 v10, 0xffff0000, v13
	v_add_f32_e32 v11, 1.0, v11
	v_cvt_pk_bf16_f32 v17, v19, v20
	s_nop 1
	v_lshlrev_b64 v[18:19], 11, v[46:47]
	v_lshl_add_u64 v[18:19], v[40:41], 0, v[18:19]
	v_rcp_f32_e32 v13, v11
	s_nop 0
	v_mul_f32_e32 v11, v22, v13
	v_mul_f32_e32 v13, 0xbfb8aa3b, v23
	global_store_dwordx4 v[18:19], v[14:17], off
	v_exp_f32_e32 v13, v13
	ds_read_b128 v[18:21], v0 offset:42240
	ds_read_b128 v[14:17], v0 offset:42256
	v_lshlrev_b32_e32 v26, 16, v12
	v_and_b32_e32 v12, 0xffff0000, v12
	v_add_f32_e32 v13, 1.0, v13
	s_waitcnt lgkmcnt(1)
	v_mul_f32_e32 v11, v11, v18
	v_rcp_f32_e32 v18, v13
	s_nop 0
	v_mul_f32_e32 v13, v23, v18
	v_mul_f32_e32 v18, 0xbfb8aa3b, v24
	v_exp_f32_e32 v18, v18
	v_mul_f32_e32 v13, v13, v19
	v_add_f32_e32 v18, 1.0, v18
	v_rcp_f32_e32 v19, v18
	s_nop 0
	v_mul_f32_e32 v18, v24, v19
	v_mul_f32_e32 v19, 0xbfb8aa3b, v25
	v_exp_f32_e32 v19, v19
	v_mul_f32_e32 v18, v18, v20
	v_add_f32_e32 v19, 1.0, v19
	v_rcp_f32_e32 v20, v19
	s_nop 0
	v_mul_f32_e32 v19, v25, v20
	v_mul_f32_e32 v20, 0xbfb8aa3b, v26
	v_exp_f32_e32 v20, v20
	v_mul_f32_e32 v19, v19, v21
	v_add_f32_e32 v20, 1.0, v20
	v_rcp_f32_e32 v21, v20
	s_nop 0
	v_mul_f32_e32 v20, v26, v21
	s_waitcnt lgkmcnt(0)
; DI u32x4 pack8(const float* f) { u32x4 o; o.x = pack2(f[0], f[1]); o.y = pack2(f[2], f[3]); o.z = pack2(f[4], f[5]); o.w = pack2(f[6], f[7]); return o; }
; DI float silu(float x) { return x / (1.f + __expf(-x)); }
; DI void pw2_tile(PREF p, int l, int idx, unsigned char* ldsb) {
;     ...
; #pragma unroll
;   for (int q = 0; q < 8; ++q) {
;     int r = (tid >> 4) + 16 * q, c = (tid & 15) * 8;
;     float v[8]; ld8(Cs + r * CST + c, v);
;     float z[8]; unpack8(zr[q], z);
; #pragma unroll
;     for (int j = 0; j < 8; ++j) v[j] *= silu(z[j]);
;     *(u32x4*)(p.ys + (size_t)(row0 + r) * 1024 + col0 + c) = pack8(v);
;   }
	v_mul_f32_e32 v14, v20, v14
	v_mul_f32_e32 v20, 0xbfb8aa3b, v12
	v_exp_f32_e32 v20, v20
	s_nop 0
	v_add_f32_e32 v20, 1.0, v20
	v_rcp_f32_e32 v21, v20
	s_nop 0
	v_mul_f32_e32 v12, v12, v21
	v_mul_f32_e32 v12, v12, v15
	v_mul_f32_e32 v15, 0xbfb8aa3b, v27
	v_exp_f32_e32 v15, v15
	v_cvt_pk_bf16_f32 v12, v14, v12
	s_nop 1
	s_nop 0
	v_add_f32_e32 v15, 1.0, v15
	v_rcp_f32_e32 v20, v15
	s_nop 0
	v_mul_f32_e32 v15, v27, v20
	v_mul_f32_e32 v15, v15, v16
	v_mul_f32_e32 v16, 0xbfb8aa3b, v10
	v_exp_f32_e32 v16, v16
	s_nop 0
	v_add_f32_e32 v16, 1.0, v16
	v_rcp_f32_e32 v20, v16
	s_nop 0
	v_mul_f32_e32 v10, v10, v20
	v_mul_f32_e32 v16, v10, v17
	v_cvt_pk_bf16_f32 v10, v11, v13
	s_nop 1
	v_cvt_pk_bf16_f32 v11, v18, v19
	s_nop 1
	s_waitcnt vmcnt(6)
	v_lshlrev_b32_e32 v18, 16, v6
	v_lshlrev_b32_e32 v20, 16, v7
	v_and_b32_e32 v21, 0xffff0000, v7
	v_mul_f32_e32 v7, 0xbfb8aa3b, v18
	v_exp_f32_e32 v7, v7
	v_and_b32_e32 v19, 0xffff0000, v6
	v_lshlrev_b32_e32 v23, 16, v9
	v_and_b32_e32 v6, 0xffff0000, v9
	v_add_f32_e32 v7, 1.0, v7
	v_cvt_pk_bf16_f32 v13, v15, v16
	s_nop 1
	v_lshlrev_b64 v[14:15], 11, v[44:45]
	v_lshl_add_u64 v[14:15], v[40:41], 0, v[14:15]
	v_rcp_f32_e32 v9, v7
	s_nop 0
	v_mul_f32_e32 v7, v18, v9
	v_mul_f32_e32 v9, 0xbfb8aa3b, v19
	global_store_dwordx4 v[14:15], v[10:13], off
	v_exp_f32_e32 v9, v9
	ds_read_b128 v[14:17], v0 offset:50688
	ds_read_b128 v[10:13], v0 offset:50704
	v_lshlrev_b32_e32 v22, 16, v8
	v_and_b32_e32 v8, 0xffff0000, v8
	v_add_f32_e32 v9, 1.0, v9
	s_waitcnt lgkmcnt(1)
	v_mul_f32_e32 v7, v7, v14
	v_rcp_f32_e32 v14, v9
	s_nop 0
	v_mul_f32_e32 v9, v19, v14
	v_mul_f32_e32 v14, 0xbfb8aa3b, v20
	v_exp_f32_e32 v14, v14
	v_mul_f32_e32 v9, v9, v15
	v_add_f32_e32 v14, 1.0, v14
	v_rcp_f32_e32 v15, v14
	s_nop 0
	v_mul_f32_e32 v14, v20, v15
	v_mul_f32_e32 v15, 0xbfb8aa3b, v21
	v_exp_f32_e32 v15, v15
	v_mul_f32_e32 v14, v14, v16
	v_add_f32_e32 v15, 1.0, v15
	v_rcp_f32_e32 v16, v15
	s_nop 0
	v_mul_f32_e32 v15, v21, v16
	v_mul_f32_e32 v16, 0xbfb8aa3b, v22
	v_exp_f32_e32 v16, v16
	v_mul_f32_e32 v15, v15, v17
	v_add_f32_e32 v16, 1.0, v16
	v_rcp_f32_e32 v17, v16
	s_nop 0
	v_mul_f32_e32 v16, v22, v17
	s_waitcnt lgkmcnt(0)
	v_mul_f32_e32 v10, v16, v10
	v_mul_f32_e32 v16, 0xbfb8aa3b, v8
	v_exp_f32_e32 v16, v16
	s_nop 0
	v_add_f32_e32 v16, 1.0, v16
	v_rcp_f32_e32 v17, v16
	s_nop 0
	v_mul_f32_e32 v8, v8, v17
	v_mul_f32_e32 v8, v8, v11
	v_mul_f32_e32 v11, 0xbfb8aa3b, v23
	v_exp_f32_e32 v11, v11
	v_cvt_pk_bf16_f32 v8, v10, v8
	s_nop 1
	s_nop 0
	v_add_f32_e32 v11, 1.0, v11
	v_rcp_f32_e32 v16, v11
	s_nop 0
	v_mul_f32_e32 v11, v23, v16
	v_mul_f32_e32 v11, v11, v12
	v_mul_f32_e32 v12, 0xbfb8aa3b, v6
	v_exp_f32_e32 v12, v12
	s_nop 0
	v_add_f32_e32 v12, 1.0, v12
	v_rcp_f32_e32 v16, v12
	s_nop 0
	v_mul_f32_e32 v6, v6, v16
	v_mul_f32_e32 v12, v6, v13
	v_cvt_pk_bf16_f32 v6, v7, v9
	s_nop 1
	v_cvt_pk_bf16_f32 v7, v14, v15
	s_nop 1
	s_waitcnt vmcnt(6)
	v_lshlrev_b32_e32 v14, 16, v2
	v_and_b32_e32 v15, 0xffff0000, v2
	v_mul_f32_e32 v2, 0xbfb8aa3b, v14
	v_exp_f32_e32 v2, v2
	v_cvt_pk_bf16_f32 v9, v11, v12
	s_nop 1
	v_lshlrev_b64 v[10:11], 11, v[42:43]
	v_lshl_add_u64 v[10:11], v[40:41], 0, v[10:11]
	global_store_dwordx4 v[10:11], v[6:9], off
	v_add_f32_e32 v2, 1.0, v2
	ds_read_b128 v[10:13], v0 offset:59136
	ds_read_b128 v[6:9], v0 offset:59152
	v_lshlrev_b32_e32 v18, 16, v5
	v_and_b32_e32 v0, 0xffff0000, v5
	v_lshlrev_b32_e32 v16, 16, v3
	v_and_b32_e32 v3, 0xffff0000, v3
	v_lshlrev_b32_e32 v17, 16, v4
	v_rcp_f32_e32 v5, v2
	s_nop 0
	v_mul_f32_e32 v2, v14, v5
	v_mul_f32_e32 v5, 0xbfb8aa3b, v15
	v_exp_f32_e32 v5, v5
	s_waitcnt lgkmcnt(1)
	v_mul_f32_e32 v2, v2, v10
	v_and_b32_e32 v4, 0xffff0000, v4
	v_add_f32_e32 v5, 1.0, v5
	v_rcp_f32_e32 v10, v5
	s_nop 0
	v_mul_f32_e32 v5, v15, v10
	v_mul_f32_e32 v10, 0xbfb8aa3b, v16
	v_exp_f32_e32 v10, v10
	v_mul_f32_e32 v5, v5, v11
	v_cvt_pk_bf16_f32 v2, v2, v5
	s_nop 1
	v_add_f32_e32 v10, 1.0, v10
	v_rcp_f32_e32 v11, v10
	s_nop 0
	v_mul_f32_e32 v10, v16, v11
	v_mul_f32_e32 v11, 0xbfb8aa3b, v3
	v_exp_f32_e32 v11, v11
	v_mul_f32_e32 v10, v10, v12
	v_add_f32_e32 v11, 1.0, v11
	v_rcp_f32_e32 v12, v11
	s_nop 0
	v_mul_f32_e32 v3, v3, v12
	v_mul_f32_e32 v11, 0xbfb8aa3b, v17
	v_exp_f32_e32 v11, v11
	v_mul_f32_e32 v3, v3, v13
	v_cvt_pk_bf16_f32 v3, v10, v3
	s_nop 1
	v_add_f32_e32 v11, 1.0, v11
	v_rcp_f32_e32 v12, v11
	s_nop 0
	v_mul_f32_e32 v11, v17, v12
	s_waitcnt lgkmcnt(0)
	v_mul_f32_e32 v6, v11, v6
	v_mul_f32_e32 v11, 0xbfb8aa3b, v4
	v_exp_f32_e32 v11, v11
	s_nop 0
	v_add_f32_e32 v11, 1.0, v11
	v_rcp_f32_e32 v12, v11
	s_nop 0
	v_mul_f32_e32 v4, v4, v12
	v_mul_f32_e32 v4, v4, v7
	v_mul_f32_e32 v7, 0xbfb8aa3b, v18
	v_exp_f32_e32 v7, v7
	v_cvt_pk_bf16_f32 v4, v6, v4
	s_nop 1
	s_nop 0
	v_add_f32_e32 v7, 1.0, v7
	v_rcp_f32_e32 v11, v7
	s_nop 0
	v_mul_f32_e32 v7, v18, v11
	v_mul_f32_e32 v7, v7, v8
	v_mul_f32_e32 v8, 0xbfb8aa3b, v0
	v_exp_f32_e32 v8, v8
	s_nop 0
	v_add_f32_e32 v8, 1.0, v8
	v_rcp_f32_e32 v11, v8
	s_nop 0
	v_mul_f32_e32 v0, v0, v11
	v_mul_f32_e32 v0, v0, v9
	v_cvt_pk_bf16_f32 v5, v7, v0
	s_nop 1
	v_lshlrev_b64 v[6:7], 11, v[38:39]
	v_lshl_add_u64 v[6:7], v[40:41], 0, v[6:7]
	global_store_dwordx4 v[6:7], v[2:5], off
	s_cbranch_scc0 .LBB0_265

; DI unsigned pack2(float a, float b) { unsigned r; asm("v_cvt_pk_bf16_f32 %0, %1, %2\n\ts_nop 1" : "=v"(r) : "v"(a), "v"(b)); return r; }
; DI void ssm2_item(PREF p, int l, int item, unsigned char* ldsb) {
;     ...
;   for (int sub = 0; sub < 4; ++sub) {
;     for (int tt = 0; tt < 16; ++tt) {
;       SSM_STEP(sub * 16 + tt)
;       *(unsigned*)(Hs + tt * 136 + 2 * lane) = pack2(hr, hi);
;     }
.LBB0_305:
	v_add_u32_e32 v39, s9, v54
	ds_read_b128 v[68:71], v39
	ds_read_b128 v[72:75], v39 offset:16
	ds_read_b128 v[76:79], v39 offset:32
	ds_read_b128 v[80:83], v39 offset:48
	s_addk_i32 s9, 0x200
	s_waitcnt lgkmcnt(3)
	v_pk_fma_f32 v[40:41], v[16:17], v[68:69], 0 op_sel_hi:[1,0,0]
	s_cmpk_eq_i32 s9, 0x1000
	v_pk_fma_f32 v[40:41], v[18:19], v[68:69], v[40:41] op_sel:[0,1,0]
	v_mov_b32_e32 v68, v71
	v_pk_fma_f32 v[40:41], v[44:45], v[70:71], v[40:41] op_sel_hi:[1,0,1]
	s_waitcnt lgkmcnt(2)
	v_mov_b32_e32 v70, v75
	v_pk_fma_f32 v[40:41], v[20:21], v[68:69], v[40:41] op_sel_hi:[1,0,1]
	v_pk_mul_f32 v[68:69], v[2:3], v[52:53] op_sel:[0,1]
	v_pk_fma_f32 v[40:41], v[62:63], v[72:73], v[40:41] op_sel_hi:[1,0,1]
	s_nop 0
	v_pk_fma_f32 v[40:41], v[14:15], v[72:73], v[40:41] op_sel:[0,1,0]
	s_nop 0
	v_pk_fma_f32 v[40:41], v[4:5], v[74:75], v[40:41] op_sel_hi:[1,0,1]
	s_nop 0
	v_pk_fma_f32 v[40:41], v[58:59], v[70:71], v[40:41] op_sel_hi:[1,0,1]
	s_waitcnt lgkmcnt(1)
	v_mov_b32_e32 v70, v79
	v_pk_fma_f32 v[40:41], v[60:61], v[76:77], v[40:41] op_sel_hi:[1,0,1]
	s_nop 0
	v_pk_fma_f32 v[40:41], v[10:11], v[76:77], v[40:41] op_sel:[0,1,0]
	s_nop 0
	v_pk_fma_f32 v[40:41], v[46:47], v[78:79], v[40:41] op_sel_hi:[1,0,1]
	s_nop 0
	v_pk_fma_f32 v[40:41], v[12:13], v[70:71], v[40:41] op_sel_hi:[1,0,1]
	s_waitcnt lgkmcnt(0)
	v_mov_b32_e32 v70, v83
	v_pk_fma_f32 v[40:41], v[48:49], v[80:81], v[40:41] op_sel_hi:[1,0,1]
	s_nop 0
	v_pk_fma_f32 v[40:41], v[6:7], v[80:81], v[40:41] op_sel:[0,1,0]
	s_nop 0
	v_pk_fma_f32 v[40:41], v[42:43], v[82:83], v[40:41] op_sel_hi:[1,0,1]
	s_nop 0
	v_pk_fma_f32 v[40:41], v[8:9], v[70:71], v[40:41] op_sel_hi:[1,0,1]
	v_pk_fma_f32 v[70:71], v[50:51], v[52:53], v[68:69] neg_lo:[0,0,1] neg_hi:[0,0,1]
	v_pk_fma_f32 v[52:53], v[50:51], v[52:53], v[68:69] op_sel_hi:[1,0,1]
	s_nop 0
	v_mov_b32_e32 v71, v53
	v_pk_add_f32 v[40:41], v[70:71], v[40:41]
	s_nop 0
	v_cvt_pk_bf16_f32 v52, v40, v41
	s_nop 1
	ds_write_b32 v38, v52
	ds_read_b128 v[68:71], v39 offset:256
	ds_read_b128 v[72:75], v39 offset:272
	ds_read_b128 v[76:79], v39 offset:288
	ds_read_b128 v[80:83], v39 offset:304
	s_waitcnt lgkmcnt(3)
	v_pk_fma_f32 v[52:53], v[16:17], v[68:69], 0 op_sel_hi:[1,0,0]
	s_nop 0
	v_pk_fma_f32 v[52:53], v[18:19], v[68:69], v[52:53] op_sel:[0,1,0]
	v_mov_b32_e32 v68, v71
	v_pk_fma_f32 v[52:53], v[44:45], v[70:71], v[52:53] op_sel_hi:[1,0,1]
	s_waitcnt lgkmcnt(2)
	v_mov_b32_e32 v70, v75
	v_pk_fma_f32 v[52:53], v[20:21], v[68:69], v[52:53] op_sel_hi:[1,0,1]
	v_pk_mul_f32 v[68:69], v[2:3], v[40:41] op_sel:[0,1]
	v_pk_fma_f32 v[52:53], v[62:63], v[72:73], v[52:53] op_sel_hi:[1,0,1]
	s_nop 0
	v_pk_fma_f32 v[52:53], v[14:15], v[72:73], v[52:53] op_sel:[0,1,0]
	s_nop 0
	v_pk_fma_f32 v[52:53], v[4:5], v[74:75], v[52:53] op_sel_hi:[1,0,1]
	s_nop 0
	v_pk_fma_f32 v[52:53], v[58:59], v[70:71], v[52:53] op_sel_hi:[1,0,1]
	s_waitcnt lgkmcnt(1)
	v_mov_b32_e32 v70, v79
	v_pk_fma_f32 v[52:53], v[60:61], v[76:77], v[52:53] op_sel_hi:[1,0,1]
	s_nop 0
	v_pk_fma_f32 v[52:53], v[10:11], v[76:77], v[52:53] op_sel:[0,1,0]
	s_nop 0
	v_pk_fma_f32 v[52:53], v[46:47], v[78:79], v[52:53] op_sel_hi:[1,0,1]
	s_nop 0
	v_pk_fma_f32 v[52:53], v[12:13], v[70:71], v[52:53] op_sel_hi:[1,0,1]
	s_waitcnt lgkmcnt(0)
	v_mov_b32_e32 v70, v83
	v_pk_fma_f32 v[52:53], v[48:49], v[80:81], v[52:53] op_sel_hi:[1,0,1]
	s_nop 0
	v_pk_fma_f32 v[52:53], v[6:7], v[80:81], v[52:53] op_sel:[0,1,0]
	s_nop 0
	v_pk_fma_f32 v[52:53], v[42:43], v[82:83], v[52:53] op_sel_hi:[1,0,1]
	s_nop 0
	v_pk_fma_f32 v[52:53], v[8:9], v[70:71], v[52:53] op_sel_hi:[1,0,1]
	v_pk_fma_f32 v[70:71], v[50:51], v[40:41], v[68:69] neg_lo:[0,0,1] neg_hi:[0,0,1]
	v_pk_fma_f32 v[40:41], v[50:51], v[40:41], v[68:69] op_sel_hi:[1,0,1]
	s_nop 0
	v_mov_b32_e32 v71, v41
	v_pk_add_f32 v[52:53], v[70:71], v[52:53]
	s_nop 0
	v_cvt_pk_bf16_f32 v39, v52, v53
	s_nop 1
	ds_write_b32 v38, v39 offset:272
	v_add_u32_e32 v38, 0x220, v38
	s_cbranch_scc0 .LBB0_305
; DI u16 f2bf(float x) { return (u16)(pack2(x, x) & 0xffffu); }
; DI float gelu_t(float x) { float u = 0.7978845608028654f * (x + 0.044715f * x * x * x); return x / (1.f + __expf(-2.f * u)); }
; #define MFMA16(a, b, c) __builtin_amdgcn_mfma_f32_16x16x32_bf16((a), (b), (c), 0, 0, 0)
; DI void ssm2_item(PREF p, int l, int item, unsigned char* ldsb) {
;     ...
;     __syncthreads();
;     f32x4 acc = {0.f, 0.f, 0.f, 0.f};
; #pragma unroll
;     for (int ks = 0; ks < 4; ++ks) {
;       bf16x8 a = *(const bf16x8*)(Hs + hcol * 136 + 32 * ks + 8 * q4);
;       acc = MFMA16(a, cf[ks], acc);
;     }
; #pragma unroll
;     for (int j = 0; j < 4; ++j) {
;       int t = sub * 16 + 4 * q4 + j;
;       float uu = uS[t * 64 + w * 16 + hcol];
;       float yv = gelu_t(acc[j] + dch * uu);
;       p.yss[(size_t)(b * S_ + c * 64 + t) * 256 + g * 16 + hcol] = f2bf(yv);
;     }
;     __syncthreads();
;   }
	s_waitcnt lgkmcnt(0)
	s_barrier
	ds_read_b128 v[38:41], v66 offset:16384
	ds_read_b128 v[68:71], v66 offset:16448
	v_lshl_or_b32 v67, s8, 4, v64
	s_add_i32 s8, s8, 1
	v_add_u32_e32 v54, 0x1000, v54
	s_cmp_eq_u32 s8, 4
	s_waitcnt lgkmcnt(1)
	v_mfma_f32_16x16x32_bf16 v[38:41], v[38:41], v[22:25], 0
	s_waitcnt lgkmcnt(0)
	v_mfma_f32_16x16x32_bf16 v[38:41], v[68:71], v[26:29], v[38:41]
	ds_read_b128 v[68:71], v66 offset:16512
	s_waitcnt lgkmcnt(0)
	v_mfma_f32_16x16x32_bf16 v[38:41], v[68:71], v[30:33], v[38:41]
	ds_read_b128 v[68:71], v66 offset:16576
	s_waitcnt lgkmcnt(0)
	v_mfma_f32_16x16x32_bf16 v[38:41], v[68:71], v[34:37], v[38:41]
	v_lshl_add_u32 v68, v67, 8, v0
	ds_read_b32 v68, v68
	s_waitcnt lgkmcnt(0)
	s_nop 4
	v_fma_f32 v38, v65, v68, v38
	v_mul_f32_e32 v68, 0x3d372713, v38
	v_mul_f32_e32 v68, v38, v68
	v_fma_f32 v68, v38, v68, v38
	v_mul_f32_e32 v68, 0x3f4c422a, v68
	v_mul_f32_e32 v68, -2.0, v68
	v_mul_f32_e32 v68, 0x3fb8aa3b, v68
	v_exp_f32_e32 v68, v68
	s_nop 0
	v_add_f32_e32 v68, 1.0, v68
	v_rcp_f32_e32 v69, v68
	s_nop 0
	v_mul_f32_e32 v38, v38, v69
	v_or_b32_e32 v68, s62, v67
	v_ashrrev_i32_e32 v69, 31, v68
	v_lshlrev_b64 v[68:69], 9, v[68:69]
	v_cvt_pk_bf16_f32 v38, v38, v38
	s_nop 1
	v_lshl_add_u64 v[68:69], v[56:57], 0, v[68:69]
	global_store_short v[68:69], v38, off
	v_or_b32_e32 v38, 1, v67
	v_lshl_add_u32 v68, v38, 8, v0
	ds_read_b32 v68, v68
	v_or_b32_e32 v38, s62, v38
	s_waitcnt lgkmcnt(0)
	v_fma_f32 v39, v65, v68, v39
	v_mul_f32_e32 v68, 0x3d372713, v39
	v_mul_f32_e32 v68, v39, v68
	v_fma_f32 v68, v39, v68, v39
	v_mul_f32_e32 v68, 0x3f4c422a, v68
	v_mul_f32_e32 v68, -2.0, v68
	v_mul_f32_e32 v68, 0x3fb8aa3b, v68
	v_exp_f32_e32 v68, v68
	s_nop 0
	v_add_f32_e32 v68, 1.0, v68
	v_rcp_f32_e32 v69, v68
	s_nop 0
	v_mul_f32_e32 v39, v39, v69
	v_cvt_pk_bf16_f32 v68, v39, v39
	s_nop 1
	v_ashrrev_i32_e32 v39, 31, v38
	v_lshlrev_b64 v[38:39], 9, v[38:39]
	v_lshl_add_u64 v[38:39], v[56:57], 0, v[38:39]
	global_store_short v[38:39], v68, off
	v_or_b32_e32 v38, 2, v67
	v_lshl_add_u32 v39, v38, 8, v0
	ds_read_b32 v39, v39
	v_or_b32_e32 v38, s62, v38
	s_waitcnt lgkmcnt(0)
	v_fma_f32 v39, v65, v39, v40
	v_mul_f32_e32 v40, 0x3d372713, v39
	v_mul_f32_e32 v40, v39, v40
	v_fma_f32 v40, v39, v40, v39
	v_mul_f32_e32 v40, 0x3f4c422a, v40
	v_mul_f32_e32 v40, -2.0, v40
	v_mul_f32_e32 v40, 0x3fb8aa3b, v40
	v_exp_f32_e32 v40, v40
	s_nop 0
	v_add_f32_e32 v40, 1.0, v40
	v_rcp_f32_e32 v68, v40
	s_nop 0
	v_mul_f32_e32 v39, v39, v68
	v_cvt_pk_bf16_f32 v40, v39, v39
	s_nop 1
	v_ashrrev_i32_e32 v39, 31, v38
	v_lshlrev_b64 v[38:39], 9, v[38:39]
	v_lshl_add_u64 v[38:39], v[56:57], 0, v[38:39]
	global_store_short v[38:39], v40, off
	v_or_b32_e32 v38, 3, v67
	v_lshl_add_u32 v39, v38, 8, v0
	ds_read_b32 v39, v39
	v_or_b32_e32 v38, s62, v38
	s_waitcnt lgkmcnt(0)
	v_fmac_f32_e32 v41, v65, v39
	v_mul_f32_e32 v39, 0x3d372713, v41
	v_mul_f32_e32 v39, v41, v39
	v_fma_f32 v39, v41, v39, v41
	v_mul_f32_e32 v39, 0x3f4c422a, v39
	v_mul_f32_e32 v39, -2.0, v39
	v_mul_f32_e32 v39, 0x3fb8aa3b, v39
	v_exp_f32_e32 v39, v39
	s_nop 0
	v_add_f32_e32 v39, 1.0, v39
	v_rcp_f32_e32 v40, v39
	s_nop 0
	v_mul_f32_e32 v39, v41, v40
	v_cvt_pk_bf16_f32 v40, v39, v39
	s_nop 1
	v_ashrrev_i32_e32 v39, 31, v38
	v_lshlrev_b64 v[38:39], 9, v[38:39]
	v_lshl_add_u64 v[38:39], v[56:57], 0, v[38:39]
	global_store_short v[38:39], v40, off
	s_barrier
	s_cbranch_scc0 .LBB0_304
	s_add_i32 s48, s48, s71
	s_sub_i32 s57, s57, s71
	s_cmpk_gt_i32 s48, 0x7ff
	s_cbranch_scc0 .LBB0_268

; DI unsigned pack2(float a, float b) { unsigned r; asm("v_cvt_pk_bf16_f32 %0, %1, %2\n\ts_nop 1" : "=v"(r) : "v"(a), "v"(b)); return r; }
; DI float lo2f(unsigned u) { return __uint_as_float(u << 16); }
; DI float hi2f(unsigned u) { return __uint_as_float(u & 0xffff0000u); }
; DI float silu(float x) { return x / (1.f + __expf(-x)); }
; template <int DQK, bool WIN>
; DI void attn_item(const u16* __restrict__ Qb, int ldq, const u16* __restrict__ Kb, int ldk, const u16* __restrict__ Vtb, int qb,
;                   float qscale, float sink2, const u16* __restrict__ zb, int ldz, u16* __restrict__ ob, int ldo, u16* lds) {
;     ...
;   float lt = lsum + __shfl_xor(lsum, 32);
;   float inv = 1.f / lt;
;   u32x2 zr[8];
; #pragma unroll
;   for (int e = 0; e < 8; ++e) zr[e] = *(const u32x2*)(zb + (size_t)qrow * ldz + (e >> 2) * 32 + 8 * (e & 3) + 4 * hh);
; #pragma unroll
;   for (int vb = 0; vb < 2; ++vb)
; #pragma unroll
;     for (int g4 = 0; g4 < 4; ++g4) {
;       int vd0 = vb * 32 + 8 * g4 + 4 * hh;
;       u32x2 z = zr[vb * 4 + g4];
;       float a0 = o[vb][4 * g4 + 0] * inv * silu(lo2f(z.x));
;       float a1 = o[vb][4 * g4 + 1] * inv * silu(hi2f(z.x));
;       float a2 = o[vb][4 * g4 + 2] * inv * silu(lo2f(z.y));
;       float a3 = o[vb][4 * g4 + 3] * inv * silu(hi2f(z.y));
;       u32x2 ov; ov.x = pack2(a0, a1); ov.y = pack2(a2, a3);
;       *(u32x2*)(ob + (size_t)qrow * ldo + vd0) = ov;
;     }
.LBB0_312:
	v_mad_i64_i32 v[34:35], s[0:1], v114, s60, 0
	s_lshl_b32 s24, s8, 1
	s_add_u32 s0, s41, s24
	s_addc_u32 s1, s42, 0
	v_and_b32_e32 v37, 64, v172
	v_xor_b32_e32 v36, 32, v172
	v_add_u32_e32 v37, 64, v37
	v_lshl_add_u64 v[34:35], s[0:1], 0, v[34:35]
	v_lshlrev_b64 v[48:49], 1, v[0:1]
	v_cmp_lt_i32_e32 vcc, v36, v37
	v_lshl_add_u64 v[34:35], v[34:35], 0, v[48:49]
	s_mov_b64 s[0:1], 0x1340
	v_cndmask_b32_e32 v36, v172, v36, vcc
	v_lshl_add_u64 v[50:51], v[34:35], 0, s[0:1]
	v_add_co_u32_e32 v34, vcc, s80, v34
	v_lshlrev_b32_e32 v36, 2, v36
	s_nop 0
	v_addc_co_u32_e32 v35, vcc, 0, v35, vcc
	ds_bpermute_b32 v162, v36, v116
	global_load_dwordx2 v[52:53], v[34:35], off offset:832
	global_load_dwordx2 v[46:47], v[50:51], off offset:16
	global_load_dwordx2 v[44:45], v[50:51], off offset:32
	global_load_dwordx2 v[42:43], v[50:51], off offset:48
	global_load_dwordx2 v[40:41], v[50:51], off offset:64
	global_load_dwordx2 v[38:39], v[50:51], off offset:80
	global_load_dwordx2 v[36:37], v[50:51], off offset:96
	global_load_dwordx2 v[34:35], v[50:51], off offset:112
	s_lshl_b64 s[8:9], s[22:23], 23
	s_add_u32 s8, s14, s8
	s_addc_u32 s9, s15, s9
	s_add_u32 s8, s8, s24
	s_addc_u32 s9, s9, 0
	v_lshlrev_b64 v[50:51], 11, v[114:115]
	v_lshl_add_u64 v[50:51], s[8:9], 0, v[50:51]
	s_add_i32 s36, s36, s71
	s_cmpk_gt_i32 s36, 0x3ff
	s_waitcnt vmcnt(7)
	v_lshlrev_b32_e32 v0, 16, v52
	v_mul_f32_e32 v54, 0xbfb8aa3b, v0
	v_exp_f32_e32 v54, v54
	s_nop 0
	v_add_f32_e32 v54, 1.0, v54
	v_rcp_f32_e32 v55, v54
	s_nop 0
	v_mul_f32_e32 v56, v0, v55
	v_and_b32_e32 v0, 0xffff0000, v52
	v_mul_f32_e32 v52, 0xbfb8aa3b, v0
	v_exp_f32_e32 v52, v52
	s_nop 0
	v_add_f32_e32 v52, 1.0, v52
	v_rcp_f32_e32 v54, v52
	s_nop 0
	v_mul_f32_e32 v52, v0, v54
	v_lshlrev_b32_e32 v0, 16, v53
	v_mul_f32_e32 v54, 0xbfb8aa3b, v0
	v_exp_f32_e32 v117, v54
	s_waitcnt lgkmcnt(0)
	v_pk_add_f32 v[54:55], v[116:117], v[162:163]
	s_nop 0
	v_rcp_f32_e32 v57, v55
	s_nop 0
	v_mul_f32_e32 v55, v0, v57
	v_rcp_f32_e32 v0, v54
	s_nop 0
	v_mul_f32_e32 v19, v19, v0
	v_mul_f32_e32 v20, v20, v0
	v_mul_f32_e32 v19, v19, v52
	v_mul_f32_e32 v52, v20, v55
	v_mul_f32_e32 v20, v21, v0
	v_and_b32_e32 v21, 0xffff0000, v53
	v_mul_f32_e32 v53, 0xbfb8aa3b, v21
	v_exp_f32_e32 v53, v53
	v_mul_f32_e32 v18, v18, v0
	v_mul_f32_e32 v18, v18, v56
	v_mul_f32_e32 v2, v2, v0
	v_add_f32_e32 v53, 1.0, v53
	v_mul_f32_e32 v3, v3, v0
	v_mul_f32_e32 v4, v4, v0
	v_mul_f32_e32 v5, v5, v0
	v_rcp_f32_e32 v54, v53
	s_nop 0
	v_mul_f32_e32 v21, v21, v54
	v_mul_f32_e32 v21, v20, v21
	v_cvt_pk_bf16_f32 v20, v18, v19
	s_nop 1
	v_cvt_pk_bf16_f32 v21, v52, v21
	s_nop 1
	v_lshl_add_u64 v[18:19], v[50:51], 0, v[48:49]
	global_store_dwordx2 v[18:19], v[20:21], off offset:1536
	s_waitcnt vmcnt(7)
	v_lshlrev_b32_e32 v21, 16, v46
	v_mul_f32_e32 v20, v22, v0
	v_mul_f32_e32 v22, 0xbfb8aa3b, v21
	v_exp_f32_e32 v22, v22
	s_nop 0
	v_add_f32_e32 v22, 1.0, v22
	v_rcp_f32_e32 v48, v22
	s_nop 0
	v_mul_f32_e32 v21, v21, v48
	v_and_b32_e32 v22, 0xffff0000, v46
	v_mul_f32_e32 v20, v20, v21
	v_mul_f32_e32 v21, v23, v0
	v_mul_f32_e32 v23, 0xbfb8aa3b, v22
	v_exp_f32_e32 v23, v23
	s_nop 0
	v_add_f32_e32 v23, 1.0, v23
	v_rcp_f32_e32 v46, v23
	s_nop 0
	v_mul_f32_e32 v22, v22, v46
	v_lshlrev_b32_e32 v23, 16, v47
	v_mul_f32_e32 v21, v21, v22
	v_mul_f32_e32 v22, v24, v0
	v_mul_f32_e32 v24, 0xbfb8aa3b, v23
	v_exp_f32_e32 v24, v24
	v_cvt_pk_bf16_f32 v20, v20, v21
	s_nop 1
	s_nop 0
	v_add_f32_e32 v24, 1.0, v24
	v_rcp_f32_e32 v46, v24
	s_nop 0
	v_mul_f32_e32 v23, v23, v46
	v_and_b32_e32 v24, 0xffff0000, v47
	v_mul_f32_e32 v22, v22, v23
	v_mul_f32_e32 v23, v25, v0
	v_mul_f32_e32 v25, 0xbfb8aa3b, v24
	v_exp_f32_e32 v25, v25
	s_nop 0
	v_add_f32_e32 v25, 1.0, v25
	v_rcp_f32_e32 v46, v25
	s_nop 0
	v_mul_f32_e32 v24, v24, v46
	v_mul_f32_e32 v23, v23, v24
	v_cvt_pk_bf16_f32 v21, v22, v23
	s_nop 1
	global_store_dwordx2 v[18:19], v[20:21], off offset:1552
	s_waitcnt vmcnt(7)
	v_lshlrev_b32_e32 v21, 16, v44
	v_mul_f32_e32 v22, 0xbfb8aa3b, v21
	v_exp_f32_e32 v22, v22
	v_mul_f32_e32 v20, v26, v0
	v_add_f32_e32 v22, 1.0, v22
	v_rcp_f32_e32 v23, v22
	s_nop 0
	v_mul_f32_e32 v21, v21, v23
	v_and_b32_e32 v22, 0xffff0000, v44
	v_mul_f32_e32 v23, 0xbfb8aa3b, v22
	v_exp_f32_e32 v23, v23
	v_mul_f32_e32 v20, v20, v21
	v_mul_f32_e32 v21, v27, v0
	v_add_f32_e32 v23, 1.0, v23
	v_rcp_f32_e32 v24, v23
	s_nop 0
	v_mul_f32_e32 v22, v22, v24
	v_lshlrev_b32_e32 v23, 16, v45
	v_mul_f32_e32 v24, 0xbfb8aa3b, v23
	v_exp_f32_e32 v24, v24
	v_mul_f32_e32 v21, v21, v22
	v_mul_f32_e32 v22, v28, v0
	v_cvt_pk_bf16_f32 v20, v20, v21
	s_nop 1
	v_add_f32_e32 v24, 1.0, v24
	v_rcp_f32_e32 v25, v24
	s_nop 0
	v_mul_f32_e32 v23, v23, v25
	v_and_b32_e32 v24, 0xffff0000, v45
	v_mul_f32_e32 v25, 0xbfb8aa3b, v24
	v_exp_f32_e32 v25, v25
	v_mul_f32_e32 v22, v22, v23
	v_mul_f32_e32 v23, v29, v0
	v_add_f32_e32 v25, 1.0, v25
	v_rcp_f32_e32 v26, v25
	s_nop 0
	v_mul_f32_e32 v24, v24, v26
	v_mul_f32_e32 v23, v23, v24
	v_cvt_pk_bf16_f32 v21, v22, v23
	s_nop 1
	global_store_dwordx2 v[18:19], v[20:21], off offset:1568
	s_waitcnt vmcnt(7)
; DI unsigned pack2(float a, float b) { unsigned r; asm("v_cvt_pk_bf16_f32 %0, %1, %2\n\ts_nop 1" : "=v"(r) : "v"(a), "v"(b)); return r; }
; DI float lo2f(unsigned u) { return __uint_as_float(u << 16); }
; DI float hi2f(unsigned u) { return __uint_as_float(u & 0xffff0000u); }
; DI float silu(float x) { return x / (1.f + __expf(-x)); }
; template <int DQK, bool WIN>
; DI void attn_item(const u16* __restrict__ Qb, int ldq, const u16* __restrict__ Kb, int ldk, const u16* __restrict__ Vtb, int qb,
;                   float qscale, float sink2, const u16* __restrict__ zb, int ldz, u16* __restrict__ ob, int ldo, u16* lds) {
;     ...
;   float lt = lsum + __shfl_xor(lsum, 32);
;   float inv = 1.f / lt;
;   u32x2 zr[8];
; #pragma unroll
;   for (int e = 0; e < 8; ++e) zr[e] = *(const u32x2*)(zb + (size_t)qrow * ldz + (e >> 2) * 32 + 8 * (e & 3) + 4 * hh);
; #pragma unroll
;   for (int vb = 0; vb < 2; ++vb)
; #pragma unroll
;     for (int g4 = 0; g4 < 4; ++g4) {
;       int vd0 = vb * 32 + 8 * g4 + 4 * hh;
;       u32x2 z = zr[vb * 4 + g4];
;       float a0 = o[vb][4 * g4 + 0] * inv * silu(lo2f(z.x));
;       float a1 = o[vb][4 * g4 + 1] * inv * silu(hi2f(z.x));
;       float a2 = o[vb][4 * g4 + 2] * inv * silu(lo2f(z.y));
;       float a3 = o[vb][4 * g4 + 3] * inv * silu(hi2f(z.y));
;       u32x2 ov; ov.x = pack2(a0, a1); ov.y = pack2(a2, a3);
;       *(u32x2*)(ob + (size_t)qrow * ldo + vd0) = ov;
;     }
	v_lshlrev_b32_e32 v21, 16, v42
	v_mul_f32_e32 v22, 0xbfb8aa3b, v21
	v_exp_f32_e32 v22, v22
	v_mul_f32_e32 v20, v30, v0
	v_add_f32_e32 v22, 1.0, v22
	v_rcp_f32_e32 v23, v22
	s_nop 0
	v_mul_f32_e32 v21, v21, v23
	v_and_b32_e32 v22, 0xffff0000, v42
	v_mul_f32_e32 v23, 0xbfb8aa3b, v22
	v_exp_f32_e32 v23, v23
	v_mul_f32_e32 v20, v20, v21
	v_mul_f32_e32 v21, v31, v0
	v_add_f32_e32 v23, 1.0, v23
	v_rcp_f32_e32 v24, v23
	s_nop 0
	v_mul_f32_e32 v22, v22, v24
	v_lshlrev_b32_e32 v23, 16, v43
	v_mul_f32_e32 v24, 0xbfb8aa3b, v23
	v_exp_f32_e32 v24, v24
	v_mul_f32_e32 v21, v21, v22
	v_mul_f32_e32 v22, v32, v0
	v_cvt_pk_bf16_f32 v20, v20, v21
	s_nop 1
	v_add_f32_e32 v24, 1.0, v24
	v_rcp_f32_e32 v25, v24
	s_nop 0
	v_mul_f32_e32 v23, v23, v25
	v_and_b32_e32 v24, 0xffff0000, v43
	v_mul_f32_e32 v25, 0xbfb8aa3b, v24
	v_exp_f32_e32 v25, v25
	v_mul_f32_e32 v22, v22, v23
	v_mul_f32_e32 v23, v33, v0
	v_add_f32_e32 v25, 1.0, v25
	v_rcp_f32_e32 v26, v25
	s_nop 0
	v_mul_f32_e32 v24, v24, v26
	v_mul_f32_e32 v23, v23, v24
	v_cvt_pk_bf16_f32 v21, v22, v23
	s_nop 1
	global_store_dwordx2 v[18:19], v[20:21], off offset:1584
	s_waitcnt vmcnt(7)
	v_lshlrev_b32_e32 v20, 16, v40
	v_mul_f32_e32 v21, 0xbfb8aa3b, v20
	v_exp_f32_e32 v21, v21
	s_nop 0
	v_add_f32_e32 v21, 1.0, v21
	v_rcp_f32_e32 v22, v21
	s_nop 0
	v_mul_f32_e32 v20, v20, v22
	v_mul_f32_e32 v2, v2, v20
	v_and_b32_e32 v20, 0xffff0000, v40
	v_mul_f32_e32 v21, 0xbfb8aa3b, v20
	v_exp_f32_e32 v21, v21
	s_nop 0
	v_add_f32_e32 v21, 1.0, v21
	v_rcp_f32_e32 v22, v21
	s_nop 0
	v_mul_f32_e32 v20, v20, v22
	v_mul_f32_e32 v3, v3, v20
	v_lshlrev_b32_e32 v20, 16, v41
	v_mul_f32_e32 v21, 0xbfb8aa3b, v20
	v_exp_f32_e32 v21, v21
	v_cvt_pk_bf16_f32 v2, v2, v3
	s_nop 1
	s_nop 0
	v_add_f32_e32 v21, 1.0, v21
	v_rcp_f32_e32 v22, v21
	s_nop 0
	v_mul_f32_e32 v20, v20, v22
	v_mul_f32_e32 v4, v4, v20
	v_and_b32_e32 v20, 0xffff0000, v41
	v_mul_f32_e32 v21, 0xbfb8aa3b, v20
	v_exp_f32_e32 v21, v21
	s_nop 0
	v_add_f32_e32 v21, 1.0, v21
	v_rcp_f32_e32 v22, v21
	s_nop 0
	v_mul_f32_e32 v20, v20, v22
	v_mul_f32_e32 v5, v5, v20
	v_cvt_pk_bf16_f32 v3, v4, v5
	s_nop 1
	global_store_dwordx2 v[18:19], v[2:3], off offset:1600
	s_waitcnt vmcnt(7)
	v_lshlrev_b32_e32 v3, 16, v38
	v_mul_f32_e32 v4, 0xbfb8aa3b, v3
	v_exp_f32_e32 v4, v4
	v_mul_f32_e32 v2, v6, v0
	v_add_f32_e32 v4, 1.0, v4
	v_rcp_f32_e32 v5, v4
	s_nop 0
	v_mul_f32_e32 v3, v3, v5
	v_and_b32_e32 v4, 0xffff0000, v38
	v_mul_f32_e32 v5, 0xbfb8aa3b, v4
	v_exp_f32_e32 v5, v5
	v_mul_f32_e32 v2, v2, v3
	v_mul_f32_e32 v3, v7, v0
	v_add_f32_e32 v5, 1.0, v5
	v_rcp_f32_e32 v6, v5
	s_nop 0
	v_mul_f32_e32 v4, v4, v6
	v_lshlrev_b32_e32 v5, 16, v39
	v_mul_f32_e32 v6, 0xbfb8aa3b, v5
	v_exp_f32_e32 v6, v6
	v_mul_f32_e32 v3, v3, v4
	v_mul_f32_e32 v4, v8, v0
	v_cvt_pk_bf16_f32 v2, v2, v3
	s_nop 1
	v_add_f32_e32 v6, 1.0, v6
	v_rcp_f32_e32 v7, v6
	s_nop 0
	v_mul_f32_e32 v5, v5, v7
	v_and_b32_e32 v6, 0xffff0000, v39
	v_mul_f32_e32 v7, 0xbfb8aa3b, v6
	v_exp_f32_e32 v7, v7
	v_mul_f32_e32 v4, v4, v5
	v_mul_f32_e32 v5, v9, v0
	v_add_f32_e32 v7, 1.0, v7
	v_rcp_f32_e32 v8, v7
	s_nop 0
	v_mul_f32_e32 v6, v6, v8
	v_mul_f32_e32 v5, v5, v6
	v_cvt_pk_bf16_f32 v3, v4, v5
	s_nop 1
	global_store_dwordx2 v[18:19], v[2:3], off offset:1616
	s_waitcnt vmcnt(7)
	v_lshlrev_b32_e32 v3, 16, v36
	v_mul_f32_e32 v4, 0xbfb8aa3b, v3
	v_exp_f32_e32 v4, v4
	v_mul_f32_e32 v2, v10, v0
	v_add_f32_e32 v4, 1.0, v4
	v_rcp_f32_e32 v5, v4
	s_nop 0
	v_mul_f32_e32 v3, v3, v5
	v_and_b32_e32 v4, 0xffff0000, v36
	v_mul_f32_e32 v5, 0xbfb8aa3b, v4
	v_exp_f32_e32 v5, v5
	v_mul_f32_e32 v2, v2, v3
	v_mul_f32_e32 v3, v11, v0
	v_add_f32_e32 v5, 1.0, v5
	v_rcp_f32_e32 v6, v5
	s_nop 0
	v_mul_f32_e32 v4, v4, v6
	v_lshlrev_b32_e32 v5, 16, v37
	v_mul_f32_e32 v6, 0xbfb8aa3b, v5
	v_exp_f32_e32 v6, v6
	v_mul_f32_e32 v3, v3, v4
	v_mul_f32_e32 v4, v12, v0
	v_cvt_pk_bf16_f32 v2, v2, v3
	s_nop 1
	v_add_f32_e32 v6, 1.0, v6
	v_rcp_f32_e32 v7, v6
	s_nop 0
	v_mul_f32_e32 v5, v5, v7
	v_and_b32_e32 v6, 0xffff0000, v37
	v_mul_f32_e32 v7, 0xbfb8aa3b, v6
	v_exp_f32_e32 v7, v7
	v_mul_f32_e32 v4, v4, v5
	v_mul_f32_e32 v5, v13, v0
	v_add_f32_e32 v7, 1.0, v7
	v_rcp_f32_e32 v8, v7
	s_nop 0
	v_mul_f32_e32 v6, v6, v8
	v_mul_f32_e32 v5, v5, v6
	v_cvt_pk_bf16_f32 v3, v4, v5
	s_nop 1
	global_store_dwordx2 v[18:19], v[2:3], off offset:1632
	s_waitcnt vmcnt(7)
	v_lshlrev_b32_e32 v3, 16, v34
	v_mul_f32_e32 v4, 0xbfb8aa3b, v3
	v_exp_f32_e32 v4, v4
	v_mul_f32_e32 v2, v14, v0
	v_add_f32_e32 v4, 1.0, v4
	v_rcp_f32_e32 v5, v4
	s_nop 0
	v_mul_f32_e32 v3, v3, v5
	v_and_b32_e32 v4, 0xffff0000, v34
	v_mul_f32_e32 v5, 0xbfb8aa3b, v4
	v_exp_f32_e32 v5, v5
	v_mul_f32_e32 v2, v2, v3
	v_mul_f32_e32 v3, v15, v0
	v_add_f32_e32 v5, 1.0, v5
	v_rcp_f32_e32 v6, v5
	s_nop 0
	v_mul_f32_e32 v4, v4, v6
	v_lshlrev_b32_e32 v5, 16, v35
	v_mul_f32_e32 v6, 0xbfb8aa3b, v5
	v_exp_f32_e32 v6, v6
	v_mul_f32_e32 v3, v3, v4
	v_mul_f32_e32 v4, v16, v0
	v_mul_f32_e32 v0, v17, v0
	v_add_f32_e32 v6, 1.0, v6
	v_cvt_pk_bf16_f32 v2, v2, v3
	s_nop 1
	s_nop 0
	v_rcp_f32_e32 v7, v6
	s_nop 0
	v_mul_f32_e32 v5, v5, v7
	v_mul_f32_e32 v4, v4, v5
	v_and_b32_e32 v5, 0xffff0000, v35
	v_mul_f32_e32 v6, 0xbfb8aa3b, v5
	v_exp_f32_e32 v6, v6
	s_nop 0
	v_add_f32_e32 v6, 1.0, v6
	v_rcp_f32_e32 v7, v6
	s_nop 0
	v_mul_f32_e32 v5, v5, v7
	v_mul_f32_e32 v0, v0, v5
	v_cvt_pk_bf16_f32 v3, v4, v0
	s_nop 1
	global_store_dwordx2 v[18:19], v[2:3], off offset:1648
	s_cbranch_scc1 .LBB0_335

; DI float sigm(float x) { return 1.f / (1.f + __expf(-x)); }
; DI void conv_item(PREF p, int l, int tile, unsigned char* ldsb) {
;     ...
;   for (int id = tid; id < 62 * 32; id += 256) {
;     int rr = id >> 5, ch = (id & 31) * 8;
;     int s = s0 - 30 + rr;
;     float v[8];
; #pragma unroll
;     for (int j = 0; j < 8; ++j) v[j] = 0.f;
;     if (s >= 0) {
;       const u16* src = p.hb + (size_t)(t0 - 30 + rr) * HW + ch;
;       float a[8], g[8];
;       unpack8(*(const u32x4*)(src + OFF_AVAL), a);
;       unpack8(*(const u32x4*)(src + OFF_AGATE), g);
; #pragma unroll
;       for (int j = 0; j < 8; ++j) v[j] = a[j] * sigm(g[j]);
;     }
;     *(float4*)(Gs + rr * 256 + ch) = make_float4(v[0], v[1], v[2], v[3]);
;     *(float4*)(Gs + rr * 256 + ch + 4) = make_float4(v[4], v[5], v[6], v[7]);
;   }
.LBB0_401:
	v_ashrrev_i32_e32 v15, 5, v17
	v_and_b32_e32 v18, 0xf8, v13
	v_cmp_lt_i32_e32 vcc, s29, v15
	v_mov_b32_e32 v10, 0
	v_mov_b32_e32 v11, 0
	v_mov_b32_e32 v2, 0
	v_mov_b32_e32 v3, 0
	v_mov_b32_e32 v4, 0
	v_mov_b32_e32 v5, 0
	v_mov_b32_e32 v8, 0
	v_mov_b32_e32 v9, 0
	s_and_saveexec_b64 s[26:27], vcc
	s_cbranch_execz .LBB0_400
	v_add_u32_e32 v0, s30, v15
	v_mov_b64_e32 v[2:3], s[16:17]
	v_mad_i64_i32 v[2:3], s[0:1], v0, s60, v[2:3]
	v_lshlrev_b32_e32 v0, 1, v18
	v_lshl_add_u64 v[2:3], v[2:3], 0, v[0:1]
	global_load_dwordx4 v[4:7], v[2:3], off
	global_load_dwordx4 v[8:11], v[2:3], off offset:512
	s_waitcnt vmcnt(0)
	v_lshlrev_b32_e32 v2, 16, v8
	v_and_b32_e32 v3, 0xffff0000, v8
	v_mul_f32_e32 v2, 0xbfb8aa3b, v2
	v_mul_f32_e32 v3, 0xbfb8aa3b, v3
	v_exp_f32_e32 v2, v2
	v_exp_f32_e32 v3, v3
	v_lshlrev_b32_e32 v20, 16, v9
	v_and_b32_e32 v21, 0xffff0000, v9
	v_lshlrev_b32_e32 v8, 16, v4
	v_pk_add_f32 v[2:3], v[2:3], 1.0 op_sel_hi:[1,0]
	v_and_b32_e32 v9, 0xffff0000, v4
	v_lshlrev_b32_e32 v22, 16, v10
	v_and_b32_e32 v23, 0xffff0000, v10
	v_lshlrev_b32_e32 v19, 16, v11
	v_and_b32_e32 v0, 0xffff0000, v11
	v_mul_f32_e32 v0, 0xbfb8aa3b, v0
	v_rcp_f32_e32 v3, v3
	v_rcp_f32_e32 v2, v2
	v_mul_f32_e32 v4, 0xbfb8aa3b, v20
	v_pk_mul_f32 v[2:3], v[2:3], v[8:9]
	v_exp_f32_e32 v8, v4
	v_mul_f32_e32 v4, 0xbfb8aa3b, v21
	v_exp_f32_e32 v9, v4
	v_lshlrev_b32_e32 v4, 16, v5
	v_and_b32_e32 v5, 0xffff0000, v5
	v_pk_add_f32 v[8:9], v[8:9], 1.0 op_sel_hi:[1,0]
	s_nop 0
	v_rcp_f32_e32 v9, v9
	v_rcp_f32_e32 v8, v8
	s_nop 0
	v_pk_mul_f32 v[4:5], v[8:9], v[4:5]
	v_mul_f32_e32 v8, 0xbfb8aa3b, v22
	v_exp_f32_e32 v10, v8
	v_mul_f32_e32 v8, 0xbfb8aa3b, v23
	v_exp_f32_e32 v11, v8
	v_lshlrev_b32_e32 v8, 16, v6
	v_and_b32_e32 v9, 0xffff0000, v6
	v_pk_add_f32 v[10:11], v[10:11], 1.0 op_sel_hi:[1,0]
	s_nop 0
	v_rcp_f32_e32 v11, v11
	v_rcp_f32_e32 v10, v10
	v_mul_f32_e32 v6, 0xbfb8aa3b, v19
	v_pk_mul_f32 v[8:9], v[10:11], v[8:9]
	v_exp_f32_e32 v10, v6
	v_exp_f32_e32 v11, v0
	v_lshlrev_b32_e32 v6, 16, v7
	v_and_b32_e32 v7, 0xffff0000, v7
	v_pk_add_f32 v[10:11], v[10:11], 1.0 op_sel_hi:[1,0]
	s_nop 0
	v_rcp_f32_e32 v11, v11
	v_rcp_f32_e32 v10, v10
	s_nop 0
	v_pk_mul_f32 v[10:11], v[10:11], v[6:7]
	s_branch .LBB0_400

; DI float sigm(float x) { return 1.f / (1.f + __expf(-x)); }
; DI void conv_item(PREF p, int l, int tile, unsigned char* ldsb) {
;     ...
;   for (int id = tid; id < 62 * 32; id += 256) {
;     int rr = id >> 5, ch = (id & 31) * 8;
;     int s = s0 - 30 + rr;
;     float v[8];
; #pragma unroll
;     for (int j = 0; j < 8; ++j) v[j] = 0.f;
;     if (s >= 0) {
;       const u16* src = p.hb + (size_t)(t0 - 30 + rr) * HW + ch;
;       float a[8], g[8];
;       unpack8(*(const u32x4*)(src + OFF_AVAL), a);
;       unpack8(*(const u32x4*)(src + OFF_AGATE), g);
; #pragma unroll
;       for (int j = 0; j < 8; ++j) v[j] = a[j] * sigm(g[j]);
;     }
;     *(float4*)(Gs + rr * 256 + ch) = make_float4(v[0], v[1], v[2], v[3]);
;     *(float4*)(Gs + rr * 256 + ch + 4) = make_float4(v[4], v[5], v[6], v[7]);
;   }
.LBB0_407:
	v_ashrrev_i32_e32 v5, 5, v17
	v_and_b32_e32 v19, 0xf8, v18
	v_cmp_lt_i32_e32 vcc, s29, v5
	v_mov_b32_e32 v4, 0
	v_lshlrev_b32_e32 v0, 1, v19
	v_mov_b32_e32 v14, 0
	v_mov_b32_e32 v15, 0
	v_mov_b32_e32 v6, 0
	v_mov_b32_e32 v7, 0
	v_mov_b32_e32 v8, 0
	v_mov_b32_e32 v9, 0
	v_mov_b32_e32 v12, 0
	v_mov_b32_e32 v13, 0
	s_and_saveexec_b64 s[24:25], vcc
	s_cbranch_execz .LBB0_409
	v_add_u32_e32 v6, s30, v5
	v_mov_b64_e32 v[2:3], s[16:17]
	v_mad_i64_i32 v[2:3], s[0:1], v6, s60, v[2:3]
	v_lshl_add_u64 v[2:3], v[2:3], 0, v[0:1]
	global_load_dwordx4 v[8:11], v[2:3], off
	global_load_dwordx4 v[20:23], v[2:3], off offset:512
	s_waitcnt vmcnt(1)
	v_lshlrev_b32_e32 v6, 16, v8
	s_waitcnt vmcnt(0)
	v_lshlrev_b32_e32 v2, 16, v20
	v_and_b32_e32 v3, 0xffff0000, v20
	v_mul_f32_e32 v2, 0xbfb8aa3b, v2
	v_mul_f32_e32 v3, 0xbfb8aa3b, v3
	v_exp_f32_e32 v2, v2
	v_exp_f32_e32 v3, v3
	v_and_b32_e32 v7, 0xffff0000, v8
	v_lshlrev_b32_e32 v12, 16, v21
	v_and_b32_e32 v13, 0xffff0000, v21
	v_pk_add_f32 v[2:3], v[2:3], 1.0 op_sel_hi:[1,0]
	v_lshlrev_b32_e32 v20, 16, v22
	v_and_b32_e32 v21, 0xffff0000, v22
	v_lshlrev_b32_e32 v15, 16, v23
	v_and_b32_e32 v14, 0xffff0000, v23
	v_rcp_f32_e32 v3, v3
	v_rcp_f32_e32 v2, v2
	s_nop 0
	v_pk_mul_f32 v[6:7], v[2:3], v[6:7]
	v_mul_f32_e32 v2, 0xbfb8aa3b, v12
	v_mul_f32_e32 v3, 0xbfb8aa3b, v13
	v_exp_f32_e32 v2, v2
	v_exp_f32_e32 v3, v3
	v_lshlrev_b32_e32 v8, 16, v9
	v_and_b32_e32 v9, 0xffff0000, v9
	v_pk_add_f32 v[2:3], v[2:3], 1.0 op_sel_hi:[1,0]
	s_nop 0
	v_rcp_f32_e32 v3, v3
	v_rcp_f32_e32 v2, v2
	s_nop 0
	v_pk_mul_f32 v[8:9], v[2:3], v[8:9]
	v_mul_f32_e32 v2, 0xbfb8aa3b, v20
	v_exp_f32_e32 v12, v2
	v_mul_f32_e32 v2, 0xbfb8aa3b, v21
	v_exp_f32_e32 v13, v2
	v_lshlrev_b32_e32 v2, 16, v10
	v_and_b32_e32 v3, 0xffff0000, v10
	v_pk_add_f32 v[12:13], v[12:13], 1.0 op_sel_hi:[1,0]
	s_nop 0
	v_rcp_f32_e32 v13, v13
	v_rcp_f32_e32 v12, v12
	s_nop 0
	v_pk_mul_f32 v[12:13], v[12:13], v[2:3]
	v_mul_f32_e32 v2, 0xbfb8aa3b, v15
	v_mul_f32_e32 v3, 0xbfb8aa3b, v14
	v_exp_f32_e32 v2, v2
	v_exp_f32_e32 v3, v3
	v_lshlrev_b32_e32 v10, 16, v11
	v_and_b32_e32 v11, 0xffff0000, v11
	v_pk_add_f32 v[2:3], v[2:3], 1.0 op_sel_hi:[1,0]
	s_nop 0
	v_rcp_f32_e32 v3, v3
	v_rcp_f32_e32 v2, v2
	s_nop 0
	v_pk_mul_f32 v[14:15], v[2:3], v[10:11]
.LBB0_409:
	s_or_b64 exec, exec, s[24:25]
	v_lshlrev_b32_e32 v2, 10, v5
	v_lshlrev_b32_e32 v19, 2, v19
	v_add3_u32 v2, s33, v2, v19
	ds_write_b128 v2, v[6:9]
	ds_write_b128 v2, v[12:15] offset:16
	v_add_u32_e32 v12, 0x100, v17
	v_ashrrev_i32_e32 v13, 5, v12
	v_cmp_lt_i32_e32 vcc, s29, v13
	v_mov_b32_e32 v5, 0
	v_mov_b32_e32 v6, 0
	v_mov_b32_e32 v7, 0
	v_mov_b32_e32 v8, 0
	v_mov_b32_e32 v9, 0
	v_mov_b32_e32 v2, 0
	v_mov_b32_e32 v3, 0
	s_and_saveexec_b64 s[24:25], vcc
	s_cbranch_execz .LBB0_411
	v_add_u32_e32 v4, s30, v13
	v_mov_b64_e32 v[2:3], s[16:17]
	v_mad_i64_i32 v[2:3], s[0:1], v4, s60, v[2:3]
	v_lshl_add_u64 v[6:7], v[2:3], 0, v[0:1]
	global_load_dwordx4 v[2:5], v[6:7], off
	s_nop 0
	global_load_dwordx4 v[6:9], v[6:7], off offset:512
	s_waitcnt vmcnt(0)
	v_lshlrev_b32_e32 v10, 16, v6
	v_and_b32_e32 v11, 0xffff0000, v6
	v_lshlrev_b32_e32 v20, 16, v7
	v_and_b32_e32 v21, 0xffff0000, v7
	v_mul_f32_e32 v6, 0xbfb8aa3b, v10
	v_mul_f32_e32 v7, 0xbfb8aa3b, v11
	v_exp_f32_e32 v6, v6
	v_exp_f32_e32 v7, v7
	v_lshlrev_b32_e32 v22, 16, v8
	v_and_b32_e32 v23, 0xffff0000, v8
	v_lshlrev_b32_e32 v15, 16, v9
	v_pk_add_f32 v[6:7], v[6:7], 1.0 op_sel_hi:[1,0]
	v_and_b32_e32 v14, 0xffff0000, v9
	v_lshlrev_b32_e32 v8, 16, v2
	v_and_b32_e32 v9, 0xffff0000, v2
	v_rcp_f32_e32 v7, v7
	v_rcp_f32_e32 v6, v6
	v_mul_f32_e32 v2, 0xbfb8aa3b, v20
	v_pk_mul_f32 v[6:7], v[6:7], v[8:9]
	v_exp_f32_e32 v8, v2
	v_mul_f32_e32 v2, 0xbfb8aa3b, v21
	v_exp_f32_e32 v9, v2
	v_lshlrev_b32_e32 v2, 16, v3
	v_and_b32_e32 v3, 0xffff0000, v3
	v_pk_add_f32 v[8:9], v[8:9], 1.0 op_sel_hi:[1,0]
	s_nop 0
	v_rcp_f32_e32 v9, v9
	v_rcp_f32_e32 v8, v8
	s_nop 0
	v_pk_mul_f32 v[8:9], v[8:9], v[2:3]
	v_mul_f32_e32 v2, 0xbfb8aa3b, v22
	v_exp_f32_e32 v10, v2
	v_mul_f32_e32 v2, 0xbfb8aa3b, v23
	v_exp_f32_e32 v11, v2
	v_lshlrev_b32_e32 v2, 16, v4
	v_and_b32_e32 v3, 0xffff0000, v4
	v_pk_add_f32 v[10:11], v[10:11], 1.0 op_sel_hi:[1,0]
	s_nop 0
	v_rcp_f32_e32 v11, v11
	v_rcp_f32_e32 v10, v10
	v_mul_f32_e32 v4, 0xbfb8aa3b, v15
	v_pk_mul_f32 v[2:3], v[10:11], v[2:3]
	v_exp_f32_e32 v10, v4
	v_mul_f32_e32 v4, 0xbfb8aa3b, v14
	v_exp_f32_e32 v11, v4
	v_lshlrev_b32_e32 v4, 16, v5
	v_and_b32_e32 v5, 0xffff0000, v5
	v_pk_add_f32 v[10:11], v[10:11], 1.0 op_sel_hi:[1,0]
	s_nop 0
	v_rcp_f32_e32 v11, v11
	v_rcp_f32_e32 v10, v10
	s_nop 0
	v_pk_mul_f32 v[4:5], v[10:11], v[4:5]
; DI float sigm(float x) { return 1.f / (1.f + __expf(-x)); }
; DI void conv_item(PREF p, int l, int tile, unsigned char* ldsb) {
;     ...
;   for (int id = tid; id < 62 * 32; id += 256) {
;     int rr = id >> 5, ch = (id & 31) * 8;
;     int s = s0 - 30 + rr;
;     float v[8];
; #pragma unroll
;     for (int j = 0; j < 8; ++j) v[j] = 0.f;
;     if (s >= 0) {
;       const u16* src = p.hb + (size_t)(t0 - 30 + rr) * HW + ch;
;       float a[8], g[8];
;       unpack8(*(const u32x4*)(src + OFF_AVAL), a);
;       unpack8(*(const u32x4*)(src + OFF_AGATE), g);
; #pragma unroll
;       for (int j = 0; j < 8; ++j) v[j] = a[j] * sigm(g[j]);
;     }
;     *(float4*)(Gs + rr * 256 + ch) = make_float4(v[0], v[1], v[2], v[3]);
;     *(float4*)(Gs + rr * 256 + ch + 4) = make_float4(v[4], v[5], v[6], v[7]);
;   }
.LBB0_411:
	s_or_b64 exec, exec, s[24:25]
	v_lshlrev_b32_e32 v10, 10, v13
	v_add3_u32 v10, s33, v10, v19
	ds_write_b128 v10, v[6:9]
	ds_write_b128 v10, v[2:5] offset:16
	v_add_u32_e32 v5, 0x100, v12
	v_ashrrev_i32_e32 v20, 5, v5
	v_cmp_lt_i32_e32 vcc, s29, v20
	v_mov_b32_e32 v4, 0
	v_mov_b32_e32 v14, 0
	v_mov_b32_e32 v15, 0
	v_mov_b32_e32 v6, 0
	v_mov_b32_e32 v7, 0
	v_mov_b32_e32 v8, 0
	v_mov_b32_e32 v9, 0
	v_mov_b32_e32 v12, 0
	v_mov_b32_e32 v13, 0
	s_and_saveexec_b64 s[24:25], vcc
	s_cbranch_execz .LBB0_413
	v_add_u32_e32 v6, s30, v20
	v_mov_b64_e32 v[2:3], s[16:17]
	v_mad_i64_i32 v[2:3], s[0:1], v6, s60, v[2:3]
	v_lshl_add_u64 v[2:3], v[2:3], 0, v[0:1]
	global_load_dwordx4 v[8:11], v[2:3], off
	global_load_dwordx4 v[22:25], v[2:3], off offset:512
	s_waitcnt vmcnt(1)
	v_lshlrev_b32_e32 v6, 16, v8
	s_waitcnt vmcnt(0)
	v_lshlrev_b32_e32 v2, 16, v22
	v_and_b32_e32 v3, 0xffff0000, v22
	v_mul_f32_e32 v2, 0xbfb8aa3b, v2
	v_mul_f32_e32 v3, 0xbfb8aa3b, v3
	v_exp_f32_e32 v2, v2
	v_exp_f32_e32 v3, v3
	v_and_b32_e32 v7, 0xffff0000, v8
	v_lshlrev_b32_e32 v12, 16, v23
	v_and_b32_e32 v13, 0xffff0000, v23
	v_pk_add_f32 v[2:3], v[2:3], 1.0 op_sel_hi:[1,0]
	v_lshlrev_b32_e32 v21, 16, v24
	v_and_b32_e32 v22, 0xffff0000, v24
	v_lshlrev_b32_e32 v15, 16, v25
	v_and_b32_e32 v14, 0xffff0000, v25
	v_rcp_f32_e32 v3, v3
	v_rcp_f32_e32 v2, v2
	s_nop 0
	v_pk_mul_f32 v[6:7], v[2:3], v[6:7]
	v_mul_f32_e32 v2, 0xbfb8aa3b, v12
	v_mul_f32_e32 v3, 0xbfb8aa3b, v13
	v_exp_f32_e32 v2, v2
	v_exp_f32_e32 v3, v3
	v_lshlrev_b32_e32 v8, 16, v9
	v_and_b32_e32 v9, 0xffff0000, v9
	v_pk_add_f32 v[2:3], v[2:3], 1.0 op_sel_hi:[1,0]
	s_nop 0
	v_rcp_f32_e32 v3, v3
	v_rcp_f32_e32 v2, v2
	s_nop 0
	v_pk_mul_f32 v[8:9], v[2:3], v[8:9]
	v_mul_f32_e32 v2, 0xbfb8aa3b, v21
	v_exp_f32_e32 v12, v2
	v_mul_f32_e32 v2, 0xbfb8aa3b, v22
	v_exp_f32_e32 v13, v2
	v_lshlrev_b32_e32 v2, 16, v10
	v_and_b32_e32 v3, 0xffff0000, v10
	v_pk_add_f32 v[12:13], v[12:13], 1.0 op_sel_hi:[1,0]
	s_nop 0
	v_rcp_f32_e32 v13, v13
	v_rcp_f32_e32 v12, v12
	s_nop 0
	v_pk_mul_f32 v[12:13], v[12:13], v[2:3]
	v_mul_f32_e32 v2, 0xbfb8aa3b, v15
	v_mul_f32_e32 v3, 0xbfb8aa3b, v14
	v_exp_f32_e32 v2, v2
	v_exp_f32_e32 v3, v3
	v_lshlrev_b32_e32 v10, 16, v11
	v_and_b32_e32 v11, 0xffff0000, v11
	v_pk_add_f32 v[2:3], v[2:3], 1.0 op_sel_hi:[1,0]
	s_nop 0
	v_rcp_f32_e32 v3, v3
	v_rcp_f32_e32 v2, v2
	s_nop 0
	v_pk_mul_f32 v[14:15], v[2:3], v[10:11]
.LBB0_413:
	s_or_b64 exec, exec, s[24:25]
	v_lshlrev_b32_e32 v2, 10, v20
	v_add3_u32 v2, s33, v2, v19
	ds_write_b128 v2, v[6:9]
	ds_write_b128 v2, v[12:15] offset:16
	v_add_u32_e32 v2, 0x100, v5
	v_ashrrev_i32_e32 v12, 5, v2
	v_cmp_lt_i32_e32 vcc, s29, v12
	v_mov_b32_e32 v5, 0
	v_mov_b32_e32 v6, 0
	v_mov_b32_e32 v7, 0
	v_mov_b32_e32 v8, 0
	v_mov_b32_e32 v9, 0
	v_mov_b32_e32 v2, 0
	v_mov_b32_e32 v3, 0
	s_and_saveexec_b64 s[24:25], vcc
	s_cbranch_execz .LBB0_406
	v_add_u32_e32 v4, s30, v12
	v_mov_b64_e32 v[2:3], s[16:17]
	v_mad_i64_i32 v[2:3], s[0:1], v4, s60, v[2:3]
	v_lshl_add_u64 v[6:7], v[2:3], 0, v[0:1]
	global_load_dwordx4 v[2:5], v[6:7], off
	s_nop 0
	global_load_dwordx4 v[6:9], v[6:7], off offset:512
	s_waitcnt vmcnt(0)
	v_lshlrev_b32_e32 v10, 16, v6
	v_and_b32_e32 v11, 0xffff0000, v6
	v_lshlrev_b32_e32 v14, 16, v7
	v_and_b32_e32 v15, 0xffff0000, v7
	v_mul_f32_e32 v6, 0xbfb8aa3b, v10
	v_mul_f32_e32 v7, 0xbfb8aa3b, v11
	v_exp_f32_e32 v6, v6
	v_exp_f32_e32 v7, v7
	v_lshlrev_b32_e32 v20, 16, v8
	v_and_b32_e32 v21, 0xffff0000, v8
	v_lshlrev_b32_e32 v13, 16, v9
	v_pk_add_f32 v[6:7], v[6:7], 1.0 op_sel_hi:[1,0]
	v_and_b32_e32 v0, 0xffff0000, v9
	v_lshlrev_b32_e32 v8, 16, v2
	v_and_b32_e32 v9, 0xffff0000, v2
	v_mul_f32_e32 v0, 0xbfb8aa3b, v0
	v_rcp_f32_e32 v7, v7
	v_rcp_f32_e32 v6, v6
	v_mul_f32_e32 v2, 0xbfb8aa3b, v14
	v_pk_mul_f32 v[6:7], v[6:7], v[8:9]
	v_exp_f32_e32 v8, v2
	v_mul_f32_e32 v2, 0xbfb8aa3b, v15
	v_exp_f32_e32 v9, v2
	v_lshlrev_b32_e32 v2, 16, v3
	v_and_b32_e32 v3, 0xffff0000, v3
	v_pk_add_f32 v[8:9], v[8:9], 1.0 op_sel_hi:[1,0]
	s_nop 0
	v_rcp_f32_e32 v9, v9
	v_rcp_f32_e32 v8, v8
	s_nop 0
	v_pk_mul_f32 v[8:9], v[8:9], v[2:3]
	v_mul_f32_e32 v2, 0xbfb8aa3b, v20
	v_exp_f32_e32 v10, v2
	v_mul_f32_e32 v2, 0xbfb8aa3b, v21
	v_exp_f32_e32 v11, v2
	v_lshlrev_b32_e32 v2, 16, v4
	v_and_b32_e32 v3, 0xffff0000, v4
	v_pk_add_f32 v[10:11], v[10:11], 1.0 op_sel_hi:[1,0]
	s_nop 0
	v_rcp_f32_e32 v11, v11
	v_rcp_f32_e32 v10, v10
	v_mul_f32_e32 v4, 0xbfb8aa3b, v13
	v_pk_mul_f32 v[2:3], v[10:11], v[2:3]
	v_exp_f32_e32 v10, v4
	v_exp_f32_e32 v11, v0
	v_lshlrev_b32_e32 v4, 16, v5
	v_and_b32_e32 v5, 0xffff0000, v5
	v_pk_add_f32 v[10:11], v[10:11], 1.0 op_sel_hi:[1,0]
	s_nop 0
	v_rcp_f32_e32 v11, v11
	v_rcp_f32_e32 v10, v10
	s_nop 0
	v_pk_mul_f32 v[4:5], v[10:11], v[4:5]
	s_branch .LBB0_406

; DI unsigned pack2(float a, float b) { unsigned r; asm("v_cvt_pk_bf16_f32 %0, %1, %2\n\ts_nop 1" : "=v"(r) : "v"(a), "v"(b)); return r; }
; DI float silu(float x) { return x / (1.f + __expf(-x)); }
; DI void conv_item(PREF p, int l, int tile, unsigned char* ldsb) {
;     ...
;   const float4 gg = *(const float4*)(p.conv_ng + l * 256 + lane * 4);
;   const float4 bb = *(const float4*)(p.conv_nb + l * 256 + lane * 4);
;   for (int q = 0; q < 8; ++q) {
;     int tt = w * 8 + q;
;     float4 v = *(const float4*)(Gs + tt * 256 + lane * 4);
;     float mu = wsum(v.x + v.y + v.z + v.w) * (1.f / 256.f);
;     float d0 = v.x - mu, d1 = v.y - mu, d2 = v.z - mu, d3 = v.w - mu;
;     float var = wsum(d0 * d0 + d1 * d1 + d2 * d2 + d3 * d3) * (1.f / 256.f);
;     float rs = rsqrtf(var + 1e-5f);
;     float y0 = silu(d0 * rs * gg.x + bb.x), y1 = silu(d1 * rs * gg.y + bb.y);
;     float y2 = silu(d2 * rs * gg.z + bb.z), y3 = silu(d3 * rs * gg.w + bb.w);
;     u32x2 ov; ov.x = pack2(y0, y1); ov.y = pack2(y2, y3);
;     *(u32x2*)(p.cA + (size_t)(t0 + tt) * 256 + lane * 4) = ov;
;   }
.LBB0_418:
	v_add_u32_e32 v13, s20, v0
	ds_read_b128 v[24:27], v13
	s_addk_i32 s20, 0x400
	s_cmpk_lg_i32 s20, 0x2000
	s_waitcnt lgkmcnt(0)
	v_add_f32_e32 v13, v24, v25
	v_add_f32_e32 v13, v13, v26
	v_add_f32_e32 v13, v13, v27
	ds_bpermute_b32 v14, v17, v13
	s_waitcnt lgkmcnt(0)
	v_add_f32_e32 v13, v13, v14
	ds_bpermute_b32 v14, v18, v13
	s_waitcnt lgkmcnt(0)
	v_add_f32_e32 v13, v13, v14
	ds_bpermute_b32 v14, v19, v13
	s_waitcnt lgkmcnt(0)
	v_add_f32_e32 v13, v13, v14
	ds_bpermute_b32 v14, v20, v13
	s_waitcnt lgkmcnt(0)
	v_add_f32_e32 v13, v13, v14
	ds_bpermute_b32 v14, v21, v13
	s_waitcnt lgkmcnt(0)
	v_add_f32_e32 v13, v13, v14
	ds_bpermute_b32 v14, v22, v13
	s_waitcnt lgkmcnt(0)
	v_add_f32_e32 v13, v13, v14
	v_mul_f32_e32 v14, 0x3b800000, v13
	v_pk_add_f32 v[24:25], v[24:25], v[14:15] op_sel_hi:[1,0] neg_lo:[0,1] neg_hi:[0,1]
	v_pk_add_f32 v[14:15], v[26:27], v[14:15] op_sel_hi:[1,0] neg_lo:[0,1] neg_hi:[0,1]
	v_pk_mul_f32 v[26:27], v[24:25], v[24:25]
	v_pk_mul_f32 v[28:29], v[14:15], v[14:15]
	v_add_f32_e32 v13, v26, v27
	v_add_f32_e32 v13, v28, v13
	v_add_f32_e32 v13, v29, v13
	ds_bpermute_b32 v16, v17, v13
	s_waitcnt lgkmcnt(0)
	v_add_f32_e32 v13, v13, v16
	ds_bpermute_b32 v16, v18, v13
	s_waitcnt lgkmcnt(0)
	v_add_f32_e32 v13, v13, v16
	ds_bpermute_b32 v16, v19, v13
	s_waitcnt lgkmcnt(0)
	v_add_f32_e32 v13, v13, v16
	ds_bpermute_b32 v16, v20, v13
	s_waitcnt lgkmcnt(0)
	v_add_f32_e32 v13, v13, v16
	ds_bpermute_b32 v16, v21, v13
	s_waitcnt lgkmcnt(0)
	v_add_f32_e32 v13, v13, v16
	ds_bpermute_b32 v16, v22, v13
	s_waitcnt lgkmcnt(0)
	v_add_f32_e32 v13, v13, v16
	v_fmamk_f32 v13, v13, 0x3b800000, v171
	v_cmp_gt_f32_e32 vcc, s61, v13
	v_mul_f32_e32 v16, 0x4b800000, v13
	s_nop 0
	v_cndmask_b32_e32 v13, v13, v16, vcc
	v_rsq_f32_e32 v13, v13
	s_nop 0
	v_mul_f32_e32 v16, 0x45800000, v13
	v_cndmask_b32_e32 v13, v13, v16, vcc
	v_mul_f32_e32 v16, v24, v13
	v_fma_f32 v16, v2, v16, v6
	v_mul_f32_e32 v23, 0xbfb8aa3b, v16
	v_exp_f32_e32 v23, v23
	v_mul_f32_e32 v14, v14, v13
	v_fma_f32 v14, v4, v14, v8
	v_add_f32_e32 v23, 1.0, v23
	v_rcp_f32_e32 v24, v23
	s_nop 0
	v_mul_f32_e32 v16, v16, v24
	v_mul_f32_e32 v23, v25, v13
	v_fma_f32 v23, v3, v23, v7
	v_mul_f32_e32 v24, 0xbfb8aa3b, v23
	v_exp_f32_e32 v24, v24
	v_mul_f32_e32 v13, v15, v13
	v_fma_f32 v13, v5, v13, v9
	v_add_f32_e32 v24, 1.0, v24
	v_rcp_f32_e32 v25, v24
	s_nop 0
	v_mul_f32_e32 v23, v23, v25
	v_mul_f32_e32 v24, 0xbfb8aa3b, v14
	v_exp_f32_e32 v24, v24
	s_nop 0
	v_add_f32_e32 v24, 1.0, v24
	v_rcp_f32_e32 v25, v24
	s_nop 0
	v_mul_f32_e32 v24, v14, v25
	v_mul_f32_e32 v14, 0xbfb8aa3b, v13
	v_exp_f32_e32 v14, v14
	s_nop 0
	v_add_f32_e32 v14, 1.0, v14
	v_rcp_f32_e32 v15, v14
	s_nop 0
	v_mul_f32_e32 v13, v13, v15
	v_cvt_pk_bf16_f32 v15, v24, v13
	s_nop 1
	v_ashrrev_i32_e32 v13, 31, v12
	v_lshlrev_b64 v[24:25], 9, v[12:13]
	v_lshl_add_u64 v[24:25], v[10:11], 0, v[24:25]
	v_add_u32_e32 v12, 1, v12
	v_cvt_pk_bf16_f32 v14, v16, v23
	s_nop 1
	global_store_dwordx2 v[24:25], v[14:15], off
	s_cbranch_scc1 .LBB0_418
	s_add_i32 s28, s28, s71
	s_add_i32 s19, s19, s85
	s_cmpk_gt_i32 s28, 0x3ff
	s_cbranch_scc0 .LBB0_397

; DI void phase_prep(PREF p, unsigned char* ldsb) {
;     ...
;   for (int idx = gtid; idx < NL * 16 * 64; idx += gsz) {
;     int lg = idx >> 6;
;     float dt = expf(p.log_dt[lg]);
;     float lr = p.a_re[idx], li = p.a_im[idx];
;     float mag = expf(lr * dt);
;     float lbr = mag * cosf(li * dt), lbi = mag * sinf(li * dt);
;     float den = lr * lr + li * li;
;     float nr = lbr - 1.f, ni = lbi;
;     float fre = (nr * lr + ni * li) / den, fim = (ni * lr - nr * li) / den;
;     p.lam[idx * 2] = lbr; p.lam[idx * 2 + 1] = lbi;
;     for (int h = 0; h < 16; ++h) {
;       float br = p.b_re[(size_t)idx * 16 + h], bi = p.b_im[(size_t)idx * 16 + h];
;       p.bbre[(size_t)idx * 16 + h] = fre * br - fim * bi;
;       p.bbim[(size_t)idx * 16 + h] = fre * bi + fim * br;
;     }
.LBB0_848:
	s_or_b64 exec, exec, s[8:9]
	s_waitcnt vmcnt(0)
	v_mul_f32_e32 v13, v13, v10
	v_mul_f32_e32 v16, 0x3fb8aa3b, v13
	v_fma_f32 v17, v13, s65, -v16
	v_rndne_f32_e32 v21, v16
	v_fmac_f32_e32 v17, 0x32a5705f, v13
	v_sub_f32_e32 v16, v16, v21
	v_add_f32_e32 v16, v16, v17
	v_exp_f32_e32 v16, v16
	v_cvt_i32_f32_e32 v17, v21
	s_mov_b32 s10, 0xc2ce8ed0
	v_cmp_ngt_f32_e32 vcc, s10, v13
	s_mov_b32 s11, 0x42b17218
	v_ldexp_f32 v16, v16, v17
	v_cndmask_b32_e32 v16, 0, v16, vcc
	v_cmp_nlt_f32_e32 vcc, s11, v13
	s_brev_b32 s0, 1
	v_add_u32_e32 v19, s64, v19
	v_cndmask_b32_e32 v13, v177, v16, vcc
	v_mul_f32_e32 v16, v15, v15
	v_fmamk_f32 v17, v16, 0xb94c1982, v174
	v_fmaak_f32 v17, v16, v17, 0xbe2aaa9d
	v_mul_f32_e32 v17, v16, v17
	v_fmac_f32_e32 v15, v15, v17
	v_fmamk_f32 v17, v16, 0x37d75334, v175
	v_fmaak_f32 v17, v16, v17, 0x3d2aabf7
	v_fmaak_f32 v17, v16, v17, 0xbf000004
	v_fma_f32 v16, v16, v17, 1.0
	v_and_b32_e32 v17, 1, v14
	v_cmp_eq_u32_e32 vcc, 0, v17
	v_lshlrev_b32_e32 v14, 30, v14
	s_nop 0
	v_cndmask_b32_e64 v15, -v15, v16, vcc
	v_bitop3_b32 v14, v14, v15, s0 bitop3:0x6c
	v_mul_f32_e32 v15, v20, v20
	v_fmamk_f32 v17, v15, 0xb94c1982, v174
	v_fmaak_f32 v17, v15, v17, 0xbe2aaa9d
	v_mul_f32_e32 v17, v15, v17
	v_fmac_f32_e32 v20, v20, v17
	v_fmamk_f32 v17, v15, 0x37d75334, v175
	v_fmaak_f32 v17, v15, v17, 0x3d2aabf7
	v_fmaak_f32 v17, v15, v17, 0xbf000004
	s_movk_i32 s0, 0x1f8
	v_fma_f32 v15, v15, v17, 1.0
	v_and_b32_e32 v17, 1, v0
	v_lshlrev_b32_e32 v0, 30, v0
	v_cmp_class_f32_e64 vcc, v11, s0
	v_cmp_eq_u32_e64 s[8:9], 0, v17
	v_and_b32_e32 v0, 0x80000000, v0
	v_xor_b32_e32 v11, v12, v11
	v_cndmask_b32_e64 v15, v15, v20, s[8:9]
	v_xor_b32_e32 v0, v11, v0
	v_xor_b32_e32 v0, v0, v15
	v_cndmask_b32_e32 v0, v180, v0, vcc
	v_cndmask_b32_e32 v16, v180, v14, vcc
	v_mul_f32_e32 v15, v13, v0
	v_mul_f32_e32 v11, v5, v5
	v_fma_f32 v12, v13, v16, -1.0
	v_mul_f32_e32 v0, v5, v15
	v_fmac_f32_e32 v11, v10, v10
	v_fmac_f32_e32 v0, v10, v12
	v_mul_f32_e32 v14, v13, v16
	v_mul_f32_e32 v5, v5, v12
	v_fma_f32 v5, v10, v15, -v5
	v_rcp_f32_e32 v13, v11
	s_nop 0
	v_mul_f32_e32 v0, v0, v13
	v_rcp_f32_e32 v10, v11
	s_nop 0
	v_mul_f32_e32 v20, v5, v10
	v_ashrrev_i32_e32 v5, 31, v4
	v_lshl_add_u64 v[10:11], v[4:5], 2, s[24:25]
	global_store_dwordx2 v[10:11], v[14:15], off
	v_lshl_add_u64 v[12:13], s[34:35], 0, v[8:9]
	v_lshl_add_u64 v[10:11], s[22:23], 0, v[8:9]
	global_load_dword v16, v[12:13], off
	global_load_dword v5, v[10:11], off
	s_add_u32 s22, s22, s72
	s_addc_u32 s23, s23, s73
	v_readlane_b32 s0, v254, 33
	s_waitcnt vmcnt(1)
	v_mul_f32_e32 v14, v16, v20
	s_waitcnt vmcnt(0)
	v_fma_f32 v17, v5, v0, -v14
	v_lshl_add_u64 v[14:15], s[26:27], 0, v[8:9]
	v_mul_f32_e32 v21, v16, v0
	global_store_dword v[14:15], v17, off
	v_fmac_f32_e32 v21, v5, v20
	v_lshl_add_u64 v[16:17], s[30:31], 0, v[8:9]
	global_store_dword v[16:17], v21, off
	global_load_dword v5, v[10:11], off offset:4
	s_nop 0
	global_load_dword v21, v[12:13], off offset:4
	s_add_u32 s30, s30, s72
	s_addc_u32 s31, s31, s73
	v_add_u32_e32 v4, s0, v4
	v_readlane_b32 s0, v254, 34
	s_add_u32 s34, s34, s72
	v_readlane_b32 s1, v254, 35
	s_addc_u32 s35, s35, s73
	s_add_u32 s26, s26, s72
	v_lshl_add_u64 v[6:7], v[6:7], 0, s[0:1]
	s_movk_i32 s0, 0xfff
	s_addc_u32 s27, s27, s73
	v_cmp_lt_i32_e32 vcc, s0, v19
	s_or_b64 s[36:37], vcc, s[36:37]
	s_waitcnt vmcnt(0)
	v_mul_f32_e32 v22, v21, v20
	v_mul_f32_e32 v21, v21, v0
	v_fma_f32 v22, v5, v0, -v22
	v_fmac_f32_e32 v21, v5, v20
	global_store_dword v[14:15], v22, off offset:4
	global_store_dword v[16:17], v21, off offset:4
	global_load_dword v5, v[10:11], off offset:8
	s_nop 0
	global_load_dword v21, v[12:13], off offset:8
	s_waitcnt vmcnt(0)
	v_mul_f32_e32 v22, v21, v20
	v_mul_f32_e32 v21, v21, v0
	v_fma_f32 v22, v5, v0, -v22
	v_fmac_f32_e32 v21, v5, v20
	global_store_dword v[14:15], v22, off offset:8
	global_store_dword v[16:17], v21, off offset:8
	global_load_dword v5, v[10:11], off offset:12
	s_nop 0
	global_load_dword v21, v[12:13], off offset:12
	s_waitcnt vmcnt(0)
; DI void phase_prep(PREF p, unsigned char* ldsb) {
;     ...
;     for (int h = 0; h < 16; ++h) {
;       float br = p.b_re[(size_t)idx * 16 + h], bi = p.b_im[(size_t)idx * 16 + h];
;       p.bbre[(size_t)idx * 16 + h] = fre * br - fim * bi;
;       p.bbim[(size_t)idx * 16 + h] = fre * bi + fim * br;
;     }
	v_mul_f32_e32 v22, v20, v21
	v_mul_f32_e32 v21, v0, v21
	v_fma_f32 v22, v0, v5, -v22
	v_fmac_f32_e32 v21, v20, v5
	global_store_dword v[14:15], v22, off offset:12
	global_store_dword v[16:17], v21, off offset:12
	global_load_dword v5, v[10:11], off offset:16
	s_nop 0
	global_load_dword v21, v[12:13], off offset:16
	s_waitcnt vmcnt(0)
	v_mul_f32_e32 v22, v20, v21
	v_mul_f32_e32 v21, v0, v21
	v_fma_f32 v22, v0, v5, -v22
	v_fmac_f32_e32 v21, v20, v5
	global_store_dword v[14:15], v22, off offset:16
	global_store_dword v[16:17], v21, off offset:16
	global_load_dword v5, v[10:11], off offset:20
	s_nop 0
	global_load_dword v21, v[12:13], off offset:20
	s_waitcnt vmcnt(0)
	v_mul_f32_e32 v22, v20, v21
	v_mul_f32_e32 v21, v0, v21
	v_fma_f32 v22, v0, v5, -v22
	v_fmac_f32_e32 v21, v20, v5
	global_store_dword v[14:15], v22, off offset:20
	global_store_dword v[16:17], v21, off offset:20
	global_load_dword v5, v[10:11], off offset:24
	s_nop 0
	global_load_dword v21, v[12:13], off offset:24
	s_waitcnt vmcnt(0)
	v_mul_f32_e32 v22, v20, v21
	v_mul_f32_e32 v21, v0, v21
	v_fma_f32 v22, v0, v5, -v22
	v_fmac_f32_e32 v21, v20, v5
	global_store_dword v[14:15], v22, off offset:24
	global_store_dword v[16:17], v21, off offset:24
	global_load_dword v5, v[10:11], off offset:28
	s_nop 0
	global_load_dword v21, v[12:13], off offset:28
	s_waitcnt vmcnt(0)
	v_mul_f32_e32 v22, v20, v21
	v_mul_f32_e32 v21, v0, v21
	v_fma_f32 v22, v0, v5, -v22
	v_fmac_f32_e32 v21, v20, v5
	global_store_dword v[14:15], v22, off offset:28
	global_store_dword v[16:17], v21, off offset:28
	global_load_dword v5, v[10:11], off offset:32
	s_nop 0
	global_load_dword v21, v[12:13], off offset:32
	s_waitcnt vmcnt(0)
	v_mul_f32_e32 v22, v20, v21
	v_mul_f32_e32 v21, v0, v21
	v_fma_f32 v22, v0, v5, -v22
	v_fmac_f32_e32 v21, v20, v5
	global_store_dword v[14:15], v22, off offset:32
	global_store_dword v[16:17], v21, off offset:32
	global_load_dword v5, v[10:11], off offset:36
	s_nop 0
	global_load_dword v21, v[12:13], off offset:36
	s_waitcnt vmcnt(0)
	v_mul_f32_e32 v22, v20, v21
	v_mul_f32_e32 v21, v0, v21
	v_fma_f32 v22, v0, v5, -v22
	v_fmac_f32_e32 v21, v20, v5
	global_store_dword v[14:15], v22, off offset:36
	global_store_dword v[16:17], v21, off offset:36
	global_load_dword v5, v[10:11], off offset:40
	s_nop 0
	global_load_dword v21, v[12:13], off offset:40
	s_waitcnt vmcnt(0)
	v_mul_f32_e32 v22, v20, v21
	v_mul_f32_e32 v21, v0, v21
	v_fma_f32 v22, v0, v5, -v22
	v_fmac_f32_e32 v21, v20, v5
	global_store_dword v[14:15], v22, off offset:40
	global_store_dword v[16:17], v21, off offset:40
	global_load_dword v5, v[10:11], off offset:44
	s_nop 0
	global_load_dword v21, v[12:13], off offset:44
	s_waitcnt vmcnt(0)
	v_mul_f32_e32 v22, v20, v21
	v_mul_f32_e32 v21, v0, v21
	v_fma_f32 v22, v0, v5, -v22
	v_fmac_f32_e32 v21, v20, v5
	global_store_dword v[14:15], v22, off offset:44
	global_store_dword v[16:17], v21, off offset:44
	global_load_dword v5, v[10:11], off offset:48
	s_nop 0
	global_load_dword v21, v[12:13], off offset:48
	s_waitcnt vmcnt(0)
	v_mul_f32_e32 v22, v20, v21
	v_mul_f32_e32 v21, v0, v21
	v_fma_f32 v22, v0, v5, -v22
	v_fmac_f32_e32 v21, v20, v5
	global_store_dword v[14:15], v22, off offset:48
	global_store_dword v[16:17], v21, off offset:48
	global_load_dword v5, v[10:11], off offset:52
	s_nop 0
	global_load_dword v21, v[12:13], off offset:52
	s_waitcnt vmcnt(0)
	v_mul_f32_e32 v22, v20, v21
	v_mul_f32_e32 v21, v0, v21
	v_fma_f32 v22, v0, v5, -v22
	v_fmac_f32_e32 v21, v20, v5
	global_store_dword v[14:15], v22, off offset:52
	global_store_dword v[16:17], v21, off offset:52
	global_load_dword v5, v[10:11], off offset:56
	s_nop 0
	global_load_dword v21, v[12:13], off offset:56
	s_waitcnt vmcnt(0)
	v_mul_f32_e32 v22, v20, v21
	v_mul_f32_e32 v21, v0, v21
	v_fma_f32 v22, v0, v5, -v22
	v_fmac_f32_e32 v21, v20, v5
	global_store_dword v[14:15], v22, off offset:56
	global_store_dword v[16:17], v21, off offset:56
	global_load_dword v5, v[10:11], off offset:60
	s_nop 0
	global_load_dword v10, v[12:13], off offset:60
	s_waitcnt vmcnt(0)
	v_mul_f32_e32 v11, v20, v10
	v_fma_f32 v11, v0, v5, -v11
	v_mul_f32_e32 v0, v0, v10
	v_fmac_f32_e32 v0, v20, v5
	global_store_dword v[14:15], v11, off offset:60
	global_store_dword v[16:17], v0, off offset:60
	s_andn2_b64 exec, exec, s[36:37]
	s_cbranch_execz .LBB0_857
